# scalar pointer updates moved from the six-DMA load segments into the preceding two-DMA segments
# baseline (speedup 1.0000x reference)
; #define PG8_STAGE(bufoff, gbase, voff) do { _Pragma("unroll") for (int _i = 0; _i < 2; ++_i) \
;         __builtin_amdgcn_global_load_lds((const unsigned*)((const char*)(gbase) + (voff)[_i]), (PG8_LAS unsigned*)(lds + (bufoff) + ldsw + _i * 8192), 16, 0, 0); } while (0)
; #define PG8_LDA(dst, b, h) do { _Pragma("unroll") for (int m = 0; m < 4; ++m) _Pragma("unroll") for (int k = 0; k < 2; ++k) dst[m][k] = *(const PG8_LAS bf16x8*)(lds + PG8_SA(b, h) + aoff + m * 2048 + k * 1024); } while (0)
; #define PG8_LDB(dst, b, h) do { _Pragma("unroll") for (int n = 0; n < 2; ++n) _Pragma("unroll") for (int k = 0; k < 2; ++k) dst[n][k] = *(const PG8_LAS bf16x8*)(lds + PG8_SB(b, h) + boff + n * 2048 + k * 1024); } while (0)
; #define PG8_MMA(ai, bj, At, Bt) do { __builtin_amdgcn_s_setprio(1); _Pragma("unroll") for (int m = 0; m < 4; ++m) _Pragma("unroll") for (int n = 0; n < 2; ++n) _Pragma("unroll") for (int k = 0; k < 2; ++k) \
;         acc[ai][bj][m][n] = __builtin_amdgcn_mfma_f32_16x16x32_bf16(Bt[n][k], At[m][k], acc[ai][bj][m][n], 0, 0, 0); __builtin_amdgcn_s_setprio(0); } while (0)
; #define PG8_BAR __builtin_amdgcn_s_barrier()
; template <class Epi, class Sched, bool ALIGN_EPI = false, bool SP2 = false>
; __device__ __forceinline__ void gemm_phase(PG8_LAS unsigned char* lds, const Gemm g, const Sched& S, const Epi& E) {
;     ...
;         const bool has_next = S.next(ui + 1, nxt);
;         const char* nA = has_next ? (const char*)g.A + (size_t)nxt.pm * tstep : cA; const char* nB = has_next ? (const char*)g.Bt + (size_t)nxt.pn * tstep : cB;
;         for (int t = 0; t < nt; t += 2) {
;             const bool last = (t == nt - 2);
;             const char* a1 = cA + (size_t)(t + 1) * kstep;
;             const char* a2 = last ? nA : cA + (size_t)(t + 2) * kstep; const char* b2 = last ? nB : cB + (size_t)(t + 2) * kstep;
;             const char* a3 = a2 + kstep; const char* b3 = b2 + kstep;
;             if (last && has_next) S.a_ready(nxt);
;             if constexpr (SP2) {
;             PG8_LDB(B0, 0, 0); PG8_LDB(B1, 0, 1); PG8_SCHED; PG8_LDA(At, 0, 0); PG8_STAGE(PG8_SA(1, 1), a1 + hstep, voffA);
;             PG8_WAIT_V(8); PG8_WAIT_L(0); PG8_BAR; PG8_MMA(0, 0, At, B0); PG8_MMA(0, 1, At, B1); PG8_BAR; PG8_SCHED;
;             PG8_LDA(At, 0, 1); PG8_STAGE(PG8_SB(0, 0), b2, voffB); PG8_STAGE(PG8_SB(0, 1), b2 + hstep, voffB); PG8_STAGE(PG8_SA(0, 0), a2, voffA);
.LBB0_128:
	s_ashr_i32 s25, s24, 31
	s_lshl_b64 s[28:29], s[24:25], 20
	v_readlane_b32 s30, v254, 51
	v_readlane_b32 s31, v254, 52
	s_add_u32 s28, s30, s28
	s_addc_u32 s29, s31, s29
	s_and_b64 s[30:31], s[26:27], exec
	s_cselect_b32 s25, s29, s9
	s_cselect_b32 s35, s28, s8
	s_ashr_i32 s23, s22, 31
	s_lshl_b64 s[30:31], s[22:23], 20
	s_add_u32 s30, s94, s30
	s_addc_u32 s31, s95, s31
	s_and_b64 s[46:47], s[26:27], exec
	s_cselect_b32 s23, s31, s45
	s_cselect_b32 s43, s30, s44
	s_add_u32 s8, s8, 0x80080
	s_addc_u32 s9, s9, 0
	s_add_u32 s48, s44, 0x100
	s_addc_u32 s49, s45, 0
	s_mov_b32 s54, -2
	s_waitcnt lgkmcnt(0)
	s_add_i32 s98, s62, 0x10000
	s_add_i32 s99, s62, 0x14000
	s_add_i32 s100, s62, 0x18000
	s_add_i32 s101, s62, 0x1c000
	ds_read_b128 v[96:99], v173
	ds_read_b128 v[100:103], v173 offset:1024
	ds_read_b128 v[104:107], v173 offset:2048
	ds_read_b128 v[112:115], v173 offset:3072
	ds_read_b128 v[178:181], v175
	ds_read_b128 v[182:185], v175 offset:1024
	ds_read_b128 v[186:189], v175 offset:2048
	ds_read_b128 v[190:193], v175 offset:3072
	s_add_u32 s44, s8, 0xfff80080
	s_addc_u32 s45, s9, -1
	s_cmp_eq_u32 s54, 28
	s_cselect_b32 s47, s25, s45
	s_cselect_b32 s46, s35, s44
	s_cselect_b32 s45, s23, s49
	s_cselect_b32 s44, s43, s48
	s_add_u32 s56, s44, 0x80000
	s_addc_u32 s57, s45, 0
	s_add_i32 m0, s63, 0xc000
	ds_read_b128 v[198:201], v177
	ds_read_b128 v[202:205], v177 offset:1024
	ds_read_b128 v[206:209], v177 offset:2048
	ds_read_b128 v[210:213], v177 offset:3072
	ds_read_b128 v[214:217], v177 offset:4096
	ds_read_b128 v[218:221], v177 offset:5120
	ds_read_b128 v[222:225], v177 offset:6144
	ds_read_b128 v[226:229], v177 offset:7168
	global_load_lds_dwordx4 v154, s[8:9]
	s_add_i32 m0, s63, 0xe000
	s_nop 0
	global_load_lds_dwordx4 v156, s[8:9]
	s_waitcnt lgkmcnt(0)
	s_setprio 1
	s_barrier
	v_mfma_f32_16x16x32_bf16 v[140:143], v[96:99], v[198:201], 0
	v_mfma_f32_16x16x32_bf16 v[132:135], v[104:107], v[198:201], 0
	v_mfma_f32_16x16x32_bf16 v[116:119], v[96:99], v[206:209], 0
	v_mfma_f32_16x16x32_bf16 v[124:127], v[104:107], v[206:209], 0
	v_mfma_f32_16x16x32_bf16 v[84:87], v[96:99], v[214:217], 0
	v_mfma_f32_16x16x32_bf16 v[92:95], v[104:107], v[214:217], 0
	v_mfma_f32_16x16x32_bf16 v[68:71], v[96:99], v[222:225], 0
	v_mfma_f32_16x16x32_bf16 v[76:79], v[104:107], v[222:225], 0
	v_mfma_f32_16x16x32_bf16 v[140:143], v[100:103], v[202:205], v[140:143]
	v_mfma_f32_16x16x32_bf16 v[132:135], v[112:115], v[202:205], v[132:135]
	v_mfma_f32_16x16x32_bf16 v[116:119], v[100:103], v[210:213], v[116:119]
	v_mfma_f32_16x16x32_bf16 v[124:127], v[112:115], v[210:213], v[124:127]
	v_mfma_f32_16x16x32_bf16 v[84:87], v[100:103], v[218:221], v[84:87]
	v_mfma_f32_16x16x32_bf16 v[92:95], v[112:115], v[218:221], v[92:95]
	v_mfma_f32_16x16x32_bf16 v[68:71], v[100:103], v[226:229], v[68:71]
	v_mfma_f32_16x16x32_bf16 v[76:79], v[112:115], v[226:229], v[76:79]
	v_mfma_f32_16x16x32_bf16 v[128:131], v[178:181], v[198:201], 0
	v_mfma_f32_16x16x32_bf16 v[136:139], v[186:189], v[198:201], 0
	v_mfma_f32_16x16x32_bf16 v[120:123], v[178:181], v[206:209], 0
	v_mfma_f32_16x16x32_bf16 v[108:111], v[186:189], v[206:209], 0
	v_mfma_f32_16x16x32_bf16 v[88:91], v[178:181], v[214:217], 0
	v_mfma_f32_16x16x32_bf16 v[80:83], v[186:189], v[214:217], 0
	v_mfma_f32_16x16x32_bf16 v[72:75], v[178:181], v[222:225], 0
	v_mfma_f32_16x16x32_bf16 v[64:67], v[186:189], v[222:225], 0
	v_mfma_f32_16x16x32_bf16 v[128:131], v[182:185], v[202:205], v[128:131]
	v_mfma_f32_16x16x32_bf16 v[136:139], v[190:193], v[202:205], v[136:139]
	v_mfma_f32_16x16x32_bf16 v[120:123], v[182:185], v[210:213], v[120:123]
	v_mfma_f32_16x16x32_bf16 v[108:111], v[190:193], v[210:213], v[108:111]
	v_mfma_f32_16x16x32_bf16 v[88:91], v[182:185], v[218:221], v[88:91]
	v_mfma_f32_16x16x32_bf16 v[80:83], v[190:193], v[218:221], v[80:83]
	v_mfma_f32_16x16x32_bf16 v[72:75], v[182:185], v[226:229], v[72:75]
	v_mfma_f32_16x16x32_bf16 v[64:67], v[190:193], v[226:229], v[64:67]
	s_barrier
	s_setprio 0
	v_lshl_add_u64 v[160:161], s[44:45], 0, v[144:145]
	s_mov_b32 m0, s98
	ds_read_b128 v[198:201], v177 offset:16384
	ds_read_b128 v[202:205], v177 offset:17408
	ds_read_b128 v[206:209], v177 offset:18432
	ds_read_b128 v[210:213], v177 offset:19456
	ds_read_b128 v[214:217], v177 offset:20480
	ds_read_b128 v[218:221], v177 offset:21504
	ds_read_b128 v[222:225], v177 offset:22528
	ds_read_b128 v[226:229], v177 offset:23552
	global_load_lds_dwordx4 v[160:161], off
	s_add_i32 m0, s98, 0x2000
	v_lshl_add_u64 v[164:165], s[44:45], 0, v[146:147]
	global_load_lds_dwordx4 v[164:165], off
	s_mov_b32 m0, s99
	v_lshl_add_u64 v[194:195], s[46:47], 0, v[146:147]
	global_load_lds_dwordx4 v144, s[56:57]
	s_add_i32 m0, s99, 0x2000
	s_nop 0
	global_load_lds_dwordx4 v146, s[56:57]
	s_mov_b32 m0, s63
	v_lshl_add_u64 v[170:171], s[46:47], 0, v[144:145]
	global_load_lds_dwordx4 v[170:171], off
	s_mov_b32 m0, s64
	s_nop 0
	global_load_lds_dwordx4 v[194:195], off
	s_waitcnt lgkmcnt(0)
	s_setprio 1
	s_barrier
; #define PG8_STAGE(bufoff, gbase, voff) do { _Pragma("unroll") for (int _i = 0; _i < 2; ++_i) \
;         __builtin_amdgcn_global_load_lds((const unsigned*)((const char*)(gbase) + (voff)[_i]), (PG8_LAS unsigned*)(lds + (bufoff) + ldsw + _i * 8192), 16, 0, 0); } while (0)
; #define PG8_LDA(dst, b, h) do { _Pragma("unroll") for (int m = 0; m < 4; ++m) _Pragma("unroll") for (int k = 0; k < 2; ++k) dst[m][k] = *(const PG8_LAS bf16x8*)(lds + PG8_SA(b, h) + aoff + m * 2048 + k * 1024); } while (0)
; #define PG8_LDB(dst, b, h) do { _Pragma("unroll") for (int n = 0; n < 2; ++n) _Pragma("unroll") for (int k = 0; k < 2; ++k) dst[n][k] = *(const PG8_LAS bf16x8*)(lds + PG8_SB(b, h) + boff + n * 2048 + k * 1024); } while (0)
; #define PG8_MMA(ai, bj, At, Bt) do { __builtin_amdgcn_s_setprio(1); _Pragma("unroll") for (int m = 0; m < 4; ++m) _Pragma("unroll") for (int n = 0; n < 2; ++n) _Pragma("unroll") for (int k = 0; k < 2; ++k) \
;         acc[ai][bj][m][n] = __builtin_amdgcn_mfma_f32_16x16x32_bf16(Bt[n][k], At[m][k], acc[ai][bj][m][n], 0, 0, 0); __builtin_amdgcn_s_setprio(0); } while (0)
; #define PG8_WAIT_V(n) asm volatile("s_waitcnt vmcnt(" #n ")" ::: "memory")
; #define PG8_WAIT_L(n) asm volatile("s_waitcnt lgkmcnt(" #n ")" ::: "memory")
; #define PG8_BAR __builtin_amdgcn_s_barrier()
; #define PG8_SCHED __builtin_amdgcn_sched_barrier(0)
; template <class Epi, class Sched, bool ALIGN_EPI = false, bool SP2 = false>
; __device__ __forceinline__ void gemm_phase(PG8_LAS unsigned char* lds, const Gemm g, const Sched& S, const Epi& E) {
;     ...
;             PG8_WAIT_V(8); PG8_WAIT_L(0); PG8_BAR; PG8_MMA(1, 0, At, B0); PG8_MMA(1, 1, At, B1); PG8_BAR; PG8_SCHED;
;             PG8_LDB(B0, 1, 0); PG8_LDB(B1, 1, 1); PG8_SCHED; PG8_LDA(At, 1, 0); PG8_STAGE(PG8_SA(0, 1), a2 + hstep, voffA);
;             PG8_WAIT_V(8); PG8_WAIT_L(0); PG8_BAR; PG8_MMA(0, 0, At, B0); PG8_MMA(0, 1, At, B1); PG8_BAR; PG8_SCHED;
	v_mfma_f32_16x16x32_bf16 v[60:63], v[96:99], v[198:201], 0
	v_mfma_f32_16x16x32_bf16 v[52:55], v[104:107], v[198:201], 0
	v_mfma_f32_16x16x32_bf16 v[36:39], v[96:99], v[206:209], 0
	v_mfma_f32_16x16x32_bf16 v[44:47], v[104:107], v[206:209], 0
	v_mfma_f32_16x16x32_bf16 v[20:23], v[96:99], v[214:217], 0
	v_mfma_f32_16x16x32_bf16 v[28:31], v[104:107], v[214:217], 0
	v_mfma_f32_16x16x32_bf16 v[4:7], v[96:99], v[222:225], 0
	v_mfma_f32_16x16x32_bf16 v[12:15], v[104:107], v[222:225], 0
	v_mfma_f32_16x16x32_bf16 v[60:63], v[100:103], v[202:205], v[60:63]
	v_mfma_f32_16x16x32_bf16 v[52:55], v[112:115], v[202:205], v[52:55]
	v_mfma_f32_16x16x32_bf16 v[36:39], v[100:103], v[210:213], v[36:39]
	v_mfma_f32_16x16x32_bf16 v[44:47], v[112:115], v[210:213], v[44:47]
	v_mfma_f32_16x16x32_bf16 v[20:23], v[100:103], v[218:221], v[20:23]
	v_mfma_f32_16x16x32_bf16 v[28:31], v[112:115], v[218:221], v[28:31]
	v_mfma_f32_16x16x32_bf16 v[4:7], v[100:103], v[226:229], v[4:7]
	v_mfma_f32_16x16x32_bf16 v[12:15], v[112:115], v[226:229], v[12:15]
	v_mfma_f32_16x16x32_bf16 v[48:51], v[178:181], v[198:201], 0
	v_mfma_f32_16x16x32_bf16 v[56:59], v[186:189], v[198:201], 0
	v_mfma_f32_16x16x32_bf16 v[40:43], v[178:181], v[206:209], 0
	v_mfma_f32_16x16x32_bf16 v[32:35], v[186:189], v[206:209], 0
	v_mfma_f32_16x16x32_bf16 v[24:27], v[178:181], v[214:217], 0
	v_mfma_f32_16x16x32_bf16 v[16:19], v[186:189], v[214:217], 0
	v_mfma_f32_16x16x32_bf16 v[8:11], v[178:181], v[222:225], 0
	v_mfma_f32_16x16x32_bf16 v[0:3], v[186:189], v[222:225], 0
	v_mfma_f32_16x16x32_bf16 v[48:51], v[182:185], v[202:205], v[48:51]
	v_mfma_f32_16x16x32_bf16 v[56:59], v[190:193], v[202:205], v[56:59]
	v_mfma_f32_16x16x32_bf16 v[40:43], v[182:185], v[210:213], v[40:43]
	v_mfma_f32_16x16x32_bf16 v[32:35], v[190:193], v[210:213], v[32:35]
	v_mfma_f32_16x16x32_bf16 v[24:27], v[182:185], v[218:221], v[24:27]
	v_mfma_f32_16x16x32_bf16 v[16:19], v[190:193], v[218:221], v[16:19]
	v_mfma_f32_16x16x32_bf16 v[8:11], v[182:185], v[226:229], v[8:11]
	v_mfma_f32_16x16x32_bf16 v[0:3], v[190:193], v[226:229], v[0:3]
	s_barrier
	s_setprio 0
	s_add_i32 s55, 0, 0x18000
	s_add_i32 s56, 0, 0x1c000
	v_add_u32_e32 v112, s55, v167
	v_add_u32_e32 v162, s56, v167
	ds_read_b128 v[96:99], v112
	ds_read_b128 v[100:103], v112 offset:1024
	ds_read_b128 v[104:107], v112 offset:2048
	ds_read_b128 v[112:115], v112 offset:3072
	ds_read_b128 v[178:181], v162
	ds_read_b128 v[182:185], v162 offset:1024
	ds_read_b128 v[186:189], v162 offset:2048
	ds_read_b128 v[190:193], v162 offset:3072
	s_add_u32 s46, s46, 0x80000
	s_addc_u32 s47, s47, 0
	s_add_u32 s44, s44, 0x80080
	s_addc_u32 s45, s45, 0
	s_mov_b32 m0, s65
	ds_read_b128 v[198:201], v177 offset:32768
	ds_read_b128 v[202:205], v177 offset:33792
	ds_read_b128 v[206:209], v177 offset:34816
	ds_read_b128 v[210:213], v177 offset:35840
	ds_read_b128 v[214:217], v177 offset:36864
	ds_read_b128 v[218:221], v177 offset:37888
	ds_read_b128 v[222:225], v177 offset:38912
	ds_read_b128 v[226:229], v177 offset:39936
	global_load_lds_dwordx4 v144, s[46:47]
	s_mov_b32 m0, s66
	v_lshl_add_u64 v[230:231], s[46:47], 0, v[146:147]
	global_load_lds_dwordx4 v[230:231], off
	s_waitcnt vmcnt(8) lgkmcnt(0)
	s_setprio 1
	s_barrier
	v_mfma_f32_16x16x32_bf16 v[140:143], v[96:99], v[198:201], v[140:143]
	v_mfma_f32_16x16x32_bf16 v[132:135], v[104:107], v[198:201], v[132:135]
	v_mfma_f32_16x16x32_bf16 v[116:119], v[96:99], v[206:209], v[116:119]
	v_mfma_f32_16x16x32_bf16 v[124:127], v[104:107], v[206:209], v[124:127]
	v_mfma_f32_16x16x32_bf16 v[84:87], v[96:99], v[214:217], v[84:87]
	v_mfma_f32_16x16x32_bf16 v[92:95], v[104:107], v[214:217], v[92:95]
	v_mfma_f32_16x16x32_bf16 v[68:71], v[96:99], v[222:225], v[68:71]
	v_mfma_f32_16x16x32_bf16 v[76:79], v[104:107], v[222:225], v[76:79]
	v_mfma_f32_16x16x32_bf16 v[140:143], v[100:103], v[202:205], v[140:143]
	v_mfma_f32_16x16x32_bf16 v[132:135], v[112:115], v[202:205], v[132:135]
	v_mfma_f32_16x16x32_bf16 v[116:119], v[100:103], v[210:213], v[116:119]
	v_mfma_f32_16x16x32_bf16 v[124:127], v[112:115], v[210:213], v[124:127]
	v_mfma_f32_16x16x32_bf16 v[84:87], v[100:103], v[218:221], v[84:87]
	v_mfma_f32_16x16x32_bf16 v[92:95], v[112:115], v[218:221], v[92:95]
	v_mfma_f32_16x16x32_bf16 v[68:71], v[100:103], v[226:229], v[68:71]
	v_mfma_f32_16x16x32_bf16 v[76:79], v[112:115], v[226:229], v[76:79]
	v_mfma_f32_16x16x32_bf16 v[128:131], v[178:181], v[198:201], v[128:131]
	v_mfma_f32_16x16x32_bf16 v[136:139], v[186:189], v[198:201], v[136:139]
	v_mfma_f32_16x16x32_bf16 v[120:123], v[178:181], v[206:209], v[120:123]
	v_mfma_f32_16x16x32_bf16 v[108:111], v[186:189], v[206:209], v[108:111]
	v_mfma_f32_16x16x32_bf16 v[88:91], v[178:181], v[214:217], v[88:91]
	v_mfma_f32_16x16x32_bf16 v[80:83], v[186:189], v[214:217], v[80:83]
	v_mfma_f32_16x16x32_bf16 v[72:75], v[178:181], v[222:225], v[72:75]
	v_mfma_f32_16x16x32_bf16 v[64:67], v[186:189], v[222:225], v[64:67]
	v_mfma_f32_16x16x32_bf16 v[128:131], v[182:185], v[202:205], v[128:131]
	v_mfma_f32_16x16x32_bf16 v[136:139], v[190:193], v[202:205], v[136:139]
	v_mfma_f32_16x16x32_bf16 v[120:123], v[182:185], v[210:213], v[120:123]
	v_mfma_f32_16x16x32_bf16 v[108:111], v[190:193], v[210:213], v[108:111]
	v_mfma_f32_16x16x32_bf16 v[88:91], v[182:185], v[218:221], v[88:91]
	v_mfma_f32_16x16x32_bf16 v[80:83], v[190:193], v[218:221], v[80:83]
	v_mfma_f32_16x16x32_bf16 v[72:75], v[182:185], v[226:229], v[72:75]
	v_mfma_f32_16x16x32_bf16 v[64:67], v[190:193], v[226:229], v[64:67]
	s_barrier
; #define PG8_STAGE(bufoff, gbase, voff) do { _Pragma("unroll") for (int _i = 0; _i < 2; ++_i) \
;         __builtin_amdgcn_global_load_lds((const unsigned*)((const char*)(gbase) + (voff)[_i]), (PG8_LAS unsigned*)(lds + (bufoff) + ldsw + _i * 8192), 16, 0, 0); } while (0)
; #define PG8_LDA(dst, b, h) do { _Pragma("unroll") for (int m = 0; m < 4; ++m) _Pragma("unroll") for (int k = 0; k < 2; ++k) dst[m][k] = *(const PG8_LAS bf16x8*)(lds + PG8_SA(b, h) + aoff + m * 2048 + k * 1024); } while (0)
; #define PG8_LDB(dst, b, h) do { _Pragma("unroll") for (int n = 0; n < 2; ++n) _Pragma("unroll") for (int k = 0; k < 2; ++k) dst[n][k] = *(const PG8_LAS bf16x8*)(lds + PG8_SB(b, h) + boff + n * 2048 + k * 1024); } while (0)
; #define PG8_MMA(ai, bj, At, Bt) do { __builtin_amdgcn_s_setprio(1); _Pragma("unroll") for (int m = 0; m < 4; ++m) _Pragma("unroll") for (int n = 0; n < 2; ++n) _Pragma("unroll") for (int k = 0; k < 2; ++k) \
;         acc[ai][bj][m][n] = __builtin_amdgcn_mfma_f32_16x16x32_bf16(Bt[n][k], At[m][k], acc[ai][bj][m][n], 0, 0, 0); __builtin_amdgcn_s_setprio(0); } while (0)
; #define PG8_WAIT_V(n) asm volatile("s_waitcnt vmcnt(" #n ")" ::: "memory")
; #define PG8_BAR __builtin_amdgcn_s_barrier()
; template <class Epi, class Sched, bool ALIGN_EPI = false, bool SP2 = false>
; __device__ __forceinline__ void gemm_phase(PG8_LAS unsigned char* lds, const Gemm g, const Sched& S, const Epi& E) {
;     ...
;         for (int t = 0; t < nt; t += 2) {
;             const bool last = (t == nt - 2);
;             const char* a1 = cA + (size_t)(t + 1) * kstep;
;             const char* a2 = last ? nA : cA + (size_t)(t + 2) * kstep; const char* b2 = last ? nB : cB + (size_t)(t + 2) * kstep;
;             const char* a3 = a2 + kstep; const char* b3 = b2 + kstep;
;             if (last && has_next) S.a_ready(nxt);
;             if constexpr (SP2) {
;             PG8_LDB(B0, 0, 0); PG8_LDB(B1, 0, 1); PG8_SCHED; PG8_LDA(At, 0, 0); PG8_STAGE(PG8_SA(1, 1), a1 + hstep, voffA);
;             PG8_WAIT_V(8); PG8_WAIT_L(0); PG8_BAR; PG8_MMA(0, 0, At, B0); PG8_MMA(0, 1, At, B1); PG8_BAR; PG8_SCHED;
;     ...
;             PG8_LDA(At, 1, 1); PG8_STAGE(PG8_SB(1, 0), b3, voffB); PG8_STAGE(PG8_SB(1, 1), b3 + hstep, voffB); PG8_STAGE(PG8_SA(1, 0), a3, voffA);
;             PG8_WAIT_V(8); PG8_WAIT_L(0); PG8_BAR; PG8_MMA(1, 0, At, B0); PG8_MMA(1, 1, At, B1); PG8_BAR; PG8_SCHED;
	s_setprio 0
	v_lshl_add_u64 v[160:161], v[160:161], 0, s[12:13]
	s_mov_b32 m0, s100
	ds_read_b128 v[198:201], v177 offset:49152
	ds_read_b128 v[202:205], v177 offset:50176
	ds_read_b128 v[206:209], v177 offset:51200
	ds_read_b128 v[210:213], v177 offset:52224
	ds_read_b128 v[214:217], v177 offset:53248
	ds_read_b128 v[218:221], v177 offset:54272
	ds_read_b128 v[222:225], v177 offset:55296
	ds_read_b128 v[226:229], v177 offset:56320
	global_load_lds_dwordx4 v[160:161], off
	s_add_i32 m0, s100, 0x2000
	v_lshl_add_u64 v[160:161], v[164:165], 0, s[12:13]
	global_load_lds_dwordx4 v[160:161], off
	s_mov_b32 m0, s101
	s_nop 0
	global_load_lds_dwordx4 v144, s[44:45]
	s_add_i32 m0, s101, 0x2000
	v_lshl_add_u64 v[160:161], s[44:45], 0, v[146:147]
	global_load_lds_dwordx4 v[160:161], off
	s_mov_b32 m0, s68
	v_lshl_add_u64 v[160:161], v[170:171], 0, s[12:13]
	global_load_lds_dwordx4 v[160:161], off
	s_mov_b32 m0, s69
	v_lshl_add_u64 v[160:161], v[194:195], 0, s[12:13]
	global_load_lds_dwordx4 v[160:161], off
	s_waitcnt vmcnt(8) lgkmcnt(0)
	s_setprio 1
	s_barrier
	v_mfma_f32_16x16x32_bf16 v[60:63], v[96:99], v[198:201], v[60:63]
	v_mfma_f32_16x16x32_bf16 v[52:55], v[104:107], v[198:201], v[52:55]
	v_mfma_f32_16x16x32_bf16 v[36:39], v[96:99], v[206:209], v[36:39]
	v_mfma_f32_16x16x32_bf16 v[44:47], v[104:107], v[206:209], v[44:47]
	v_mfma_f32_16x16x32_bf16 v[20:23], v[96:99], v[214:217], v[20:23]
	v_mfma_f32_16x16x32_bf16 v[28:31], v[104:107], v[214:217], v[28:31]
	v_mfma_f32_16x16x32_bf16 v[4:7], v[96:99], v[222:225], v[4:7]
	v_mfma_f32_16x16x32_bf16 v[12:15], v[104:107], v[222:225], v[12:15]
	v_mfma_f32_16x16x32_bf16 v[60:63], v[100:103], v[202:205], v[60:63]
	v_mfma_f32_16x16x32_bf16 v[52:55], v[112:115], v[202:205], v[52:55]
	v_mfma_f32_16x16x32_bf16 v[36:39], v[100:103], v[210:213], v[36:39]
	v_mfma_f32_16x16x32_bf16 v[44:47], v[112:115], v[210:213], v[44:47]
	v_mfma_f32_16x16x32_bf16 v[20:23], v[100:103], v[218:221], v[20:23]
	v_mfma_f32_16x16x32_bf16 v[28:31], v[112:115], v[218:221], v[28:31]
	v_mfma_f32_16x16x32_bf16 v[4:7], v[100:103], v[226:229], v[4:7]
	v_mfma_f32_16x16x32_bf16 v[12:15], v[112:115], v[226:229], v[12:15]
	v_mfma_f32_16x16x32_bf16 v[48:51], v[178:181], v[198:201], v[48:51]
	v_mfma_f32_16x16x32_bf16 v[56:59], v[186:189], v[198:201], v[56:59]
	v_mfma_f32_16x16x32_bf16 v[40:43], v[178:181], v[206:209], v[40:43]
	v_mfma_f32_16x16x32_bf16 v[32:35], v[186:189], v[206:209], v[32:35]
	v_mfma_f32_16x16x32_bf16 v[24:27], v[178:181], v[214:217], v[24:27]
	v_mfma_f32_16x16x32_bf16 v[16:19], v[186:189], v[214:217], v[16:19]
	v_mfma_f32_16x16x32_bf16 v[8:11], v[178:181], v[222:225], v[8:11]
	v_mfma_f32_16x16x32_bf16 v[0:3], v[186:189], v[222:225], v[0:3]
	v_mfma_f32_16x16x32_bf16 v[48:51], v[182:185], v[202:205], v[48:51]
	v_mfma_f32_16x16x32_bf16 v[56:59], v[190:193], v[202:205], v[56:59]
	v_mfma_f32_16x16x32_bf16 v[40:43], v[182:185], v[210:213], v[40:43]
	v_mfma_f32_16x16x32_bf16 v[32:35], v[190:193], v[210:213], v[32:35]
	v_mfma_f32_16x16x32_bf16 v[24:27], v[182:185], v[218:221], v[24:27]
	v_mfma_f32_16x16x32_bf16 v[16:19], v[190:193], v[218:221], v[16:19]
	v_mfma_f32_16x16x32_bf16 v[8:11], v[182:185], v[226:229], v[8:11]
	v_mfma_f32_16x16x32_bf16 v[0:3], v[190:193], v[226:229], v[0:3]
	s_barrier
	s_setprio 0
	s_add_i32 s54, s54, 2
	s_add_u32 s8, s8, 0x100
	s_addc_u32 s9, s9, 0
	s_add_u32 s48, s48, 0x100
	s_addc_u32 s49, s49, 0
.LBB0_129:
	ds_read_b128 v[96:99], v173
	ds_read_b128 v[100:103], v173 offset:1024
	ds_read_b128 v[104:107], v173 offset:2048
	ds_read_b128 v[112:115], v173 offset:3072
	ds_read_b128 v[178:181], v175
	ds_read_b128 v[182:185], v175 offset:1024
	ds_read_b128 v[186:189], v175 offset:2048
	ds_read_b128 v[190:193], v175 offset:3072
	s_add_u32 s44, s8, 0xfff80080
	s_addc_u32 s45, s9, -1
	s_cmp_eq_u32 s54, 28
	s_cselect_b32 s47, s25, s45
	s_cselect_b32 s46, s35, s44
	s_cselect_b32 s45, s23, s49
	s_cselect_b32 s44, s43, s48
	s_add_u32 s56, s44, 0x80000
	s_addc_u32 s57, s45, 0
	s_add_i32 m0, s63, 0xc000
	ds_read_b128 v[198:201], v177
	ds_read_b128 v[202:205], v177 offset:1024
	ds_read_b128 v[206:209], v177 offset:2048
	ds_read_b128 v[210:213], v177 offset:3072
	ds_read_b128 v[214:217], v177 offset:4096
	ds_read_b128 v[218:221], v177 offset:5120
	ds_read_b128 v[222:225], v177 offset:6144
	ds_read_b128 v[226:229], v177 offset:7168
	global_load_lds_dwordx4 v154, s[8:9]
	s_add_i32 m0, s63, 0xe000
	s_nop 0
	global_load_lds_dwordx4 v156, s[8:9]
	s_waitcnt vmcnt(8) lgkmcnt(0)
	s_setprio 1
	s_barrier
	v_mfma_f32_16x16x32_bf16 v[140:143], v[96:99], v[198:201], v[140:143]
	v_mfma_f32_16x16x32_bf16 v[132:135], v[104:107], v[198:201], v[132:135]
	v_mfma_f32_16x16x32_bf16 v[116:119], v[96:99], v[206:209], v[116:119]
	v_mfma_f32_16x16x32_bf16 v[124:127], v[104:107], v[206:209], v[124:127]
	v_mfma_f32_16x16x32_bf16 v[84:87], v[96:99], v[214:217], v[84:87]
	v_mfma_f32_16x16x32_bf16 v[92:95], v[104:107], v[214:217], v[92:95]
	v_mfma_f32_16x16x32_bf16 v[68:71], v[96:99], v[222:225], v[68:71]
	v_mfma_f32_16x16x32_bf16 v[76:79], v[104:107], v[222:225], v[76:79]
	v_mfma_f32_16x16x32_bf16 v[140:143], v[100:103], v[202:205], v[140:143]
	v_mfma_f32_16x16x32_bf16 v[132:135], v[112:115], v[202:205], v[132:135]
	v_mfma_f32_16x16x32_bf16 v[116:119], v[100:103], v[210:213], v[116:119]
	v_mfma_f32_16x16x32_bf16 v[124:127], v[112:115], v[210:213], v[124:127]
	v_mfma_f32_16x16x32_bf16 v[84:87], v[100:103], v[218:221], v[84:87]
	v_mfma_f32_16x16x32_bf16 v[92:95], v[112:115], v[218:221], v[92:95]
	v_mfma_f32_16x16x32_bf16 v[68:71], v[100:103], v[226:229], v[68:71]
	v_mfma_f32_16x16x32_bf16 v[76:79], v[112:115], v[226:229], v[76:79]
	v_mfma_f32_16x16x32_bf16 v[128:131], v[178:181], v[198:201], v[128:131]
	v_mfma_f32_16x16x32_bf16 v[136:139], v[186:189], v[198:201], v[136:139]
	v_mfma_f32_16x16x32_bf16 v[120:123], v[178:181], v[206:209], v[120:123]
	v_mfma_f32_16x16x32_bf16 v[108:111], v[186:189], v[206:209], v[108:111]
	v_mfma_f32_16x16x32_bf16 v[88:91], v[178:181], v[214:217], v[88:91]
	v_mfma_f32_16x16x32_bf16 v[80:83], v[186:189], v[214:217], v[80:83]
	v_mfma_f32_16x16x32_bf16 v[72:75], v[178:181], v[222:225], v[72:75]
	v_mfma_f32_16x16x32_bf16 v[64:67], v[186:189], v[222:225], v[64:67]
	v_mfma_f32_16x16x32_bf16 v[128:131], v[182:185], v[202:205], v[128:131]
	v_mfma_f32_16x16x32_bf16 v[136:139], v[190:193], v[202:205], v[136:139]
	v_mfma_f32_16x16x32_bf16 v[120:123], v[182:185], v[210:213], v[120:123]
	v_mfma_f32_16x16x32_bf16 v[108:111], v[190:193], v[210:213], v[108:111]
	v_mfma_f32_16x16x32_bf16 v[88:91], v[182:185], v[218:221], v[88:91]
	v_mfma_f32_16x16x32_bf16 v[80:83], v[190:193], v[218:221], v[80:83]
	v_mfma_f32_16x16x32_bf16 v[72:75], v[182:185], v[226:229], v[72:75]
	v_mfma_f32_16x16x32_bf16 v[64:67], v[190:193], v[226:229], v[64:67]
	s_barrier
; #define PG8_STAGE(bufoff, gbase, voff) do { _Pragma("unroll") for (int _i = 0; _i < 2; ++_i) \
;         __builtin_amdgcn_global_load_lds((const unsigned*)((const char*)(gbase) + (voff)[_i]), (PG8_LAS unsigned*)(lds + (bufoff) + ldsw + _i * 8192), 16, 0, 0); } while (0)
; #define PG8_LDA(dst, b, h) do { _Pragma("unroll") for (int m = 0; m < 4; ++m) _Pragma("unroll") for (int k = 0; k < 2; ++k) dst[m][k] = *(const PG8_LAS bf16x8*)(lds + PG8_SA(b, h) + aoff + m * 2048 + k * 1024); } while (0)
; #define PG8_LDB(dst, b, h) do { _Pragma("unroll") for (int n = 0; n < 2; ++n) _Pragma("unroll") for (int k = 0; k < 2; ++k) dst[n][k] = *(const PG8_LAS bf16x8*)(lds + PG8_SB(b, h) + boff + n * 2048 + k * 1024); } while (0)
; #define PG8_MMA(ai, bj, At, Bt) do { __builtin_amdgcn_s_setprio(1); _Pragma("unroll") for (int m = 0; m < 4; ++m) _Pragma("unroll") for (int n = 0; n < 2; ++n) _Pragma("unroll") for (int k = 0; k < 2; ++k) \
;         acc[ai][bj][m][n] = __builtin_amdgcn_mfma_f32_16x16x32_bf16(Bt[n][k], At[m][k], acc[ai][bj][m][n], 0, 0, 0); __builtin_amdgcn_s_setprio(0); } while (0)
; #define PG8_WAIT_V(n) asm volatile("s_waitcnt vmcnt(" #n ")" ::: "memory")
; #define PG8_WAIT_L(n) asm volatile("s_waitcnt lgkmcnt(" #n ")" ::: "memory")
; #define PG8_BAR __builtin_amdgcn_s_barrier()
; #define PG8_SCHED __builtin_amdgcn_sched_barrier(0)
; template <class Epi, class Sched, bool ALIGN_EPI = false, bool SP2 = false>
; __device__ __forceinline__ void gemm_phase(PG8_LAS unsigned char* lds, const Gemm g, const Sched& S, const Epi& E) {
;     ...
;             PG8_LDA(At, 0, 1); PG8_STAGE(PG8_SB(0, 0), b2, voffB); PG8_STAGE(PG8_SB(0, 1), b2 + hstep, voffB); PG8_STAGE(PG8_SA(0, 0), a2, voffA);
;             PG8_WAIT_V(8); PG8_WAIT_L(0); PG8_BAR; PG8_MMA(1, 0, At, B0); PG8_MMA(1, 1, At, B1); PG8_BAR; PG8_SCHED;
;             PG8_LDB(B0, 1, 0); PG8_LDB(B1, 1, 1); PG8_SCHED; PG8_LDA(At, 1, 0); PG8_STAGE(PG8_SA(0, 1), a2 + hstep, voffA);
;             PG8_WAIT_V(8); PG8_WAIT_L(0); PG8_BAR; PG8_MMA(0, 0, At, B0); PG8_MMA(0, 1, At, B1); PG8_BAR; PG8_SCHED;
	s_setprio 0
	v_lshl_add_u64 v[160:161], s[44:45], 0, v[144:145]
	s_mov_b32 m0, s98
	ds_read_b128 v[198:201], v177 offset:16384
	ds_read_b128 v[202:205], v177 offset:17408
	ds_read_b128 v[206:209], v177 offset:18432
	ds_read_b128 v[210:213], v177 offset:19456
	ds_read_b128 v[214:217], v177 offset:20480
	ds_read_b128 v[218:221], v177 offset:21504
	ds_read_b128 v[222:225], v177 offset:22528
	ds_read_b128 v[226:229], v177 offset:23552
	global_load_lds_dwordx4 v[160:161], off
	s_add_i32 m0, s98, 0x2000
	v_lshl_add_u64 v[164:165], s[44:45], 0, v[146:147]
	global_load_lds_dwordx4 v[164:165], off
	s_mov_b32 m0, s99
	v_lshl_add_u64 v[194:195], s[46:47], 0, v[146:147]
	global_load_lds_dwordx4 v144, s[56:57]
	s_add_i32 m0, s99, 0x2000
	s_nop 0
	global_load_lds_dwordx4 v146, s[56:57]
	s_mov_b32 m0, s63
	v_lshl_add_u64 v[170:171], s[46:47], 0, v[144:145]
	global_load_lds_dwordx4 v[170:171], off
	s_mov_b32 m0, s64
	s_nop 0
	global_load_lds_dwordx4 v[194:195], off
	s_waitcnt vmcnt(8) lgkmcnt(0)
	s_setprio 1
	s_barrier
	v_mfma_f32_16x16x32_bf16 v[60:63], v[96:99], v[198:201], v[60:63]
	v_mfma_f32_16x16x32_bf16 v[52:55], v[104:107], v[198:201], v[52:55]
	v_mfma_f32_16x16x32_bf16 v[36:39], v[96:99], v[206:209], v[36:39]
	v_mfma_f32_16x16x32_bf16 v[44:47], v[104:107], v[206:209], v[44:47]
	v_mfma_f32_16x16x32_bf16 v[20:23], v[96:99], v[214:217], v[20:23]
	v_mfma_f32_16x16x32_bf16 v[28:31], v[104:107], v[214:217], v[28:31]
	v_mfma_f32_16x16x32_bf16 v[4:7], v[96:99], v[222:225], v[4:7]
	v_mfma_f32_16x16x32_bf16 v[12:15], v[104:107], v[222:225], v[12:15]
	v_mfma_f32_16x16x32_bf16 v[60:63], v[100:103], v[202:205], v[60:63]
	v_mfma_f32_16x16x32_bf16 v[52:55], v[112:115], v[202:205], v[52:55]
	v_mfma_f32_16x16x32_bf16 v[36:39], v[100:103], v[210:213], v[36:39]
	v_mfma_f32_16x16x32_bf16 v[44:47], v[112:115], v[210:213], v[44:47]
	v_mfma_f32_16x16x32_bf16 v[20:23], v[100:103], v[218:221], v[20:23]
	v_mfma_f32_16x16x32_bf16 v[28:31], v[112:115], v[218:221], v[28:31]
	v_mfma_f32_16x16x32_bf16 v[4:7], v[100:103], v[226:229], v[4:7]
	v_mfma_f32_16x16x32_bf16 v[12:15], v[112:115], v[226:229], v[12:15]
	v_mfma_f32_16x16x32_bf16 v[48:51], v[178:181], v[198:201], v[48:51]
	v_mfma_f32_16x16x32_bf16 v[56:59], v[186:189], v[198:201], v[56:59]
	v_mfma_f32_16x16x32_bf16 v[40:43], v[178:181], v[206:209], v[40:43]
	v_mfma_f32_16x16x32_bf16 v[32:35], v[186:189], v[206:209], v[32:35]
	v_mfma_f32_16x16x32_bf16 v[24:27], v[178:181], v[214:217], v[24:27]
	v_mfma_f32_16x16x32_bf16 v[16:19], v[186:189], v[214:217], v[16:19]
	v_mfma_f32_16x16x32_bf16 v[8:11], v[178:181], v[222:225], v[8:11]
	v_mfma_f32_16x16x32_bf16 v[0:3], v[186:189], v[222:225], v[0:3]
	v_mfma_f32_16x16x32_bf16 v[48:51], v[182:185], v[202:205], v[48:51]
	v_mfma_f32_16x16x32_bf16 v[56:59], v[190:193], v[202:205], v[56:59]
	v_mfma_f32_16x16x32_bf16 v[40:43], v[182:185], v[210:213], v[40:43]
	v_mfma_f32_16x16x32_bf16 v[32:35], v[190:193], v[210:213], v[32:35]
	v_mfma_f32_16x16x32_bf16 v[24:27], v[182:185], v[218:221], v[24:27]
	v_mfma_f32_16x16x32_bf16 v[16:19], v[190:193], v[218:221], v[16:19]
	v_mfma_f32_16x16x32_bf16 v[8:11], v[182:185], v[226:229], v[8:11]
	v_mfma_f32_16x16x32_bf16 v[0:3], v[190:193], v[226:229], v[0:3]
	s_barrier
	s_setprio 0
	s_add_i32 s55, 0, 0x18000
	s_add_i32 s56, 0, 0x1c000
	v_add_u32_e32 v112, s55, v167
	v_add_u32_e32 v162, s56, v167
	ds_read_b128 v[96:99], v112
	ds_read_b128 v[100:103], v112 offset:1024
	ds_read_b128 v[104:107], v112 offset:2048
	ds_read_b128 v[112:115], v112 offset:3072
	ds_read_b128 v[178:181], v162
	ds_read_b128 v[182:185], v162 offset:1024
	ds_read_b128 v[186:189], v162 offset:2048
	ds_read_b128 v[190:193], v162 offset:3072
	s_add_u32 s46, s46, 0x80000
	s_addc_u32 s47, s47, 0
	s_add_u32 s44, s44, 0x80080
	s_addc_u32 s45, s45, 0
	s_mov_b32 m0, s65
	ds_read_b128 v[198:201], v177 offset:32768
	ds_read_b128 v[202:205], v177 offset:33792
	ds_read_b128 v[206:209], v177 offset:34816
	ds_read_b128 v[210:213], v177 offset:35840
	ds_read_b128 v[214:217], v177 offset:36864
	ds_read_b128 v[218:221], v177 offset:37888
	ds_read_b128 v[222:225], v177 offset:38912
	ds_read_b128 v[226:229], v177 offset:39936
	global_load_lds_dwordx4 v144, s[46:47]
	s_mov_b32 m0, s66
	s_nop 0
	global_load_lds_dwordx4 v146, s[46:47]
	s_waitcnt vmcnt(8) lgkmcnt(0)
	s_setprio 1
	s_barrier
; #define PG8_STAGE(bufoff, gbase, voff) do { _Pragma("unroll") for (int _i = 0; _i < 2; ++_i) \
;         __builtin_amdgcn_global_load_lds((const unsigned*)((const char*)(gbase) + (voff)[_i]), (PG8_LAS unsigned*)(lds + (bufoff) + ldsw + _i * 8192), 16, 0, 0); } while (0)
; #define PG8_LDA(dst, b, h) do { _Pragma("unroll") for (int m = 0; m < 4; ++m) _Pragma("unroll") for (int k = 0; k < 2; ++k) dst[m][k] = *(const PG8_LAS bf16x8*)(lds + PG8_SA(b, h) + aoff + m * 2048 + k * 1024); } while (0)
; #define PG8_MMA(ai, bj, At, Bt) do { __builtin_amdgcn_s_setprio(1); _Pragma("unroll") for (int m = 0; m < 4; ++m) _Pragma("unroll") for (int n = 0; n < 2; ++n) _Pragma("unroll") for (int k = 0; k < 2; ++k) \
;         acc[ai][bj][m][n] = __builtin_amdgcn_mfma_f32_16x16x32_bf16(Bt[n][k], At[m][k], acc[ai][bj][m][n], 0, 0, 0); __builtin_amdgcn_s_setprio(0); } while (0)
; #define PG8_WAIT_V(n) asm volatile("s_waitcnt vmcnt(" #n ")" ::: "memory")
; #define PG8_WAIT_L(n) asm volatile("s_waitcnt lgkmcnt(" #n ")" ::: "memory")
; #define PG8_BAR __builtin_amdgcn_s_barrier()
; #define PG8_SCHED __builtin_amdgcn_sched_barrier(0)
; template <class Epi, class Sched, bool ALIGN_EPI = false, bool SP2 = false>
; __device__ __forceinline__ void gemm_phase(PG8_LAS unsigned char* lds, const Gemm g, const Sched& S, const Epi& E) {
;     ...
;             PG8_WAIT_V(8); PG8_WAIT_L(0); PG8_BAR; PG8_MMA(0, 0, At, B0); PG8_MMA(0, 1, At, B1); PG8_BAR; PG8_SCHED;
;             PG8_LDA(At, 1, 1); PG8_STAGE(PG8_SB(1, 0), b3, voffB); PG8_STAGE(PG8_SB(1, 1), b3 + hstep, voffB); PG8_STAGE(PG8_SA(1, 0), a3, voffA);
;             PG8_WAIT_V(8); PG8_WAIT_L(0); PG8_BAR; PG8_MMA(1, 0, At, B0); PG8_MMA(1, 1, At, B1); PG8_BAR; PG8_SCHED;
	v_mfma_f32_16x16x32_bf16 v[140:143], v[96:99], v[198:201], v[140:143]
	v_mfma_f32_16x16x32_bf16 v[132:135], v[104:107], v[198:201], v[132:135]
	v_mfma_f32_16x16x32_bf16 v[116:119], v[96:99], v[206:209], v[116:119]
	v_mfma_f32_16x16x32_bf16 v[124:127], v[104:107], v[206:209], v[124:127]
	v_mfma_f32_16x16x32_bf16 v[84:87], v[96:99], v[214:217], v[84:87]
	v_mfma_f32_16x16x32_bf16 v[92:95], v[104:107], v[214:217], v[92:95]
	v_mfma_f32_16x16x32_bf16 v[68:71], v[96:99], v[222:225], v[68:71]
	v_mfma_f32_16x16x32_bf16 v[76:79], v[104:107], v[222:225], v[76:79]
	v_mfma_f32_16x16x32_bf16 v[140:143], v[100:103], v[202:205], v[140:143]
	v_mfma_f32_16x16x32_bf16 v[132:135], v[112:115], v[202:205], v[132:135]
	v_mfma_f32_16x16x32_bf16 v[116:119], v[100:103], v[210:213], v[116:119]
	v_mfma_f32_16x16x32_bf16 v[124:127], v[112:115], v[210:213], v[124:127]
	v_mfma_f32_16x16x32_bf16 v[84:87], v[100:103], v[218:221], v[84:87]
	v_mfma_f32_16x16x32_bf16 v[92:95], v[112:115], v[218:221], v[92:95]
	v_mfma_f32_16x16x32_bf16 v[68:71], v[100:103], v[226:229], v[68:71]
	v_mfma_f32_16x16x32_bf16 v[76:79], v[112:115], v[226:229], v[76:79]
	v_mfma_f32_16x16x32_bf16 v[128:131], v[178:181], v[198:201], v[128:131]
	v_mfma_f32_16x16x32_bf16 v[136:139], v[186:189], v[198:201], v[136:139]
	v_mfma_f32_16x16x32_bf16 v[120:123], v[178:181], v[206:209], v[120:123]
	v_mfma_f32_16x16x32_bf16 v[108:111], v[186:189], v[206:209], v[108:111]
	v_mfma_f32_16x16x32_bf16 v[88:91], v[178:181], v[214:217], v[88:91]
	v_mfma_f32_16x16x32_bf16 v[80:83], v[186:189], v[214:217], v[80:83]
	v_mfma_f32_16x16x32_bf16 v[72:75], v[178:181], v[222:225], v[72:75]
	v_mfma_f32_16x16x32_bf16 v[64:67], v[186:189], v[222:225], v[64:67]
	v_mfma_f32_16x16x32_bf16 v[128:131], v[182:185], v[202:205], v[128:131]
	v_mfma_f32_16x16x32_bf16 v[136:139], v[190:193], v[202:205], v[136:139]
	v_mfma_f32_16x16x32_bf16 v[120:123], v[182:185], v[210:213], v[120:123]
	v_mfma_f32_16x16x32_bf16 v[108:111], v[190:193], v[210:213], v[108:111]
	v_mfma_f32_16x16x32_bf16 v[88:91], v[182:185], v[218:221], v[88:91]
	v_mfma_f32_16x16x32_bf16 v[80:83], v[190:193], v[218:221], v[80:83]
	v_mfma_f32_16x16x32_bf16 v[72:75], v[182:185], v[226:229], v[72:75]
	v_mfma_f32_16x16x32_bf16 v[64:67], v[190:193], v[226:229], v[64:67]
	s_barrier
	s_setprio 0
	v_lshl_add_u64 v[160:161], v[160:161], 0, s[12:13]
	s_mov_b32 m0, s100
	ds_read_b128 v[198:201], v177 offset:49152
	ds_read_b128 v[202:205], v177 offset:50176
	ds_read_b128 v[206:209], v177 offset:51200
	ds_read_b128 v[210:213], v177 offset:52224
	ds_read_b128 v[214:217], v177 offset:53248
	ds_read_b128 v[218:221], v177 offset:54272
	ds_read_b128 v[222:225], v177 offset:55296
	ds_read_b128 v[226:229], v177 offset:56320
	global_load_lds_dwordx4 v[160:161], off
	s_add_i32 m0, s100, 0x2000
	v_lshl_add_u64 v[160:161], v[164:165], 0, s[12:13]
	global_load_lds_dwordx4 v[160:161], off
	s_mov_b32 m0, s101
	s_nop 0
	global_load_lds_dwordx4 v144, s[44:45]
	s_add_i32 m0, s101, 0x2000
	v_lshl_add_u64 v[160:161], s[44:45], 0, v[146:147]
	global_load_lds_dwordx4 v[160:161], off
	s_mov_b32 m0, s68
	v_lshl_add_u64 v[160:161], v[170:171], 0, s[12:13]
	global_load_lds_dwordx4 v[160:161], off
	s_mov_b32 m0, s69
	v_lshl_add_u64 v[160:161], v[194:195], 0, s[12:13]
	global_load_lds_dwordx4 v[160:161], off
	s_waitcnt vmcnt(8) lgkmcnt(0)
	s_setprio 1
	s_barrier
	v_mfma_f32_16x16x32_bf16 v[60:63], v[96:99], v[198:201], v[60:63]
	v_mfma_f32_16x16x32_bf16 v[52:55], v[104:107], v[198:201], v[52:55]
	v_mfma_f32_16x16x32_bf16 v[36:39], v[96:99], v[206:209], v[36:39]
	v_mfma_f32_16x16x32_bf16 v[44:47], v[104:107], v[206:209], v[44:47]
	v_mfma_f32_16x16x32_bf16 v[20:23], v[96:99], v[214:217], v[20:23]
	v_mfma_f32_16x16x32_bf16 v[28:31], v[104:107], v[214:217], v[28:31]
	v_mfma_f32_16x16x32_bf16 v[4:7], v[96:99], v[222:225], v[4:7]
	v_mfma_f32_16x16x32_bf16 v[12:15], v[104:107], v[222:225], v[12:15]
	v_mfma_f32_16x16x32_bf16 v[60:63], v[100:103], v[202:205], v[60:63]
	v_mfma_f32_16x16x32_bf16 v[52:55], v[112:115], v[202:205], v[52:55]
	v_mfma_f32_16x16x32_bf16 v[36:39], v[100:103], v[210:213], v[36:39]
	v_mfma_f32_16x16x32_bf16 v[44:47], v[112:115], v[210:213], v[44:47]
	v_mfma_f32_16x16x32_bf16 v[20:23], v[100:103], v[218:221], v[20:23]
	v_mfma_f32_16x16x32_bf16 v[28:31], v[112:115], v[218:221], v[28:31]
	v_mfma_f32_16x16x32_bf16 v[4:7], v[100:103], v[226:229], v[4:7]
	v_mfma_f32_16x16x32_bf16 v[12:15], v[112:115], v[226:229], v[12:15]
	v_mfma_f32_16x16x32_bf16 v[48:51], v[178:181], v[198:201], v[48:51]
	v_mfma_f32_16x16x32_bf16 v[56:59], v[186:189], v[198:201], v[56:59]
	v_mfma_f32_16x16x32_bf16 v[40:43], v[178:181], v[206:209], v[40:43]
	v_mfma_f32_16x16x32_bf16 v[32:35], v[186:189], v[206:209], v[32:35]
	v_mfma_f32_16x16x32_bf16 v[24:27], v[178:181], v[214:217], v[24:27]
	v_mfma_f32_16x16x32_bf16 v[16:19], v[186:189], v[214:217], v[16:19]
	v_mfma_f32_16x16x32_bf16 v[8:11], v[178:181], v[222:225], v[8:11]
	v_mfma_f32_16x16x32_bf16 v[0:3], v[186:189], v[222:225], v[0:3]
	v_mfma_f32_16x16x32_bf16 v[48:51], v[182:185], v[202:205], v[48:51]
	v_mfma_f32_16x16x32_bf16 v[56:59], v[190:193], v[202:205], v[56:59]
	v_mfma_f32_16x16x32_bf16 v[40:43], v[182:185], v[210:213], v[40:43]
	v_mfma_f32_16x16x32_bf16 v[32:35], v[190:193], v[210:213], v[32:35]
	v_mfma_f32_16x16x32_bf16 v[24:27], v[182:185], v[218:221], v[24:27]
	v_mfma_f32_16x16x32_bf16 v[16:19], v[190:193], v[218:221], v[16:19]
	v_mfma_f32_16x16x32_bf16 v[8:11], v[182:185], v[226:229], v[8:11]
	v_mfma_f32_16x16x32_bf16 v[0:3], v[190:193], v[226:229], v[0:3]
	s_barrier
	s_setprio 0
	s_add_i32 s54, s54, 2
	s_add_u32 s8, s8, 0x100
	s_addc_u32 s9, s9, 0
	s_add_u32 s48, s48, 0x100
	s_addc_u32 s49, s49, 0
	s_cmp_gt_u32 s54, 29
	s_cbranch_scc0 .LBB0_129
	s_and_b64 vcc, exec, s[14:15]
	s_cbranch_vccz .LBB0_132
	s_barrier

; #define PG8_STAGE(bufoff, gbase, voff) do { _Pragma("unroll") for (int _i = 0; _i < 2; ++_i) \
;         __builtin_amdgcn_global_load_lds((const unsigned*)((const char*)(gbase) + (voff)[_i]), (PG8_LAS unsigned*)(lds + (bufoff) + ldsw + _i * 8192), 16, 0, 0); } while (0)
; #define PG8_LDA(dst, b, h) do { _Pragma("unroll") for (int m = 0; m < 4; ++m) _Pragma("unroll") for (int k = 0; k < 2; ++k) dst[m][k] = *(const PG8_LAS bf16x8*)(lds + PG8_SA(b, h) + aoff + m * 2048 + k * 1024); } while (0)
; #define PG8_LDB(dst, b, h) do { _Pragma("unroll") for (int n = 0; n < 2; ++n) _Pragma("unroll") for (int k = 0; k < 2; ++k) dst[n][k] = *(const PG8_LAS bf16x8*)(lds + PG8_SB(b, h) + boff + n * 2048 + k * 1024); } while (0)
; #define PG8_MMA(ai, bj, At, Bt) do { __builtin_amdgcn_s_setprio(1); _Pragma("unroll") for (int m = 0; m < 4; ++m) _Pragma("unroll") for (int n = 0; n < 2; ++n) _Pragma("unroll") for (int k = 0; k < 2; ++k) \
;         acc[ai][bj][m][n] = __builtin_amdgcn_mfma_f32_16x16x32_bf16(Bt[n][k], At[m][k], acc[ai][bj][m][n], 0, 0, 0); __builtin_amdgcn_s_setprio(0); } while (0)
; #define PG8_BAR __builtin_amdgcn_s_barrier()
; template <class Epi, class Sched, bool ALIGN_EPI = false, bool SP2 = false>
; __device__ __forceinline__ void gemm_phase(PG8_LAS unsigned char* lds, const Gemm g, const Sched& S, const Epi& E) {
;     ...
;         const bool has_next = S.next(ui + 1, nxt);
;         const char* nA = has_next ? (const char*)g.A + (size_t)nxt.pm * tstep : cA; const char* nB = has_next ? (const char*)g.Bt + (size_t)nxt.pn * tstep : cB;
;         for (int t = 0; t < nt; t += 2) {
;             const bool last = (t == nt - 2);
;             const char* a1 = cA + (size_t)(t + 1) * kstep;
;             const char* a2 = last ? nA : cA + (size_t)(t + 2) * kstep; const char* b2 = last ? nB : cB + (size_t)(t + 2) * kstep;
;             const char* a3 = a2 + kstep; const char* b3 = b2 + kstep;
;             if (last && has_next) S.a_ready(nxt);
;             if constexpr (SP2) {
;             PG8_LDB(B0, 0, 0); PG8_LDB(B1, 0, 1); PG8_SCHED; PG8_LDA(At, 0, 0); PG8_STAGE(PG8_SA(1, 1), a1 + hstep, voffA);
;             PG8_WAIT_V(8); PG8_WAIT_L(0); PG8_BAR; PG8_MMA(0, 0, At, B0); PG8_MMA(0, 1, At, B1); PG8_BAR; PG8_SCHED;
;             PG8_LDA(At, 0, 1); PG8_STAGE(PG8_SB(0, 0), b2, voffB); PG8_STAGE(PG8_SB(0, 1), b2 + hstep, voffB); PG8_STAGE(PG8_SA(0, 0), a2, voffA);
.LBB0_306:
	s_ashr_i32 s21, s20, 31
	s_lshl_b64 s[22:23], s[20:21], 20
	s_add_u32 s22, s60, s22
	s_addc_u32 s23, s61, s23
	s_and_b64 s[24:25], s[4:5], exec
	s_cselect_b32 s7, s23, s27
	s_cselect_b32 s21, s22, s26
	s_ashr_i32 s19, s18, 31
	s_lshl_b64 s[24:25], s[18:19], 20
	s_add_u32 s24, s68, s24
	s_addc_u32 s25, s69, s25
	s_and_b64 s[30:31], s[4:5], exec
	s_cselect_b32 s19, s25, s29
	s_cselect_b32 s33, s24, s28
	s_add_u32 s26, s26, 0x80080
	s_addc_u32 s27, s27, 0
	s_add_u32 s48, s28, 0x100
	s_addc_u32 s49, s29, 0
	s_mov_b32 s50, -2
	s_waitcnt lgkmcnt(0)
	s_waitcnt lgkmcnt(0)
	s_add_i32 s98, s34, 0x10000
	s_add_i32 s99, s34, 0x14000
	s_add_i32 s100, s34, 0x18000
	s_add_i32 s101, s34, 0x1c000
	ds_read_b128 v[128:131], v181
	ds_read_b128 v[132:135], v181 offset:1024
	ds_read_b128 v[136:139], v181 offset:2048
	ds_read_b128 v[140:143], v181 offset:3072
	ds_read_b128 v[144:147], v182
	ds_read_b128 v[148:151], v182 offset:1024
	ds_read_b128 v[168:171], v182 offset:2048
	ds_read_b128 v[172:175], v182 offset:3072
	s_add_u32 s28, s26, 0xfff80080
	s_addc_u32 s29, s27, -1
	s_cmp_eq_u32 s50, 28
	s_cselect_b32 s31, s7, s29
	s_cselect_b32 s30, s21, s28
	s_cselect_b32 s29, s19, s49
	s_cselect_b32 s28, s33, s48
	s_add_u32 s52, s28, 0x80000
	s_addc_u32 s53, s29, 0
	s_add_i32 m0, s35, 0xc000
	ds_read_b128 v[186:189], v183
	ds_read_b128 v[190:193], v183 offset:1024
	ds_read_b128 v[198:201], v183 offset:2048
	ds_read_b128 v[202:205], v183 offset:3072
	ds_read_b128 v[206:209], v183 offset:4096
	ds_read_b128 v[210:213], v183 offset:5120
	ds_read_b128 v[214:217], v183 offset:6144
	ds_read_b128 v[218:221], v183 offset:7168
	global_load_lds_dwordx4 v160, s[26:27]
	s_add_i32 m0, s35, 0xe000
	s_nop 0
	global_load_lds_dwordx4 v162, s[26:27]
	s_waitcnt lgkmcnt(0)
	s_setprio 1
	s_barrier
	v_mfma_f32_16x16x32_bf16 v[124:127], v[128:131], v[186:189], 0
	v_mfma_f32_16x16x32_bf16 v[120:123], v[136:139], v[186:189], 0
	v_mfma_f32_16x16x32_bf16 v[104:107], v[128:131], v[198:201], 0
	v_mfma_f32_16x16x32_bf16 v[108:111], v[136:139], v[198:201], 0
	v_mfma_f32_16x16x32_bf16 v[88:91], v[128:131], v[206:209], 0
	v_mfma_f32_16x16x32_bf16 v[92:95], v[136:139], v[206:209], 0
	v_mfma_f32_16x16x32_bf16 v[72:75], v[128:131], v[214:217], 0
	v_mfma_f32_16x16x32_bf16 v[76:79], v[136:139], v[214:217], 0
	v_mfma_f32_16x16x32_bf16 v[124:127], v[132:135], v[190:193], v[124:127]
	v_mfma_f32_16x16x32_bf16 v[120:123], v[140:143], v[190:193], v[120:123]
	v_mfma_f32_16x16x32_bf16 v[104:107], v[132:135], v[202:205], v[104:107]
	v_mfma_f32_16x16x32_bf16 v[108:111], v[140:143], v[202:205], v[108:111]
	v_mfma_f32_16x16x32_bf16 v[88:91], v[132:135], v[210:213], v[88:91]
	v_mfma_f32_16x16x32_bf16 v[92:95], v[140:143], v[210:213], v[92:95]
	v_mfma_f32_16x16x32_bf16 v[72:75], v[132:135], v[218:221], v[72:75]
	v_mfma_f32_16x16x32_bf16 v[76:79], v[140:143], v[218:221], v[76:79]
	v_mfma_f32_16x16x32_bf16 v[116:119], v[144:147], v[186:189], 0
	v_mfma_f32_16x16x32_bf16 v[112:115], v[168:171], v[186:189], 0
	v_mfma_f32_16x16x32_bf16 v[100:103], v[144:147], v[198:201], 0
	v_mfma_f32_16x16x32_bf16 v[96:99], v[168:171], v[198:201], 0
	v_mfma_f32_16x16x32_bf16 v[84:87], v[144:147], v[206:209], 0
	v_mfma_f32_16x16x32_bf16 v[80:83], v[168:171], v[206:209], 0
	v_mfma_f32_16x16x32_bf16 v[68:71], v[144:147], v[214:217], 0
	v_mfma_f32_16x16x32_bf16 v[64:67], v[168:171], v[214:217], 0
	v_mfma_f32_16x16x32_bf16 v[116:119], v[148:151], v[190:193], v[116:119]
	v_mfma_f32_16x16x32_bf16 v[112:115], v[172:175], v[190:193], v[112:115]
	v_mfma_f32_16x16x32_bf16 v[100:103], v[148:151], v[202:205], v[100:103]
	v_mfma_f32_16x16x32_bf16 v[96:99], v[172:175], v[202:205], v[96:99]
	v_mfma_f32_16x16x32_bf16 v[84:87], v[148:151], v[210:213], v[84:87]
	v_mfma_f32_16x16x32_bf16 v[80:83], v[172:175], v[210:213], v[80:83]
	v_mfma_f32_16x16x32_bf16 v[68:71], v[148:151], v[218:221], v[68:71]
	v_mfma_f32_16x16x32_bf16 v[64:67], v[172:175], v[218:221], v[64:67]
	s_barrier
	s_setprio 0
	v_lshl_add_u64 v[176:177], s[28:29], 0, v[154:155]
	s_mov_b32 m0, s98
	ds_read_b128 v[186:189], v183 offset:16384
	ds_read_b128 v[190:193], v183 offset:17408
	ds_read_b128 v[198:201], v183 offset:18432
	ds_read_b128 v[202:205], v183 offset:19456
	ds_read_b128 v[206:209], v183 offset:20480
	ds_read_b128 v[210:213], v183 offset:21504
	ds_read_b128 v[214:217], v183 offset:22528
	ds_read_b128 v[218:221], v183 offset:23552
	global_load_lds_dwordx4 v[176:177], off
	s_add_i32 m0, s98, 0x2000
	v_lshl_add_u64 v[194:195], s[28:29], 0, v[158:159]
	global_load_lds_dwordx4 v[194:195], off
	s_mov_b32 m0, s99
	v_lshl_add_u64 v[224:225], s[30:31], 0, v[156:157]
	global_load_lds_dwordx4 v154, s[52:53]
	s_add_i32 m0, s99, 0x2000
	s_nop 0
	global_load_lds_dwordx4 v158, s[52:53]
	s_mov_b32 m0, s35
	v_lshl_add_u64 v[222:223], s[30:31], 0, v[152:153]
	global_load_lds_dwordx4 v[222:223], off
	s_mov_b32 m0, s37
	s_nop 0
	global_load_lds_dwordx4 v[224:225], off
	s_waitcnt lgkmcnt(0)
	s_setprio 1
	s_barrier
; #define PG8_STAGE(bufoff, gbase, voff) do { _Pragma("unroll") for (int _i = 0; _i < 2; ++_i) \
;         __builtin_amdgcn_global_load_lds((const unsigned*)((const char*)(gbase) + (voff)[_i]), (PG8_LAS unsigned*)(lds + (bufoff) + ldsw + _i * 8192), 16, 0, 0); } while (0)
; #define PG8_LDA(dst, b, h) do { _Pragma("unroll") for (int m = 0; m < 4; ++m) _Pragma("unroll") for (int k = 0; k < 2; ++k) dst[m][k] = *(const PG8_LAS bf16x8*)(lds + PG8_SA(b, h) + aoff + m * 2048 + k * 1024); } while (0)
; #define PG8_LDB(dst, b, h) do { _Pragma("unroll") for (int n = 0; n < 2; ++n) _Pragma("unroll") for (int k = 0; k < 2; ++k) dst[n][k] = *(const PG8_LAS bf16x8*)(lds + PG8_SB(b, h) + boff + n * 2048 + k * 1024); } while (0)
; #define PG8_MMA(ai, bj, At, Bt) do { __builtin_amdgcn_s_setprio(1); _Pragma("unroll") for (int m = 0; m < 4; ++m) _Pragma("unroll") for (int n = 0; n < 2; ++n) _Pragma("unroll") for (int k = 0; k < 2; ++k) \
;         acc[ai][bj][m][n] = __builtin_amdgcn_mfma_f32_16x16x32_bf16(Bt[n][k], At[m][k], acc[ai][bj][m][n], 0, 0, 0); __builtin_amdgcn_s_setprio(0); } while (0)
; #define PG8_WAIT_V(n) asm volatile("s_waitcnt vmcnt(" #n ")" ::: "memory")
; #define PG8_WAIT_L(n) asm volatile("s_waitcnt lgkmcnt(" #n ")" ::: "memory")
; #define PG8_BAR __builtin_amdgcn_s_barrier()
; #define PG8_SCHED __builtin_amdgcn_sched_barrier(0)
; template <class Epi, class Sched, bool ALIGN_EPI = false, bool SP2 = false>
; __device__ __forceinline__ void gemm_phase(PG8_LAS unsigned char* lds, const Gemm g, const Sched& S, const Epi& E) {
;     ...
;             PG8_WAIT_V(8); PG8_WAIT_L(0); PG8_BAR; PG8_MMA(1, 0, At, B0); PG8_MMA(1, 1, At, B1); PG8_BAR; PG8_SCHED;
;             PG8_LDB(B0, 1, 0); PG8_LDB(B1, 1, 1); PG8_SCHED; PG8_LDA(At, 1, 0); PG8_STAGE(PG8_SA(0, 1), a2 + hstep, voffA);
;             PG8_WAIT_V(8); PG8_WAIT_L(0); PG8_BAR; PG8_MMA(0, 0, At, B0); PG8_MMA(0, 1, At, B1); PG8_BAR; PG8_SCHED;
	v_mfma_f32_16x16x32_bf16 v[56:59], v[128:131], v[186:189], 0
	v_mfma_f32_16x16x32_bf16 v[60:63], v[136:139], v[186:189], 0
	v_mfma_f32_16x16x32_bf16 v[40:43], v[128:131], v[198:201], 0
	v_mfma_f32_16x16x32_bf16 v[44:47], v[136:139], v[198:201], 0
	v_mfma_f32_16x16x32_bf16 v[24:27], v[128:131], v[206:209], 0
	v_mfma_f32_16x16x32_bf16 v[28:31], v[136:139], v[206:209], 0
	v_mfma_f32_16x16x32_bf16 v[8:11], v[128:131], v[214:217], 0
	v_mfma_f32_16x16x32_bf16 v[12:15], v[136:139], v[214:217], 0
	v_mfma_f32_16x16x32_bf16 v[56:59], v[132:135], v[190:193], v[56:59]
	v_mfma_f32_16x16x32_bf16 v[60:63], v[140:143], v[190:193], v[60:63]
	v_mfma_f32_16x16x32_bf16 v[40:43], v[132:135], v[202:205], v[40:43]
	v_mfma_f32_16x16x32_bf16 v[44:47], v[140:143], v[202:205], v[44:47]
	v_mfma_f32_16x16x32_bf16 v[24:27], v[132:135], v[210:213], v[24:27]
	v_mfma_f32_16x16x32_bf16 v[28:31], v[140:143], v[210:213], v[28:31]
	v_mfma_f32_16x16x32_bf16 v[8:11], v[132:135], v[218:221], v[8:11]
	v_mfma_f32_16x16x32_bf16 v[12:15], v[140:143], v[218:221], v[12:15]
	v_mfma_f32_16x16x32_bf16 v[52:55], v[144:147], v[186:189], 0
	v_mfma_f32_16x16x32_bf16 v[48:51], v[168:171], v[186:189], 0
	v_mfma_f32_16x16x32_bf16 v[36:39], v[144:147], v[198:201], 0
	v_mfma_f32_16x16x32_bf16 v[32:35], v[168:171], v[198:201], 0
	v_mfma_f32_16x16x32_bf16 v[20:23], v[144:147], v[206:209], 0
	v_mfma_f32_16x16x32_bf16 v[16:19], v[168:171], v[206:209], 0
	v_mfma_f32_16x16x32_bf16 v[4:7], v[144:147], v[214:217], 0
	v_mfma_f32_16x16x32_bf16 v[0:3], v[168:171], v[214:217], 0
	v_mfma_f32_16x16x32_bf16 v[52:55], v[148:151], v[190:193], v[52:55]
	v_mfma_f32_16x16x32_bf16 v[48:51], v[172:175], v[190:193], v[48:51]
	v_mfma_f32_16x16x32_bf16 v[36:39], v[148:151], v[202:205], v[36:39]
	v_mfma_f32_16x16x32_bf16 v[32:35], v[172:175], v[202:205], v[32:35]
	v_mfma_f32_16x16x32_bf16 v[20:23], v[148:151], v[210:213], v[20:23]
	v_mfma_f32_16x16x32_bf16 v[16:19], v[172:175], v[210:213], v[16:19]
	v_mfma_f32_16x16x32_bf16 v[4:7], v[148:151], v[218:221], v[4:7]
	v_mfma_f32_16x16x32_bf16 v[0:3], v[172:175], v[218:221], v[0:3]
	s_barrier
	s_setprio 0
	s_add_i32 s51, 0, 0x18000
	s_add_i32 s52, 0, 0x1c000
	v_add_u32_e32 v140, s51, v179
	v_add_u32_e32 v172, s52, v179
	ds_read_b128 v[128:131], v140
	ds_read_b128 v[132:135], v140 offset:1024
	ds_read_b128 v[136:139], v140 offset:2048
	ds_read_b128 v[140:143], v140 offset:3072
	ds_read_b128 v[144:147], v172
	ds_read_b128 v[148:151], v172 offset:1024
	ds_read_b128 v[168:171], v172 offset:2048
	ds_read_b128 v[172:175], v172 offset:3072
	s_add_u32 s30, s30, 0x80000
	s_addc_u32 s31, s31, 0
	s_add_u32 s28, s28, 0x80080
	s_addc_u32 s29, s29, 0
	s_mov_b32 m0, s39
	ds_read_b128 v[186:189], v183 offset:32768
	ds_read_b128 v[190:193], v183 offset:33792
	ds_read_b128 v[198:201], v183 offset:34816
	ds_read_b128 v[202:205], v183 offset:35840
	ds_read_b128 v[206:209], v183 offset:36864
	ds_read_b128 v[210:213], v183 offset:37888
	ds_read_b128 v[214:217], v183 offset:38912
	ds_read_b128 v[218:221], v183 offset:39936
	global_load_lds_dwordx4 v152, s[30:31]
	s_mov_b32 m0, s42
	v_lshl_add_u64 v[226:227], s[30:31], 0, v[156:157]
	global_load_lds_dwordx4 v[226:227], off
	s_waitcnt vmcnt(8) lgkmcnt(0)
	s_setprio 1
	s_barrier
	v_mfma_f32_16x16x32_bf16 v[124:127], v[128:131], v[186:189], v[124:127]
	v_mfma_f32_16x16x32_bf16 v[120:123], v[136:139], v[186:189], v[120:123]
	v_mfma_f32_16x16x32_bf16 v[104:107], v[128:131], v[198:201], v[104:107]
	v_mfma_f32_16x16x32_bf16 v[108:111], v[136:139], v[198:201], v[108:111]
	v_mfma_f32_16x16x32_bf16 v[88:91], v[128:131], v[206:209], v[88:91]
	v_mfma_f32_16x16x32_bf16 v[92:95], v[136:139], v[206:209], v[92:95]
	v_mfma_f32_16x16x32_bf16 v[72:75], v[128:131], v[214:217], v[72:75]
	v_mfma_f32_16x16x32_bf16 v[76:79], v[136:139], v[214:217], v[76:79]
	v_mfma_f32_16x16x32_bf16 v[124:127], v[132:135], v[190:193], v[124:127]
	v_mfma_f32_16x16x32_bf16 v[120:123], v[140:143], v[190:193], v[120:123]
	v_mfma_f32_16x16x32_bf16 v[104:107], v[132:135], v[202:205], v[104:107]
	v_mfma_f32_16x16x32_bf16 v[108:111], v[140:143], v[202:205], v[108:111]
	v_mfma_f32_16x16x32_bf16 v[88:91], v[132:135], v[210:213], v[88:91]
	v_mfma_f32_16x16x32_bf16 v[92:95], v[140:143], v[210:213], v[92:95]
	v_mfma_f32_16x16x32_bf16 v[72:75], v[132:135], v[218:221], v[72:75]
	v_mfma_f32_16x16x32_bf16 v[76:79], v[140:143], v[218:221], v[76:79]
	v_mfma_f32_16x16x32_bf16 v[116:119], v[144:147], v[186:189], v[116:119]
	v_mfma_f32_16x16x32_bf16 v[112:115], v[168:171], v[186:189], v[112:115]
	v_mfma_f32_16x16x32_bf16 v[100:103], v[144:147], v[198:201], v[100:103]
	v_mfma_f32_16x16x32_bf16 v[96:99], v[168:171], v[198:201], v[96:99]
	v_mfma_f32_16x16x32_bf16 v[84:87], v[144:147], v[206:209], v[84:87]
	v_mfma_f32_16x16x32_bf16 v[80:83], v[168:171], v[206:209], v[80:83]
	v_mfma_f32_16x16x32_bf16 v[68:71], v[144:147], v[214:217], v[68:71]
	v_mfma_f32_16x16x32_bf16 v[64:67], v[168:171], v[214:217], v[64:67]
	v_mfma_f32_16x16x32_bf16 v[116:119], v[148:151], v[190:193], v[116:119]
	v_mfma_f32_16x16x32_bf16 v[112:115], v[172:175], v[190:193], v[112:115]
	v_mfma_f32_16x16x32_bf16 v[100:103], v[148:151], v[202:205], v[100:103]
	v_mfma_f32_16x16x32_bf16 v[96:99], v[172:175], v[202:205], v[96:99]
	v_mfma_f32_16x16x32_bf16 v[84:87], v[148:151], v[210:213], v[84:87]
	v_mfma_f32_16x16x32_bf16 v[80:83], v[172:175], v[210:213], v[80:83]
	v_mfma_f32_16x16x32_bf16 v[68:71], v[148:151], v[218:221], v[68:71]
	v_mfma_f32_16x16x32_bf16 v[64:67], v[172:175], v[218:221], v[64:67]
	s_barrier
; #define PG8_STAGE(bufoff, gbase, voff) do { _Pragma("unroll") for (int _i = 0; _i < 2; ++_i) \
;         __builtin_amdgcn_global_load_lds((const unsigned*)((const char*)(gbase) + (voff)[_i]), (PG8_LAS unsigned*)(lds + (bufoff) + ldsw + _i * 8192), 16, 0, 0); } while (0)
; #define PG8_LDA(dst, b, h) do { _Pragma("unroll") for (int m = 0; m < 4; ++m) _Pragma("unroll") for (int k = 0; k < 2; ++k) dst[m][k] = *(const PG8_LAS bf16x8*)(lds + PG8_SA(b, h) + aoff + m * 2048 + k * 1024); } while (0)
; #define PG8_LDB(dst, b, h) do { _Pragma("unroll") for (int n = 0; n < 2; ++n) _Pragma("unroll") for (int k = 0; k < 2; ++k) dst[n][k] = *(const PG8_LAS bf16x8*)(lds + PG8_SB(b, h) + boff + n * 2048 + k * 1024); } while (0)
; #define PG8_MMA(ai, bj, At, Bt) do { __builtin_amdgcn_s_setprio(1); _Pragma("unroll") for (int m = 0; m < 4; ++m) _Pragma("unroll") for (int n = 0; n < 2; ++n) _Pragma("unroll") for (int k = 0; k < 2; ++k) \
;         acc[ai][bj][m][n] = __builtin_amdgcn_mfma_f32_16x16x32_bf16(Bt[n][k], At[m][k], acc[ai][bj][m][n], 0, 0, 0); __builtin_amdgcn_s_setprio(0); } while (0)
; #define PG8_WAIT_V(n) asm volatile("s_waitcnt vmcnt(" #n ")" ::: "memory")
; #define PG8_BAR __builtin_amdgcn_s_barrier()
; template <class Epi, class Sched, bool ALIGN_EPI = false, bool SP2 = false>
; __device__ __forceinline__ void gemm_phase(PG8_LAS unsigned char* lds, const Gemm g, const Sched& S, const Epi& E) {
;     ...
;         for (int t = 0; t < nt; t += 2) {
;             const bool last = (t == nt - 2);
;             const char* a1 = cA + (size_t)(t + 1) * kstep;
;             const char* a2 = last ? nA : cA + (size_t)(t + 2) * kstep; const char* b2 = last ? nB : cB + (size_t)(t + 2) * kstep;
;             const char* a3 = a2 + kstep; const char* b3 = b2 + kstep;
;             if (last && has_next) S.a_ready(nxt);
;             if constexpr (SP2) {
;             PG8_LDB(B0, 0, 0); PG8_LDB(B1, 0, 1); PG8_SCHED; PG8_LDA(At, 0, 0); PG8_STAGE(PG8_SA(1, 1), a1 + hstep, voffA);
;             PG8_WAIT_V(8); PG8_WAIT_L(0); PG8_BAR; PG8_MMA(0, 0, At, B0); PG8_MMA(0, 1, At, B1); PG8_BAR; PG8_SCHED;
;     ...
;             PG8_LDA(At, 1, 1); PG8_STAGE(PG8_SB(1, 0), b3, voffB); PG8_STAGE(PG8_SB(1, 1), b3 + hstep, voffB); PG8_STAGE(PG8_SA(1, 0), a3, voffA);
;             PG8_WAIT_V(8); PG8_WAIT_L(0); PG8_BAR; PG8_MMA(1, 0, At, B0); PG8_MMA(1, 1, At, B1); PG8_BAR; PG8_SCHED;
	s_setprio 0
	v_lshl_add_u64 v[176:177], v[176:177], 0, s[12:13]
	s_mov_b32 m0, s100
	ds_read_b128 v[186:189], v183 offset:49152
	ds_read_b128 v[190:193], v183 offset:50176
	ds_read_b128 v[198:201], v183 offset:51200
	ds_read_b128 v[202:205], v183 offset:52224
	ds_read_b128 v[206:209], v183 offset:53248
	ds_read_b128 v[210:213], v183 offset:54272
	ds_read_b128 v[214:217], v183 offset:55296
	ds_read_b128 v[218:221], v183 offset:56320
	global_load_lds_dwordx4 v[176:177], off
	s_add_i32 m0, s100, 0x2000
	v_lshl_add_u64 v[176:177], v[194:195], 0, s[12:13]
	global_load_lds_dwordx4 v[176:177], off
	s_mov_b32 m0, s101
	s_nop 0
	global_load_lds_dwordx4 v154, s[28:29]
	s_add_i32 m0, s101, 0x2000
	v_lshl_add_u64 v[176:177], s[28:29], 0, v[158:159]
	global_load_lds_dwordx4 v[176:177], off
	s_mov_b32 m0, s44
	v_lshl_add_u64 v[176:177], v[222:223], 0, s[12:13]
	global_load_lds_dwordx4 v[176:177], off
	s_mov_b32 m0, s45
	v_lshl_add_u64 v[176:177], v[224:225], 0, s[12:13]
	global_load_lds_dwordx4 v[176:177], off
	s_waitcnt vmcnt(8) lgkmcnt(0)
	s_setprio 1
	s_barrier
	v_mfma_f32_16x16x32_bf16 v[56:59], v[128:131], v[186:189], v[56:59]
	v_mfma_f32_16x16x32_bf16 v[60:63], v[136:139], v[186:189], v[60:63]
	v_mfma_f32_16x16x32_bf16 v[40:43], v[128:131], v[198:201], v[40:43]
	v_mfma_f32_16x16x32_bf16 v[44:47], v[136:139], v[198:201], v[44:47]
	v_mfma_f32_16x16x32_bf16 v[24:27], v[128:131], v[206:209], v[24:27]
	v_mfma_f32_16x16x32_bf16 v[28:31], v[136:139], v[206:209], v[28:31]
	v_mfma_f32_16x16x32_bf16 v[8:11], v[128:131], v[214:217], v[8:11]
	v_mfma_f32_16x16x32_bf16 v[12:15], v[136:139], v[214:217], v[12:15]
	v_mfma_f32_16x16x32_bf16 v[56:59], v[132:135], v[190:193], v[56:59]
	v_mfma_f32_16x16x32_bf16 v[60:63], v[140:143], v[190:193], v[60:63]
	v_mfma_f32_16x16x32_bf16 v[40:43], v[132:135], v[202:205], v[40:43]
	v_mfma_f32_16x16x32_bf16 v[44:47], v[140:143], v[202:205], v[44:47]
	v_mfma_f32_16x16x32_bf16 v[24:27], v[132:135], v[210:213], v[24:27]
	v_mfma_f32_16x16x32_bf16 v[28:31], v[140:143], v[210:213], v[28:31]
	v_mfma_f32_16x16x32_bf16 v[8:11], v[132:135], v[218:221], v[8:11]
	v_mfma_f32_16x16x32_bf16 v[12:15], v[140:143], v[218:221], v[12:15]
	v_mfma_f32_16x16x32_bf16 v[52:55], v[144:147], v[186:189], v[52:55]
	v_mfma_f32_16x16x32_bf16 v[48:51], v[168:171], v[186:189], v[48:51]
	v_mfma_f32_16x16x32_bf16 v[36:39], v[144:147], v[198:201], v[36:39]
	v_mfma_f32_16x16x32_bf16 v[32:35], v[168:171], v[198:201], v[32:35]
	v_mfma_f32_16x16x32_bf16 v[20:23], v[144:147], v[206:209], v[20:23]
	v_mfma_f32_16x16x32_bf16 v[16:19], v[168:171], v[206:209], v[16:19]
	v_mfma_f32_16x16x32_bf16 v[4:7], v[144:147], v[214:217], v[4:7]
	v_mfma_f32_16x16x32_bf16 v[0:3], v[168:171], v[214:217], v[0:3]
	v_mfma_f32_16x16x32_bf16 v[52:55], v[148:151], v[190:193], v[52:55]
	v_mfma_f32_16x16x32_bf16 v[48:51], v[172:175], v[190:193], v[48:51]
	v_mfma_f32_16x16x32_bf16 v[36:39], v[148:151], v[202:205], v[36:39]
	v_mfma_f32_16x16x32_bf16 v[32:35], v[172:175], v[202:205], v[32:35]
	v_mfma_f32_16x16x32_bf16 v[20:23], v[148:151], v[210:213], v[20:23]
	v_mfma_f32_16x16x32_bf16 v[16:19], v[172:175], v[210:213], v[16:19]
	v_mfma_f32_16x16x32_bf16 v[4:7], v[148:151], v[218:221], v[4:7]
	v_mfma_f32_16x16x32_bf16 v[0:3], v[172:175], v[218:221], v[0:3]
	s_barrier
	s_setprio 0
	s_add_i32 s50, s50, 2
	s_add_u32 s26, s26, 0x100
	s_addc_u32 s27, s27, 0
	s_add_u32 s48, s48, 0x100
	s_addc_u32 s49, s49, 0
.LBB0_307:
	ds_read_b128 v[128:131], v181
	ds_read_b128 v[132:135], v181 offset:1024
	ds_read_b128 v[136:139], v181 offset:2048
	ds_read_b128 v[140:143], v181 offset:3072
	ds_read_b128 v[144:147], v182
	ds_read_b128 v[148:151], v182 offset:1024
	ds_read_b128 v[168:171], v182 offset:2048
	ds_read_b128 v[172:175], v182 offset:3072
	s_add_u32 s28, s26, 0xfff80080
	s_addc_u32 s29, s27, -1
	s_cmp_eq_u32 s50, 28
	s_cselect_b32 s31, s7, s29
	s_cselect_b32 s30, s21, s28
	s_cselect_b32 s29, s19, s49
	s_cselect_b32 s28, s33, s48
	s_add_u32 s52, s28, 0x80000
	s_addc_u32 s53, s29, 0
	s_add_i32 m0, s35, 0xc000
	ds_read_b128 v[186:189], v183
	ds_read_b128 v[190:193], v183 offset:1024
	ds_read_b128 v[198:201], v183 offset:2048
	ds_read_b128 v[202:205], v183 offset:3072
	ds_read_b128 v[206:209], v183 offset:4096
	ds_read_b128 v[210:213], v183 offset:5120
	ds_read_b128 v[214:217], v183 offset:6144
	ds_read_b128 v[218:221], v183 offset:7168
	global_load_lds_dwordx4 v160, s[26:27]
	s_add_i32 m0, s35, 0xe000
	s_nop 0
	global_load_lds_dwordx4 v162, s[26:27]
	s_waitcnt vmcnt(8) lgkmcnt(0)
	s_setprio 1
	s_barrier
; #define PG8_STAGE(bufoff, gbase, voff) do { _Pragma("unroll") for (int _i = 0; _i < 2; ++_i) \
;         __builtin_amdgcn_global_load_lds((const unsigned*)((const char*)(gbase) + (voff)[_i]), (PG8_LAS unsigned*)(lds + (bufoff) + ldsw + _i * 8192), 16, 0, 0); } while (0)
; #define PG8_LDA(dst, b, h) do { _Pragma("unroll") for (int m = 0; m < 4; ++m) _Pragma("unroll") for (int k = 0; k < 2; ++k) dst[m][k] = *(const PG8_LAS bf16x8*)(lds + PG8_SA(b, h) + aoff + m * 2048 + k * 1024); } while (0)
; #define PG8_MMA(ai, bj, At, Bt) do { __builtin_amdgcn_s_setprio(1); _Pragma("unroll") for (int m = 0; m < 4; ++m) _Pragma("unroll") for (int n = 0; n < 2; ++n) _Pragma("unroll") for (int k = 0; k < 2; ++k) \
;         acc[ai][bj][m][n] = __builtin_amdgcn_mfma_f32_16x16x32_bf16(Bt[n][k], At[m][k], acc[ai][bj][m][n], 0, 0, 0); __builtin_amdgcn_s_setprio(0); } while (0)
; #define PG8_WAIT_V(n) asm volatile("s_waitcnt vmcnt(" #n ")" ::: "memory")
; #define PG8_WAIT_L(n) asm volatile("s_waitcnt lgkmcnt(" #n ")" ::: "memory")
; #define PG8_BAR __builtin_amdgcn_s_barrier()
; #define PG8_SCHED __builtin_amdgcn_sched_barrier(0)
; template <class Epi, class Sched, bool ALIGN_EPI = false, bool SP2 = false>
; __device__ __forceinline__ void gemm_phase(PG8_LAS unsigned char* lds, const Gemm g, const Sched& S, const Epi& E) {
;     ...
;             PG8_WAIT_V(8); PG8_WAIT_L(0); PG8_BAR; PG8_MMA(0, 0, At, B0); PG8_MMA(0, 1, At, B1); PG8_BAR; PG8_SCHED;
;             PG8_LDA(At, 0, 1); PG8_STAGE(PG8_SB(0, 0), b2, voffB); PG8_STAGE(PG8_SB(0, 1), b2 + hstep, voffB); PG8_STAGE(PG8_SA(0, 0), a2, voffA);
;             PG8_WAIT_V(8); PG8_WAIT_L(0); PG8_BAR; PG8_MMA(1, 0, At, B0); PG8_MMA(1, 1, At, B1); PG8_BAR; PG8_SCHED;
	v_mfma_f32_16x16x32_bf16 v[124:127], v[128:131], v[186:189], v[124:127]
	v_mfma_f32_16x16x32_bf16 v[120:123], v[136:139], v[186:189], v[120:123]
	v_mfma_f32_16x16x32_bf16 v[104:107], v[128:131], v[198:201], v[104:107]
	v_mfma_f32_16x16x32_bf16 v[108:111], v[136:139], v[198:201], v[108:111]
	v_mfma_f32_16x16x32_bf16 v[88:91], v[128:131], v[206:209], v[88:91]
	v_mfma_f32_16x16x32_bf16 v[92:95], v[136:139], v[206:209], v[92:95]
	v_mfma_f32_16x16x32_bf16 v[72:75], v[128:131], v[214:217], v[72:75]
	v_mfma_f32_16x16x32_bf16 v[76:79], v[136:139], v[214:217], v[76:79]
	v_mfma_f32_16x16x32_bf16 v[124:127], v[132:135], v[190:193], v[124:127]
	v_mfma_f32_16x16x32_bf16 v[120:123], v[140:143], v[190:193], v[120:123]
	v_mfma_f32_16x16x32_bf16 v[104:107], v[132:135], v[202:205], v[104:107]
	v_mfma_f32_16x16x32_bf16 v[108:111], v[140:143], v[202:205], v[108:111]
	v_mfma_f32_16x16x32_bf16 v[88:91], v[132:135], v[210:213], v[88:91]
	v_mfma_f32_16x16x32_bf16 v[92:95], v[140:143], v[210:213], v[92:95]
	v_mfma_f32_16x16x32_bf16 v[72:75], v[132:135], v[218:221], v[72:75]
	v_mfma_f32_16x16x32_bf16 v[76:79], v[140:143], v[218:221], v[76:79]
	v_mfma_f32_16x16x32_bf16 v[116:119], v[144:147], v[186:189], v[116:119]
	v_mfma_f32_16x16x32_bf16 v[112:115], v[168:171], v[186:189], v[112:115]
	v_mfma_f32_16x16x32_bf16 v[100:103], v[144:147], v[198:201], v[100:103]
	v_mfma_f32_16x16x32_bf16 v[96:99], v[168:171], v[198:201], v[96:99]
	v_mfma_f32_16x16x32_bf16 v[84:87], v[144:147], v[206:209], v[84:87]
	v_mfma_f32_16x16x32_bf16 v[80:83], v[168:171], v[206:209], v[80:83]
	v_mfma_f32_16x16x32_bf16 v[68:71], v[144:147], v[214:217], v[68:71]
	v_mfma_f32_16x16x32_bf16 v[64:67], v[168:171], v[214:217], v[64:67]
	v_mfma_f32_16x16x32_bf16 v[116:119], v[148:151], v[190:193], v[116:119]
	v_mfma_f32_16x16x32_bf16 v[112:115], v[172:175], v[190:193], v[112:115]
	v_mfma_f32_16x16x32_bf16 v[100:103], v[148:151], v[202:205], v[100:103]
	v_mfma_f32_16x16x32_bf16 v[96:99], v[172:175], v[202:205], v[96:99]
	v_mfma_f32_16x16x32_bf16 v[84:87], v[148:151], v[210:213], v[84:87]
	v_mfma_f32_16x16x32_bf16 v[80:83], v[172:175], v[210:213], v[80:83]
	v_mfma_f32_16x16x32_bf16 v[68:71], v[148:151], v[218:221], v[68:71]
	v_mfma_f32_16x16x32_bf16 v[64:67], v[172:175], v[218:221], v[64:67]
	s_barrier
	s_setprio 0
	v_lshl_add_u64 v[176:177], s[28:29], 0, v[154:155]
	s_mov_b32 m0, s98
	ds_read_b128 v[186:189], v183 offset:16384
	ds_read_b128 v[190:193], v183 offset:17408
	ds_read_b128 v[198:201], v183 offset:18432
	ds_read_b128 v[202:205], v183 offset:19456
	ds_read_b128 v[206:209], v183 offset:20480
	ds_read_b128 v[210:213], v183 offset:21504
	ds_read_b128 v[214:217], v183 offset:22528
	ds_read_b128 v[218:221], v183 offset:23552
	global_load_lds_dwordx4 v[176:177], off
	s_add_i32 m0, s98, 0x2000
	v_lshl_add_u64 v[194:195], s[28:29], 0, v[158:159]
	global_load_lds_dwordx4 v[194:195], off
	s_mov_b32 m0, s99
	v_lshl_add_u64 v[224:225], s[30:31], 0, v[156:157]
	global_load_lds_dwordx4 v154, s[52:53]
	s_add_i32 m0, s99, 0x2000
	s_nop 0
	global_load_lds_dwordx4 v158, s[52:53]
	s_mov_b32 m0, s35
	v_lshl_add_u64 v[222:223], s[30:31], 0, v[152:153]
	global_load_lds_dwordx4 v[222:223], off
	s_mov_b32 m0, s37
	s_nop 0
	global_load_lds_dwordx4 v[224:225], off
	s_waitcnt vmcnt(8) lgkmcnt(0)
	s_setprio 1
	s_barrier
	v_mfma_f32_16x16x32_bf16 v[56:59], v[128:131], v[186:189], v[56:59]
	v_mfma_f32_16x16x32_bf16 v[60:63], v[136:139], v[186:189], v[60:63]
	v_mfma_f32_16x16x32_bf16 v[40:43], v[128:131], v[198:201], v[40:43]
	v_mfma_f32_16x16x32_bf16 v[44:47], v[136:139], v[198:201], v[44:47]
	v_mfma_f32_16x16x32_bf16 v[24:27], v[128:131], v[206:209], v[24:27]
	v_mfma_f32_16x16x32_bf16 v[28:31], v[136:139], v[206:209], v[28:31]
	v_mfma_f32_16x16x32_bf16 v[8:11], v[128:131], v[214:217], v[8:11]
	v_mfma_f32_16x16x32_bf16 v[12:15], v[136:139], v[214:217], v[12:15]
	v_mfma_f32_16x16x32_bf16 v[56:59], v[132:135], v[190:193], v[56:59]
	v_mfma_f32_16x16x32_bf16 v[60:63], v[140:143], v[190:193], v[60:63]
	v_mfma_f32_16x16x32_bf16 v[40:43], v[132:135], v[202:205], v[40:43]
	v_mfma_f32_16x16x32_bf16 v[44:47], v[140:143], v[202:205], v[44:47]
	v_mfma_f32_16x16x32_bf16 v[24:27], v[132:135], v[210:213], v[24:27]
	v_mfma_f32_16x16x32_bf16 v[28:31], v[140:143], v[210:213], v[28:31]
	v_mfma_f32_16x16x32_bf16 v[8:11], v[132:135], v[218:221], v[8:11]
	v_mfma_f32_16x16x32_bf16 v[12:15], v[140:143], v[218:221], v[12:15]
	v_mfma_f32_16x16x32_bf16 v[52:55], v[144:147], v[186:189], v[52:55]
	v_mfma_f32_16x16x32_bf16 v[48:51], v[168:171], v[186:189], v[48:51]
	v_mfma_f32_16x16x32_bf16 v[36:39], v[144:147], v[198:201], v[36:39]
	v_mfma_f32_16x16x32_bf16 v[32:35], v[168:171], v[198:201], v[32:35]
	v_mfma_f32_16x16x32_bf16 v[20:23], v[144:147], v[206:209], v[20:23]
	v_mfma_f32_16x16x32_bf16 v[16:19], v[168:171], v[206:209], v[16:19]
	v_mfma_f32_16x16x32_bf16 v[4:7], v[144:147], v[214:217], v[4:7]
	v_mfma_f32_16x16x32_bf16 v[0:3], v[168:171], v[214:217], v[0:3]
	v_mfma_f32_16x16x32_bf16 v[52:55], v[148:151], v[190:193], v[52:55]
	v_mfma_f32_16x16x32_bf16 v[48:51], v[172:175], v[190:193], v[48:51]
	v_mfma_f32_16x16x32_bf16 v[36:39], v[148:151], v[202:205], v[36:39]
	v_mfma_f32_16x16x32_bf16 v[32:35], v[172:175], v[202:205], v[32:35]
	v_mfma_f32_16x16x32_bf16 v[20:23], v[148:151], v[210:213], v[20:23]
	v_mfma_f32_16x16x32_bf16 v[16:19], v[172:175], v[210:213], v[16:19]
	v_mfma_f32_16x16x32_bf16 v[4:7], v[148:151], v[218:221], v[4:7]
	v_mfma_f32_16x16x32_bf16 v[0:3], v[172:175], v[218:221], v[0:3]
	s_barrier
; #define PG8_STAGE(bufoff, gbase, voff) do { _Pragma("unroll") for (int _i = 0; _i < 2; ++_i) \
;         __builtin_amdgcn_global_load_lds((const unsigned*)((const char*)(gbase) + (voff)[_i]), (PG8_LAS unsigned*)(lds + (bufoff) + ldsw + _i * 8192), 16, 0, 0); } while (0)
; #define PG8_LDA(dst, b, h) do { _Pragma("unroll") for (int m = 0; m < 4; ++m) _Pragma("unroll") for (int k = 0; k < 2; ++k) dst[m][k] = *(const PG8_LAS bf16x8*)(lds + PG8_SA(b, h) + aoff + m * 2048 + k * 1024); } while (0)
; #define PG8_LDB(dst, b, h) do { _Pragma("unroll") for (int n = 0; n < 2; ++n) _Pragma("unroll") for (int k = 0; k < 2; ++k) dst[n][k] = *(const PG8_LAS bf16x8*)(lds + PG8_SB(b, h) + boff + n * 2048 + k * 1024); } while (0)
; #define PG8_MMA(ai, bj, At, Bt) do { __builtin_amdgcn_s_setprio(1); _Pragma("unroll") for (int m = 0; m < 4; ++m) _Pragma("unroll") for (int n = 0; n < 2; ++n) _Pragma("unroll") for (int k = 0; k < 2; ++k) \
;         acc[ai][bj][m][n] = __builtin_amdgcn_mfma_f32_16x16x32_bf16(Bt[n][k], At[m][k], acc[ai][bj][m][n], 0, 0, 0); __builtin_amdgcn_s_setprio(0); } while (0)
; #define PG8_WAIT_V(n) asm volatile("s_waitcnt vmcnt(" #n ")" ::: "memory")
; #define PG8_WAIT_L(n) asm volatile("s_waitcnt lgkmcnt(" #n ")" ::: "memory")
; #define PG8_BAR __builtin_amdgcn_s_barrier()
; #define PG8_SCHED __builtin_amdgcn_sched_barrier(0)
; template <class Epi, class Sched, bool ALIGN_EPI = false, bool SP2 = false>
; __device__ __forceinline__ void gemm_phase(PG8_LAS unsigned char* lds, const Gemm g, const Sched& S, const Epi& E) {
;     ...
;             PG8_LDB(B0, 1, 0); PG8_LDB(B1, 1, 1); PG8_SCHED; PG8_LDA(At, 1, 0); PG8_STAGE(PG8_SA(0, 1), a2 + hstep, voffA);
;             PG8_WAIT_V(8); PG8_WAIT_L(0); PG8_BAR; PG8_MMA(0, 0, At, B0); PG8_MMA(0, 1, At, B1); PG8_BAR; PG8_SCHED;
;             PG8_LDA(At, 1, 1); PG8_STAGE(PG8_SB(1, 0), b3, voffB); PG8_STAGE(PG8_SB(1, 1), b3 + hstep, voffB); PG8_STAGE(PG8_SA(1, 0), a3, voffA);
;             PG8_WAIT_V(8); PG8_WAIT_L(0); PG8_BAR; PG8_MMA(1, 0, At, B0); PG8_MMA(1, 1, At, B1); PG8_BAR; PG8_SCHED;
	s_setprio 0
	s_add_i32 s51, 0, 0x18000
	s_add_i32 s52, 0, 0x1c000
	v_add_u32_e32 v140, s51, v179
	v_add_u32_e32 v172, s52, v179
	ds_read_b128 v[128:131], v140
	ds_read_b128 v[132:135], v140 offset:1024
	ds_read_b128 v[136:139], v140 offset:2048
	ds_read_b128 v[140:143], v140 offset:3072
	ds_read_b128 v[144:147], v172
	ds_read_b128 v[148:151], v172 offset:1024
	ds_read_b128 v[168:171], v172 offset:2048
	ds_read_b128 v[172:175], v172 offset:3072
	s_add_u32 s30, s30, 0x80000
	s_addc_u32 s31, s31, 0
	s_add_u32 s28, s28, 0x80080
	s_addc_u32 s29, s29, 0
	s_mov_b32 m0, s39
	ds_read_b128 v[186:189], v183 offset:32768
	ds_read_b128 v[190:193], v183 offset:33792
	ds_read_b128 v[198:201], v183 offset:34816
	ds_read_b128 v[202:205], v183 offset:35840
	ds_read_b128 v[206:209], v183 offset:36864
	ds_read_b128 v[210:213], v183 offset:37888
	ds_read_b128 v[214:217], v183 offset:38912
	ds_read_b128 v[218:221], v183 offset:39936
	global_load_lds_dwordx4 v152, s[30:31]
	s_mov_b32 m0, s42
	s_nop 0
	global_load_lds_dwordx4 v156, s[30:31]
	s_waitcnt vmcnt(8) lgkmcnt(0)
	s_setprio 1
	s_barrier
	v_mfma_f32_16x16x32_bf16 v[124:127], v[128:131], v[186:189], v[124:127]
	v_mfma_f32_16x16x32_bf16 v[120:123], v[136:139], v[186:189], v[120:123]
	v_mfma_f32_16x16x32_bf16 v[104:107], v[128:131], v[198:201], v[104:107]
	v_mfma_f32_16x16x32_bf16 v[108:111], v[136:139], v[198:201], v[108:111]
	v_mfma_f32_16x16x32_bf16 v[88:91], v[128:131], v[206:209], v[88:91]
	v_mfma_f32_16x16x32_bf16 v[92:95], v[136:139], v[206:209], v[92:95]
	v_mfma_f32_16x16x32_bf16 v[72:75], v[128:131], v[214:217], v[72:75]
	v_mfma_f32_16x16x32_bf16 v[76:79], v[136:139], v[214:217], v[76:79]
	v_mfma_f32_16x16x32_bf16 v[124:127], v[132:135], v[190:193], v[124:127]
	v_mfma_f32_16x16x32_bf16 v[120:123], v[140:143], v[190:193], v[120:123]
	v_mfma_f32_16x16x32_bf16 v[104:107], v[132:135], v[202:205], v[104:107]
	v_mfma_f32_16x16x32_bf16 v[108:111], v[140:143], v[202:205], v[108:111]
	v_mfma_f32_16x16x32_bf16 v[88:91], v[132:135], v[210:213], v[88:91]
	v_mfma_f32_16x16x32_bf16 v[92:95], v[140:143], v[210:213], v[92:95]
	v_mfma_f32_16x16x32_bf16 v[72:75], v[132:135], v[218:221], v[72:75]
	v_mfma_f32_16x16x32_bf16 v[76:79], v[140:143], v[218:221], v[76:79]
	v_mfma_f32_16x16x32_bf16 v[116:119], v[144:147], v[186:189], v[116:119]
	v_mfma_f32_16x16x32_bf16 v[112:115], v[168:171], v[186:189], v[112:115]
	v_mfma_f32_16x16x32_bf16 v[100:103], v[144:147], v[198:201], v[100:103]
	v_mfma_f32_16x16x32_bf16 v[96:99], v[168:171], v[198:201], v[96:99]
	v_mfma_f32_16x16x32_bf16 v[84:87], v[144:147], v[206:209], v[84:87]
	v_mfma_f32_16x16x32_bf16 v[80:83], v[168:171], v[206:209], v[80:83]
	v_mfma_f32_16x16x32_bf16 v[68:71], v[144:147], v[214:217], v[68:71]
	v_mfma_f32_16x16x32_bf16 v[64:67], v[168:171], v[214:217], v[64:67]
	v_mfma_f32_16x16x32_bf16 v[116:119], v[148:151], v[190:193], v[116:119]
	v_mfma_f32_16x16x32_bf16 v[112:115], v[172:175], v[190:193], v[112:115]
	v_mfma_f32_16x16x32_bf16 v[100:103], v[148:151], v[202:205], v[100:103]
	v_mfma_f32_16x16x32_bf16 v[96:99], v[172:175], v[202:205], v[96:99]
	v_mfma_f32_16x16x32_bf16 v[84:87], v[148:151], v[210:213], v[84:87]
	v_mfma_f32_16x16x32_bf16 v[80:83], v[172:175], v[210:213], v[80:83]
	v_mfma_f32_16x16x32_bf16 v[68:71], v[148:151], v[218:221], v[68:71]
	v_mfma_f32_16x16x32_bf16 v[64:67], v[172:175], v[218:221], v[64:67]
	s_barrier
	s_setprio 0
	v_lshl_add_u64 v[176:177], v[176:177], 0, s[12:13]
	s_mov_b32 m0, s100
	ds_read_b128 v[186:189], v183 offset:49152
	ds_read_b128 v[190:193], v183 offset:50176
	ds_read_b128 v[198:201], v183 offset:51200
	ds_read_b128 v[202:205], v183 offset:52224
	ds_read_b128 v[206:209], v183 offset:53248
	ds_read_b128 v[210:213], v183 offset:54272
	ds_read_b128 v[214:217], v183 offset:55296
	ds_read_b128 v[218:221], v183 offset:56320
	global_load_lds_dwordx4 v[176:177], off
	s_add_i32 m0, s100, 0x2000
	v_lshl_add_u64 v[176:177], v[194:195], 0, s[12:13]
	global_load_lds_dwordx4 v[176:177], off
	s_mov_b32 m0, s101
	s_nop 0
	global_load_lds_dwordx4 v154, s[28:29]
	s_add_i32 m0, s101, 0x2000
	v_lshl_add_u64 v[176:177], s[28:29], 0, v[158:159]
	global_load_lds_dwordx4 v[176:177], off
	s_mov_b32 m0, s44
	v_lshl_add_u64 v[176:177], v[222:223], 0, s[12:13]
	global_load_lds_dwordx4 v[176:177], off
	s_mov_b32 m0, s45
	v_lshl_add_u64 v[176:177], v[224:225], 0, s[12:13]
	global_load_lds_dwordx4 v[176:177], off
	s_waitcnt vmcnt(8) lgkmcnt(0)
	s_setprio 1
	s_barrier
	v_mfma_f32_16x16x32_bf16 v[56:59], v[128:131], v[186:189], v[56:59]
	v_mfma_f32_16x16x32_bf16 v[60:63], v[136:139], v[186:189], v[60:63]
	v_mfma_f32_16x16x32_bf16 v[40:43], v[128:131], v[198:201], v[40:43]
	v_mfma_f32_16x16x32_bf16 v[44:47], v[136:139], v[198:201], v[44:47]
	v_mfma_f32_16x16x32_bf16 v[24:27], v[128:131], v[206:209], v[24:27]
	v_mfma_f32_16x16x32_bf16 v[28:31], v[136:139], v[206:209], v[28:31]
	v_mfma_f32_16x16x32_bf16 v[8:11], v[128:131], v[214:217], v[8:11]
	v_mfma_f32_16x16x32_bf16 v[12:15], v[136:139], v[214:217], v[12:15]
	v_mfma_f32_16x16x32_bf16 v[56:59], v[132:135], v[190:193], v[56:59]
	v_mfma_f32_16x16x32_bf16 v[60:63], v[140:143], v[190:193], v[60:63]
	v_mfma_f32_16x16x32_bf16 v[40:43], v[132:135], v[202:205], v[40:43]
	v_mfma_f32_16x16x32_bf16 v[44:47], v[140:143], v[202:205], v[44:47]
	v_mfma_f32_16x16x32_bf16 v[24:27], v[132:135], v[210:213], v[24:27]
	v_mfma_f32_16x16x32_bf16 v[28:31], v[140:143], v[210:213], v[28:31]
	v_mfma_f32_16x16x32_bf16 v[8:11], v[132:135], v[218:221], v[8:11]
	v_mfma_f32_16x16x32_bf16 v[12:15], v[140:143], v[218:221], v[12:15]
	v_mfma_f32_16x16x32_bf16 v[52:55], v[144:147], v[186:189], v[52:55]
	v_mfma_f32_16x16x32_bf16 v[48:51], v[168:171], v[186:189], v[48:51]
	v_mfma_f32_16x16x32_bf16 v[36:39], v[144:147], v[198:201], v[36:39]
	v_mfma_f32_16x16x32_bf16 v[32:35], v[168:171], v[198:201], v[32:35]
	v_mfma_f32_16x16x32_bf16 v[20:23], v[144:147], v[206:209], v[20:23]
	v_mfma_f32_16x16x32_bf16 v[16:19], v[168:171], v[206:209], v[16:19]
	v_mfma_f32_16x16x32_bf16 v[4:7], v[144:147], v[214:217], v[4:7]
	v_mfma_f32_16x16x32_bf16 v[0:3], v[168:171], v[214:217], v[0:3]
	v_mfma_f32_16x16x32_bf16 v[52:55], v[148:151], v[190:193], v[52:55]
	v_mfma_f32_16x16x32_bf16 v[48:51], v[172:175], v[190:193], v[48:51]
	v_mfma_f32_16x16x32_bf16 v[36:39], v[148:151], v[202:205], v[36:39]
	v_mfma_f32_16x16x32_bf16 v[32:35], v[172:175], v[202:205], v[32:35]
	v_mfma_f32_16x16x32_bf16 v[20:23], v[148:151], v[210:213], v[20:23]
	v_mfma_f32_16x16x32_bf16 v[16:19], v[172:175], v[210:213], v[16:19]
	v_mfma_f32_16x16x32_bf16 v[4:7], v[148:151], v[218:221], v[4:7]
	v_mfma_f32_16x16x32_bf16 v[0:3], v[172:175], v[218:221], v[0:3]
	s_barrier
	s_setprio 0
	s_add_i32 s50, s50, 2
	s_add_u32 s26, s26, 0x100
	s_addc_u32 s27, s27, 0
	s_add_u32 s48, s48, 0x100
	s_addc_u32 s49, s49, 0
	s_cmp_gt_u32 s50, 29
	s_cbranch_scc0 .LBB0_307
	s_and_b64 vcc, exec, s[14:15]
	s_cbranch_vccz .LBB0_310
	s_barrier

; #define PG8_STAGE(bufoff, gbase, voff) do { _Pragma("unroll") for (int _i = 0; _i < 2; ++_i) \
;         __builtin_amdgcn_global_load_lds((const unsigned*)((const char*)(gbase) + (voff)[_i]), (PG8_LAS unsigned*)(lds + (bufoff) + ldsw + _i * 8192), 16, 0, 0); } while (0)
; #define PG8_LDA(dst, b, h) do { _Pragma("unroll") for (int m = 0; m < 4; ++m) _Pragma("unroll") for (int k = 0; k < 2; ++k) dst[m][k] = *(const PG8_LAS bf16x8*)(lds + PG8_SA(b, h) + aoff + m * 2048 + k * 1024); } while (0)
; #define PG8_LDB(dst, b, h) do { _Pragma("unroll") for (int n = 0; n < 2; ++n) _Pragma("unroll") for (int k = 0; k < 2; ++k) dst[n][k] = *(const PG8_LAS bf16x8*)(lds + PG8_SB(b, h) + boff + n * 2048 + k * 1024); } while (0)
; #define PG8_MMA(ai, bj, At, Bt) do { __builtin_amdgcn_s_setprio(1); _Pragma("unroll") for (int m = 0; m < 4; ++m) _Pragma("unroll") for (int n = 0; n < 2; ++n) _Pragma("unroll") for (int k = 0; k < 2; ++k) \
;         acc[ai][bj][m][n] = __builtin_amdgcn_mfma_f32_16x16x32_bf16(Bt[n][k], At[m][k], acc[ai][bj][m][n], 0, 0, 0); __builtin_amdgcn_s_setprio(0); } while (0)
; #define PG8_BAR __builtin_amdgcn_s_barrier()
; template <class Epi, class Sched, bool ALIGN_EPI = false, bool SP2 = false>
; __device__ __forceinline__ void gemm_phase(PG8_LAS unsigned char* lds, const Gemm g, const Sched& S, const Epi& E) {
;     ...
;         const bool has_next = S.next(ui + 1, nxt);
;         const char* nA = has_next ? (const char*)g.A + (size_t)nxt.pm * tstep : cA; const char* nB = has_next ? (const char*)g.Bt + (size_t)nxt.pn * tstep : cB;
;         for (int t = 0; t < nt; t += 2) {
;             const bool last = (t == nt - 2);
;             const char* a1 = cA + (size_t)(t + 1) * kstep;
;             const char* a2 = last ? nA : cA + (size_t)(t + 2) * kstep; const char* b2 = last ? nB : cB + (size_t)(t + 2) * kstep;
;             const char* a3 = a2 + kstep; const char* b3 = b2 + kstep;
;             if (last && has_next) S.a_ready(nxt);
;             if constexpr (SP2) {
;             PG8_LDB(B0, 0, 0); PG8_LDB(B1, 0, 1); PG8_SCHED; PG8_LDA(At, 0, 0); PG8_STAGE(PG8_SA(1, 1), a1 + hstep, voffA);
;             PG8_WAIT_V(8); PG8_WAIT_L(0); PG8_BAR; PG8_MMA(0, 0, At, B0); PG8_MMA(0, 1, At, B1); PG8_BAR; PG8_SCHED;
;             PG8_LDA(At, 0, 1); PG8_STAGE(PG8_SB(0, 0), b2, voffB); PG8_STAGE(PG8_SB(0, 1), b2 + hstep, voffB); PG8_STAGE(PG8_SA(0, 0), a2, voffA);
.LBB0_490:
	s_ashr_i32 s21, s20, 31
	s_lshl_b64 s[0:1], s[20:21], 20
	v_readlane_b32 s24, v254, 51
	v_readlane_b32 s25, v254, 52
	s_add_u32 s24, s24, s0
	s_addc_u32 s25, s25, s1
	s_and_b64 s[0:1], s[22:23], exec
	s_cselect_b32 s5, s25, s31
	s_cselect_b32 s21, s24, s30
	s_ashr_i32 s19, s18, 31
	s_lshl_b64 s[0:1], s[18:19], 20
	v_readlane_b32 s26, v254, 22
	v_readlane_b32 s27, v254, 23
	s_add_u32 s26, s26, s0
	s_addc_u32 s27, s27, s1
	s_and_b64 s[0:1], s[22:23], exec
	s_cselect_b32 s19, s27, s29
	s_cselect_b32 s33, s26, s28
	s_add_u32 s0, s30, 0x80080
	s_addc_u32 s1, s31, 0
	s_add_u32 s44, s28, 0x100
	s_addc_u32 s45, s29, 0
	s_mov_b32 s48, -2
	s_add_i32 s98, s34, 0x10000
	s_add_i32 s99, s34, 0x14000
	s_add_i32 s100, s34, 0x18000
	s_add_i32 s101, s34, 0x1c000
	v_add_u32_e32 v140, s68, v163
	v_add_u32_e32 v152, s69, v163
	ds_read_b128 v[128:131], v140
	ds_read_b128 v[132:135], v140 offset:1024
	ds_read_b128 v[136:139], v140 offset:2048
	ds_read_b128 v[140:143], v140 offset:3072
	ds_read_b128 v[184:187], v152
	ds_read_b128 v[218:221], v152 offset:1024
	ds_read_b128 v[222:225], v152 offset:2048
	ds_read_b128 v[226:229], v152 offset:3072
	s_add_u32 s28, s0, 0xfff80080
	s_addc_u32 s29, s1, -1
	s_cmp_eq_u32 s48, 28
	s_cselect_b32 s31, s5, s29
	s_cselect_b32 s30, s21, s28
	s_cselect_b32 s29, s19, s45
	s_cselect_b32 s28, s33, s44
	s_add_u32 s50, s28, 0x80000
	s_addc_u32 s51, s29, 0
	s_add_i32 m0, s17, 0xc000
	ds_read_b128 v[230:233], v214
	ds_read_b128 v[234:237], v214 offset:1024
	ds_read_b128 v[238:241], v214 offset:2048
	ds_read_b128 v[242:245], v214 offset:3072
	ds_read_b128 v[246:249], v214 offset:4096
	ds_read_b128 v[250:253], v214 offset:5120
	ds_read_b128 v[206:209], v214 offset:6144
	ds_read_b128 v[210:213], v214 offset:7168
	global_load_lds_dwordx4 v156, s[0:1]
	s_add_i32 m0, s17, 0xe000
	s_nop 0
	global_load_lds_dwordx4 v158, s[0:1]
	s_waitcnt lgkmcnt(0)
	s_setprio 1
	s_barrier
	v_mfma_f32_16x16x32_bf16 v[124:127], v[128:131], v[230:233], 0
	v_mfma_f32_16x16x32_bf16 v[120:123], v[136:139], v[230:233], 0
	v_mfma_f32_16x16x32_bf16 v[116:119], v[128:131], v[238:241], 0
	v_mfma_f32_16x16x32_bf16 v[108:111], v[136:139], v[238:241], 0
	v_mfma_f32_16x16x32_bf16 v[100:103], v[128:131], v[246:249], 0
	v_mfma_f32_16x16x32_bf16 v[92:95], v[136:139], v[246:249], 0
	v_mfma_f32_16x16x32_bf16 v[84:87], v[128:131], v[206:209], 0
	v_mfma_f32_16x16x32_bf16 v[76:79], v[136:139], v[206:209], 0
	v_mfma_f32_16x16x32_bf16 v[124:127], v[132:135], v[234:237], v[124:127]
	v_mfma_f32_16x16x32_bf16 v[120:123], v[140:143], v[234:237], v[120:123]
	v_mfma_f32_16x16x32_bf16 v[116:119], v[132:135], v[242:245], v[116:119]
	v_mfma_f32_16x16x32_bf16 v[108:111], v[140:143], v[242:245], v[108:111]
	v_mfma_f32_16x16x32_bf16 v[100:103], v[132:135], v[250:253], v[100:103]
	v_mfma_f32_16x16x32_bf16 v[92:95], v[140:143], v[250:253], v[92:95]
	v_mfma_f32_16x16x32_bf16 v[84:87], v[132:135], v[210:213], v[84:87]
	v_mfma_f32_16x16x32_bf16 v[76:79], v[140:143], v[210:213], v[76:79]
	v_mfma_f32_16x16x32_bf16 v[112:115], v[184:187], v[230:233], 0
	v_mfma_f32_16x16x32_bf16 v[104:107], v[222:225], v[230:233], 0
	v_mfma_f32_16x16x32_bf16 v[96:99], v[184:187], v[238:241], 0
	v_mfma_f32_16x16x32_bf16 v[88:91], v[222:225], v[238:241], 0
	v_mfma_f32_16x16x32_bf16 v[80:83], v[184:187], v[246:249], 0
	v_mfma_f32_16x16x32_bf16 v[72:75], v[222:225], v[246:249], 0
	v_mfma_f32_16x16x32_bf16 v[68:71], v[184:187], v[206:209], 0
	v_mfma_f32_16x16x32_bf16 v[64:67], v[222:225], v[206:209], 0
	v_mfma_f32_16x16x32_bf16 v[112:115], v[218:221], v[234:237], v[112:115]
	v_mfma_f32_16x16x32_bf16 v[104:107], v[226:229], v[234:237], v[104:107]
	v_mfma_f32_16x16x32_bf16 v[96:99], v[218:221], v[242:245], v[96:99]
	v_mfma_f32_16x16x32_bf16 v[88:91], v[226:229], v[242:245], v[88:91]
	v_mfma_f32_16x16x32_bf16 v[80:83], v[218:221], v[250:253], v[80:83]
	v_mfma_f32_16x16x32_bf16 v[72:75], v[226:229], v[250:253], v[72:75]
	v_mfma_f32_16x16x32_bf16 v[68:71], v[218:221], v[210:213], v[68:71]
	v_mfma_f32_16x16x32_bf16 v[64:67], v[226:229], v[210:213], v[64:67]
	s_barrier
	s_setprio 0
	v_lshl_add_u64 v[172:173], s[28:29], 0, v[146:147]
	s_mov_b32 m0, s98
	ds_read_b128 v[206:209], v214 offset:16384
	ds_read_b128 v[210:213], v214 offset:17408
	ds_read_b128 v[230:233], v214 offset:18432
	ds_read_b128 v[234:237], v214 offset:19456
	ds_read_b128 v[238:241], v214 offset:20480
	ds_read_b128 v[242:245], v214 offset:21504
	ds_read_b128 v[246:249], v214 offset:22528
	ds_read_b128 v[250:253], v214 offset:23552
	global_load_lds_dwordx4 v[172:173], off
	s_add_i32 m0, s98, 0x2000
	v_lshl_add_u64 v[176:177], s[28:29], 0, v[150:151]
	global_load_lds_dwordx4 v[176:177], off
	s_mov_b32 m0, s99
	v_lshl_add_u64 v[188:189], s[30:31], 0, v[148:149]
	global_load_lds_dwordx4 v146, s[50:51]
	s_add_i32 m0, s99, 0x2000
	s_nop 0
	global_load_lds_dwordx4 v150, s[50:51]
	s_mov_b32 m0, s17
	v_lshl_add_u64 v[180:181], s[30:31], 0, v[144:145]
	global_load_lds_dwordx4 v[180:181], off
	s_mov_b32 m0, s35
	s_nop 0
	global_load_lds_dwordx4 v[188:189], off
	s_waitcnt lgkmcnt(0)
	s_setprio 1
	s_barrier
; #define PG8_STAGE(bufoff, gbase, voff) do { _Pragma("unroll") for (int _i = 0; _i < 2; ++_i) \
;         __builtin_amdgcn_global_load_lds((const unsigned*)((const char*)(gbase) + (voff)[_i]), (PG8_LAS unsigned*)(lds + (bufoff) + ldsw + _i * 8192), 16, 0, 0); } while (0)
; #define PG8_LDA(dst, b, h) do { _Pragma("unroll") for (int m = 0; m < 4; ++m) _Pragma("unroll") for (int k = 0; k < 2; ++k) dst[m][k] = *(const PG8_LAS bf16x8*)(lds + PG8_SA(b, h) + aoff + m * 2048 + k * 1024); } while (0)
; #define PG8_LDB(dst, b, h) do { _Pragma("unroll") for (int n = 0; n < 2; ++n) _Pragma("unroll") for (int k = 0; k < 2; ++k) dst[n][k] = *(const PG8_LAS bf16x8*)(lds + PG8_SB(b, h) + boff + n * 2048 + k * 1024); } while (0)
; #define PG8_MMA(ai, bj, At, Bt) do { __builtin_amdgcn_s_setprio(1); _Pragma("unroll") for (int m = 0; m < 4; ++m) _Pragma("unroll") for (int n = 0; n < 2; ++n) _Pragma("unroll") for (int k = 0; k < 2; ++k) \
;         acc[ai][bj][m][n] = __builtin_amdgcn_mfma_f32_16x16x32_bf16(Bt[n][k], At[m][k], acc[ai][bj][m][n], 0, 0, 0); __builtin_amdgcn_s_setprio(0); } while (0)
; #define PG8_WAIT_V(n) asm volatile("s_waitcnt vmcnt(" #n ")" ::: "memory")
; #define PG8_WAIT_L(n) asm volatile("s_waitcnt lgkmcnt(" #n ")" ::: "memory")
; #define PG8_BAR __builtin_amdgcn_s_barrier()
; #define PG8_SCHED __builtin_amdgcn_sched_barrier(0)
; template <class Epi, class Sched, bool ALIGN_EPI = false, bool SP2 = false>
; __device__ __forceinline__ void gemm_phase(PG8_LAS unsigned char* lds, const Gemm g, const Sched& S, const Epi& E) {
;     ...
;             PG8_WAIT_V(8); PG8_WAIT_L(0); PG8_BAR; PG8_MMA(1, 0, At, B0); PG8_MMA(1, 1, At, B1); PG8_BAR; PG8_SCHED;
;             PG8_LDB(B0, 1, 0); PG8_LDB(B1, 1, 1); PG8_SCHED; PG8_LDA(At, 1, 0); PG8_STAGE(PG8_SA(0, 1), a2 + hstep, voffA);
;             PG8_WAIT_V(8); PG8_WAIT_L(0); PG8_BAR; PG8_MMA(0, 0, At, B0); PG8_MMA(0, 1, At, B1); PG8_BAR; PG8_SCHED;
	v_mfma_f32_16x16x32_bf16 v[60:63], v[128:131], v[206:209], 0
	v_mfma_f32_16x16x32_bf16 v[56:59], v[136:139], v[206:209], 0
	v_mfma_f32_16x16x32_bf16 v[52:55], v[128:131], v[230:233], 0
	v_mfma_f32_16x16x32_bf16 v[44:47], v[136:139], v[230:233], 0
	v_mfma_f32_16x16x32_bf16 v[36:39], v[128:131], v[238:241], 0
	v_mfma_f32_16x16x32_bf16 v[28:31], v[136:139], v[238:241], 0
	v_mfma_f32_16x16x32_bf16 v[20:23], v[128:131], v[246:249], 0
	v_mfma_f32_16x16x32_bf16 v[12:15], v[136:139], v[246:249], 0
	v_mfma_f32_16x16x32_bf16 v[60:63], v[132:135], v[210:213], v[60:63]
	v_mfma_f32_16x16x32_bf16 v[56:59], v[140:143], v[210:213], v[56:59]
	v_mfma_f32_16x16x32_bf16 v[52:55], v[132:135], v[234:237], v[52:55]
	v_mfma_f32_16x16x32_bf16 v[44:47], v[140:143], v[234:237], v[44:47]
	v_mfma_f32_16x16x32_bf16 v[36:39], v[132:135], v[242:245], v[36:39]
	v_mfma_f32_16x16x32_bf16 v[28:31], v[140:143], v[242:245], v[28:31]
	v_mfma_f32_16x16x32_bf16 v[20:23], v[132:135], v[250:253], v[20:23]
	v_mfma_f32_16x16x32_bf16 v[12:15], v[140:143], v[250:253], v[12:15]
	v_mfma_f32_16x16x32_bf16 v[48:51], v[184:187], v[206:209], 0
	v_mfma_f32_16x16x32_bf16 v[40:43], v[222:225], v[206:209], 0
	v_mfma_f32_16x16x32_bf16 v[32:35], v[184:187], v[230:233], 0
	v_mfma_f32_16x16x32_bf16 v[24:27], v[222:225], v[230:233], 0
	v_mfma_f32_16x16x32_bf16 v[16:19], v[184:187], v[238:241], 0
	v_mfma_f32_16x16x32_bf16 v[8:11], v[222:225], v[238:241], 0
	v_mfma_f32_16x16x32_bf16 v[4:7], v[184:187], v[246:249], 0
	v_mfma_f32_16x16x32_bf16 v[0:3], v[222:225], v[246:249], 0
	v_mfma_f32_16x16x32_bf16 v[48:51], v[218:221], v[210:213], v[48:51]
	v_mfma_f32_16x16x32_bf16 v[40:43], v[226:229], v[210:213], v[40:43]
	v_mfma_f32_16x16x32_bf16 v[32:35], v[218:221], v[234:237], v[32:35]
	v_mfma_f32_16x16x32_bf16 v[24:27], v[226:229], v[234:237], v[24:27]
	v_mfma_f32_16x16x32_bf16 v[16:19], v[218:221], v[242:245], v[16:19]
	v_mfma_f32_16x16x32_bf16 v[8:11], v[226:229], v[242:245], v[8:11]
	v_mfma_f32_16x16x32_bf16 v[4:7], v[218:221], v[250:253], v[4:7]
	v_mfma_f32_16x16x32_bf16 v[0:3], v[226:229], v[250:253], v[0:3]
	s_barrier
	s_setprio 0
	s_add_i32 s49, 0, 0x18000
	s_add_i32 s50, 0, 0x1c000
	v_add_u32_e32 v140, s49, v163
	v_add_u32_e32 v152, s50, v163
	ds_read_b128 v[128:131], v140
	ds_read_b128 v[132:135], v140 offset:1024
	ds_read_b128 v[136:139], v140 offset:2048
	ds_read_b128 v[140:143], v140 offset:3072
	ds_read_b128 v[184:187], v152
	ds_read_b128 v[206:209], v152 offset:1024
	ds_read_b128 v[210:213], v152 offset:2048
	ds_read_b128 v[218:221], v152 offset:3072
	s_add_u32 s30, s30, 0x80000
	s_addc_u32 s31, s31, 0
	s_add_u32 s28, s28, 0x80080
	s_addc_u32 s29, s29, 0
	s_mov_b32 m0, s37
	ds_read_b128 v[222:225], v214 offset:32768
	ds_read_b128 v[226:229], v214 offset:33792
	ds_read_b128 v[230:233], v214 offset:34816
	ds_read_b128 v[234:237], v214 offset:35840
	ds_read_b128 v[238:241], v214 offset:36864
	ds_read_b128 v[242:245], v214 offset:37888
	ds_read_b128 v[246:249], v214 offset:38912
	ds_read_b128 v[250:253], v214 offset:39936
	global_load_lds_dwordx4 v144, s[30:31]
	s_mov_b32 m0, s39
	v_lshl_add_u64 v[216:217], s[30:31], 0, v[148:149]
	global_load_lds_dwordx4 v[216:217], off
	s_waitcnt vmcnt(8) lgkmcnt(0)
	s_setprio 1
	s_barrier
	v_mfma_f32_16x16x32_bf16 v[124:127], v[128:131], v[222:225], v[124:127]
	v_mfma_f32_16x16x32_bf16 v[120:123], v[136:139], v[222:225], v[120:123]
	v_mfma_f32_16x16x32_bf16 v[116:119], v[128:131], v[230:233], v[116:119]
	v_mfma_f32_16x16x32_bf16 v[108:111], v[136:139], v[230:233], v[108:111]
	v_mfma_f32_16x16x32_bf16 v[100:103], v[128:131], v[238:241], v[100:103]
	v_mfma_f32_16x16x32_bf16 v[92:95], v[136:139], v[238:241], v[92:95]
	v_mfma_f32_16x16x32_bf16 v[84:87], v[128:131], v[246:249], v[84:87]
	v_mfma_f32_16x16x32_bf16 v[76:79], v[136:139], v[246:249], v[76:79]
	v_mfma_f32_16x16x32_bf16 v[124:127], v[132:135], v[226:229], v[124:127]
	v_mfma_f32_16x16x32_bf16 v[120:123], v[140:143], v[226:229], v[120:123]
	v_mfma_f32_16x16x32_bf16 v[116:119], v[132:135], v[234:237], v[116:119]
	v_mfma_f32_16x16x32_bf16 v[108:111], v[140:143], v[234:237], v[108:111]
	v_mfma_f32_16x16x32_bf16 v[100:103], v[132:135], v[242:245], v[100:103]
	v_mfma_f32_16x16x32_bf16 v[92:95], v[140:143], v[242:245], v[92:95]
	v_mfma_f32_16x16x32_bf16 v[84:87], v[132:135], v[250:253], v[84:87]
	v_mfma_f32_16x16x32_bf16 v[76:79], v[140:143], v[250:253], v[76:79]
	v_mfma_f32_16x16x32_bf16 v[112:115], v[184:187], v[222:225], v[112:115]
	v_mfma_f32_16x16x32_bf16 v[104:107], v[210:213], v[222:225], v[104:107]
	v_mfma_f32_16x16x32_bf16 v[96:99], v[184:187], v[230:233], v[96:99]
	v_mfma_f32_16x16x32_bf16 v[88:91], v[210:213], v[230:233], v[88:91]
	v_mfma_f32_16x16x32_bf16 v[80:83], v[184:187], v[238:241], v[80:83]
	v_mfma_f32_16x16x32_bf16 v[72:75], v[210:213], v[238:241], v[72:75]
	v_mfma_f32_16x16x32_bf16 v[68:71], v[184:187], v[246:249], v[68:71]
	v_mfma_f32_16x16x32_bf16 v[64:67], v[210:213], v[246:249], v[64:67]
	v_mfma_f32_16x16x32_bf16 v[112:115], v[206:209], v[226:229], v[112:115]
	v_mfma_f32_16x16x32_bf16 v[104:107], v[218:221], v[226:229], v[104:107]
	v_mfma_f32_16x16x32_bf16 v[96:99], v[206:209], v[234:237], v[96:99]
	v_mfma_f32_16x16x32_bf16 v[88:91], v[218:221], v[234:237], v[88:91]
	v_mfma_f32_16x16x32_bf16 v[80:83], v[206:209], v[242:245], v[80:83]
	v_mfma_f32_16x16x32_bf16 v[72:75], v[218:221], v[242:245], v[72:75]
	v_mfma_f32_16x16x32_bf16 v[68:71], v[206:209], v[250:253], v[68:71]
	v_mfma_f32_16x16x32_bf16 v[64:67], v[218:221], v[250:253], v[64:67]
	s_barrier
; #define PG8_STAGE(bufoff, gbase, voff) do { _Pragma("unroll") for (int _i = 0; _i < 2; ++_i) \
;         __builtin_amdgcn_global_load_lds((const unsigned*)((const char*)(gbase) + (voff)[_i]), (PG8_LAS unsigned*)(lds + (bufoff) + ldsw + _i * 8192), 16, 0, 0); } while (0)
; #define PG8_LDA(dst, b, h) do { _Pragma("unroll") for (int m = 0; m < 4; ++m) _Pragma("unroll") for (int k = 0; k < 2; ++k) dst[m][k] = *(const PG8_LAS bf16x8*)(lds + PG8_SA(b, h) + aoff + m * 2048 + k * 1024); } while (0)
; #define PG8_LDB(dst, b, h) do { _Pragma("unroll") for (int n = 0; n < 2; ++n) _Pragma("unroll") for (int k = 0; k < 2; ++k) dst[n][k] = *(const PG8_LAS bf16x8*)(lds + PG8_SB(b, h) + boff + n * 2048 + k * 1024); } while (0)
; #define PG8_MMA(ai, bj, At, Bt) do { __builtin_amdgcn_s_setprio(1); _Pragma("unroll") for (int m = 0; m < 4; ++m) _Pragma("unroll") for (int n = 0; n < 2; ++n) _Pragma("unroll") for (int k = 0; k < 2; ++k) \
;         acc[ai][bj][m][n] = __builtin_amdgcn_mfma_f32_16x16x32_bf16(Bt[n][k], At[m][k], acc[ai][bj][m][n], 0, 0, 0); __builtin_amdgcn_s_setprio(0); } while (0)
; #define PG8_WAIT_V(n) asm volatile("s_waitcnt vmcnt(" #n ")" ::: "memory")
; #define PG8_BAR __builtin_amdgcn_s_barrier()
; template <class Epi, class Sched, bool ALIGN_EPI = false, bool SP2 = false>
; __device__ __forceinline__ void gemm_phase(PG8_LAS unsigned char* lds, const Gemm g, const Sched& S, const Epi& E) {
;     ...
;         for (int t = 0; t < nt; t += 2) {
;             const bool last = (t == nt - 2);
;             const char* a1 = cA + (size_t)(t + 1) * kstep;
;             const char* a2 = last ? nA : cA + (size_t)(t + 2) * kstep; const char* b2 = last ? nB : cB + (size_t)(t + 2) * kstep;
;             const char* a3 = a2 + kstep; const char* b3 = b2 + kstep;
;             if (last && has_next) S.a_ready(nxt);
;             if constexpr (SP2) {
;             PG8_LDB(B0, 0, 0); PG8_LDB(B1, 0, 1); PG8_SCHED; PG8_LDA(At, 0, 0); PG8_STAGE(PG8_SA(1, 1), a1 + hstep, voffA);
;             PG8_WAIT_V(8); PG8_WAIT_L(0); PG8_BAR; PG8_MMA(0, 0, At, B0); PG8_MMA(0, 1, At, B1); PG8_BAR; PG8_SCHED;
;     ...
;             PG8_LDA(At, 1, 1); PG8_STAGE(PG8_SB(1, 0), b3, voffB); PG8_STAGE(PG8_SB(1, 1), b3 + hstep, voffB); PG8_STAGE(PG8_SA(1, 0), a3, voffA);
;             PG8_WAIT_V(8); PG8_WAIT_L(0); PG8_BAR; PG8_MMA(1, 0, At, B0); PG8_MMA(1, 1, At, B1); PG8_BAR; PG8_SCHED;
	s_setprio 0
	v_lshl_add_u64 v[172:173], v[172:173], 0, s[10:11]
	s_mov_b32 m0, s100
	ds_read_b128 v[222:225], v214 offset:49152
	ds_read_b128 v[226:229], v214 offset:50176
	ds_read_b128 v[230:233], v214 offset:51200
	ds_read_b128 v[234:237], v214 offset:52224
	ds_read_b128 v[238:241], v214 offset:53248
	ds_read_b128 v[242:245], v214 offset:54272
	ds_read_b128 v[246:249], v214 offset:55296
	ds_read_b128 v[250:253], v214 offset:56320
	global_load_lds_dwordx4 v[172:173], off
	s_add_i32 m0, s100, 0x2000
	v_lshl_add_u64 v[172:173], v[176:177], 0, s[10:11]
	global_load_lds_dwordx4 v[172:173], off
	s_mov_b32 m0, s101
	s_nop 0
	global_load_lds_dwordx4 v146, s[28:29]
	s_add_i32 m0, s101, 0x2000
	v_lshl_add_u64 v[172:173], s[28:29], 0, v[150:151]
	global_load_lds_dwordx4 v[172:173], off
	s_mov_b32 m0, s43
	v_lshl_add_u64 v[172:173], v[180:181], 0, s[10:11]
	global_load_lds_dwordx4 v[172:173], off
	s_mov_b32 m0, s46
	v_lshl_add_u64 v[172:173], v[188:189], 0, s[10:11]
	global_load_lds_dwordx4 v[172:173], off
	s_waitcnt vmcnt(8) lgkmcnt(0)
	s_setprio 1
	s_barrier
	v_mfma_f32_16x16x32_bf16 v[60:63], v[128:131], v[222:225], v[60:63]
	v_mfma_f32_16x16x32_bf16 v[56:59], v[136:139], v[222:225], v[56:59]
	v_mfma_f32_16x16x32_bf16 v[52:55], v[128:131], v[230:233], v[52:55]
	v_mfma_f32_16x16x32_bf16 v[44:47], v[136:139], v[230:233], v[44:47]
	v_mfma_f32_16x16x32_bf16 v[36:39], v[128:131], v[238:241], v[36:39]
	v_mfma_f32_16x16x32_bf16 v[28:31], v[136:139], v[238:241], v[28:31]
	v_mfma_f32_16x16x32_bf16 v[20:23], v[128:131], v[246:249], v[20:23]
	v_mfma_f32_16x16x32_bf16 v[12:15], v[136:139], v[246:249], v[12:15]
	v_mfma_f32_16x16x32_bf16 v[60:63], v[132:135], v[226:229], v[60:63]
	v_mfma_f32_16x16x32_bf16 v[56:59], v[140:143], v[226:229], v[56:59]
	v_mfma_f32_16x16x32_bf16 v[52:55], v[132:135], v[234:237], v[52:55]
	v_mfma_f32_16x16x32_bf16 v[44:47], v[140:143], v[234:237], v[44:47]
	v_mfma_f32_16x16x32_bf16 v[36:39], v[132:135], v[242:245], v[36:39]
	v_mfma_f32_16x16x32_bf16 v[28:31], v[140:143], v[242:245], v[28:31]
	v_mfma_f32_16x16x32_bf16 v[20:23], v[132:135], v[250:253], v[20:23]
	v_mfma_f32_16x16x32_bf16 v[12:15], v[140:143], v[250:253], v[12:15]
	v_mfma_f32_16x16x32_bf16 v[48:51], v[184:187], v[222:225], v[48:51]
	v_mfma_f32_16x16x32_bf16 v[40:43], v[210:213], v[222:225], v[40:43]
	v_mfma_f32_16x16x32_bf16 v[32:35], v[184:187], v[230:233], v[32:35]
	v_mfma_f32_16x16x32_bf16 v[24:27], v[210:213], v[230:233], v[24:27]
	v_mfma_f32_16x16x32_bf16 v[16:19], v[184:187], v[238:241], v[16:19]
	v_mfma_f32_16x16x32_bf16 v[8:11], v[210:213], v[238:241], v[8:11]
	v_mfma_f32_16x16x32_bf16 v[4:7], v[184:187], v[246:249], v[4:7]
	v_mfma_f32_16x16x32_bf16 v[0:3], v[210:213], v[246:249], v[0:3]
	v_mfma_f32_16x16x32_bf16 v[48:51], v[206:209], v[226:229], v[48:51]
	v_mfma_f32_16x16x32_bf16 v[40:43], v[218:221], v[226:229], v[40:43]
	v_mfma_f32_16x16x32_bf16 v[32:35], v[206:209], v[234:237], v[32:35]
	v_mfma_f32_16x16x32_bf16 v[24:27], v[218:221], v[234:237], v[24:27]
	v_mfma_f32_16x16x32_bf16 v[16:19], v[206:209], v[242:245], v[16:19]
	v_mfma_f32_16x16x32_bf16 v[8:11], v[218:221], v[242:245], v[8:11]
	v_mfma_f32_16x16x32_bf16 v[4:7], v[206:209], v[250:253], v[4:7]
	v_mfma_f32_16x16x32_bf16 v[0:3], v[218:221], v[250:253], v[0:3]
	s_barrier
	s_setprio 0
	s_add_i32 s48, s48, 2
	s_add_u32 s0, s0, 0x100
	s_addc_u32 s1, s1, 0
	s_add_u32 s44, s44, 0x100
	s_addc_u32 s45, s45, 0
.LBB0_491:
	v_add_u32_e32 v140, s68, v163
	v_add_u32_e32 v152, s69, v163
	ds_read_b128 v[128:131], v140
	ds_read_b128 v[132:135], v140 offset:1024
	ds_read_b128 v[136:139], v140 offset:2048
	ds_read_b128 v[140:143], v140 offset:3072
	ds_read_b128 v[184:187], v152
	ds_read_b128 v[218:221], v152 offset:1024
	ds_read_b128 v[222:225], v152 offset:2048
	ds_read_b128 v[226:229], v152 offset:3072
	s_add_u32 s28, s0, 0xfff80080
	s_addc_u32 s29, s1, -1
	s_cmp_eq_u32 s48, 28
	s_cselect_b32 s31, s5, s29
	s_cselect_b32 s30, s21, s28
	s_cselect_b32 s29, s19, s45
	s_cselect_b32 s28, s33, s44
	s_add_u32 s50, s28, 0x80000
	s_addc_u32 s51, s29, 0
	s_add_i32 m0, s17, 0xc000
	ds_read_b128 v[230:233], v214
	ds_read_b128 v[234:237], v214 offset:1024
	ds_read_b128 v[238:241], v214 offset:2048
	ds_read_b128 v[242:245], v214 offset:3072
	ds_read_b128 v[246:249], v214 offset:4096
	ds_read_b128 v[250:253], v214 offset:5120
	ds_read_b128 v[206:209], v214 offset:6144
	ds_read_b128 v[210:213], v214 offset:7168
	global_load_lds_dwordx4 v156, s[0:1]
	s_add_i32 m0, s17, 0xe000
	s_nop 0
	global_load_lds_dwordx4 v158, s[0:1]
	s_waitcnt vmcnt(8) lgkmcnt(0)
	s_setprio 1
	s_barrier
; #define PG8_STAGE(bufoff, gbase, voff) do { _Pragma("unroll") for (int _i = 0; _i < 2; ++_i) \
;         __builtin_amdgcn_global_load_lds((const unsigned*)((const char*)(gbase) + (voff)[_i]), (PG8_LAS unsigned*)(lds + (bufoff) + ldsw + _i * 8192), 16, 0, 0); } while (0)
; #define PG8_LDA(dst, b, h) do { _Pragma("unroll") for (int m = 0; m < 4; ++m) _Pragma("unroll") for (int k = 0; k < 2; ++k) dst[m][k] = *(const PG8_LAS bf16x8*)(lds + PG8_SA(b, h) + aoff + m * 2048 + k * 1024); } while (0)
; #define PG8_MMA(ai, bj, At, Bt) do { __builtin_amdgcn_s_setprio(1); _Pragma("unroll") for (int m = 0; m < 4; ++m) _Pragma("unroll") for (int n = 0; n < 2; ++n) _Pragma("unroll") for (int k = 0; k < 2; ++k) \
;         acc[ai][bj][m][n] = __builtin_amdgcn_mfma_f32_16x16x32_bf16(Bt[n][k], At[m][k], acc[ai][bj][m][n], 0, 0, 0); __builtin_amdgcn_s_setprio(0); } while (0)
; #define PG8_WAIT_V(n) asm volatile("s_waitcnt vmcnt(" #n ")" ::: "memory")
; #define PG8_WAIT_L(n) asm volatile("s_waitcnt lgkmcnt(" #n ")" ::: "memory")
; #define PG8_BAR __builtin_amdgcn_s_barrier()
; #define PG8_SCHED __builtin_amdgcn_sched_barrier(0)
; template <class Epi, class Sched, bool ALIGN_EPI = false, bool SP2 = false>
; __device__ __forceinline__ void gemm_phase(PG8_LAS unsigned char* lds, const Gemm g, const Sched& S, const Epi& E) {
;     ...
;             PG8_WAIT_V(8); PG8_WAIT_L(0); PG8_BAR; PG8_MMA(0, 0, At, B0); PG8_MMA(0, 1, At, B1); PG8_BAR; PG8_SCHED;
;             PG8_LDA(At, 0, 1); PG8_STAGE(PG8_SB(0, 0), b2, voffB); PG8_STAGE(PG8_SB(0, 1), b2 + hstep, voffB); PG8_STAGE(PG8_SA(0, 0), a2, voffA);
;             PG8_WAIT_V(8); PG8_WAIT_L(0); PG8_BAR; PG8_MMA(1, 0, At, B0); PG8_MMA(1, 1, At, B1); PG8_BAR; PG8_SCHED;
	v_mfma_f32_16x16x32_bf16 v[124:127], v[128:131], v[230:233], v[124:127]
	v_mfma_f32_16x16x32_bf16 v[120:123], v[136:139], v[230:233], v[120:123]
	v_mfma_f32_16x16x32_bf16 v[116:119], v[128:131], v[238:241], v[116:119]
	v_mfma_f32_16x16x32_bf16 v[108:111], v[136:139], v[238:241], v[108:111]
	v_mfma_f32_16x16x32_bf16 v[100:103], v[128:131], v[246:249], v[100:103]
	v_mfma_f32_16x16x32_bf16 v[92:95], v[136:139], v[246:249], v[92:95]
	v_mfma_f32_16x16x32_bf16 v[84:87], v[128:131], v[206:209], v[84:87]
	v_mfma_f32_16x16x32_bf16 v[76:79], v[136:139], v[206:209], v[76:79]
	v_mfma_f32_16x16x32_bf16 v[124:127], v[132:135], v[234:237], v[124:127]
	v_mfma_f32_16x16x32_bf16 v[120:123], v[140:143], v[234:237], v[120:123]
	v_mfma_f32_16x16x32_bf16 v[116:119], v[132:135], v[242:245], v[116:119]
	v_mfma_f32_16x16x32_bf16 v[108:111], v[140:143], v[242:245], v[108:111]
	v_mfma_f32_16x16x32_bf16 v[100:103], v[132:135], v[250:253], v[100:103]
	v_mfma_f32_16x16x32_bf16 v[92:95], v[140:143], v[250:253], v[92:95]
	v_mfma_f32_16x16x32_bf16 v[84:87], v[132:135], v[210:213], v[84:87]
	v_mfma_f32_16x16x32_bf16 v[76:79], v[140:143], v[210:213], v[76:79]
	v_mfma_f32_16x16x32_bf16 v[112:115], v[184:187], v[230:233], v[112:115]
	v_mfma_f32_16x16x32_bf16 v[104:107], v[222:225], v[230:233], v[104:107]
	v_mfma_f32_16x16x32_bf16 v[96:99], v[184:187], v[238:241], v[96:99]
	v_mfma_f32_16x16x32_bf16 v[88:91], v[222:225], v[238:241], v[88:91]
	v_mfma_f32_16x16x32_bf16 v[80:83], v[184:187], v[246:249], v[80:83]
	v_mfma_f32_16x16x32_bf16 v[72:75], v[222:225], v[246:249], v[72:75]
	v_mfma_f32_16x16x32_bf16 v[68:71], v[184:187], v[206:209], v[68:71]
	v_mfma_f32_16x16x32_bf16 v[64:67], v[222:225], v[206:209], v[64:67]
	v_mfma_f32_16x16x32_bf16 v[112:115], v[218:221], v[234:237], v[112:115]
	v_mfma_f32_16x16x32_bf16 v[104:107], v[226:229], v[234:237], v[104:107]
	v_mfma_f32_16x16x32_bf16 v[96:99], v[218:221], v[242:245], v[96:99]
	v_mfma_f32_16x16x32_bf16 v[88:91], v[226:229], v[242:245], v[88:91]
	v_mfma_f32_16x16x32_bf16 v[80:83], v[218:221], v[250:253], v[80:83]
	v_mfma_f32_16x16x32_bf16 v[72:75], v[226:229], v[250:253], v[72:75]
	v_mfma_f32_16x16x32_bf16 v[68:71], v[218:221], v[210:213], v[68:71]
	v_mfma_f32_16x16x32_bf16 v[64:67], v[226:229], v[210:213], v[64:67]
	s_barrier
	s_setprio 0
	v_lshl_add_u64 v[172:173], s[28:29], 0, v[146:147]
	s_mov_b32 m0, s98
	ds_read_b128 v[206:209], v214 offset:16384
	ds_read_b128 v[210:213], v214 offset:17408
	ds_read_b128 v[230:233], v214 offset:18432
	ds_read_b128 v[234:237], v214 offset:19456
	ds_read_b128 v[238:241], v214 offset:20480
	ds_read_b128 v[242:245], v214 offset:21504
	ds_read_b128 v[246:249], v214 offset:22528
	ds_read_b128 v[250:253], v214 offset:23552
	global_load_lds_dwordx4 v[172:173], off
	s_add_i32 m0, s98, 0x2000
	v_lshl_add_u64 v[176:177], s[28:29], 0, v[150:151]
	global_load_lds_dwordx4 v[176:177], off
	s_mov_b32 m0, s99
	v_lshl_add_u64 v[188:189], s[30:31], 0, v[148:149]
	global_load_lds_dwordx4 v146, s[50:51]
	s_add_i32 m0, s99, 0x2000
	s_nop 0
	global_load_lds_dwordx4 v150, s[50:51]
	s_mov_b32 m0, s17
	v_lshl_add_u64 v[180:181], s[30:31], 0, v[144:145]
	global_load_lds_dwordx4 v[180:181], off
	s_mov_b32 m0, s35
	s_nop 0
	global_load_lds_dwordx4 v[188:189], off
	s_waitcnt vmcnt(8) lgkmcnt(0)
	s_setprio 1
	s_barrier
	v_mfma_f32_16x16x32_bf16 v[60:63], v[128:131], v[206:209], v[60:63]
	v_mfma_f32_16x16x32_bf16 v[56:59], v[136:139], v[206:209], v[56:59]
	v_mfma_f32_16x16x32_bf16 v[52:55], v[128:131], v[230:233], v[52:55]
	v_mfma_f32_16x16x32_bf16 v[44:47], v[136:139], v[230:233], v[44:47]
	v_mfma_f32_16x16x32_bf16 v[36:39], v[128:131], v[238:241], v[36:39]
	v_mfma_f32_16x16x32_bf16 v[28:31], v[136:139], v[238:241], v[28:31]
	v_mfma_f32_16x16x32_bf16 v[20:23], v[128:131], v[246:249], v[20:23]
	v_mfma_f32_16x16x32_bf16 v[12:15], v[136:139], v[246:249], v[12:15]
	v_mfma_f32_16x16x32_bf16 v[60:63], v[132:135], v[210:213], v[60:63]
	v_mfma_f32_16x16x32_bf16 v[56:59], v[140:143], v[210:213], v[56:59]
	v_mfma_f32_16x16x32_bf16 v[52:55], v[132:135], v[234:237], v[52:55]
	v_mfma_f32_16x16x32_bf16 v[44:47], v[140:143], v[234:237], v[44:47]
	v_mfma_f32_16x16x32_bf16 v[36:39], v[132:135], v[242:245], v[36:39]
	v_mfma_f32_16x16x32_bf16 v[28:31], v[140:143], v[242:245], v[28:31]
	v_mfma_f32_16x16x32_bf16 v[20:23], v[132:135], v[250:253], v[20:23]
	v_mfma_f32_16x16x32_bf16 v[12:15], v[140:143], v[250:253], v[12:15]
	v_mfma_f32_16x16x32_bf16 v[48:51], v[184:187], v[206:209], v[48:51]
	v_mfma_f32_16x16x32_bf16 v[40:43], v[222:225], v[206:209], v[40:43]
	v_mfma_f32_16x16x32_bf16 v[32:35], v[184:187], v[230:233], v[32:35]
	v_mfma_f32_16x16x32_bf16 v[24:27], v[222:225], v[230:233], v[24:27]
	v_mfma_f32_16x16x32_bf16 v[16:19], v[184:187], v[238:241], v[16:19]
	v_mfma_f32_16x16x32_bf16 v[8:11], v[222:225], v[238:241], v[8:11]
	v_mfma_f32_16x16x32_bf16 v[4:7], v[184:187], v[246:249], v[4:7]
	v_mfma_f32_16x16x32_bf16 v[0:3], v[222:225], v[246:249], v[0:3]
	v_mfma_f32_16x16x32_bf16 v[48:51], v[218:221], v[210:213], v[48:51]
	v_mfma_f32_16x16x32_bf16 v[40:43], v[226:229], v[210:213], v[40:43]
	v_mfma_f32_16x16x32_bf16 v[32:35], v[218:221], v[234:237], v[32:35]
	v_mfma_f32_16x16x32_bf16 v[24:27], v[226:229], v[234:237], v[24:27]
	v_mfma_f32_16x16x32_bf16 v[16:19], v[218:221], v[242:245], v[16:19]
	v_mfma_f32_16x16x32_bf16 v[8:11], v[226:229], v[242:245], v[8:11]
	v_mfma_f32_16x16x32_bf16 v[4:7], v[218:221], v[250:253], v[4:7]
	v_mfma_f32_16x16x32_bf16 v[0:3], v[226:229], v[250:253], v[0:3]
	s_barrier
; #define PG8_STAGE(bufoff, gbase, voff) do { _Pragma("unroll") for (int _i = 0; _i < 2; ++_i) \
;         __builtin_amdgcn_global_load_lds((const unsigned*)((const char*)(gbase) + (voff)[_i]), (PG8_LAS unsigned*)(lds + (bufoff) + ldsw + _i * 8192), 16, 0, 0); } while (0)
; #define PG8_LDA(dst, b, h) do { _Pragma("unroll") for (int m = 0; m < 4; ++m) _Pragma("unroll") for (int k = 0; k < 2; ++k) dst[m][k] = *(const PG8_LAS bf16x8*)(lds + PG8_SA(b, h) + aoff + m * 2048 + k * 1024); } while (0)
; #define PG8_LDB(dst, b, h) do { _Pragma("unroll") for (int n = 0; n < 2; ++n) _Pragma("unroll") for (int k = 0; k < 2; ++k) dst[n][k] = *(const PG8_LAS bf16x8*)(lds + PG8_SB(b, h) + boff + n * 2048 + k * 1024); } while (0)
; #define PG8_MMA(ai, bj, At, Bt) do { __builtin_amdgcn_s_setprio(1); _Pragma("unroll") for (int m = 0; m < 4; ++m) _Pragma("unroll") for (int n = 0; n < 2; ++n) _Pragma("unroll") for (int k = 0; k < 2; ++k) \
;         acc[ai][bj][m][n] = __builtin_amdgcn_mfma_f32_16x16x32_bf16(Bt[n][k], At[m][k], acc[ai][bj][m][n], 0, 0, 0); __builtin_amdgcn_s_setprio(0); } while (0)
; #define PG8_WAIT_V(n) asm volatile("s_waitcnt vmcnt(" #n ")" ::: "memory")
; #define PG8_WAIT_L(n) asm volatile("s_waitcnt lgkmcnt(" #n ")" ::: "memory")
; #define PG8_BAR __builtin_amdgcn_s_barrier()
; #define PG8_SCHED __builtin_amdgcn_sched_barrier(0)
; template <class Epi, class Sched, bool ALIGN_EPI = false, bool SP2 = false>
; __device__ __forceinline__ void gemm_phase(PG8_LAS unsigned char* lds, const Gemm g, const Sched& S, const Epi& E) {
;     ...
;             PG8_LDB(B0, 1, 0); PG8_LDB(B1, 1, 1); PG8_SCHED; PG8_LDA(At, 1, 0); PG8_STAGE(PG8_SA(0, 1), a2 + hstep, voffA);
;             PG8_WAIT_V(8); PG8_WAIT_L(0); PG8_BAR; PG8_MMA(0, 0, At, B0); PG8_MMA(0, 1, At, B1); PG8_BAR; PG8_SCHED;
;             PG8_LDA(At, 1, 1); PG8_STAGE(PG8_SB(1, 0), b3, voffB); PG8_STAGE(PG8_SB(1, 1), b3 + hstep, voffB); PG8_STAGE(PG8_SA(1, 0), a3, voffA);
;             PG8_WAIT_V(8); PG8_WAIT_L(0); PG8_BAR; PG8_MMA(1, 0, At, B0); PG8_MMA(1, 1, At, B1); PG8_BAR; PG8_SCHED;
	s_setprio 0
	s_add_i32 s49, 0, 0x18000
	s_add_i32 s50, 0, 0x1c000
	v_add_u32_e32 v140, s49, v163
	v_add_u32_e32 v152, s50, v163
	ds_read_b128 v[128:131], v140
	ds_read_b128 v[132:135], v140 offset:1024
	ds_read_b128 v[136:139], v140 offset:2048
	ds_read_b128 v[140:143], v140 offset:3072
	ds_read_b128 v[184:187], v152
	ds_read_b128 v[206:209], v152 offset:1024
	ds_read_b128 v[210:213], v152 offset:2048
	ds_read_b128 v[218:221], v152 offset:3072
	s_add_u32 s30, s30, 0x80000
	s_addc_u32 s31, s31, 0
	s_add_u32 s28, s28, 0x80080
	s_addc_u32 s29, s29, 0
	s_mov_b32 m0, s37
	ds_read_b128 v[222:225], v214 offset:32768
	ds_read_b128 v[226:229], v214 offset:33792
	ds_read_b128 v[230:233], v214 offset:34816
	ds_read_b128 v[234:237], v214 offset:35840
	ds_read_b128 v[238:241], v214 offset:36864
	ds_read_b128 v[242:245], v214 offset:37888
	ds_read_b128 v[246:249], v214 offset:38912
	ds_read_b128 v[250:253], v214 offset:39936
	global_load_lds_dwordx4 v144, s[30:31]
	s_mov_b32 m0, s39
	s_nop 0
	global_load_lds_dwordx4 v148, s[30:31]
	s_waitcnt vmcnt(8) lgkmcnt(0)
	s_setprio 1
	s_barrier
	v_mfma_f32_16x16x32_bf16 v[124:127], v[128:131], v[222:225], v[124:127]
	v_mfma_f32_16x16x32_bf16 v[120:123], v[136:139], v[222:225], v[120:123]
	v_mfma_f32_16x16x32_bf16 v[116:119], v[128:131], v[230:233], v[116:119]
	v_mfma_f32_16x16x32_bf16 v[108:111], v[136:139], v[230:233], v[108:111]
	v_mfma_f32_16x16x32_bf16 v[100:103], v[128:131], v[238:241], v[100:103]
	v_mfma_f32_16x16x32_bf16 v[92:95], v[136:139], v[238:241], v[92:95]
	v_mfma_f32_16x16x32_bf16 v[84:87], v[128:131], v[246:249], v[84:87]
	v_mfma_f32_16x16x32_bf16 v[76:79], v[136:139], v[246:249], v[76:79]
	v_mfma_f32_16x16x32_bf16 v[124:127], v[132:135], v[226:229], v[124:127]
	v_mfma_f32_16x16x32_bf16 v[120:123], v[140:143], v[226:229], v[120:123]
	v_mfma_f32_16x16x32_bf16 v[116:119], v[132:135], v[234:237], v[116:119]
	v_mfma_f32_16x16x32_bf16 v[108:111], v[140:143], v[234:237], v[108:111]
	v_mfma_f32_16x16x32_bf16 v[100:103], v[132:135], v[242:245], v[100:103]
	v_mfma_f32_16x16x32_bf16 v[92:95], v[140:143], v[242:245], v[92:95]
	v_mfma_f32_16x16x32_bf16 v[84:87], v[132:135], v[250:253], v[84:87]
	v_mfma_f32_16x16x32_bf16 v[76:79], v[140:143], v[250:253], v[76:79]
	v_mfma_f32_16x16x32_bf16 v[112:115], v[184:187], v[222:225], v[112:115]
	v_mfma_f32_16x16x32_bf16 v[104:107], v[210:213], v[222:225], v[104:107]
	v_mfma_f32_16x16x32_bf16 v[96:99], v[184:187], v[230:233], v[96:99]
	v_mfma_f32_16x16x32_bf16 v[88:91], v[210:213], v[230:233], v[88:91]
	v_mfma_f32_16x16x32_bf16 v[80:83], v[184:187], v[238:241], v[80:83]
	v_mfma_f32_16x16x32_bf16 v[72:75], v[210:213], v[238:241], v[72:75]
	v_mfma_f32_16x16x32_bf16 v[68:71], v[184:187], v[246:249], v[68:71]
	v_mfma_f32_16x16x32_bf16 v[64:67], v[210:213], v[246:249], v[64:67]
	v_mfma_f32_16x16x32_bf16 v[112:115], v[206:209], v[226:229], v[112:115]
	v_mfma_f32_16x16x32_bf16 v[104:107], v[218:221], v[226:229], v[104:107]
	v_mfma_f32_16x16x32_bf16 v[96:99], v[206:209], v[234:237], v[96:99]
	v_mfma_f32_16x16x32_bf16 v[88:91], v[218:221], v[234:237], v[88:91]
	v_mfma_f32_16x16x32_bf16 v[80:83], v[206:209], v[242:245], v[80:83]
	v_mfma_f32_16x16x32_bf16 v[72:75], v[218:221], v[242:245], v[72:75]
	v_mfma_f32_16x16x32_bf16 v[68:71], v[206:209], v[250:253], v[68:71]
	v_mfma_f32_16x16x32_bf16 v[64:67], v[218:221], v[250:253], v[64:67]
	s_barrier
	s_setprio 0
	v_lshl_add_u64 v[172:173], v[172:173], 0, s[10:11]
	s_mov_b32 m0, s100
	ds_read_b128 v[222:225], v214 offset:49152
	ds_read_b128 v[226:229], v214 offset:50176
	ds_read_b128 v[230:233], v214 offset:51200
	ds_read_b128 v[234:237], v214 offset:52224
	ds_read_b128 v[238:241], v214 offset:53248
	ds_read_b128 v[242:245], v214 offset:54272
	ds_read_b128 v[246:249], v214 offset:55296
	ds_read_b128 v[250:253], v214 offset:56320
	global_load_lds_dwordx4 v[172:173], off
	s_add_i32 m0, s100, 0x2000
	v_lshl_add_u64 v[172:173], v[176:177], 0, s[10:11]
	global_load_lds_dwordx4 v[172:173], off
	s_mov_b32 m0, s101
	s_nop 0
	global_load_lds_dwordx4 v146, s[28:29]
	s_add_i32 m0, s101, 0x2000
	v_lshl_add_u64 v[172:173], s[28:29], 0, v[150:151]
	global_load_lds_dwordx4 v[172:173], off
	s_mov_b32 m0, s43
	v_lshl_add_u64 v[172:173], v[180:181], 0, s[10:11]
	global_load_lds_dwordx4 v[172:173], off
	s_mov_b32 m0, s46
	v_lshl_add_u64 v[172:173], v[188:189], 0, s[10:11]
	global_load_lds_dwordx4 v[172:173], off
	s_waitcnt vmcnt(8) lgkmcnt(0)
	s_setprio 1
	s_barrier
	v_mfma_f32_16x16x32_bf16 v[60:63], v[128:131], v[222:225], v[60:63]
	v_mfma_f32_16x16x32_bf16 v[56:59], v[136:139], v[222:225], v[56:59]
	v_mfma_f32_16x16x32_bf16 v[52:55], v[128:131], v[230:233], v[52:55]
	v_mfma_f32_16x16x32_bf16 v[44:47], v[136:139], v[230:233], v[44:47]
	v_mfma_f32_16x16x32_bf16 v[36:39], v[128:131], v[238:241], v[36:39]
	v_mfma_f32_16x16x32_bf16 v[28:31], v[136:139], v[238:241], v[28:31]
	v_mfma_f32_16x16x32_bf16 v[20:23], v[128:131], v[246:249], v[20:23]
	v_mfma_f32_16x16x32_bf16 v[12:15], v[136:139], v[246:249], v[12:15]
	v_mfma_f32_16x16x32_bf16 v[60:63], v[132:135], v[226:229], v[60:63]
	v_mfma_f32_16x16x32_bf16 v[56:59], v[140:143], v[226:229], v[56:59]
	v_mfma_f32_16x16x32_bf16 v[52:55], v[132:135], v[234:237], v[52:55]
	v_mfma_f32_16x16x32_bf16 v[44:47], v[140:143], v[234:237], v[44:47]
	v_mfma_f32_16x16x32_bf16 v[36:39], v[132:135], v[242:245], v[36:39]
	v_mfma_f32_16x16x32_bf16 v[28:31], v[140:143], v[242:245], v[28:31]
	v_mfma_f32_16x16x32_bf16 v[20:23], v[132:135], v[250:253], v[20:23]
	v_mfma_f32_16x16x32_bf16 v[12:15], v[140:143], v[250:253], v[12:15]
	v_mfma_f32_16x16x32_bf16 v[48:51], v[184:187], v[222:225], v[48:51]
	v_mfma_f32_16x16x32_bf16 v[40:43], v[210:213], v[222:225], v[40:43]
	v_mfma_f32_16x16x32_bf16 v[32:35], v[184:187], v[230:233], v[32:35]
	v_mfma_f32_16x16x32_bf16 v[24:27], v[210:213], v[230:233], v[24:27]
	v_mfma_f32_16x16x32_bf16 v[16:19], v[184:187], v[238:241], v[16:19]
	v_mfma_f32_16x16x32_bf16 v[8:11], v[210:213], v[238:241], v[8:11]
	v_mfma_f32_16x16x32_bf16 v[4:7], v[184:187], v[246:249], v[4:7]
	v_mfma_f32_16x16x32_bf16 v[0:3], v[210:213], v[246:249], v[0:3]
	v_mfma_f32_16x16x32_bf16 v[48:51], v[206:209], v[226:229], v[48:51]
	v_mfma_f32_16x16x32_bf16 v[40:43], v[218:221], v[226:229], v[40:43]
	v_mfma_f32_16x16x32_bf16 v[32:35], v[206:209], v[234:237], v[32:35]
	v_mfma_f32_16x16x32_bf16 v[24:27], v[218:221], v[234:237], v[24:27]
	v_mfma_f32_16x16x32_bf16 v[16:19], v[206:209], v[242:245], v[16:19]
	v_mfma_f32_16x16x32_bf16 v[8:11], v[218:221], v[242:245], v[8:11]
	v_mfma_f32_16x16x32_bf16 v[4:7], v[206:209], v[250:253], v[4:7]
	v_mfma_f32_16x16x32_bf16 v[0:3], v[218:221], v[250:253], v[0:3]
	s_barrier
	s_setprio 0
	s_add_i32 s48, s48, 2
	s_add_u32 s0, s0, 0x100
	s_addc_u32 s1, s1, 0
	s_add_u32 s44, s44, 0x100
	s_addc_u32 s45, s45, 0
	s_cmp_gt_u32 s48, 29
	s_cbranch_scc0 .LBB0_491
	s_and_b64 vcc, exec, s[12:13]
	s_cbranch_vccz .LBB0_494
	s_barrier

; #define PG8_STAGE(bufoff, gbase, voff) do { _Pragma("unroll") for (int _i = 0; _i < 2; ++_i) \
;         __builtin_amdgcn_global_load_lds((const unsigned*)((const char*)(gbase) + (voff)[_i]), (PG8_LAS unsigned*)(lds + (bufoff) + ldsw + _i * 8192), 16, 0, 0); } while (0)
; #define PG8_LDA(dst, b, h) do { _Pragma("unroll") for (int m = 0; m < 4; ++m) _Pragma("unroll") for (int k = 0; k < 2; ++k) dst[m][k] = *(const PG8_LAS bf16x8*)(lds + PG8_SA(b, h) + aoff + m * 2048 + k * 1024); } while (0)
; #define PG8_LDB(dst, b, h) do { _Pragma("unroll") for (int n = 0; n < 2; ++n) _Pragma("unroll") for (int k = 0; k < 2; ++k) dst[n][k] = *(const PG8_LAS bf16x8*)(lds + PG8_SB(b, h) + boff + n * 2048 + k * 1024); } while (0)
; #define PG8_MMA(ai, bj, At, Bt) do { __builtin_amdgcn_s_setprio(1); _Pragma("unroll") for (int m = 0; m < 4; ++m) _Pragma("unroll") for (int n = 0; n < 2; ++n) _Pragma("unroll") for (int k = 0; k < 2; ++k) \
;         acc[ai][bj][m][n] = __builtin_amdgcn_mfma_f32_16x16x32_bf16(Bt[n][k], At[m][k], acc[ai][bj][m][n], 0, 0, 0); __builtin_amdgcn_s_setprio(0); } while (0)
; #define PG8_BAR __builtin_amdgcn_s_barrier()
; template <class Epi, class Sched, bool ALIGN_EPI = false, bool SP2 = false>
; __device__ __forceinline__ void gemm_phase(PG8_LAS unsigned char* lds, const Gemm g, const Sched& S, const Epi& E) {
;     ...
;         const bool has_next = S.next(ui + 1, nxt);
;         const char* nA = has_next ? (const char*)g.A + (size_t)nxt.pm * tstep : cA; const char* nB = has_next ? (const char*)g.Bt + (size_t)nxt.pn * tstep : cB;
;         for (int t = 0; t < nt; t += 2) {
;             const bool last = (t == nt - 2);
;             const char* a1 = cA + (size_t)(t + 1) * kstep;
;             const char* a2 = last ? nA : cA + (size_t)(t + 2) * kstep; const char* b2 = last ? nB : cB + (size_t)(t + 2) * kstep;
;             const char* a3 = a2 + kstep; const char* b3 = b2 + kstep;
;             if (last && has_next) S.a_ready(nxt);
;             if constexpr (SP2) {
;             PG8_LDB(B0, 0, 0); PG8_LDB(B1, 0, 1); PG8_SCHED; PG8_LDA(At, 0, 0); PG8_STAGE(PG8_SA(1, 1), a1 + hstep, voffA);
;             PG8_WAIT_V(8); PG8_WAIT_L(0); PG8_BAR; PG8_MMA(0, 0, At, B0); PG8_MMA(0, 1, At, B1); PG8_BAR; PG8_SCHED;
;             PG8_LDA(At, 0, 1); PG8_STAGE(PG8_SB(0, 0), b2, voffB); PG8_STAGE(PG8_SB(0, 1), b2 + hstep, voffB); PG8_STAGE(PG8_SA(0, 0), a2, voffA);
.LBB0_762:
	s_ashr_i32 s21, s20, 31
	s_lshl_b64 s[22:23], s[20:21], 21
	s_add_u32 s22, s60, s22
	s_addc_u32 s23, s61, s23
	s_and_b64 s[24:25], s[4:5], exec
	s_cselect_b32 s7, s23, s27
	s_cselect_b32 s21, s22, s26
	s_ashr_i32 s19, s18, 31
	s_lshl_b64 s[24:25], s[18:19], 21
	v_readlane_b32 s30, v254, 32
	v_readlane_b32 s31, v254, 33
	s_add_u32 s24, s30, s24
	s_addc_u32 s25, s31, s25
	s_and_b64 s[30:31], s[4:5], exec
	s_cselect_b32 s19, s25, s29
	s_cselect_b32 s48, s24, s28
	s_add_u32 s26, s26, 0x100080
	s_addc_u32 s27, s27, 0
	s_add_u32 s49, s28, 0x100
	s_addc_u32 s52, s29, 0
	s_mov_b32 s53, -2
	s_waitcnt lgkmcnt(0)
	s_add_i32 s98, s34, 0x10000
	s_add_i32 s99, s34, 0x14000
	s_add_i32 s100, s34, 0x18000
	s_add_i32 s101, s34, 0x1c000
	ds_read_b128 v[128:131], v181
	ds_read_b128 v[132:135], v181 offset:1024
	ds_read_b128 v[136:139], v181 offset:2048
	ds_read_b128 v[140:143], v181 offset:3072
	ds_read_b128 v[144:147], v182
	ds_read_b128 v[148:151], v182 offset:1024
	ds_read_b128 v[168:171], v182 offset:2048
	ds_read_b128 v[172:175], v182 offset:3072
	s_add_u32 s28, s26, 0xfff00080
	s_addc_u32 s29, s27, -1
	s_cmp_eq_u32 s53, 60
	s_cselect_b32 s31, s7, s29
	s_cselect_b32 s30, s21, s28
	s_cselect_b32 s29, s19, s52
	s_cselect_b32 s28, s48, s49
	s_add_u32 s54, s28, 0x100000
	s_addc_u32 s55, s29, 0
	s_add_i32 m0, s35, 0xc000
	ds_read_b128 v[186:189], v183
	ds_read_b128 v[190:193], v183 offset:1024
	ds_read_b128 v[198:201], v183 offset:2048
	ds_read_b128 v[202:205], v183 offset:3072
	ds_read_b128 v[206:209], v183 offset:4096
	ds_read_b128 v[210:213], v183 offset:5120
	ds_read_b128 v[214:217], v183 offset:6144
	ds_read_b128 v[218:221], v183 offset:7168
	global_load_lds_dwordx4 v160, s[26:27]
	s_add_i32 m0, s35, 0xe000
	s_nop 0
	global_load_lds_dwordx4 v162, s[26:27]
	s_waitcnt lgkmcnt(0)
	s_setprio 1
	s_barrier
	v_mfma_f32_16x16x32_bf16 v[124:127], v[128:131], v[186:189], 0
	v_mfma_f32_16x16x32_bf16 v[120:123], v[136:139], v[186:189], 0
	v_mfma_f32_16x16x32_bf16 v[104:107], v[128:131], v[198:201], 0
	v_mfma_f32_16x16x32_bf16 v[108:111], v[136:139], v[198:201], 0
	v_mfma_f32_16x16x32_bf16 v[88:91], v[128:131], v[206:209], 0
	v_mfma_f32_16x16x32_bf16 v[92:95], v[136:139], v[206:209], 0
	v_mfma_f32_16x16x32_bf16 v[72:75], v[128:131], v[214:217], 0
	v_mfma_f32_16x16x32_bf16 v[76:79], v[136:139], v[214:217], 0
	v_mfma_f32_16x16x32_bf16 v[124:127], v[132:135], v[190:193], v[124:127]
	v_mfma_f32_16x16x32_bf16 v[120:123], v[140:143], v[190:193], v[120:123]
	v_mfma_f32_16x16x32_bf16 v[104:107], v[132:135], v[202:205], v[104:107]
	v_mfma_f32_16x16x32_bf16 v[108:111], v[140:143], v[202:205], v[108:111]
	v_mfma_f32_16x16x32_bf16 v[88:91], v[132:135], v[210:213], v[88:91]
	v_mfma_f32_16x16x32_bf16 v[92:95], v[140:143], v[210:213], v[92:95]
	v_mfma_f32_16x16x32_bf16 v[72:75], v[132:135], v[218:221], v[72:75]
	v_mfma_f32_16x16x32_bf16 v[76:79], v[140:143], v[218:221], v[76:79]
	v_mfma_f32_16x16x32_bf16 v[116:119], v[144:147], v[186:189], 0
	v_mfma_f32_16x16x32_bf16 v[112:115], v[168:171], v[186:189], 0
	v_mfma_f32_16x16x32_bf16 v[100:103], v[144:147], v[198:201], 0
	v_mfma_f32_16x16x32_bf16 v[96:99], v[168:171], v[198:201], 0
	v_mfma_f32_16x16x32_bf16 v[84:87], v[144:147], v[206:209], 0
	v_mfma_f32_16x16x32_bf16 v[80:83], v[168:171], v[206:209], 0
	v_mfma_f32_16x16x32_bf16 v[68:71], v[144:147], v[214:217], 0
	v_mfma_f32_16x16x32_bf16 v[64:67], v[168:171], v[214:217], 0
	v_mfma_f32_16x16x32_bf16 v[116:119], v[148:151], v[190:193], v[116:119]
	v_mfma_f32_16x16x32_bf16 v[112:115], v[172:175], v[190:193], v[112:115]
	v_mfma_f32_16x16x32_bf16 v[100:103], v[148:151], v[202:205], v[100:103]
	v_mfma_f32_16x16x32_bf16 v[96:99], v[172:175], v[202:205], v[96:99]
	v_mfma_f32_16x16x32_bf16 v[84:87], v[148:151], v[210:213], v[84:87]
	v_mfma_f32_16x16x32_bf16 v[80:83], v[172:175], v[210:213], v[80:83]
	v_mfma_f32_16x16x32_bf16 v[68:71], v[148:151], v[218:221], v[68:71]
	v_mfma_f32_16x16x32_bf16 v[64:67], v[172:175], v[218:221], v[64:67]
	s_barrier
	s_setprio 0
	v_lshl_add_u64 v[176:177], s[28:29], 0, v[154:155]
	s_mov_b32 m0, s98
	ds_read_b128 v[186:189], v183 offset:16384
	ds_read_b128 v[190:193], v183 offset:17408
	ds_read_b128 v[198:201], v183 offset:18432
	ds_read_b128 v[202:205], v183 offset:19456
	ds_read_b128 v[206:209], v183 offset:20480
	ds_read_b128 v[210:213], v183 offset:21504
	ds_read_b128 v[214:217], v183 offset:22528
	ds_read_b128 v[218:221], v183 offset:23552
	global_load_lds_dwordx4 v[176:177], off
	s_add_i32 m0, s98, 0x2000
	v_lshl_add_u64 v[194:195], s[28:29], 0, v[158:159]
	global_load_lds_dwordx4 v[194:195], off
	s_mov_b32 m0, s99
	v_lshl_add_u64 v[224:225], s[30:31], 0, v[156:157]
	global_load_lds_dwordx4 v154, s[54:55]
	s_add_i32 m0, s99, 0x2000
	s_nop 0
	global_load_lds_dwordx4 v158, s[54:55]
	s_mov_b32 m0, s35
	v_lshl_add_u64 v[222:223], s[30:31], 0, v[152:153]
	global_load_lds_dwordx4 v[222:223], off
	s_mov_b32 m0, s33
	s_nop 0
	global_load_lds_dwordx4 v[224:225], off
	s_waitcnt lgkmcnt(0)
	s_setprio 1
	s_barrier
; #define PG8_STAGE(bufoff, gbase, voff) do { _Pragma("unroll") for (int _i = 0; _i < 2; ++_i) \
;         __builtin_amdgcn_global_load_lds((const unsigned*)((const char*)(gbase) + (voff)[_i]), (PG8_LAS unsigned*)(lds + (bufoff) + ldsw + _i * 8192), 16, 0, 0); } while (0)
; #define PG8_LDA(dst, b, h) do { _Pragma("unroll") for (int m = 0; m < 4; ++m) _Pragma("unroll") for (int k = 0; k < 2; ++k) dst[m][k] = *(const PG8_LAS bf16x8*)(lds + PG8_SA(b, h) + aoff + m * 2048 + k * 1024); } while (0)
; #define PG8_LDB(dst, b, h) do { _Pragma("unroll") for (int n = 0; n < 2; ++n) _Pragma("unroll") for (int k = 0; k < 2; ++k) dst[n][k] = *(const PG8_LAS bf16x8*)(lds + PG8_SB(b, h) + boff + n * 2048 + k * 1024); } while (0)
; #define PG8_MMA(ai, bj, At, Bt) do { __builtin_amdgcn_s_setprio(1); _Pragma("unroll") for (int m = 0; m < 4; ++m) _Pragma("unroll") for (int n = 0; n < 2; ++n) _Pragma("unroll") for (int k = 0; k < 2; ++k) \
;         acc[ai][bj][m][n] = __builtin_amdgcn_mfma_f32_16x16x32_bf16(Bt[n][k], At[m][k], acc[ai][bj][m][n], 0, 0, 0); __builtin_amdgcn_s_setprio(0); } while (0)
; #define PG8_WAIT_V(n) asm volatile("s_waitcnt vmcnt(" #n ")" ::: "memory")
; #define PG8_WAIT_L(n) asm volatile("s_waitcnt lgkmcnt(" #n ")" ::: "memory")
; #define PG8_BAR __builtin_amdgcn_s_barrier()
; #define PG8_SCHED __builtin_amdgcn_sched_barrier(0)
; template <class Epi, class Sched, bool ALIGN_EPI = false, bool SP2 = false>
; __device__ __forceinline__ void gemm_phase(PG8_LAS unsigned char* lds, const Gemm g, const Sched& S, const Epi& E) {
;     ...
;             PG8_WAIT_V(8); PG8_WAIT_L(0); PG8_BAR; PG8_MMA(1, 0, At, B0); PG8_MMA(1, 1, At, B1); PG8_BAR; PG8_SCHED;
;             PG8_LDB(B0, 1, 0); PG8_LDB(B1, 1, 1); PG8_SCHED; PG8_LDA(At, 1, 0); PG8_STAGE(PG8_SA(0, 1), a2 + hstep, voffA);
;             PG8_WAIT_V(8); PG8_WAIT_L(0); PG8_BAR; PG8_MMA(0, 0, At, B0); PG8_MMA(0, 1, At, B1); PG8_BAR; PG8_SCHED;
	v_mfma_f32_16x16x32_bf16 v[56:59], v[128:131], v[186:189], 0
	v_mfma_f32_16x16x32_bf16 v[60:63], v[136:139], v[186:189], 0
	v_mfma_f32_16x16x32_bf16 v[40:43], v[128:131], v[198:201], 0
	v_mfma_f32_16x16x32_bf16 v[44:47], v[136:139], v[198:201], 0
	v_mfma_f32_16x16x32_bf16 v[24:27], v[128:131], v[206:209], 0
	v_mfma_f32_16x16x32_bf16 v[28:31], v[136:139], v[206:209], 0
	v_mfma_f32_16x16x32_bf16 v[8:11], v[128:131], v[214:217], 0
	v_mfma_f32_16x16x32_bf16 v[12:15], v[136:139], v[214:217], 0
	v_mfma_f32_16x16x32_bf16 v[56:59], v[132:135], v[190:193], v[56:59]
	v_mfma_f32_16x16x32_bf16 v[60:63], v[140:143], v[190:193], v[60:63]
	v_mfma_f32_16x16x32_bf16 v[40:43], v[132:135], v[202:205], v[40:43]
	v_mfma_f32_16x16x32_bf16 v[44:47], v[140:143], v[202:205], v[44:47]
	v_mfma_f32_16x16x32_bf16 v[24:27], v[132:135], v[210:213], v[24:27]
	v_mfma_f32_16x16x32_bf16 v[28:31], v[140:143], v[210:213], v[28:31]
	v_mfma_f32_16x16x32_bf16 v[8:11], v[132:135], v[218:221], v[8:11]
	v_mfma_f32_16x16x32_bf16 v[12:15], v[140:143], v[218:221], v[12:15]
	v_mfma_f32_16x16x32_bf16 v[52:55], v[144:147], v[186:189], 0
	v_mfma_f32_16x16x32_bf16 v[48:51], v[168:171], v[186:189], 0
	v_mfma_f32_16x16x32_bf16 v[36:39], v[144:147], v[198:201], 0
	v_mfma_f32_16x16x32_bf16 v[32:35], v[168:171], v[198:201], 0
	v_mfma_f32_16x16x32_bf16 v[20:23], v[144:147], v[206:209], 0
	v_mfma_f32_16x16x32_bf16 v[16:19], v[168:171], v[206:209], 0
	v_mfma_f32_16x16x32_bf16 v[4:7], v[144:147], v[214:217], 0
	v_mfma_f32_16x16x32_bf16 v[0:3], v[168:171], v[214:217], 0
	v_mfma_f32_16x16x32_bf16 v[52:55], v[148:151], v[190:193], v[52:55]
	v_mfma_f32_16x16x32_bf16 v[48:51], v[172:175], v[190:193], v[48:51]
	v_mfma_f32_16x16x32_bf16 v[36:39], v[148:151], v[202:205], v[36:39]
	v_mfma_f32_16x16x32_bf16 v[32:35], v[172:175], v[202:205], v[32:35]
	v_mfma_f32_16x16x32_bf16 v[20:23], v[148:151], v[210:213], v[20:23]
	v_mfma_f32_16x16x32_bf16 v[16:19], v[172:175], v[210:213], v[16:19]
	v_mfma_f32_16x16x32_bf16 v[4:7], v[148:151], v[218:221], v[4:7]
	v_mfma_f32_16x16x32_bf16 v[0:3], v[172:175], v[218:221], v[0:3]
	s_barrier
	s_setprio 0
	s_add_i32 s54, 0, 0x18000
	s_add_i32 s55, 0, 0x1c000
	v_add_u32_e32 v140, s54, v179
	v_add_u32_e32 v172, s55, v179
	ds_read_b128 v[128:131], v140
	ds_read_b128 v[132:135], v140 offset:1024
	ds_read_b128 v[136:139], v140 offset:2048
	ds_read_b128 v[140:143], v140 offset:3072
	ds_read_b128 v[144:147], v172
	ds_read_b128 v[148:151], v172 offset:1024
	ds_read_b128 v[168:171], v172 offset:2048
	ds_read_b128 v[172:175], v172 offset:3072
	s_add_u32 s30, s30, 0x100000
	s_addc_u32 s31, s31, 0
	s_add_u32 s28, s28, 0x100080
	s_addc_u32 s29, s29, 0
	s_mov_b32 m0, s37
	ds_read_b128 v[186:189], v183 offset:32768
	ds_read_b128 v[190:193], v183 offset:33792
	ds_read_b128 v[198:201], v183 offset:34816
	ds_read_b128 v[202:205], v183 offset:35840
	ds_read_b128 v[206:209], v183 offset:36864
	ds_read_b128 v[210:213], v183 offset:37888
	ds_read_b128 v[214:217], v183 offset:38912
	ds_read_b128 v[218:221], v183 offset:39936
	global_load_lds_dwordx4 v152, s[30:31]
	s_mov_b32 m0, s39
	v_lshl_add_u64 v[226:227], s[30:31], 0, v[156:157]
	global_load_lds_dwordx4 v[226:227], off
	s_waitcnt vmcnt(8) lgkmcnt(0)
	s_setprio 1
	s_barrier
	v_mfma_f32_16x16x32_bf16 v[124:127], v[128:131], v[186:189], v[124:127]
	v_mfma_f32_16x16x32_bf16 v[120:123], v[136:139], v[186:189], v[120:123]
	v_mfma_f32_16x16x32_bf16 v[104:107], v[128:131], v[198:201], v[104:107]
	v_mfma_f32_16x16x32_bf16 v[108:111], v[136:139], v[198:201], v[108:111]
	v_mfma_f32_16x16x32_bf16 v[88:91], v[128:131], v[206:209], v[88:91]
	v_mfma_f32_16x16x32_bf16 v[92:95], v[136:139], v[206:209], v[92:95]
	v_mfma_f32_16x16x32_bf16 v[72:75], v[128:131], v[214:217], v[72:75]
	v_mfma_f32_16x16x32_bf16 v[76:79], v[136:139], v[214:217], v[76:79]
	v_mfma_f32_16x16x32_bf16 v[124:127], v[132:135], v[190:193], v[124:127]
	v_mfma_f32_16x16x32_bf16 v[120:123], v[140:143], v[190:193], v[120:123]
	v_mfma_f32_16x16x32_bf16 v[104:107], v[132:135], v[202:205], v[104:107]
	v_mfma_f32_16x16x32_bf16 v[108:111], v[140:143], v[202:205], v[108:111]
	v_mfma_f32_16x16x32_bf16 v[88:91], v[132:135], v[210:213], v[88:91]
	v_mfma_f32_16x16x32_bf16 v[92:95], v[140:143], v[210:213], v[92:95]
	v_mfma_f32_16x16x32_bf16 v[72:75], v[132:135], v[218:221], v[72:75]
	v_mfma_f32_16x16x32_bf16 v[76:79], v[140:143], v[218:221], v[76:79]
	v_mfma_f32_16x16x32_bf16 v[116:119], v[144:147], v[186:189], v[116:119]
	v_mfma_f32_16x16x32_bf16 v[112:115], v[168:171], v[186:189], v[112:115]
	v_mfma_f32_16x16x32_bf16 v[100:103], v[144:147], v[198:201], v[100:103]
	v_mfma_f32_16x16x32_bf16 v[96:99], v[168:171], v[198:201], v[96:99]
	v_mfma_f32_16x16x32_bf16 v[84:87], v[144:147], v[206:209], v[84:87]
	v_mfma_f32_16x16x32_bf16 v[80:83], v[168:171], v[206:209], v[80:83]
	v_mfma_f32_16x16x32_bf16 v[68:71], v[144:147], v[214:217], v[68:71]
	v_mfma_f32_16x16x32_bf16 v[64:67], v[168:171], v[214:217], v[64:67]
	v_mfma_f32_16x16x32_bf16 v[116:119], v[148:151], v[190:193], v[116:119]
	v_mfma_f32_16x16x32_bf16 v[112:115], v[172:175], v[190:193], v[112:115]
	v_mfma_f32_16x16x32_bf16 v[100:103], v[148:151], v[202:205], v[100:103]
	v_mfma_f32_16x16x32_bf16 v[96:99], v[172:175], v[202:205], v[96:99]
	v_mfma_f32_16x16x32_bf16 v[84:87], v[148:151], v[210:213], v[84:87]
	v_mfma_f32_16x16x32_bf16 v[80:83], v[172:175], v[210:213], v[80:83]
	v_mfma_f32_16x16x32_bf16 v[68:71], v[148:151], v[218:221], v[68:71]
	v_mfma_f32_16x16x32_bf16 v[64:67], v[172:175], v[218:221], v[64:67]
	s_barrier
; #define PG8_STAGE(bufoff, gbase, voff) do { _Pragma("unroll") for (int _i = 0; _i < 2; ++_i) \
;         __builtin_amdgcn_global_load_lds((const unsigned*)((const char*)(gbase) + (voff)[_i]), (PG8_LAS unsigned*)(lds + (bufoff) + ldsw + _i * 8192), 16, 0, 0); } while (0)
; #define PG8_LDA(dst, b, h) do { _Pragma("unroll") for (int m = 0; m < 4; ++m) _Pragma("unroll") for (int k = 0; k < 2; ++k) dst[m][k] = *(const PG8_LAS bf16x8*)(lds + PG8_SA(b, h) + aoff + m * 2048 + k * 1024); } while (0)
; #define PG8_LDB(dst, b, h) do { _Pragma("unroll") for (int n = 0; n < 2; ++n) _Pragma("unroll") for (int k = 0; k < 2; ++k) dst[n][k] = *(const PG8_LAS bf16x8*)(lds + PG8_SB(b, h) + boff + n * 2048 + k * 1024); } while (0)
; #define PG8_MMA(ai, bj, At, Bt) do { __builtin_amdgcn_s_setprio(1); _Pragma("unroll") for (int m = 0; m < 4; ++m) _Pragma("unroll") for (int n = 0; n < 2; ++n) _Pragma("unroll") for (int k = 0; k < 2; ++k) \
;         acc[ai][bj][m][n] = __builtin_amdgcn_mfma_f32_16x16x32_bf16(Bt[n][k], At[m][k], acc[ai][bj][m][n], 0, 0, 0); __builtin_amdgcn_s_setprio(0); } while (0)
; #define PG8_WAIT_V(n) asm volatile("s_waitcnt vmcnt(" #n ")" ::: "memory")
; #define PG8_BAR __builtin_amdgcn_s_barrier()
; template <class Epi, class Sched, bool ALIGN_EPI = false, bool SP2 = false>
; __device__ __forceinline__ void gemm_phase(PG8_LAS unsigned char* lds, const Gemm g, const Sched& S, const Epi& E) {
;     ...
;         for (int t = 0; t < nt; t += 2) {
;             const bool last = (t == nt - 2);
;             const char* a1 = cA + (size_t)(t + 1) * kstep;
;             const char* a2 = last ? nA : cA + (size_t)(t + 2) * kstep; const char* b2 = last ? nB : cB + (size_t)(t + 2) * kstep;
;             const char* a3 = a2 + kstep; const char* b3 = b2 + kstep;
;             if (last && has_next) S.a_ready(nxt);
;             if constexpr (SP2) {
;             PG8_LDB(B0, 0, 0); PG8_LDB(B1, 0, 1); PG8_SCHED; PG8_LDA(At, 0, 0); PG8_STAGE(PG8_SA(1, 1), a1 + hstep, voffA);
;             PG8_WAIT_V(8); PG8_WAIT_L(0); PG8_BAR; PG8_MMA(0, 0, At, B0); PG8_MMA(0, 1, At, B1); PG8_BAR; PG8_SCHED;
;     ...
;             PG8_LDA(At, 1, 1); PG8_STAGE(PG8_SB(1, 0), b3, voffB); PG8_STAGE(PG8_SB(1, 1), b3 + hstep, voffB); PG8_STAGE(PG8_SA(1, 0), a3, voffA);
;             PG8_WAIT_V(8); PG8_WAIT_L(0); PG8_BAR; PG8_MMA(1, 0, At, B0); PG8_MMA(1, 1, At, B1); PG8_BAR; PG8_SCHED;
	s_setprio 0
	v_lshl_add_u64 v[176:177], v[176:177], 0, s[12:13]
	s_mov_b32 m0, s100
	ds_read_b128 v[186:189], v183 offset:49152
	ds_read_b128 v[190:193], v183 offset:50176
	ds_read_b128 v[198:201], v183 offset:51200
	ds_read_b128 v[202:205], v183 offset:52224
	ds_read_b128 v[206:209], v183 offset:53248
	ds_read_b128 v[210:213], v183 offset:54272
	ds_read_b128 v[214:217], v183 offset:55296
	ds_read_b128 v[218:221], v183 offset:56320
	global_load_lds_dwordx4 v[176:177], off
	s_add_i32 m0, s100, 0x2000
	v_lshl_add_u64 v[176:177], v[194:195], 0, s[12:13]
	global_load_lds_dwordx4 v[176:177], off
	s_mov_b32 m0, s101
	s_nop 0
	global_load_lds_dwordx4 v154, s[28:29]
	s_add_i32 m0, s101, 0x2000
	v_lshl_add_u64 v[176:177], s[28:29], 0, v[158:159]
	global_load_lds_dwordx4 v[176:177], off
	s_mov_b32 m0, s43
	v_lshl_add_u64 v[176:177], v[222:223], 0, s[12:13]
	global_load_lds_dwordx4 v[176:177], off
	s_mov_b32 m0, s44
	v_lshl_add_u64 v[176:177], v[224:225], 0, s[12:13]
	global_load_lds_dwordx4 v[176:177], off
	s_waitcnt vmcnt(8) lgkmcnt(0)
	s_setprio 1
	s_barrier
	v_mfma_f32_16x16x32_bf16 v[56:59], v[128:131], v[186:189], v[56:59]
	v_mfma_f32_16x16x32_bf16 v[60:63], v[136:139], v[186:189], v[60:63]
	v_mfma_f32_16x16x32_bf16 v[40:43], v[128:131], v[198:201], v[40:43]
	v_mfma_f32_16x16x32_bf16 v[44:47], v[136:139], v[198:201], v[44:47]
	v_mfma_f32_16x16x32_bf16 v[24:27], v[128:131], v[206:209], v[24:27]
	v_mfma_f32_16x16x32_bf16 v[28:31], v[136:139], v[206:209], v[28:31]
	v_mfma_f32_16x16x32_bf16 v[8:11], v[128:131], v[214:217], v[8:11]
	v_mfma_f32_16x16x32_bf16 v[12:15], v[136:139], v[214:217], v[12:15]
	v_mfma_f32_16x16x32_bf16 v[56:59], v[132:135], v[190:193], v[56:59]
	v_mfma_f32_16x16x32_bf16 v[60:63], v[140:143], v[190:193], v[60:63]
	v_mfma_f32_16x16x32_bf16 v[40:43], v[132:135], v[202:205], v[40:43]
	v_mfma_f32_16x16x32_bf16 v[44:47], v[140:143], v[202:205], v[44:47]
	v_mfma_f32_16x16x32_bf16 v[24:27], v[132:135], v[210:213], v[24:27]
	v_mfma_f32_16x16x32_bf16 v[28:31], v[140:143], v[210:213], v[28:31]
	v_mfma_f32_16x16x32_bf16 v[8:11], v[132:135], v[218:221], v[8:11]
	v_mfma_f32_16x16x32_bf16 v[12:15], v[140:143], v[218:221], v[12:15]
	v_mfma_f32_16x16x32_bf16 v[52:55], v[144:147], v[186:189], v[52:55]
	v_mfma_f32_16x16x32_bf16 v[48:51], v[168:171], v[186:189], v[48:51]
	v_mfma_f32_16x16x32_bf16 v[36:39], v[144:147], v[198:201], v[36:39]
	v_mfma_f32_16x16x32_bf16 v[32:35], v[168:171], v[198:201], v[32:35]
	v_mfma_f32_16x16x32_bf16 v[20:23], v[144:147], v[206:209], v[20:23]
	v_mfma_f32_16x16x32_bf16 v[16:19], v[168:171], v[206:209], v[16:19]
	v_mfma_f32_16x16x32_bf16 v[4:7], v[144:147], v[214:217], v[4:7]
	v_mfma_f32_16x16x32_bf16 v[0:3], v[168:171], v[214:217], v[0:3]
	v_mfma_f32_16x16x32_bf16 v[52:55], v[148:151], v[190:193], v[52:55]
	v_mfma_f32_16x16x32_bf16 v[48:51], v[172:175], v[190:193], v[48:51]
	v_mfma_f32_16x16x32_bf16 v[36:39], v[148:151], v[202:205], v[36:39]
	v_mfma_f32_16x16x32_bf16 v[32:35], v[172:175], v[202:205], v[32:35]
	v_mfma_f32_16x16x32_bf16 v[20:23], v[148:151], v[210:213], v[20:23]
	v_mfma_f32_16x16x32_bf16 v[16:19], v[172:175], v[210:213], v[16:19]
	v_mfma_f32_16x16x32_bf16 v[4:7], v[148:151], v[218:221], v[4:7]
	v_mfma_f32_16x16x32_bf16 v[0:3], v[172:175], v[218:221], v[0:3]
	s_barrier
	s_setprio 0
	s_add_i32 s53, s53, 2
	s_add_u32 s26, s26, 0x100
	s_addc_u32 s27, s27, 0
	s_add_u32 s49, s49, 0x100
	s_addc_u32 s52, s52, 0
.LBB0_763:
	ds_read_b128 v[128:131], v181
	ds_read_b128 v[132:135], v181 offset:1024
	ds_read_b128 v[136:139], v181 offset:2048
	ds_read_b128 v[140:143], v181 offset:3072
	ds_read_b128 v[144:147], v182
	ds_read_b128 v[148:151], v182 offset:1024
	ds_read_b128 v[168:171], v182 offset:2048
	ds_read_b128 v[172:175], v182 offset:3072
	s_add_u32 s28, s26, 0xfff00080
	s_addc_u32 s29, s27, -1
	s_cmp_eq_u32 s53, 60
	s_cselect_b32 s31, s7, s29
	s_cselect_b32 s30, s21, s28
	s_cselect_b32 s29, s19, s52
	s_cselect_b32 s28, s48, s49
	s_add_u32 s54, s28, 0x100000
	s_addc_u32 s55, s29, 0
	s_add_i32 m0, s35, 0xc000
	ds_read_b128 v[186:189], v183
	ds_read_b128 v[190:193], v183 offset:1024
	ds_read_b128 v[198:201], v183 offset:2048
	ds_read_b128 v[202:205], v183 offset:3072
	ds_read_b128 v[206:209], v183 offset:4096
	ds_read_b128 v[210:213], v183 offset:5120
	ds_read_b128 v[214:217], v183 offset:6144
	ds_read_b128 v[218:221], v183 offset:7168
	global_load_lds_dwordx4 v160, s[26:27]
	s_add_i32 m0, s35, 0xe000
	s_nop 0
	global_load_lds_dwordx4 v162, s[26:27]
	s_waitcnt vmcnt(8) lgkmcnt(0)
	s_setprio 1
	s_barrier
; #define PG8_STAGE(bufoff, gbase, voff) do { _Pragma("unroll") for (int _i = 0; _i < 2; ++_i) \
;         __builtin_amdgcn_global_load_lds((const unsigned*)((const char*)(gbase) + (voff)[_i]), (PG8_LAS unsigned*)(lds + (bufoff) + ldsw + _i * 8192), 16, 0, 0); } while (0)
; #define PG8_LDA(dst, b, h) do { _Pragma("unroll") for (int m = 0; m < 4; ++m) _Pragma("unroll") for (int k = 0; k < 2; ++k) dst[m][k] = *(const PG8_LAS bf16x8*)(lds + PG8_SA(b, h) + aoff + m * 2048 + k * 1024); } while (0)
; #define PG8_MMA(ai, bj, At, Bt) do { __builtin_amdgcn_s_setprio(1); _Pragma("unroll") for (int m = 0; m < 4; ++m) _Pragma("unroll") for (int n = 0; n < 2; ++n) _Pragma("unroll") for (int k = 0; k < 2; ++k) \
;         acc[ai][bj][m][n] = __builtin_amdgcn_mfma_f32_16x16x32_bf16(Bt[n][k], At[m][k], acc[ai][bj][m][n], 0, 0, 0); __builtin_amdgcn_s_setprio(0); } while (0)
; #define PG8_WAIT_V(n) asm volatile("s_waitcnt vmcnt(" #n ")" ::: "memory")
; #define PG8_WAIT_L(n) asm volatile("s_waitcnt lgkmcnt(" #n ")" ::: "memory")
; #define PG8_BAR __builtin_amdgcn_s_barrier()
; #define PG8_SCHED __builtin_amdgcn_sched_barrier(0)
; template <class Epi, class Sched, bool ALIGN_EPI = false, bool SP2 = false>
; __device__ __forceinline__ void gemm_phase(PG8_LAS unsigned char* lds, const Gemm g, const Sched& S, const Epi& E) {
;     ...
;             PG8_WAIT_V(8); PG8_WAIT_L(0); PG8_BAR; PG8_MMA(0, 0, At, B0); PG8_MMA(0, 1, At, B1); PG8_BAR; PG8_SCHED;
;             PG8_LDA(At, 0, 1); PG8_STAGE(PG8_SB(0, 0), b2, voffB); PG8_STAGE(PG8_SB(0, 1), b2 + hstep, voffB); PG8_STAGE(PG8_SA(0, 0), a2, voffA);
;             PG8_WAIT_V(8); PG8_WAIT_L(0); PG8_BAR; PG8_MMA(1, 0, At, B0); PG8_MMA(1, 1, At, B1); PG8_BAR; PG8_SCHED;
	v_mfma_f32_16x16x32_bf16 v[124:127], v[128:131], v[186:189], v[124:127]
	v_mfma_f32_16x16x32_bf16 v[120:123], v[136:139], v[186:189], v[120:123]
	v_mfma_f32_16x16x32_bf16 v[104:107], v[128:131], v[198:201], v[104:107]
	v_mfma_f32_16x16x32_bf16 v[108:111], v[136:139], v[198:201], v[108:111]
	v_mfma_f32_16x16x32_bf16 v[88:91], v[128:131], v[206:209], v[88:91]
	v_mfma_f32_16x16x32_bf16 v[92:95], v[136:139], v[206:209], v[92:95]
	v_mfma_f32_16x16x32_bf16 v[72:75], v[128:131], v[214:217], v[72:75]
	v_mfma_f32_16x16x32_bf16 v[76:79], v[136:139], v[214:217], v[76:79]
	v_mfma_f32_16x16x32_bf16 v[124:127], v[132:135], v[190:193], v[124:127]
	v_mfma_f32_16x16x32_bf16 v[120:123], v[140:143], v[190:193], v[120:123]
	v_mfma_f32_16x16x32_bf16 v[104:107], v[132:135], v[202:205], v[104:107]
	v_mfma_f32_16x16x32_bf16 v[108:111], v[140:143], v[202:205], v[108:111]
	v_mfma_f32_16x16x32_bf16 v[88:91], v[132:135], v[210:213], v[88:91]
	v_mfma_f32_16x16x32_bf16 v[92:95], v[140:143], v[210:213], v[92:95]
	v_mfma_f32_16x16x32_bf16 v[72:75], v[132:135], v[218:221], v[72:75]
	v_mfma_f32_16x16x32_bf16 v[76:79], v[140:143], v[218:221], v[76:79]
	v_mfma_f32_16x16x32_bf16 v[116:119], v[144:147], v[186:189], v[116:119]
	v_mfma_f32_16x16x32_bf16 v[112:115], v[168:171], v[186:189], v[112:115]
	v_mfma_f32_16x16x32_bf16 v[100:103], v[144:147], v[198:201], v[100:103]
	v_mfma_f32_16x16x32_bf16 v[96:99], v[168:171], v[198:201], v[96:99]
	v_mfma_f32_16x16x32_bf16 v[84:87], v[144:147], v[206:209], v[84:87]
	v_mfma_f32_16x16x32_bf16 v[80:83], v[168:171], v[206:209], v[80:83]
	v_mfma_f32_16x16x32_bf16 v[68:71], v[144:147], v[214:217], v[68:71]
	v_mfma_f32_16x16x32_bf16 v[64:67], v[168:171], v[214:217], v[64:67]
	v_mfma_f32_16x16x32_bf16 v[116:119], v[148:151], v[190:193], v[116:119]
	v_mfma_f32_16x16x32_bf16 v[112:115], v[172:175], v[190:193], v[112:115]
	v_mfma_f32_16x16x32_bf16 v[100:103], v[148:151], v[202:205], v[100:103]
	v_mfma_f32_16x16x32_bf16 v[96:99], v[172:175], v[202:205], v[96:99]
	v_mfma_f32_16x16x32_bf16 v[84:87], v[148:151], v[210:213], v[84:87]
	v_mfma_f32_16x16x32_bf16 v[80:83], v[172:175], v[210:213], v[80:83]
	v_mfma_f32_16x16x32_bf16 v[68:71], v[148:151], v[218:221], v[68:71]
	v_mfma_f32_16x16x32_bf16 v[64:67], v[172:175], v[218:221], v[64:67]
	s_barrier
	s_setprio 0
	v_lshl_add_u64 v[176:177], s[28:29], 0, v[154:155]
	s_mov_b32 m0, s98
	ds_read_b128 v[186:189], v183 offset:16384
	ds_read_b128 v[190:193], v183 offset:17408
	ds_read_b128 v[198:201], v183 offset:18432
	ds_read_b128 v[202:205], v183 offset:19456
	ds_read_b128 v[206:209], v183 offset:20480
	ds_read_b128 v[210:213], v183 offset:21504
	ds_read_b128 v[214:217], v183 offset:22528
	ds_read_b128 v[218:221], v183 offset:23552
	global_load_lds_dwordx4 v[176:177], off
	s_add_i32 m0, s98, 0x2000
	v_lshl_add_u64 v[194:195], s[28:29], 0, v[158:159]
	global_load_lds_dwordx4 v[194:195], off
	s_mov_b32 m0, s99
	v_lshl_add_u64 v[224:225], s[30:31], 0, v[156:157]
	global_load_lds_dwordx4 v154, s[54:55]
	s_add_i32 m0, s99, 0x2000
	s_nop 0
	global_load_lds_dwordx4 v158, s[54:55]
	s_mov_b32 m0, s35
	v_lshl_add_u64 v[222:223], s[30:31], 0, v[152:153]
	global_load_lds_dwordx4 v[222:223], off
	s_mov_b32 m0, s33
	s_nop 0
	global_load_lds_dwordx4 v[224:225], off
	s_waitcnt vmcnt(8) lgkmcnt(0)
	s_setprio 1
	s_barrier
	v_mfma_f32_16x16x32_bf16 v[56:59], v[128:131], v[186:189], v[56:59]
	v_mfma_f32_16x16x32_bf16 v[60:63], v[136:139], v[186:189], v[60:63]
	v_mfma_f32_16x16x32_bf16 v[40:43], v[128:131], v[198:201], v[40:43]
	v_mfma_f32_16x16x32_bf16 v[44:47], v[136:139], v[198:201], v[44:47]
	v_mfma_f32_16x16x32_bf16 v[24:27], v[128:131], v[206:209], v[24:27]
	v_mfma_f32_16x16x32_bf16 v[28:31], v[136:139], v[206:209], v[28:31]
	v_mfma_f32_16x16x32_bf16 v[8:11], v[128:131], v[214:217], v[8:11]
	v_mfma_f32_16x16x32_bf16 v[12:15], v[136:139], v[214:217], v[12:15]
	v_mfma_f32_16x16x32_bf16 v[56:59], v[132:135], v[190:193], v[56:59]
	v_mfma_f32_16x16x32_bf16 v[60:63], v[140:143], v[190:193], v[60:63]
	v_mfma_f32_16x16x32_bf16 v[40:43], v[132:135], v[202:205], v[40:43]
	v_mfma_f32_16x16x32_bf16 v[44:47], v[140:143], v[202:205], v[44:47]
	v_mfma_f32_16x16x32_bf16 v[24:27], v[132:135], v[210:213], v[24:27]
	v_mfma_f32_16x16x32_bf16 v[28:31], v[140:143], v[210:213], v[28:31]
	v_mfma_f32_16x16x32_bf16 v[8:11], v[132:135], v[218:221], v[8:11]
	v_mfma_f32_16x16x32_bf16 v[12:15], v[140:143], v[218:221], v[12:15]
	v_mfma_f32_16x16x32_bf16 v[52:55], v[144:147], v[186:189], v[52:55]
	v_mfma_f32_16x16x32_bf16 v[48:51], v[168:171], v[186:189], v[48:51]
	v_mfma_f32_16x16x32_bf16 v[36:39], v[144:147], v[198:201], v[36:39]
	v_mfma_f32_16x16x32_bf16 v[32:35], v[168:171], v[198:201], v[32:35]
	v_mfma_f32_16x16x32_bf16 v[20:23], v[144:147], v[206:209], v[20:23]
	v_mfma_f32_16x16x32_bf16 v[16:19], v[168:171], v[206:209], v[16:19]
	v_mfma_f32_16x16x32_bf16 v[4:7], v[144:147], v[214:217], v[4:7]
	v_mfma_f32_16x16x32_bf16 v[0:3], v[168:171], v[214:217], v[0:3]
	v_mfma_f32_16x16x32_bf16 v[52:55], v[148:151], v[190:193], v[52:55]
	v_mfma_f32_16x16x32_bf16 v[48:51], v[172:175], v[190:193], v[48:51]
	v_mfma_f32_16x16x32_bf16 v[36:39], v[148:151], v[202:205], v[36:39]
	v_mfma_f32_16x16x32_bf16 v[32:35], v[172:175], v[202:205], v[32:35]
	v_mfma_f32_16x16x32_bf16 v[20:23], v[148:151], v[210:213], v[20:23]
	v_mfma_f32_16x16x32_bf16 v[16:19], v[172:175], v[210:213], v[16:19]
	v_mfma_f32_16x16x32_bf16 v[4:7], v[148:151], v[218:221], v[4:7]
	v_mfma_f32_16x16x32_bf16 v[0:3], v[172:175], v[218:221], v[0:3]
	s_barrier
; #define PG8_STAGE(bufoff, gbase, voff) do { _Pragma("unroll") for (int _i = 0; _i < 2; ++_i) \
;         __builtin_amdgcn_global_load_lds((const unsigned*)((const char*)(gbase) + (voff)[_i]), (PG8_LAS unsigned*)(lds + (bufoff) + ldsw + _i * 8192), 16, 0, 0); } while (0)
; #define PG8_LDA(dst, b, h) do { _Pragma("unroll") for (int m = 0; m < 4; ++m) _Pragma("unroll") for (int k = 0; k < 2; ++k) dst[m][k] = *(const PG8_LAS bf16x8*)(lds + PG8_SA(b, h) + aoff + m * 2048 + k * 1024); } while (0)
; #define PG8_LDB(dst, b, h) do { _Pragma("unroll") for (int n = 0; n < 2; ++n) _Pragma("unroll") for (int k = 0; k < 2; ++k) dst[n][k] = *(const PG8_LAS bf16x8*)(lds + PG8_SB(b, h) + boff + n * 2048 + k * 1024); } while (0)
; #define PG8_MMA(ai, bj, At, Bt) do { __builtin_amdgcn_s_setprio(1); _Pragma("unroll") for (int m = 0; m < 4; ++m) _Pragma("unroll") for (int n = 0; n < 2; ++n) _Pragma("unroll") for (int k = 0; k < 2; ++k) \
;         acc[ai][bj][m][n] = __builtin_amdgcn_mfma_f32_16x16x32_bf16(Bt[n][k], At[m][k], acc[ai][bj][m][n], 0, 0, 0); __builtin_amdgcn_s_setprio(0); } while (0)
; #define PG8_WAIT_V(n) asm volatile("s_waitcnt vmcnt(" #n ")" ::: "memory")
; #define PG8_WAIT_L(n) asm volatile("s_waitcnt lgkmcnt(" #n ")" ::: "memory")
; #define PG8_BAR __builtin_amdgcn_s_barrier()
; #define PG8_SCHED __builtin_amdgcn_sched_barrier(0)
; template <class Epi, class Sched, bool ALIGN_EPI = false, bool SP2 = false>
; __device__ __forceinline__ void gemm_phase(PG8_LAS unsigned char* lds, const Gemm g, const Sched& S, const Epi& E) {
;     ...
;             PG8_LDB(B0, 1, 0); PG8_LDB(B1, 1, 1); PG8_SCHED; PG8_LDA(At, 1, 0); PG8_STAGE(PG8_SA(0, 1), a2 + hstep, voffA);
;             PG8_WAIT_V(8); PG8_WAIT_L(0); PG8_BAR; PG8_MMA(0, 0, At, B0); PG8_MMA(0, 1, At, B1); PG8_BAR; PG8_SCHED;
;             PG8_LDA(At, 1, 1); PG8_STAGE(PG8_SB(1, 0), b3, voffB); PG8_STAGE(PG8_SB(1, 1), b3 + hstep, voffB); PG8_STAGE(PG8_SA(1, 0), a3, voffA);
;             PG8_WAIT_V(8); PG8_WAIT_L(0); PG8_BAR; PG8_MMA(1, 0, At, B0); PG8_MMA(1, 1, At, B1); PG8_BAR; PG8_SCHED;
	s_setprio 0
	s_add_i32 s54, 0, 0x18000
	s_add_i32 s55, 0, 0x1c000
	v_add_u32_e32 v140, s54, v179
	v_add_u32_e32 v172, s55, v179
	ds_read_b128 v[128:131], v140
	ds_read_b128 v[132:135], v140 offset:1024
	ds_read_b128 v[136:139], v140 offset:2048
	ds_read_b128 v[140:143], v140 offset:3072
	ds_read_b128 v[144:147], v172
	ds_read_b128 v[148:151], v172 offset:1024
	ds_read_b128 v[168:171], v172 offset:2048
	ds_read_b128 v[172:175], v172 offset:3072
	s_add_u32 s30, s30, 0x100000
	s_addc_u32 s31, s31, 0
	s_add_u32 s28, s28, 0x100080
	s_addc_u32 s29, s29, 0
	s_mov_b32 m0, s37
	ds_read_b128 v[186:189], v183 offset:32768
	ds_read_b128 v[190:193], v183 offset:33792
	ds_read_b128 v[198:201], v183 offset:34816
	ds_read_b128 v[202:205], v183 offset:35840
	ds_read_b128 v[206:209], v183 offset:36864
	ds_read_b128 v[210:213], v183 offset:37888
	ds_read_b128 v[214:217], v183 offset:38912
	ds_read_b128 v[218:221], v183 offset:39936
	global_load_lds_dwordx4 v152, s[30:31]
	s_mov_b32 m0, s39
	s_nop 0
	global_load_lds_dwordx4 v156, s[30:31]
	s_waitcnt vmcnt(8) lgkmcnt(0)
	s_setprio 1
	s_barrier
	v_mfma_f32_16x16x32_bf16 v[124:127], v[128:131], v[186:189], v[124:127]
	v_mfma_f32_16x16x32_bf16 v[120:123], v[136:139], v[186:189], v[120:123]
	v_mfma_f32_16x16x32_bf16 v[104:107], v[128:131], v[198:201], v[104:107]
	v_mfma_f32_16x16x32_bf16 v[108:111], v[136:139], v[198:201], v[108:111]
	v_mfma_f32_16x16x32_bf16 v[88:91], v[128:131], v[206:209], v[88:91]
	v_mfma_f32_16x16x32_bf16 v[92:95], v[136:139], v[206:209], v[92:95]
	v_mfma_f32_16x16x32_bf16 v[72:75], v[128:131], v[214:217], v[72:75]
	v_mfma_f32_16x16x32_bf16 v[76:79], v[136:139], v[214:217], v[76:79]
	v_mfma_f32_16x16x32_bf16 v[124:127], v[132:135], v[190:193], v[124:127]
	v_mfma_f32_16x16x32_bf16 v[120:123], v[140:143], v[190:193], v[120:123]
	v_mfma_f32_16x16x32_bf16 v[104:107], v[132:135], v[202:205], v[104:107]
	v_mfma_f32_16x16x32_bf16 v[108:111], v[140:143], v[202:205], v[108:111]
	v_mfma_f32_16x16x32_bf16 v[88:91], v[132:135], v[210:213], v[88:91]
	v_mfma_f32_16x16x32_bf16 v[92:95], v[140:143], v[210:213], v[92:95]
	v_mfma_f32_16x16x32_bf16 v[72:75], v[132:135], v[218:221], v[72:75]
	v_mfma_f32_16x16x32_bf16 v[76:79], v[140:143], v[218:221], v[76:79]
	v_mfma_f32_16x16x32_bf16 v[116:119], v[144:147], v[186:189], v[116:119]
	v_mfma_f32_16x16x32_bf16 v[112:115], v[168:171], v[186:189], v[112:115]
	v_mfma_f32_16x16x32_bf16 v[100:103], v[144:147], v[198:201], v[100:103]
	v_mfma_f32_16x16x32_bf16 v[96:99], v[168:171], v[198:201], v[96:99]
	v_mfma_f32_16x16x32_bf16 v[84:87], v[144:147], v[206:209], v[84:87]
	v_mfma_f32_16x16x32_bf16 v[80:83], v[168:171], v[206:209], v[80:83]
	v_mfma_f32_16x16x32_bf16 v[68:71], v[144:147], v[214:217], v[68:71]
	v_mfma_f32_16x16x32_bf16 v[64:67], v[168:171], v[214:217], v[64:67]
	v_mfma_f32_16x16x32_bf16 v[116:119], v[148:151], v[190:193], v[116:119]
	v_mfma_f32_16x16x32_bf16 v[112:115], v[172:175], v[190:193], v[112:115]
	v_mfma_f32_16x16x32_bf16 v[100:103], v[148:151], v[202:205], v[100:103]
	v_mfma_f32_16x16x32_bf16 v[96:99], v[172:175], v[202:205], v[96:99]
	v_mfma_f32_16x16x32_bf16 v[84:87], v[148:151], v[210:213], v[84:87]
	v_mfma_f32_16x16x32_bf16 v[80:83], v[172:175], v[210:213], v[80:83]
	v_mfma_f32_16x16x32_bf16 v[68:71], v[148:151], v[218:221], v[68:71]
	v_mfma_f32_16x16x32_bf16 v[64:67], v[172:175], v[218:221], v[64:67]
	s_barrier
	s_setprio 0
	v_lshl_add_u64 v[176:177], v[176:177], 0, s[12:13]
	s_mov_b32 m0, s100
	ds_read_b128 v[186:189], v183 offset:49152
	ds_read_b128 v[190:193], v183 offset:50176
	ds_read_b128 v[198:201], v183 offset:51200
	ds_read_b128 v[202:205], v183 offset:52224
	ds_read_b128 v[206:209], v183 offset:53248
	ds_read_b128 v[210:213], v183 offset:54272
	ds_read_b128 v[214:217], v183 offset:55296
	ds_read_b128 v[218:221], v183 offset:56320
	global_load_lds_dwordx4 v[176:177], off
	s_add_i32 m0, s100, 0x2000
	v_lshl_add_u64 v[176:177], v[194:195], 0, s[12:13]
	global_load_lds_dwordx4 v[176:177], off
	s_mov_b32 m0, s101
	s_nop 0
	global_load_lds_dwordx4 v154, s[28:29]
	s_add_i32 m0, s101, 0x2000
	v_lshl_add_u64 v[176:177], s[28:29], 0, v[158:159]
	global_load_lds_dwordx4 v[176:177], off
	s_mov_b32 m0, s43
	v_lshl_add_u64 v[176:177], v[222:223], 0, s[12:13]
	global_load_lds_dwordx4 v[176:177], off
	s_mov_b32 m0, s44
	v_lshl_add_u64 v[176:177], v[224:225], 0, s[12:13]
	global_load_lds_dwordx4 v[176:177], off
	s_waitcnt vmcnt(8) lgkmcnt(0)
	s_setprio 1
	s_barrier
	v_mfma_f32_16x16x32_bf16 v[56:59], v[128:131], v[186:189], v[56:59]
	v_mfma_f32_16x16x32_bf16 v[60:63], v[136:139], v[186:189], v[60:63]
	v_mfma_f32_16x16x32_bf16 v[40:43], v[128:131], v[198:201], v[40:43]
	v_mfma_f32_16x16x32_bf16 v[44:47], v[136:139], v[198:201], v[44:47]
	v_mfma_f32_16x16x32_bf16 v[24:27], v[128:131], v[206:209], v[24:27]
	v_mfma_f32_16x16x32_bf16 v[28:31], v[136:139], v[206:209], v[28:31]
	v_mfma_f32_16x16x32_bf16 v[8:11], v[128:131], v[214:217], v[8:11]
	v_mfma_f32_16x16x32_bf16 v[12:15], v[136:139], v[214:217], v[12:15]
	v_mfma_f32_16x16x32_bf16 v[56:59], v[132:135], v[190:193], v[56:59]
	v_mfma_f32_16x16x32_bf16 v[60:63], v[140:143], v[190:193], v[60:63]
	v_mfma_f32_16x16x32_bf16 v[40:43], v[132:135], v[202:205], v[40:43]
	v_mfma_f32_16x16x32_bf16 v[44:47], v[140:143], v[202:205], v[44:47]
	v_mfma_f32_16x16x32_bf16 v[24:27], v[132:135], v[210:213], v[24:27]
	v_mfma_f32_16x16x32_bf16 v[28:31], v[140:143], v[210:213], v[28:31]
	v_mfma_f32_16x16x32_bf16 v[8:11], v[132:135], v[218:221], v[8:11]
	v_mfma_f32_16x16x32_bf16 v[12:15], v[140:143], v[218:221], v[12:15]
	v_mfma_f32_16x16x32_bf16 v[52:55], v[144:147], v[186:189], v[52:55]
	v_mfma_f32_16x16x32_bf16 v[48:51], v[168:171], v[186:189], v[48:51]
	v_mfma_f32_16x16x32_bf16 v[36:39], v[144:147], v[198:201], v[36:39]
	v_mfma_f32_16x16x32_bf16 v[32:35], v[168:171], v[198:201], v[32:35]
	v_mfma_f32_16x16x32_bf16 v[20:23], v[144:147], v[206:209], v[20:23]
	v_mfma_f32_16x16x32_bf16 v[16:19], v[168:171], v[206:209], v[16:19]
	v_mfma_f32_16x16x32_bf16 v[4:7], v[144:147], v[214:217], v[4:7]
	v_mfma_f32_16x16x32_bf16 v[0:3], v[168:171], v[214:217], v[0:3]
	v_mfma_f32_16x16x32_bf16 v[52:55], v[148:151], v[190:193], v[52:55]
	v_mfma_f32_16x16x32_bf16 v[48:51], v[172:175], v[190:193], v[48:51]
	v_mfma_f32_16x16x32_bf16 v[36:39], v[148:151], v[202:205], v[36:39]
	v_mfma_f32_16x16x32_bf16 v[32:35], v[172:175], v[202:205], v[32:35]
	v_mfma_f32_16x16x32_bf16 v[20:23], v[148:151], v[210:213], v[20:23]
	v_mfma_f32_16x16x32_bf16 v[16:19], v[172:175], v[210:213], v[16:19]
	v_mfma_f32_16x16x32_bf16 v[4:7], v[148:151], v[218:221], v[4:7]
	v_mfma_f32_16x16x32_bf16 v[0:3], v[172:175], v[218:221], v[0:3]
	s_barrier
	s_setprio 0
	s_add_i32 s53, s53, 2
	s_add_u32 s26, s26, 0x100
	s_addc_u32 s27, s27, 0
	s_add_u32 s49, s49, 0x100
	s_addc_u32 s52, s52, 0
	s_cmp_gt_u32 s53, 61
	s_cbranch_scc0 .LBB0_763
	s_and_b64 vcc, exec, s[14:15]
	s_cbranch_vccz .LBB0_766
	s_barrier

; #define PG8_STAGE(bufoff, gbase, voff) do { _Pragma("unroll") for (int _i = 0; _i < 2; ++_i) \
;         __builtin_amdgcn_global_load_lds((const unsigned*)((const char*)(gbase) + (voff)[_i]), (PG8_LAS unsigned*)(lds + (bufoff) + ldsw + _i * 8192), 16, 0, 0); } while (0)
; #define PG8_LDA(dst, b, h) do { _Pragma("unroll") for (int m = 0; m < 4; ++m) _Pragma("unroll") for (int k = 0; k < 2; ++k) dst[m][k] = *(const PG8_LAS bf16x8*)(lds + PG8_SA(b, h) + aoff + m * 2048 + k * 1024); } while (0)
; #define PG8_LDB(dst, b, h) do { _Pragma("unroll") for (int n = 0; n < 2; ++n) _Pragma("unroll") for (int k = 0; k < 2; ++k) dst[n][k] = *(const PG8_LAS bf16x8*)(lds + PG8_SB(b, h) + boff + n * 2048 + k * 1024); } while (0)
; #define PG8_MMA(ai, bj, At, Bt) do { __builtin_amdgcn_s_setprio(1); _Pragma("unroll") for (int m = 0; m < 4; ++m) _Pragma("unroll") for (int n = 0; n < 2; ++n) _Pragma("unroll") for (int k = 0; k < 2; ++k) \
;         acc[ai][bj][m][n] = __builtin_amdgcn_mfma_f32_16x16x32_bf16(Bt[n][k], At[m][k], acc[ai][bj][m][n], 0, 0, 0); __builtin_amdgcn_s_setprio(0); } while (0)
; #define PG8_BAR __builtin_amdgcn_s_barrier()
; template <class Epi, class Sched, bool ALIGN_EPI = false, bool SP2 = false>
; __device__ __forceinline__ void gemm_phase(PG8_LAS unsigned char* lds, const Gemm g, const Sched& S, const Epi& E) {
;     ...
;         const bool has_next = S.next(ui + 1, nxt);
;         const char* nA = has_next ? (const char*)g.A + (size_t)nxt.pm * tstep : cA; const char* nB = has_next ? (const char*)g.Bt + (size_t)nxt.pn * tstep : cB;
;         for (int t = 0; t < nt; t += 2) {
;             const bool last = (t == nt - 2);
;             const char* a1 = cA + (size_t)(t + 1) * kstep;
;             const char* a2 = last ? nA : cA + (size_t)(t + 2) * kstep; const char* b2 = last ? nB : cB + (size_t)(t + 2) * kstep;
;             const char* a3 = a2 + kstep; const char* b3 = b2 + kstep;
;             if (last && has_next) S.a_ready(nxt);
;             if constexpr (SP2) {
;             PG8_LDB(B0, 0, 0); PG8_LDB(B1, 0, 1); PG8_SCHED; PG8_LDA(At, 0, 0); PG8_STAGE(PG8_SA(1, 1), a1 + hstep, voffA);
;             PG8_WAIT_V(8); PG8_WAIT_L(0); PG8_BAR; PG8_MMA(0, 0, At, B0); PG8_MMA(0, 1, At, B1); PG8_BAR; PG8_SCHED;
;             PG8_LDA(At, 0, 1); PG8_STAGE(PG8_SB(0, 0), b2, voffB); PG8_STAGE(PG8_SB(0, 1), b2 + hstep, voffB); PG8_STAGE(PG8_SA(0, 0), a2, voffA);
.LBB0_954:
	s_ashr_i32 s53, s52, 31
	s_lshl_b64 s[22:23], s[52:53], 20
	s_add_u32 s54, s74, s22
	s_addc_u32 s55, s75, s23
	s_and_b64 s[24:25], s[62:63], exec
	s_cselect_b32 s1, s55, s27
	s_cselect_b32 s5, s54, s26
	s_ashr_i32 s41, s40, 31
	s_lshl_b64 s[24:25], s[40:41], 20
	s_add_u32 s56, s94, s24
	s_addc_u32 s57, s95, s25
	s_and_b64 s[30:31], s[62:63], exec
	s_cselect_b32 s17, s57, s29
	s_cselect_b32 s19, s56, s28
	s_add_u32 s26, s26, 0x80080
	s_addc_u32 s27, s27, 0
	s_add_u32 s33, s28, 0x100
	s_addc_u32 s44, s29, 0
	s_mov_b32 s45, -2
	s_waitcnt vmcnt(0)
	s_add_i32 s98, s34, 0x10000
	s_add_i32 s99, s34, 0x14000
	s_add_i32 s100, s34, 0x18000
	s_add_i32 s101, s34, 0x1c000
	ds_read_b128 v[128:131], v209
	ds_read_b128 v[132:135], v209 offset:1024
	ds_read_b128 v[136:139], v209 offset:2048
	ds_read_b128 v[178:181], v209 offset:3072
	ds_read_b128 v[182:185], v210
	ds_read_b128 v[186:189], v210 offset:1024
	ds_read_b128 v[190:193], v210 offset:2048
	ds_read_b128 v[222:225], v210 offset:3072
	s_add_u32 s28, s26, 0xfff80080
	s_addc_u32 s29, s27, -1
	s_cmp_eq_u32 s45, 28
	s_cselect_b32 s31, s1, s29
	s_cselect_b32 s30, s5, s28
	s_cselect_b32 s29, s17, s44
	s_cselect_b32 s28, s19, s33
	s_add_u32 s48, s28, 0x80000
	s_addc_u32 s49, s29, 0
	s_add_i32 m0, s35, 0xc000
	ds_read_b128 v[226:229], v211
	ds_read_b128 v[230:233], v211 offset:1024
	ds_read_b128 v[234:237], v211 offset:2048
	ds_read_b128 v[238:241], v211 offset:3072
	ds_read_b128 v[242:245], v211 offset:4096
	ds_read_b128 v[246:249], v211 offset:5120
	ds_read_b128 v[250:253], v211 offset:6144
	ds_read_b128 v[160:163], v211 offset:7168
	global_load_lds_dwordx4 v150, s[26:27]
	s_add_i32 m0, s35, 0xe000
	s_nop 0
	global_load_lds_dwordx4 v152, s[26:27]
	s_waitcnt lgkmcnt(0)
	s_setprio 1
	s_barrier
	v_mfma_f32_16x16x32_bf16 v[124:127], v[128:131], v[226:229], 0
	v_mfma_f32_16x16x32_bf16 v[120:123], v[136:139], v[226:229], 0
	v_mfma_f32_16x16x32_bf16 v[116:119], v[128:131], v[234:237], 0
	v_mfma_f32_16x16x32_bf16 v[108:111], v[136:139], v[234:237], 0
	v_mfma_f32_16x16x32_bf16 v[100:103], v[128:131], v[242:245], 0
	v_mfma_f32_16x16x32_bf16 v[92:95], v[136:139], v[242:245], 0
	v_mfma_f32_16x16x32_bf16 v[84:87], v[128:131], v[250:253], 0
	v_mfma_f32_16x16x32_bf16 v[76:79], v[136:139], v[250:253], 0
	v_mfma_f32_16x16x32_bf16 v[124:127], v[132:135], v[230:233], v[124:127]
	v_mfma_f32_16x16x32_bf16 v[120:123], v[178:181], v[230:233], v[120:123]
	v_mfma_f32_16x16x32_bf16 v[116:119], v[132:135], v[238:241], v[116:119]
	v_mfma_f32_16x16x32_bf16 v[108:111], v[178:181], v[238:241], v[108:111]
	v_mfma_f32_16x16x32_bf16 v[100:103], v[132:135], v[246:249], v[100:103]
	v_mfma_f32_16x16x32_bf16 v[92:95], v[178:181], v[246:249], v[92:95]
	v_mfma_f32_16x16x32_bf16 v[84:87], v[132:135], v[160:163], v[84:87]
	v_mfma_f32_16x16x32_bf16 v[76:79], v[178:181], v[160:163], v[76:79]
	v_mfma_f32_16x16x32_bf16 v[112:115], v[182:185], v[226:229], 0
	v_mfma_f32_16x16x32_bf16 v[104:107], v[190:193], v[226:229], 0
	v_mfma_f32_16x16x32_bf16 v[96:99], v[182:185], v[234:237], 0
	v_mfma_f32_16x16x32_bf16 v[88:91], v[190:193], v[234:237], 0
	v_mfma_f32_16x16x32_bf16 v[80:83], v[182:185], v[242:245], 0
	v_mfma_f32_16x16x32_bf16 v[72:75], v[190:193], v[242:245], 0
	v_mfma_f32_16x16x32_bf16 v[68:71], v[182:185], v[250:253], 0
	v_mfma_f32_16x16x32_bf16 v[64:67], v[190:193], v[250:253], 0
	v_mfma_f32_16x16x32_bf16 v[112:115], v[186:189], v[230:233], v[112:115]
	v_mfma_f32_16x16x32_bf16 v[104:107], v[222:225], v[230:233], v[104:107]
	v_mfma_f32_16x16x32_bf16 v[96:99], v[186:189], v[238:241], v[96:99]
	v_mfma_f32_16x16x32_bf16 v[88:91], v[222:225], v[238:241], v[88:91]
	v_mfma_f32_16x16x32_bf16 v[80:83], v[186:189], v[246:249], v[80:83]
	v_mfma_f32_16x16x32_bf16 v[72:75], v[222:225], v[246:249], v[72:75]
	v_mfma_f32_16x16x32_bf16 v[68:71], v[186:189], v[160:163], v[68:71]
	v_mfma_f32_16x16x32_bf16 v[64:67], v[222:225], v[160:163], v[64:67]
	s_barrier
	s_setprio 0
	v_lshl_add_u64 v[166:167], s[28:29], 0, v[142:143]
	s_mov_b32 m0, s98
	ds_read_b128 v[160:163], v211 offset:16384
	ds_read_b128 v[226:229], v211 offset:17408
	ds_read_b128 v[230:233], v211 offset:18432
	ds_read_b128 v[234:237], v211 offset:19456
	ds_read_b128 v[238:241], v211 offset:20480
	ds_read_b128 v[242:245], v211 offset:21504
	ds_read_b128 v[246:249], v211 offset:22528
	ds_read_b128 v[250:253], v211 offset:23552
	global_load_lds_dwordx4 v[166:167], off
	s_add_i32 m0, s98, 0x2000
	v_lshl_add_u64 v[170:171], s[28:29], 0, v[146:147]
	global_load_lds_dwordx4 v[170:171], off
	s_mov_b32 m0, s99
	v_lshl_add_u64 v[194:195], s[30:31], 0, v[144:145]
	global_load_lds_dwordx4 v142, s[48:49]
	s_add_i32 m0, s99, 0x2000
	s_nop 0
	global_load_lds_dwordx4 v146, s[48:49]
	s_mov_b32 m0, s35
	v_lshl_add_u64 v[174:175], s[30:31], 0, v[140:141]
	global_load_lds_dwordx4 v[174:175], off
	s_mov_b32 m0, s37
	s_nop 0
	global_load_lds_dwordx4 v[194:195], off
	s_waitcnt lgkmcnt(0)
	s_setprio 1
	s_barrier
; #define PG8_STAGE(bufoff, gbase, voff) do { _Pragma("unroll") for (int _i = 0; _i < 2; ++_i) \
;         __builtin_amdgcn_global_load_lds((const unsigned*)((const char*)(gbase) + (voff)[_i]), (PG8_LAS unsigned*)(lds + (bufoff) + ldsw + _i * 8192), 16, 0, 0); } while (0)
; #define PG8_LDA(dst, b, h) do { _Pragma("unroll") for (int m = 0; m < 4; ++m) _Pragma("unroll") for (int k = 0; k < 2; ++k) dst[m][k] = *(const PG8_LAS bf16x8*)(lds + PG8_SA(b, h) + aoff + m * 2048 + k * 1024); } while (0)
; #define PG8_LDB(dst, b, h) do { _Pragma("unroll") for (int n = 0; n < 2; ++n) _Pragma("unroll") for (int k = 0; k < 2; ++k) dst[n][k] = *(const PG8_LAS bf16x8*)(lds + PG8_SB(b, h) + boff + n * 2048 + k * 1024); } while (0)
; #define PG8_MMA(ai, bj, At, Bt) do { __builtin_amdgcn_s_setprio(1); _Pragma("unroll") for (int m = 0; m < 4; ++m) _Pragma("unroll") for (int n = 0; n < 2; ++n) _Pragma("unroll") for (int k = 0; k < 2; ++k) \
;         acc[ai][bj][m][n] = __builtin_amdgcn_mfma_f32_16x16x32_bf16(Bt[n][k], At[m][k], acc[ai][bj][m][n], 0, 0, 0); __builtin_amdgcn_s_setprio(0); } while (0)
; #define PG8_WAIT_V(n) asm volatile("s_waitcnt vmcnt(" #n ")" ::: "memory")
; #define PG8_WAIT_L(n) asm volatile("s_waitcnt lgkmcnt(" #n ")" ::: "memory")
; #define PG8_BAR __builtin_amdgcn_s_barrier()
; #define PG8_SCHED __builtin_amdgcn_sched_barrier(0)
; template <class Epi, class Sched, bool ALIGN_EPI = false, bool SP2 = false>
; __device__ __forceinline__ void gemm_phase(PG8_LAS unsigned char* lds, const Gemm g, const Sched& S, const Epi& E) {
;     ...
;             PG8_WAIT_V(8); PG8_WAIT_L(0); PG8_BAR; PG8_MMA(1, 0, At, B0); PG8_MMA(1, 1, At, B1); PG8_BAR; PG8_SCHED;
;             PG8_LDB(B0, 1, 0); PG8_LDB(B1, 1, 1); PG8_SCHED; PG8_LDA(At, 1, 0); PG8_STAGE(PG8_SA(0, 1), a2 + hstep, voffA);
;             PG8_WAIT_V(8); PG8_WAIT_L(0); PG8_BAR; PG8_MMA(0, 0, At, B0); PG8_MMA(0, 1, At, B1); PG8_BAR; PG8_SCHED;
	v_mfma_f32_16x16x32_bf16 v[60:63], v[128:131], v[160:163], 0
	v_mfma_f32_16x16x32_bf16 v[56:59], v[136:139], v[160:163], 0
	v_mfma_f32_16x16x32_bf16 v[52:55], v[128:131], v[230:233], 0
	v_mfma_f32_16x16x32_bf16 v[44:47], v[136:139], v[230:233], 0
	v_mfma_f32_16x16x32_bf16 v[36:39], v[128:131], v[238:241], 0
	v_mfma_f32_16x16x32_bf16 v[28:31], v[136:139], v[238:241], 0
	v_mfma_f32_16x16x32_bf16 v[20:23], v[128:131], v[246:249], 0
	v_mfma_f32_16x16x32_bf16 v[12:15], v[136:139], v[246:249], 0
	v_mfma_f32_16x16x32_bf16 v[60:63], v[132:135], v[226:229], v[60:63]
	v_mfma_f32_16x16x32_bf16 v[56:59], v[178:181], v[226:229], v[56:59]
	v_mfma_f32_16x16x32_bf16 v[52:55], v[132:135], v[234:237], v[52:55]
	v_mfma_f32_16x16x32_bf16 v[44:47], v[178:181], v[234:237], v[44:47]
	v_mfma_f32_16x16x32_bf16 v[36:39], v[132:135], v[242:245], v[36:39]
	v_mfma_f32_16x16x32_bf16 v[28:31], v[178:181], v[242:245], v[28:31]
	v_mfma_f32_16x16x32_bf16 v[20:23], v[132:135], v[250:253], v[20:23]
	v_mfma_f32_16x16x32_bf16 v[12:15], v[178:181], v[250:253], v[12:15]
	v_mfma_f32_16x16x32_bf16 v[48:51], v[182:185], v[160:163], 0
	v_mfma_f32_16x16x32_bf16 v[40:43], v[190:193], v[160:163], 0
	v_mfma_f32_16x16x32_bf16 v[32:35], v[182:185], v[230:233], 0
	v_mfma_f32_16x16x32_bf16 v[24:27], v[190:193], v[230:233], 0
	v_mfma_f32_16x16x32_bf16 v[16:19], v[182:185], v[238:241], 0
	v_mfma_f32_16x16x32_bf16 v[8:11], v[190:193], v[238:241], 0
	v_mfma_f32_16x16x32_bf16 v[4:7], v[182:185], v[246:249], 0
	v_mfma_f32_16x16x32_bf16 v[0:3], v[190:193], v[246:249], 0
	v_mfma_f32_16x16x32_bf16 v[48:51], v[186:189], v[226:229], v[48:51]
	v_mfma_f32_16x16x32_bf16 v[40:43], v[222:225], v[226:229], v[40:43]
	v_mfma_f32_16x16x32_bf16 v[32:35], v[186:189], v[234:237], v[32:35]
	v_mfma_f32_16x16x32_bf16 v[24:27], v[222:225], v[234:237], v[24:27]
	v_mfma_f32_16x16x32_bf16 v[16:19], v[186:189], v[242:245], v[16:19]
	v_mfma_f32_16x16x32_bf16 v[8:11], v[222:225], v[242:245], v[8:11]
	v_mfma_f32_16x16x32_bf16 v[4:7], v[186:189], v[250:253], v[4:7]
	v_mfma_f32_16x16x32_bf16 v[0:3], v[222:225], v[250:253], v[0:3]
	s_barrier
	s_setprio 0
	s_add_i32 s48, 0, 0x18000
	v_add_u32_e32 v148, s48, v159
	s_add_i32 s49, 0, 0x1c000
	ds_read_b128 v[128:131], v148
	ds_read_b128 v[132:135], v148 offset:1024
	ds_read_b128 v[136:139], v148 offset:2048
	ds_read_b128 v[160:163], v148 offset:3072
	v_add_u32_e32 v148, s49, v159
	ds_read_b128 v[178:181], v148
	ds_read_b128 v[182:185], v148 offset:1024
	ds_read_b128 v[186:189], v148 offset:2048
	ds_read_b128 v[190:193], v148 offset:3072
	s_add_u32 s30, s30, 0x80000
	s_addc_u32 s31, s31, 0
	s_add_u32 s28, s28, 0x80080
	s_addc_u32 s29, s29, 0
	s_mov_b32 m0, s39
	ds_read_b128 v[222:225], v211 offset:32768
	ds_read_b128 v[226:229], v211 offset:33792
	ds_read_b128 v[230:233], v211 offset:34816
	ds_read_b128 v[234:237], v211 offset:35840
	ds_read_b128 v[238:241], v211 offset:36864
	ds_read_b128 v[242:245], v211 offset:37888
	ds_read_b128 v[246:249], v211 offset:38912
	ds_read_b128 v[250:253], v211 offset:39936
	global_load_lds_dwordx4 v140, s[30:31]
	s_mov_b32 m0, s42
	v_lshl_add_u64 v[154:155], s[30:31], 0, v[144:145]
	global_load_lds_dwordx4 v[154:155], off
	s_waitcnt vmcnt(8) lgkmcnt(0)
	s_setprio 1
	s_barrier
	v_mfma_f32_16x16x32_bf16 v[124:127], v[128:131], v[222:225], v[124:127]
	v_mfma_f32_16x16x32_bf16 v[120:123], v[136:139], v[222:225], v[120:123]
	v_mfma_f32_16x16x32_bf16 v[116:119], v[128:131], v[230:233], v[116:119]
	v_mfma_f32_16x16x32_bf16 v[108:111], v[136:139], v[230:233], v[108:111]
	v_mfma_f32_16x16x32_bf16 v[100:103], v[128:131], v[238:241], v[100:103]
	v_mfma_f32_16x16x32_bf16 v[92:95], v[136:139], v[238:241], v[92:95]
	v_mfma_f32_16x16x32_bf16 v[84:87], v[128:131], v[246:249], v[84:87]
	v_mfma_f32_16x16x32_bf16 v[76:79], v[136:139], v[246:249], v[76:79]
	v_mfma_f32_16x16x32_bf16 v[124:127], v[132:135], v[226:229], v[124:127]
	v_mfma_f32_16x16x32_bf16 v[120:123], v[160:163], v[226:229], v[120:123]
	v_mfma_f32_16x16x32_bf16 v[116:119], v[132:135], v[234:237], v[116:119]
	v_mfma_f32_16x16x32_bf16 v[108:111], v[160:163], v[234:237], v[108:111]
	v_mfma_f32_16x16x32_bf16 v[100:103], v[132:135], v[242:245], v[100:103]
	v_mfma_f32_16x16x32_bf16 v[92:95], v[160:163], v[242:245], v[92:95]
	v_mfma_f32_16x16x32_bf16 v[84:87], v[132:135], v[250:253], v[84:87]
	v_mfma_f32_16x16x32_bf16 v[76:79], v[160:163], v[250:253], v[76:79]
	v_mfma_f32_16x16x32_bf16 v[112:115], v[178:181], v[222:225], v[112:115]
	v_mfma_f32_16x16x32_bf16 v[104:107], v[186:189], v[222:225], v[104:107]
	v_mfma_f32_16x16x32_bf16 v[96:99], v[178:181], v[230:233], v[96:99]
	v_mfma_f32_16x16x32_bf16 v[88:91], v[186:189], v[230:233], v[88:91]
	v_mfma_f32_16x16x32_bf16 v[80:83], v[178:181], v[238:241], v[80:83]
	v_mfma_f32_16x16x32_bf16 v[72:75], v[186:189], v[238:241], v[72:75]
	v_mfma_f32_16x16x32_bf16 v[68:71], v[178:181], v[246:249], v[68:71]
	v_mfma_f32_16x16x32_bf16 v[64:67], v[186:189], v[246:249], v[64:67]
	v_mfma_f32_16x16x32_bf16 v[112:115], v[182:185], v[226:229], v[112:115]
	v_mfma_f32_16x16x32_bf16 v[104:107], v[190:193], v[226:229], v[104:107]
	v_mfma_f32_16x16x32_bf16 v[96:99], v[182:185], v[234:237], v[96:99]
	v_mfma_f32_16x16x32_bf16 v[88:91], v[190:193], v[234:237], v[88:91]
	v_mfma_f32_16x16x32_bf16 v[80:83], v[182:185], v[242:245], v[80:83]
	v_mfma_f32_16x16x32_bf16 v[72:75], v[190:193], v[242:245], v[72:75]
	v_mfma_f32_16x16x32_bf16 v[68:71], v[182:185], v[250:253], v[68:71]
	v_mfma_f32_16x16x32_bf16 v[64:67], v[190:193], v[250:253], v[64:67]
	s_barrier
; #define PG8_STAGE(bufoff, gbase, voff) do { _Pragma("unroll") for (int _i = 0; _i < 2; ++_i) \
;         __builtin_amdgcn_global_load_lds((const unsigned*)((const char*)(gbase) + (voff)[_i]), (PG8_LAS unsigned*)(lds + (bufoff) + ldsw + _i * 8192), 16, 0, 0); } while (0)
; #define PG8_LDA(dst, b, h) do { _Pragma("unroll") for (int m = 0; m < 4; ++m) _Pragma("unroll") for (int k = 0; k < 2; ++k) dst[m][k] = *(const PG8_LAS bf16x8*)(lds + PG8_SA(b, h) + aoff + m * 2048 + k * 1024); } while (0)
; #define PG8_LDB(dst, b, h) do { _Pragma("unroll") for (int n = 0; n < 2; ++n) _Pragma("unroll") for (int k = 0; k < 2; ++k) dst[n][k] = *(const PG8_LAS bf16x8*)(lds + PG8_SB(b, h) + boff + n * 2048 + k * 1024); } while (0)
; #define PG8_MMA(ai, bj, At, Bt) do { __builtin_amdgcn_s_setprio(1); _Pragma("unroll") for (int m = 0; m < 4; ++m) _Pragma("unroll") for (int n = 0; n < 2; ++n) _Pragma("unroll") for (int k = 0; k < 2; ++k) \
;         acc[ai][bj][m][n] = __builtin_amdgcn_mfma_f32_16x16x32_bf16(Bt[n][k], At[m][k], acc[ai][bj][m][n], 0, 0, 0); __builtin_amdgcn_s_setprio(0); } while (0)
; #define PG8_WAIT_V(n) asm volatile("s_waitcnt vmcnt(" #n ")" ::: "memory")
; template <class Epi, class Sched, bool ALIGN_EPI = false, bool SP2 = false>
; __device__ __forceinline__ void gemm_phase(PG8_LAS unsigned char* lds, const Gemm g, const Sched& S, const Epi& E) {
;     ...
;             PG8_LDB(B0, 0, 0); PG8_LDB(B1, 0, 1); PG8_SCHED; PG8_LDA(At, 0, 0); PG8_STAGE(PG8_SA(1, 1), a1 + hstep, voffA);
;             PG8_WAIT_V(8); PG8_WAIT_L(0); PG8_BAR; PG8_MMA(0, 0, At, B0); PG8_MMA(0, 1, At, B1); PG8_BAR; PG8_SCHED;
;             PG8_LDA(At, 0, 1); PG8_STAGE(PG8_SB(0, 0), b2, voffB); PG8_STAGE(PG8_SB(0, 1), b2 + hstep, voffB); PG8_STAGE(PG8_SA(0, 0), a2, voffA);
;             PG8_WAIT_V(8); PG8_WAIT_L(0); PG8_BAR; PG8_MMA(1, 0, At, B0); PG8_MMA(1, 1, At, B1); PG8_BAR; PG8_SCHED;
;             PG8_LDB(B0, 1, 0); PG8_LDB(B1, 1, 1); PG8_SCHED; PG8_LDA(At, 1, 0); PG8_STAGE(PG8_SA(0, 1), a2 + hstep, voffA);
;             PG8_WAIT_V(8); PG8_WAIT_L(0); PG8_BAR; PG8_MMA(0, 0, At, B0); PG8_MMA(0, 1, At, B1); PG8_BAR; PG8_SCHED;
;             PG8_LDA(At, 1, 1); PG8_STAGE(PG8_SB(1, 0), b3, voffB); PG8_STAGE(PG8_SB(1, 1), b3 + hstep, voffB); PG8_STAGE(PG8_SA(1, 0), a3, voffA);
;             PG8_WAIT_V(8); PG8_WAIT_L(0); PG8_BAR; PG8_MMA(1, 0, At, B0); PG8_MMA(1, 1, At, B1); PG8_BAR; PG8_SCHED;
	s_setprio 0
	v_lshl_add_u64 v[154:155], v[166:167], 0, s[10:11]
	s_mov_b32 m0, s100
	ds_read_b128 v[222:225], v211 offset:49152
	ds_read_b128 v[226:229], v211 offset:50176
	ds_read_b128 v[230:233], v211 offset:51200
	ds_read_b128 v[234:237], v211 offset:52224
	ds_read_b128 v[238:241], v211 offset:53248
	ds_read_b128 v[242:245], v211 offset:54272
	ds_read_b128 v[246:249], v211 offset:55296
	ds_read_b128 v[250:253], v211 offset:56320
	global_load_lds_dwordx4 v[154:155], off
	s_add_i32 m0, s100, 0x2000
	v_lshl_add_u64 v[154:155], v[170:171], 0, s[10:11]
	global_load_lds_dwordx4 v[154:155], off
	s_mov_b32 m0, s101
	s_nop 0
	global_load_lds_dwordx4 v142, s[28:29]
	s_add_i32 m0, s101, 0x2000
	v_lshl_add_u64 v[154:155], s[28:29], 0, v[146:147]
	global_load_lds_dwordx4 v[154:155], off
	s_mov_b32 m0, s46
	v_lshl_add_u64 v[154:155], v[174:175], 0, s[10:11]
	global_load_lds_dwordx4 v[154:155], off
	s_mov_b32 m0, s47
	v_lshl_add_u64 v[154:155], v[194:195], 0, s[10:11]
	global_load_lds_dwordx4 v[154:155], off
	s_waitcnt vmcnt(8) lgkmcnt(0)
	s_setprio 1
	s_barrier
	v_mfma_f32_16x16x32_bf16 v[60:63], v[128:131], v[222:225], v[60:63]
	v_mfma_f32_16x16x32_bf16 v[56:59], v[136:139], v[222:225], v[56:59]
	v_mfma_f32_16x16x32_bf16 v[52:55], v[128:131], v[230:233], v[52:55]
	v_mfma_f32_16x16x32_bf16 v[44:47], v[136:139], v[230:233], v[44:47]
	v_mfma_f32_16x16x32_bf16 v[36:39], v[128:131], v[238:241], v[36:39]
	v_mfma_f32_16x16x32_bf16 v[28:31], v[136:139], v[238:241], v[28:31]
	v_mfma_f32_16x16x32_bf16 v[20:23], v[128:131], v[246:249], v[20:23]
	v_mfma_f32_16x16x32_bf16 v[12:15], v[136:139], v[246:249], v[12:15]
	v_mfma_f32_16x16x32_bf16 v[60:63], v[132:135], v[226:229], v[60:63]
	v_mfma_f32_16x16x32_bf16 v[56:59], v[160:163], v[226:229], v[56:59]
	v_mfma_f32_16x16x32_bf16 v[52:55], v[132:135], v[234:237], v[52:55]
	v_mfma_f32_16x16x32_bf16 v[44:47], v[160:163], v[234:237], v[44:47]
	v_mfma_f32_16x16x32_bf16 v[36:39], v[132:135], v[242:245], v[36:39]
	v_mfma_f32_16x16x32_bf16 v[28:31], v[160:163], v[242:245], v[28:31]
	v_mfma_f32_16x16x32_bf16 v[20:23], v[132:135], v[250:253], v[20:23]
	v_mfma_f32_16x16x32_bf16 v[12:15], v[160:163], v[250:253], v[12:15]
	v_mfma_f32_16x16x32_bf16 v[48:51], v[178:181], v[222:225], v[48:51]
	v_mfma_f32_16x16x32_bf16 v[40:43], v[186:189], v[222:225], v[40:43]
	v_mfma_f32_16x16x32_bf16 v[32:35], v[178:181], v[230:233], v[32:35]
	v_mfma_f32_16x16x32_bf16 v[24:27], v[186:189], v[230:233], v[24:27]
	v_mfma_f32_16x16x32_bf16 v[16:19], v[178:181], v[238:241], v[16:19]
	v_mfma_f32_16x16x32_bf16 v[8:11], v[186:189], v[238:241], v[8:11]
	v_mfma_f32_16x16x32_bf16 v[4:7], v[178:181], v[246:249], v[4:7]
	v_mfma_f32_16x16x32_bf16 v[0:3], v[186:189], v[246:249], v[0:3]
	v_mfma_f32_16x16x32_bf16 v[48:51], v[182:185], v[226:229], v[48:51]
	v_mfma_f32_16x16x32_bf16 v[40:43], v[190:193], v[226:229], v[40:43]
	v_mfma_f32_16x16x32_bf16 v[32:35], v[182:185], v[234:237], v[32:35]
	v_mfma_f32_16x16x32_bf16 v[24:27], v[190:193], v[234:237], v[24:27]
	v_mfma_f32_16x16x32_bf16 v[16:19], v[182:185], v[242:245], v[16:19]
	v_mfma_f32_16x16x32_bf16 v[8:11], v[190:193], v[242:245], v[8:11]
	v_mfma_f32_16x16x32_bf16 v[4:7], v[182:185], v[250:253], v[4:7]
	v_mfma_f32_16x16x32_bf16 v[0:3], v[190:193], v[250:253], v[0:3]
	s_barrier
	s_setprio 0
	s_add_i32 s45, s45, 2
	s_add_u32 s26, s26, 0x100
	s_addc_u32 s27, s27, 0
	s_add_u32 s33, s33, 0x100
	s_addc_u32 s44, s44, 0
.LBB0_955:
	ds_read_b128 v[128:131], v209
	ds_read_b128 v[132:135], v209 offset:1024
	ds_read_b128 v[136:139], v209 offset:2048
	ds_read_b128 v[178:181], v209 offset:3072
	ds_read_b128 v[182:185], v210
	ds_read_b128 v[186:189], v210 offset:1024
	ds_read_b128 v[190:193], v210 offset:2048
	ds_read_b128 v[222:225], v210 offset:3072
	s_add_u32 s28, s26, 0xfff80080
	s_addc_u32 s29, s27, -1
	s_cmp_eq_u32 s45, 28
	s_cselect_b32 s31, s1, s29
	s_cselect_b32 s30, s5, s28
	s_cselect_b32 s29, s17, s44
	s_cselect_b32 s28, s19, s33
	s_add_u32 s48, s28, 0x80000
	s_addc_u32 s49, s29, 0
	s_add_i32 m0, s35, 0xc000
	ds_read_b128 v[226:229], v211
	ds_read_b128 v[230:233], v211 offset:1024
	ds_read_b128 v[234:237], v211 offset:2048
	ds_read_b128 v[238:241], v211 offset:3072
	ds_read_b128 v[242:245], v211 offset:4096
	ds_read_b128 v[246:249], v211 offset:5120
	ds_read_b128 v[250:253], v211 offset:6144
	ds_read_b128 v[160:163], v211 offset:7168
	global_load_lds_dwordx4 v150, s[26:27]
	s_add_i32 m0, s35, 0xe000
	s_nop 0
	global_load_lds_dwordx4 v152, s[26:27]
	s_waitcnt vmcnt(8) lgkmcnt(0)
	s_setprio 1
	s_barrier
; #define PG8_STAGE(bufoff, gbase, voff) do { _Pragma("unroll") for (int _i = 0; _i < 2; ++_i) \
;         __builtin_amdgcn_global_load_lds((const unsigned*)((const char*)(gbase) + (voff)[_i]), (PG8_LAS unsigned*)(lds + (bufoff) + ldsw + _i * 8192), 16, 0, 0); } while (0)
; #define PG8_LDA(dst, b, h) do { _Pragma("unroll") for (int m = 0; m < 4; ++m) _Pragma("unroll") for (int k = 0; k < 2; ++k) dst[m][k] = *(const PG8_LAS bf16x8*)(lds + PG8_SA(b, h) + aoff + m * 2048 + k * 1024); } while (0)
; #define PG8_MMA(ai, bj, At, Bt) do { __builtin_amdgcn_s_setprio(1); _Pragma("unroll") for (int m = 0; m < 4; ++m) _Pragma("unroll") for (int n = 0; n < 2; ++n) _Pragma("unroll") for (int k = 0; k < 2; ++k) \
;         acc[ai][bj][m][n] = __builtin_amdgcn_mfma_f32_16x16x32_bf16(Bt[n][k], At[m][k], acc[ai][bj][m][n], 0, 0, 0); __builtin_amdgcn_s_setprio(0); } while (0)
; #define PG8_WAIT_V(n) asm volatile("s_waitcnt vmcnt(" #n ")" ::: "memory")
; #define PG8_WAIT_L(n) asm volatile("s_waitcnt lgkmcnt(" #n ")" ::: "memory")
; #define PG8_BAR __builtin_amdgcn_s_barrier()
; #define PG8_SCHED __builtin_amdgcn_sched_barrier(0)
; template <class Epi, class Sched, bool ALIGN_EPI = false, bool SP2 = false>
; __device__ __forceinline__ void gemm_phase(PG8_LAS unsigned char* lds, const Gemm g, const Sched& S, const Epi& E) {
;     ...
;             PG8_WAIT_V(8); PG8_WAIT_L(0); PG8_BAR; PG8_MMA(0, 0, At, B0); PG8_MMA(0, 1, At, B1); PG8_BAR; PG8_SCHED;
;             PG8_LDA(At, 0, 1); PG8_STAGE(PG8_SB(0, 0), b2, voffB); PG8_STAGE(PG8_SB(0, 1), b2 + hstep, voffB); PG8_STAGE(PG8_SA(0, 0), a2, voffA);
;             PG8_WAIT_V(8); PG8_WAIT_L(0); PG8_BAR; PG8_MMA(1, 0, At, B0); PG8_MMA(1, 1, At, B1); PG8_BAR; PG8_SCHED;
	v_mfma_f32_16x16x32_bf16 v[124:127], v[128:131], v[226:229], v[124:127]
	v_mfma_f32_16x16x32_bf16 v[120:123], v[136:139], v[226:229], v[120:123]
	v_mfma_f32_16x16x32_bf16 v[116:119], v[128:131], v[234:237], v[116:119]
	v_mfma_f32_16x16x32_bf16 v[108:111], v[136:139], v[234:237], v[108:111]
	v_mfma_f32_16x16x32_bf16 v[100:103], v[128:131], v[242:245], v[100:103]
	v_mfma_f32_16x16x32_bf16 v[92:95], v[136:139], v[242:245], v[92:95]
	v_mfma_f32_16x16x32_bf16 v[84:87], v[128:131], v[250:253], v[84:87]
	v_mfma_f32_16x16x32_bf16 v[76:79], v[136:139], v[250:253], v[76:79]
	v_mfma_f32_16x16x32_bf16 v[124:127], v[132:135], v[230:233], v[124:127]
	v_mfma_f32_16x16x32_bf16 v[120:123], v[178:181], v[230:233], v[120:123]
	v_mfma_f32_16x16x32_bf16 v[116:119], v[132:135], v[238:241], v[116:119]
	v_mfma_f32_16x16x32_bf16 v[108:111], v[178:181], v[238:241], v[108:111]
	v_mfma_f32_16x16x32_bf16 v[100:103], v[132:135], v[246:249], v[100:103]
	v_mfma_f32_16x16x32_bf16 v[92:95], v[178:181], v[246:249], v[92:95]
	v_mfma_f32_16x16x32_bf16 v[84:87], v[132:135], v[160:163], v[84:87]
	v_mfma_f32_16x16x32_bf16 v[76:79], v[178:181], v[160:163], v[76:79]
	v_mfma_f32_16x16x32_bf16 v[112:115], v[182:185], v[226:229], v[112:115]
	v_mfma_f32_16x16x32_bf16 v[104:107], v[190:193], v[226:229], v[104:107]
	v_mfma_f32_16x16x32_bf16 v[96:99], v[182:185], v[234:237], v[96:99]
	v_mfma_f32_16x16x32_bf16 v[88:91], v[190:193], v[234:237], v[88:91]
	v_mfma_f32_16x16x32_bf16 v[80:83], v[182:185], v[242:245], v[80:83]
	v_mfma_f32_16x16x32_bf16 v[72:75], v[190:193], v[242:245], v[72:75]
	v_mfma_f32_16x16x32_bf16 v[68:71], v[182:185], v[250:253], v[68:71]
	v_mfma_f32_16x16x32_bf16 v[64:67], v[190:193], v[250:253], v[64:67]
	v_mfma_f32_16x16x32_bf16 v[112:115], v[186:189], v[230:233], v[112:115]
	v_mfma_f32_16x16x32_bf16 v[104:107], v[222:225], v[230:233], v[104:107]
	v_mfma_f32_16x16x32_bf16 v[96:99], v[186:189], v[238:241], v[96:99]
	v_mfma_f32_16x16x32_bf16 v[88:91], v[222:225], v[238:241], v[88:91]
	v_mfma_f32_16x16x32_bf16 v[80:83], v[186:189], v[246:249], v[80:83]
	v_mfma_f32_16x16x32_bf16 v[72:75], v[222:225], v[246:249], v[72:75]
	v_mfma_f32_16x16x32_bf16 v[68:71], v[186:189], v[160:163], v[68:71]
	v_mfma_f32_16x16x32_bf16 v[64:67], v[222:225], v[160:163], v[64:67]
	s_barrier
	s_setprio 0
	v_lshl_add_u64 v[166:167], s[28:29], 0, v[142:143]
	s_mov_b32 m0, s98
	ds_read_b128 v[160:163], v211 offset:16384
	ds_read_b128 v[226:229], v211 offset:17408
	ds_read_b128 v[230:233], v211 offset:18432
	ds_read_b128 v[234:237], v211 offset:19456
	ds_read_b128 v[238:241], v211 offset:20480
	ds_read_b128 v[242:245], v211 offset:21504
	ds_read_b128 v[246:249], v211 offset:22528
	ds_read_b128 v[250:253], v211 offset:23552
	global_load_lds_dwordx4 v[166:167], off
	s_add_i32 m0, s98, 0x2000
	v_lshl_add_u64 v[170:171], s[28:29], 0, v[146:147]
	global_load_lds_dwordx4 v[170:171], off
	s_mov_b32 m0, s99
	v_lshl_add_u64 v[194:195], s[30:31], 0, v[144:145]
	global_load_lds_dwordx4 v142, s[48:49]
	s_add_i32 m0, s99, 0x2000
	s_nop 0
	global_load_lds_dwordx4 v146, s[48:49]
	s_mov_b32 m0, s35
	v_lshl_add_u64 v[174:175], s[30:31], 0, v[140:141]
	global_load_lds_dwordx4 v[174:175], off
	s_mov_b32 m0, s37
	s_nop 0
	global_load_lds_dwordx4 v[194:195], off
	s_waitcnt vmcnt(8) lgkmcnt(0)
	s_setprio 1
	s_barrier
	v_mfma_f32_16x16x32_bf16 v[60:63], v[128:131], v[160:163], v[60:63]
	v_mfma_f32_16x16x32_bf16 v[56:59], v[136:139], v[160:163], v[56:59]
	v_mfma_f32_16x16x32_bf16 v[52:55], v[128:131], v[230:233], v[52:55]
	v_mfma_f32_16x16x32_bf16 v[44:47], v[136:139], v[230:233], v[44:47]
	v_mfma_f32_16x16x32_bf16 v[36:39], v[128:131], v[238:241], v[36:39]
	v_mfma_f32_16x16x32_bf16 v[28:31], v[136:139], v[238:241], v[28:31]
	v_mfma_f32_16x16x32_bf16 v[20:23], v[128:131], v[246:249], v[20:23]
	v_mfma_f32_16x16x32_bf16 v[12:15], v[136:139], v[246:249], v[12:15]
	v_mfma_f32_16x16x32_bf16 v[60:63], v[132:135], v[226:229], v[60:63]
	v_mfma_f32_16x16x32_bf16 v[56:59], v[178:181], v[226:229], v[56:59]
	v_mfma_f32_16x16x32_bf16 v[52:55], v[132:135], v[234:237], v[52:55]
	v_mfma_f32_16x16x32_bf16 v[44:47], v[178:181], v[234:237], v[44:47]
	v_mfma_f32_16x16x32_bf16 v[36:39], v[132:135], v[242:245], v[36:39]
	v_mfma_f32_16x16x32_bf16 v[28:31], v[178:181], v[242:245], v[28:31]
	v_mfma_f32_16x16x32_bf16 v[20:23], v[132:135], v[250:253], v[20:23]
	v_mfma_f32_16x16x32_bf16 v[12:15], v[178:181], v[250:253], v[12:15]
	v_mfma_f32_16x16x32_bf16 v[48:51], v[182:185], v[160:163], v[48:51]
	v_mfma_f32_16x16x32_bf16 v[40:43], v[190:193], v[160:163], v[40:43]
	v_mfma_f32_16x16x32_bf16 v[32:35], v[182:185], v[230:233], v[32:35]
	v_mfma_f32_16x16x32_bf16 v[24:27], v[190:193], v[230:233], v[24:27]
	v_mfma_f32_16x16x32_bf16 v[16:19], v[182:185], v[238:241], v[16:19]
	v_mfma_f32_16x16x32_bf16 v[8:11], v[190:193], v[238:241], v[8:11]
	v_mfma_f32_16x16x32_bf16 v[4:7], v[182:185], v[246:249], v[4:7]
	v_mfma_f32_16x16x32_bf16 v[0:3], v[190:193], v[246:249], v[0:3]
	v_mfma_f32_16x16x32_bf16 v[48:51], v[186:189], v[226:229], v[48:51]
	v_mfma_f32_16x16x32_bf16 v[40:43], v[222:225], v[226:229], v[40:43]
	v_mfma_f32_16x16x32_bf16 v[32:35], v[186:189], v[234:237], v[32:35]
	v_mfma_f32_16x16x32_bf16 v[24:27], v[222:225], v[234:237], v[24:27]
	v_mfma_f32_16x16x32_bf16 v[16:19], v[186:189], v[242:245], v[16:19]
	v_mfma_f32_16x16x32_bf16 v[8:11], v[222:225], v[242:245], v[8:11]
	v_mfma_f32_16x16x32_bf16 v[4:7], v[186:189], v[250:253], v[4:7]
	v_mfma_f32_16x16x32_bf16 v[0:3], v[222:225], v[250:253], v[0:3]
	s_barrier
; #define PG8_STAGE(bufoff, gbase, voff) do { _Pragma("unroll") for (int _i = 0; _i < 2; ++_i) \
;         __builtin_amdgcn_global_load_lds((const unsigned*)((const char*)(gbase) + (voff)[_i]), (PG8_LAS unsigned*)(lds + (bufoff) + ldsw + _i * 8192), 16, 0, 0); } while (0)
; #define PG8_LDA(dst, b, h) do { _Pragma("unroll") for (int m = 0; m < 4; ++m) _Pragma("unroll") for (int k = 0; k < 2; ++k) dst[m][k] = *(const PG8_LAS bf16x8*)(lds + PG8_SA(b, h) + aoff + m * 2048 + k * 1024); } while (0)
; #define PG8_LDB(dst, b, h) do { _Pragma("unroll") for (int n = 0; n < 2; ++n) _Pragma("unroll") for (int k = 0; k < 2; ++k) dst[n][k] = *(const PG8_LAS bf16x8*)(lds + PG8_SB(b, h) + boff + n * 2048 + k * 1024); } while (0)
; #define PG8_MMA(ai, bj, At, Bt) do { __builtin_amdgcn_s_setprio(1); _Pragma("unroll") for (int m = 0; m < 4; ++m) _Pragma("unroll") for (int n = 0; n < 2; ++n) _Pragma("unroll") for (int k = 0; k < 2; ++k) \
;         acc[ai][bj][m][n] = __builtin_amdgcn_mfma_f32_16x16x32_bf16(Bt[n][k], At[m][k], acc[ai][bj][m][n], 0, 0, 0); __builtin_amdgcn_s_setprio(0); } while (0)
; #define PG8_WAIT_V(n) asm volatile("s_waitcnt vmcnt(" #n ")" ::: "memory")
; #define PG8_WAIT_L(n) asm volatile("s_waitcnt lgkmcnt(" #n ")" ::: "memory")
; #define PG8_BAR __builtin_amdgcn_s_barrier()
; #define PG8_SCHED __builtin_amdgcn_sched_barrier(0)
; template <class Epi, class Sched, bool ALIGN_EPI = false, bool SP2 = false>
; __device__ __forceinline__ void gemm_phase(PG8_LAS unsigned char* lds, const Gemm g, const Sched& S, const Epi& E) {
;     ...
;             PG8_LDB(B0, 1, 0); PG8_LDB(B1, 1, 1); PG8_SCHED; PG8_LDA(At, 1, 0); PG8_STAGE(PG8_SA(0, 1), a2 + hstep, voffA);
;             PG8_WAIT_V(8); PG8_WAIT_L(0); PG8_BAR; PG8_MMA(0, 0, At, B0); PG8_MMA(0, 1, At, B1); PG8_BAR; PG8_SCHED;
;             PG8_LDA(At, 1, 1); PG8_STAGE(PG8_SB(1, 0), b3, voffB); PG8_STAGE(PG8_SB(1, 1), b3 + hstep, voffB); PG8_STAGE(PG8_SA(1, 0), a3, voffA);
;             PG8_WAIT_V(8); PG8_WAIT_L(0); PG8_BAR; PG8_MMA(1, 0, At, B0); PG8_MMA(1, 1, At, B1); PG8_BAR; PG8_SCHED;
;     ...
;         if constexpr (ALIGN_EPI) { if (wr == 0) PG8_BAR; }
	s_setprio 0
	s_add_i32 s48, 0, 0x18000
	v_add_u32_e32 v148, s48, v159
	s_add_i32 s49, 0, 0x1c000
	ds_read_b128 v[128:131], v148
	ds_read_b128 v[132:135], v148 offset:1024
	ds_read_b128 v[136:139], v148 offset:2048
	ds_read_b128 v[160:163], v148 offset:3072
	v_add_u32_e32 v148, s49, v159
	ds_read_b128 v[178:181], v148
	ds_read_b128 v[182:185], v148 offset:1024
	ds_read_b128 v[186:189], v148 offset:2048
	ds_read_b128 v[190:193], v148 offset:3072
	s_add_u32 s30, s30, 0x80000
	s_addc_u32 s31, s31, 0
	s_add_u32 s28, s28, 0x80080
	s_addc_u32 s29, s29, 0
	s_mov_b32 m0, s39
	ds_read_b128 v[222:225], v211 offset:32768
	ds_read_b128 v[226:229], v211 offset:33792
	ds_read_b128 v[230:233], v211 offset:34816
	ds_read_b128 v[234:237], v211 offset:35840
	ds_read_b128 v[238:241], v211 offset:36864
	ds_read_b128 v[242:245], v211 offset:37888
	ds_read_b128 v[246:249], v211 offset:38912
	ds_read_b128 v[250:253], v211 offset:39936
	global_load_lds_dwordx4 v140, s[30:31]
	s_mov_b32 m0, s42
	v_lshl_add_u64 v[154:155], s[30:31], 0, v[144:145]
	global_load_lds_dwordx4 v[154:155], off
	s_waitcnt vmcnt(8) lgkmcnt(0)
	s_setprio 1
	s_barrier
	v_mfma_f32_16x16x32_bf16 v[124:127], v[128:131], v[222:225], v[124:127]
	v_mfma_f32_16x16x32_bf16 v[120:123], v[136:139], v[222:225], v[120:123]
	v_mfma_f32_16x16x32_bf16 v[116:119], v[128:131], v[230:233], v[116:119]
	v_mfma_f32_16x16x32_bf16 v[108:111], v[136:139], v[230:233], v[108:111]
	v_mfma_f32_16x16x32_bf16 v[100:103], v[128:131], v[238:241], v[100:103]
	v_mfma_f32_16x16x32_bf16 v[92:95], v[136:139], v[238:241], v[92:95]
	v_mfma_f32_16x16x32_bf16 v[84:87], v[128:131], v[246:249], v[84:87]
	v_mfma_f32_16x16x32_bf16 v[76:79], v[136:139], v[246:249], v[76:79]
	v_mfma_f32_16x16x32_bf16 v[124:127], v[132:135], v[226:229], v[124:127]
	v_mfma_f32_16x16x32_bf16 v[120:123], v[160:163], v[226:229], v[120:123]
	v_mfma_f32_16x16x32_bf16 v[116:119], v[132:135], v[234:237], v[116:119]
	v_mfma_f32_16x16x32_bf16 v[108:111], v[160:163], v[234:237], v[108:111]
	v_mfma_f32_16x16x32_bf16 v[100:103], v[132:135], v[242:245], v[100:103]
	v_mfma_f32_16x16x32_bf16 v[92:95], v[160:163], v[242:245], v[92:95]
	v_mfma_f32_16x16x32_bf16 v[84:87], v[132:135], v[250:253], v[84:87]
	v_mfma_f32_16x16x32_bf16 v[76:79], v[160:163], v[250:253], v[76:79]
	v_mfma_f32_16x16x32_bf16 v[112:115], v[178:181], v[222:225], v[112:115]
	v_mfma_f32_16x16x32_bf16 v[104:107], v[186:189], v[222:225], v[104:107]
	v_mfma_f32_16x16x32_bf16 v[96:99], v[178:181], v[230:233], v[96:99]
	v_mfma_f32_16x16x32_bf16 v[88:91], v[186:189], v[230:233], v[88:91]
	v_mfma_f32_16x16x32_bf16 v[80:83], v[178:181], v[238:241], v[80:83]
	v_mfma_f32_16x16x32_bf16 v[72:75], v[186:189], v[238:241], v[72:75]
	v_mfma_f32_16x16x32_bf16 v[68:71], v[178:181], v[246:249], v[68:71]
	v_mfma_f32_16x16x32_bf16 v[64:67], v[186:189], v[246:249], v[64:67]
	v_mfma_f32_16x16x32_bf16 v[112:115], v[182:185], v[226:229], v[112:115]
	v_mfma_f32_16x16x32_bf16 v[104:107], v[190:193], v[226:229], v[104:107]
	v_mfma_f32_16x16x32_bf16 v[96:99], v[182:185], v[234:237], v[96:99]
	v_mfma_f32_16x16x32_bf16 v[88:91], v[190:193], v[234:237], v[88:91]
	v_mfma_f32_16x16x32_bf16 v[80:83], v[182:185], v[242:245], v[80:83]
	v_mfma_f32_16x16x32_bf16 v[72:75], v[190:193], v[242:245], v[72:75]
	v_mfma_f32_16x16x32_bf16 v[68:71], v[182:185], v[250:253], v[68:71]
	v_mfma_f32_16x16x32_bf16 v[64:67], v[190:193], v[250:253], v[64:67]
	s_barrier
	s_setprio 0
	v_lshl_add_u64 v[154:155], v[166:167], 0, s[10:11]
	s_mov_b32 m0, s100
	ds_read_b128 v[222:225], v211 offset:49152
	ds_read_b128 v[226:229], v211 offset:50176
	ds_read_b128 v[230:233], v211 offset:51200
	ds_read_b128 v[234:237], v211 offset:52224
	ds_read_b128 v[238:241], v211 offset:53248
	ds_read_b128 v[242:245], v211 offset:54272
	ds_read_b128 v[246:249], v211 offset:55296
	ds_read_b128 v[250:253], v211 offset:56320
	global_load_lds_dwordx4 v[154:155], off
	s_add_i32 m0, s100, 0x2000
	v_lshl_add_u64 v[154:155], v[170:171], 0, s[10:11]
	global_load_lds_dwordx4 v[154:155], off
	s_mov_b32 m0, s101
	s_nop 0
	global_load_lds_dwordx4 v142, s[28:29]
	s_add_i32 m0, s101, 0x2000
	v_lshl_add_u64 v[154:155], s[28:29], 0, v[146:147]
	global_load_lds_dwordx4 v[154:155], off
	s_mov_b32 m0, s46
	v_lshl_add_u64 v[154:155], v[174:175], 0, s[10:11]
	global_load_lds_dwordx4 v[154:155], off
	s_mov_b32 m0, s47
	v_lshl_add_u64 v[154:155], v[194:195], 0, s[10:11]
	global_load_lds_dwordx4 v[154:155], off
	s_waitcnt vmcnt(8) lgkmcnt(0)
	s_setprio 1
	s_barrier
	v_mfma_f32_16x16x32_bf16 v[60:63], v[128:131], v[222:225], v[60:63]
	v_mfma_f32_16x16x32_bf16 v[56:59], v[136:139], v[222:225], v[56:59]
	v_mfma_f32_16x16x32_bf16 v[52:55], v[128:131], v[230:233], v[52:55]
	v_mfma_f32_16x16x32_bf16 v[44:47], v[136:139], v[230:233], v[44:47]
	v_mfma_f32_16x16x32_bf16 v[36:39], v[128:131], v[238:241], v[36:39]
	v_mfma_f32_16x16x32_bf16 v[28:31], v[136:139], v[238:241], v[28:31]
	v_mfma_f32_16x16x32_bf16 v[20:23], v[128:131], v[246:249], v[20:23]
	v_mfma_f32_16x16x32_bf16 v[12:15], v[136:139], v[246:249], v[12:15]
	v_mfma_f32_16x16x32_bf16 v[60:63], v[132:135], v[226:229], v[60:63]
	v_mfma_f32_16x16x32_bf16 v[56:59], v[160:163], v[226:229], v[56:59]
	v_mfma_f32_16x16x32_bf16 v[52:55], v[132:135], v[234:237], v[52:55]
	v_mfma_f32_16x16x32_bf16 v[44:47], v[160:163], v[234:237], v[44:47]
	v_mfma_f32_16x16x32_bf16 v[36:39], v[132:135], v[242:245], v[36:39]
	v_mfma_f32_16x16x32_bf16 v[28:31], v[160:163], v[242:245], v[28:31]
	v_mfma_f32_16x16x32_bf16 v[20:23], v[132:135], v[250:253], v[20:23]
	v_mfma_f32_16x16x32_bf16 v[12:15], v[160:163], v[250:253], v[12:15]
	v_mfma_f32_16x16x32_bf16 v[48:51], v[178:181], v[222:225], v[48:51]
	v_mfma_f32_16x16x32_bf16 v[40:43], v[186:189], v[222:225], v[40:43]
	v_mfma_f32_16x16x32_bf16 v[32:35], v[178:181], v[230:233], v[32:35]
	v_mfma_f32_16x16x32_bf16 v[24:27], v[186:189], v[230:233], v[24:27]
	v_mfma_f32_16x16x32_bf16 v[16:19], v[178:181], v[238:241], v[16:19]
	v_mfma_f32_16x16x32_bf16 v[8:11], v[186:189], v[238:241], v[8:11]
	v_mfma_f32_16x16x32_bf16 v[4:7], v[178:181], v[246:249], v[4:7]
	v_mfma_f32_16x16x32_bf16 v[0:3], v[186:189], v[246:249], v[0:3]
	v_mfma_f32_16x16x32_bf16 v[48:51], v[182:185], v[226:229], v[48:51]
	v_mfma_f32_16x16x32_bf16 v[40:43], v[190:193], v[226:229], v[40:43]
	v_mfma_f32_16x16x32_bf16 v[32:35], v[182:185], v[234:237], v[32:35]
	v_mfma_f32_16x16x32_bf16 v[24:27], v[190:193], v[234:237], v[24:27]
	v_mfma_f32_16x16x32_bf16 v[16:19], v[182:185], v[242:245], v[16:19]
	v_mfma_f32_16x16x32_bf16 v[8:11], v[190:193], v[242:245], v[8:11]
	v_mfma_f32_16x16x32_bf16 v[4:7], v[182:185], v[250:253], v[4:7]
	v_mfma_f32_16x16x32_bf16 v[0:3], v[190:193], v[250:253], v[0:3]
	s_barrier
	s_setprio 0
	s_add_i32 s45, s45, 2
	s_add_u32 s26, s26, 0x100
	s_addc_u32 s27, s27, 0
	s_add_u32 s33, s33, 0x100
	s_addc_u32 s44, s44, 0
	s_cmp_gt_u32 s45, 29
	s_cbranch_scc0 .LBB0_955
	s_and_b64 vcc, exec, s[12:13]
	s_cbranch_vccz .LBB0_958
	s_barrier

; #define PG8_STAGE(bufoff, gbase, voff) do { _Pragma("unroll") for (int _i = 0; _i < 2; ++_i) \
;         __builtin_amdgcn_global_load_lds((const unsigned*)((const char*)(gbase) + (voff)[_i]), (PG8_LAS unsigned*)(lds + (bufoff) + ldsw + _i * 8192), 16, 0, 0); } while (0)
; #define PG8_LDA(dst, b, h) do { _Pragma("unroll") for (int m = 0; m < 4; ++m) _Pragma("unroll") for (int k = 0; k < 2; ++k) dst[m][k] = *(const PG8_LAS bf16x8*)(lds + PG8_SA(b, h) + aoff + m * 2048 + k * 1024); } while (0)
; #define PG8_LDB(dst, b, h) do { _Pragma("unroll") for (int n = 0; n < 2; ++n) _Pragma("unroll") for (int k = 0; k < 2; ++k) dst[n][k] = *(const PG8_LAS bf16x8*)(lds + PG8_SB(b, h) + boff + n * 2048 + k * 1024); } while (0)
; #define PG8_MMA(ai, bj, At, Bt) do { __builtin_amdgcn_s_setprio(1); _Pragma("unroll") for (int m = 0; m < 4; ++m) _Pragma("unroll") for (int n = 0; n < 2; ++n) _Pragma("unroll") for (int k = 0; k < 2; ++k) \
;         acc[ai][bj][m][n] = __builtin_amdgcn_mfma_f32_16x16x32_bf16(Bt[n][k], At[m][k], acc[ai][bj][m][n], 0, 0, 0); __builtin_amdgcn_s_setprio(0); } while (0)
; #define PG8_BAR __builtin_amdgcn_s_barrier()
; template <class Epi, class Sched, bool ALIGN_EPI = false, bool SP2 = false>
; __device__ __forceinline__ void gemm_phase(PG8_LAS unsigned char* lds, const Gemm g, const Sched& S, const Epi& E) {
;     ...
;         const bool has_next = S.next(ui + 1, nxt);
;         const char* nA = has_next ? (const char*)g.A + (size_t)nxt.pm * tstep : cA; const char* nB = has_next ? (const char*)g.Bt + (size_t)nxt.pn * tstep : cB;
;         for (int t = 0; t < nt; t += 2) {
;             const bool last = (t == nt - 2);
;             const char* a1 = cA + (size_t)(t + 1) * kstep;
;             const char* a2 = last ? nA : cA + (size_t)(t + 2) * kstep; const char* b2 = last ? nB : cB + (size_t)(t + 2) * kstep;
;             const char* a3 = a2 + kstep; const char* b3 = b2 + kstep;
;             if (last && has_next) S.a_ready(nxt);
;             if constexpr (SP2) {
;             PG8_LDB(B0, 0, 0); PG8_LDB(B1, 0, 1); PG8_SCHED; PG8_LDA(At, 0, 0); PG8_STAGE(PG8_SA(1, 1), a1 + hstep, voffA);
;             PG8_WAIT_V(8); PG8_WAIT_L(0); PG8_BAR; PG8_MMA(0, 0, At, B0); PG8_MMA(0, 1, At, B1); PG8_BAR; PG8_SCHED;
;             PG8_LDA(At, 0, 1); PG8_STAGE(PG8_SB(0, 0), b2, voffB); PG8_STAGE(PG8_SB(0, 1), b2 + hstep, voffB); PG8_STAGE(PG8_SA(0, 0), a2, voffA);
.LBB0_1179:
	s_ashr_i32 s21, s20, 31
	s_lshl_b64 s[22:23], s[20:21], 20
	s_add_u32 s22, s56, s22
	s_addc_u32 s23, s57, s23
	s_and_b64 s[24:25], s[4:5], exec
	s_cselect_b32 s7, s23, s27
	s_cselect_b32 s21, s22, s26
	s_ashr_i32 s19, s18, 31
	s_lshl_b64 s[24:25], s[18:19], 20
	s_add_u32 s24, s68, s24
	s_addc_u32 s25, s69, s25
	s_and_b64 s[30:31], s[4:5], exec
	s_cselect_b32 s19, s25, s29
	s_cselect_b32 s46, s24, s28
	s_add_u32 s26, s26, 0x80080
	s_addc_u32 s27, s27, 0
	s_add_u32 s47, s28, 0x100
	s_addc_u32 s48, s29, 0
	s_mov_b32 s49, -2
	s_waitcnt lgkmcnt(0)
	s_add_i32 s98, s34, 0x10000
	s_add_i32 s99, s34, 0x14000
	s_add_i32 s100, s34, 0x18000
	s_add_i32 s101, s34, 0x1c000
	ds_read_b128 v[128:131], v181
	ds_read_b128 v[132:135], v181 offset:1024
	ds_read_b128 v[136:139], v181 offset:2048
	ds_read_b128 v[140:143], v181 offset:3072
	ds_read_b128 v[144:147], v182
	ds_read_b128 v[148:151], v182 offset:1024
	ds_read_b128 v[168:171], v182 offset:2048
	ds_read_b128 v[172:175], v182 offset:3072
	s_add_u32 s28, s26, 0xfff80080
	s_addc_u32 s29, s27, -1
	s_cmp_eq_u32 s49, 28
	s_cselect_b32 s31, s7, s29
	s_cselect_b32 s30, s21, s28
	s_cselect_b32 s29, s19, s48
	s_cselect_b32 s28, s46, s47
	s_add_u32 s50, s28, 0x80000
	s_addc_u32 s51, s29, 0
	s_add_i32 m0, s35, 0xc000
	ds_read_b128 v[186:189], v183
	ds_read_b128 v[190:193], v183 offset:1024
	ds_read_b128 v[198:201], v183 offset:2048
	ds_read_b128 v[202:205], v183 offset:3072
	ds_read_b128 v[206:209], v183 offset:4096
	ds_read_b128 v[210:213], v183 offset:5120
	ds_read_b128 v[214:217], v183 offset:6144
	ds_read_b128 v[218:221], v183 offset:7168
	global_load_lds_dwordx4 v160, s[26:27]
	s_add_i32 m0, s35, 0xe000
	s_nop 0
	global_load_lds_dwordx4 v162, s[26:27]
	s_waitcnt lgkmcnt(0)
	s_setprio 1
	s_barrier
	v_mfma_f32_16x16x32_bf16 v[124:127], v[128:131], v[186:189], 0
	v_mfma_f32_16x16x32_bf16 v[120:123], v[136:139], v[186:189], 0
	v_mfma_f32_16x16x32_bf16 v[104:107], v[128:131], v[198:201], 0
	v_mfma_f32_16x16x32_bf16 v[108:111], v[136:139], v[198:201], 0
	v_mfma_f32_16x16x32_bf16 v[88:91], v[128:131], v[206:209], 0
	v_mfma_f32_16x16x32_bf16 v[92:95], v[136:139], v[206:209], 0
	v_mfma_f32_16x16x32_bf16 v[72:75], v[128:131], v[214:217], 0
	v_mfma_f32_16x16x32_bf16 v[76:79], v[136:139], v[214:217], 0
	v_mfma_f32_16x16x32_bf16 v[124:127], v[132:135], v[190:193], v[124:127]
	v_mfma_f32_16x16x32_bf16 v[120:123], v[140:143], v[190:193], v[120:123]
	v_mfma_f32_16x16x32_bf16 v[104:107], v[132:135], v[202:205], v[104:107]
	v_mfma_f32_16x16x32_bf16 v[108:111], v[140:143], v[202:205], v[108:111]
	v_mfma_f32_16x16x32_bf16 v[88:91], v[132:135], v[210:213], v[88:91]
	v_mfma_f32_16x16x32_bf16 v[92:95], v[140:143], v[210:213], v[92:95]
	v_mfma_f32_16x16x32_bf16 v[72:75], v[132:135], v[218:221], v[72:75]
	v_mfma_f32_16x16x32_bf16 v[76:79], v[140:143], v[218:221], v[76:79]
	v_mfma_f32_16x16x32_bf16 v[116:119], v[144:147], v[186:189], 0
	v_mfma_f32_16x16x32_bf16 v[112:115], v[168:171], v[186:189], 0
	v_mfma_f32_16x16x32_bf16 v[100:103], v[144:147], v[198:201], 0
	v_mfma_f32_16x16x32_bf16 v[96:99], v[168:171], v[198:201], 0
	v_mfma_f32_16x16x32_bf16 v[84:87], v[144:147], v[206:209], 0
	v_mfma_f32_16x16x32_bf16 v[80:83], v[168:171], v[206:209], 0
	v_mfma_f32_16x16x32_bf16 v[68:71], v[144:147], v[214:217], 0
	v_mfma_f32_16x16x32_bf16 v[64:67], v[168:171], v[214:217], 0
	v_mfma_f32_16x16x32_bf16 v[116:119], v[148:151], v[190:193], v[116:119]
	v_mfma_f32_16x16x32_bf16 v[112:115], v[172:175], v[190:193], v[112:115]
	v_mfma_f32_16x16x32_bf16 v[100:103], v[148:151], v[202:205], v[100:103]
	v_mfma_f32_16x16x32_bf16 v[96:99], v[172:175], v[202:205], v[96:99]
	v_mfma_f32_16x16x32_bf16 v[84:87], v[148:151], v[210:213], v[84:87]
	v_mfma_f32_16x16x32_bf16 v[80:83], v[172:175], v[210:213], v[80:83]
	v_mfma_f32_16x16x32_bf16 v[68:71], v[148:151], v[218:221], v[68:71]
	v_mfma_f32_16x16x32_bf16 v[64:67], v[172:175], v[218:221], v[64:67]
	s_barrier
	s_setprio 0
	v_lshl_add_u64 v[176:177], s[28:29], 0, v[154:155]
	s_mov_b32 m0, s98
	ds_read_b128 v[186:189], v183 offset:16384
	ds_read_b128 v[190:193], v183 offset:17408
	ds_read_b128 v[198:201], v183 offset:18432
	ds_read_b128 v[202:205], v183 offset:19456
	ds_read_b128 v[206:209], v183 offset:20480
	ds_read_b128 v[210:213], v183 offset:21504
	ds_read_b128 v[214:217], v183 offset:22528
	ds_read_b128 v[218:221], v183 offset:23552
	global_load_lds_dwordx4 v[176:177], off
	s_add_i32 m0, s98, 0x2000
	v_lshl_add_u64 v[194:195], s[28:29], 0, v[158:159]
	global_load_lds_dwordx4 v[194:195], off
	s_mov_b32 m0, s99
	v_lshl_add_u64 v[224:225], s[30:31], 0, v[156:157]
	global_load_lds_dwordx4 v154, s[50:51]
	s_add_i32 m0, s99, 0x2000
	s_nop 0
	global_load_lds_dwordx4 v158, s[50:51]
	s_mov_b32 m0, s35
	v_lshl_add_u64 v[222:223], s[30:31], 0, v[152:153]
	global_load_lds_dwordx4 v[222:223], off
	s_mov_b32 m0, s33
	s_nop 0
	global_load_lds_dwordx4 v[224:225], off
	s_waitcnt lgkmcnt(0)
	s_setprio 1
	s_barrier
; #define PG8_STAGE(bufoff, gbase, voff) do { _Pragma("unroll") for (int _i = 0; _i < 2; ++_i) \
;         __builtin_amdgcn_global_load_lds((const unsigned*)((const char*)(gbase) + (voff)[_i]), (PG8_LAS unsigned*)(lds + (bufoff) + ldsw + _i * 8192), 16, 0, 0); } while (0)
; #define PG8_LDA(dst, b, h) do { _Pragma("unroll") for (int m = 0; m < 4; ++m) _Pragma("unroll") for (int k = 0; k < 2; ++k) dst[m][k] = *(const PG8_LAS bf16x8*)(lds + PG8_SA(b, h) + aoff + m * 2048 + k * 1024); } while (0)
; #define PG8_LDB(dst, b, h) do { _Pragma("unroll") for (int n = 0; n < 2; ++n) _Pragma("unroll") for (int k = 0; k < 2; ++k) dst[n][k] = *(const PG8_LAS bf16x8*)(lds + PG8_SB(b, h) + boff + n * 2048 + k * 1024); } while (0)
; #define PG8_MMA(ai, bj, At, Bt) do { __builtin_amdgcn_s_setprio(1); _Pragma("unroll") for (int m = 0; m < 4; ++m) _Pragma("unroll") for (int n = 0; n < 2; ++n) _Pragma("unroll") for (int k = 0; k < 2; ++k) \
;         acc[ai][bj][m][n] = __builtin_amdgcn_mfma_f32_16x16x32_bf16(Bt[n][k], At[m][k], acc[ai][bj][m][n], 0, 0, 0); __builtin_amdgcn_s_setprio(0); } while (0)
; #define PG8_WAIT_V(n) asm volatile("s_waitcnt vmcnt(" #n ")" ::: "memory")
; #define PG8_WAIT_L(n) asm volatile("s_waitcnt lgkmcnt(" #n ")" ::: "memory")
; #define PG8_BAR __builtin_amdgcn_s_barrier()
; #define PG8_SCHED __builtin_amdgcn_sched_barrier(0)
; template <class Epi, class Sched, bool ALIGN_EPI = false, bool SP2 = false>
; __device__ __forceinline__ void gemm_phase(PG8_LAS unsigned char* lds, const Gemm g, const Sched& S, const Epi& E) {
;     ...
;             PG8_WAIT_V(8); PG8_WAIT_L(0); PG8_BAR; PG8_MMA(1, 0, At, B0); PG8_MMA(1, 1, At, B1); PG8_BAR; PG8_SCHED;
;             PG8_LDB(B0, 1, 0); PG8_LDB(B1, 1, 1); PG8_SCHED; PG8_LDA(At, 1, 0); PG8_STAGE(PG8_SA(0, 1), a2 + hstep, voffA);
;             PG8_WAIT_V(8); PG8_WAIT_L(0); PG8_BAR; PG8_MMA(0, 0, At, B0); PG8_MMA(0, 1, At, B1); PG8_BAR; PG8_SCHED;
	v_mfma_f32_16x16x32_bf16 v[56:59], v[128:131], v[186:189], 0
	v_mfma_f32_16x16x32_bf16 v[60:63], v[136:139], v[186:189], 0
	v_mfma_f32_16x16x32_bf16 v[40:43], v[128:131], v[198:201], 0
	v_mfma_f32_16x16x32_bf16 v[44:47], v[136:139], v[198:201], 0
	v_mfma_f32_16x16x32_bf16 v[24:27], v[128:131], v[206:209], 0
	v_mfma_f32_16x16x32_bf16 v[28:31], v[136:139], v[206:209], 0
	v_mfma_f32_16x16x32_bf16 v[8:11], v[128:131], v[214:217], 0
	v_mfma_f32_16x16x32_bf16 v[12:15], v[136:139], v[214:217], 0
	v_mfma_f32_16x16x32_bf16 v[56:59], v[132:135], v[190:193], v[56:59]
	v_mfma_f32_16x16x32_bf16 v[60:63], v[140:143], v[190:193], v[60:63]
	v_mfma_f32_16x16x32_bf16 v[40:43], v[132:135], v[202:205], v[40:43]
	v_mfma_f32_16x16x32_bf16 v[44:47], v[140:143], v[202:205], v[44:47]
	v_mfma_f32_16x16x32_bf16 v[24:27], v[132:135], v[210:213], v[24:27]
	v_mfma_f32_16x16x32_bf16 v[28:31], v[140:143], v[210:213], v[28:31]
	v_mfma_f32_16x16x32_bf16 v[8:11], v[132:135], v[218:221], v[8:11]
	v_mfma_f32_16x16x32_bf16 v[12:15], v[140:143], v[218:221], v[12:15]
	v_mfma_f32_16x16x32_bf16 v[52:55], v[144:147], v[186:189], 0
	v_mfma_f32_16x16x32_bf16 v[48:51], v[168:171], v[186:189], 0
	v_mfma_f32_16x16x32_bf16 v[36:39], v[144:147], v[198:201], 0
	v_mfma_f32_16x16x32_bf16 v[32:35], v[168:171], v[198:201], 0
	v_mfma_f32_16x16x32_bf16 v[20:23], v[144:147], v[206:209], 0
	v_mfma_f32_16x16x32_bf16 v[16:19], v[168:171], v[206:209], 0
	v_mfma_f32_16x16x32_bf16 v[4:7], v[144:147], v[214:217], 0
	v_mfma_f32_16x16x32_bf16 v[0:3], v[168:171], v[214:217], 0
	v_mfma_f32_16x16x32_bf16 v[52:55], v[148:151], v[190:193], v[52:55]
	v_mfma_f32_16x16x32_bf16 v[48:51], v[172:175], v[190:193], v[48:51]
	v_mfma_f32_16x16x32_bf16 v[36:39], v[148:151], v[202:205], v[36:39]
	v_mfma_f32_16x16x32_bf16 v[32:35], v[172:175], v[202:205], v[32:35]
	v_mfma_f32_16x16x32_bf16 v[20:23], v[148:151], v[210:213], v[20:23]
	v_mfma_f32_16x16x32_bf16 v[16:19], v[172:175], v[210:213], v[16:19]
	v_mfma_f32_16x16x32_bf16 v[4:7], v[148:151], v[218:221], v[4:7]
	v_mfma_f32_16x16x32_bf16 v[0:3], v[172:175], v[218:221], v[0:3]
	s_barrier
	s_setprio 0
	s_add_i32 s50, 0, 0x18000
	s_add_i32 s51, 0, 0x1c000
	v_add_u32_e32 v140, s50, v179
	v_add_u32_e32 v172, s51, v179
	ds_read_b128 v[128:131], v140
	ds_read_b128 v[132:135], v140 offset:1024
	ds_read_b128 v[136:139], v140 offset:2048
	ds_read_b128 v[140:143], v140 offset:3072
	ds_read_b128 v[144:147], v172
	ds_read_b128 v[148:151], v172 offset:1024
	ds_read_b128 v[168:171], v172 offset:2048
	ds_read_b128 v[172:175], v172 offset:3072
	s_add_u32 s30, s30, 0x80000
	s_addc_u32 s31, s31, 0
	s_add_u32 s28, s28, 0x80080
	s_addc_u32 s29, s29, 0
	s_mov_b32 m0, s36
	ds_read_b128 v[186:189], v183 offset:32768
	ds_read_b128 v[190:193], v183 offset:33792
	ds_read_b128 v[198:201], v183 offset:34816
	ds_read_b128 v[202:205], v183 offset:35840
	ds_read_b128 v[206:209], v183 offset:36864
	ds_read_b128 v[210:213], v183 offset:37888
	ds_read_b128 v[214:217], v183 offset:38912
	ds_read_b128 v[218:221], v183 offset:39936
	global_load_lds_dwordx4 v152, s[30:31]
	s_mov_b32 m0, s37
	v_lshl_add_u64 v[226:227], s[30:31], 0, v[156:157]
	global_load_lds_dwordx4 v[226:227], off
	s_waitcnt vmcnt(8) lgkmcnt(0)
	s_setprio 1
	s_barrier
	v_mfma_f32_16x16x32_bf16 v[124:127], v[128:131], v[186:189], v[124:127]
	v_mfma_f32_16x16x32_bf16 v[120:123], v[136:139], v[186:189], v[120:123]
	v_mfma_f32_16x16x32_bf16 v[104:107], v[128:131], v[198:201], v[104:107]
	v_mfma_f32_16x16x32_bf16 v[108:111], v[136:139], v[198:201], v[108:111]
	v_mfma_f32_16x16x32_bf16 v[88:91], v[128:131], v[206:209], v[88:91]
	v_mfma_f32_16x16x32_bf16 v[92:95], v[136:139], v[206:209], v[92:95]
	v_mfma_f32_16x16x32_bf16 v[72:75], v[128:131], v[214:217], v[72:75]
	v_mfma_f32_16x16x32_bf16 v[76:79], v[136:139], v[214:217], v[76:79]
	v_mfma_f32_16x16x32_bf16 v[124:127], v[132:135], v[190:193], v[124:127]
	v_mfma_f32_16x16x32_bf16 v[120:123], v[140:143], v[190:193], v[120:123]
	v_mfma_f32_16x16x32_bf16 v[104:107], v[132:135], v[202:205], v[104:107]
	v_mfma_f32_16x16x32_bf16 v[108:111], v[140:143], v[202:205], v[108:111]
	v_mfma_f32_16x16x32_bf16 v[88:91], v[132:135], v[210:213], v[88:91]
	v_mfma_f32_16x16x32_bf16 v[92:95], v[140:143], v[210:213], v[92:95]
	v_mfma_f32_16x16x32_bf16 v[72:75], v[132:135], v[218:221], v[72:75]
	v_mfma_f32_16x16x32_bf16 v[76:79], v[140:143], v[218:221], v[76:79]
	v_mfma_f32_16x16x32_bf16 v[116:119], v[144:147], v[186:189], v[116:119]
	v_mfma_f32_16x16x32_bf16 v[112:115], v[168:171], v[186:189], v[112:115]
	v_mfma_f32_16x16x32_bf16 v[100:103], v[144:147], v[198:201], v[100:103]
	v_mfma_f32_16x16x32_bf16 v[96:99], v[168:171], v[198:201], v[96:99]
	v_mfma_f32_16x16x32_bf16 v[84:87], v[144:147], v[206:209], v[84:87]
	v_mfma_f32_16x16x32_bf16 v[80:83], v[168:171], v[206:209], v[80:83]
	v_mfma_f32_16x16x32_bf16 v[68:71], v[144:147], v[214:217], v[68:71]
	v_mfma_f32_16x16x32_bf16 v[64:67], v[168:171], v[214:217], v[64:67]
	v_mfma_f32_16x16x32_bf16 v[116:119], v[148:151], v[190:193], v[116:119]
	v_mfma_f32_16x16x32_bf16 v[112:115], v[172:175], v[190:193], v[112:115]
	v_mfma_f32_16x16x32_bf16 v[100:103], v[148:151], v[202:205], v[100:103]
	v_mfma_f32_16x16x32_bf16 v[96:99], v[172:175], v[202:205], v[96:99]
	v_mfma_f32_16x16x32_bf16 v[84:87], v[148:151], v[210:213], v[84:87]
	v_mfma_f32_16x16x32_bf16 v[80:83], v[172:175], v[210:213], v[80:83]
	v_mfma_f32_16x16x32_bf16 v[68:71], v[148:151], v[218:221], v[68:71]
	v_mfma_f32_16x16x32_bf16 v[64:67], v[172:175], v[218:221], v[64:67]
	s_barrier
; #define PG8_STAGE(bufoff, gbase, voff) do { _Pragma("unroll") for (int _i = 0; _i < 2; ++_i) \
;         __builtin_amdgcn_global_load_lds((const unsigned*)((const char*)(gbase) + (voff)[_i]), (PG8_LAS unsigned*)(lds + (bufoff) + ldsw + _i * 8192), 16, 0, 0); } while (0)
; #define PG8_LDA(dst, b, h) do { _Pragma("unroll") for (int m = 0; m < 4; ++m) _Pragma("unroll") for (int k = 0; k < 2; ++k) dst[m][k] = *(const PG8_LAS bf16x8*)(lds + PG8_SA(b, h) + aoff + m * 2048 + k * 1024); } while (0)
; #define PG8_LDB(dst, b, h) do { _Pragma("unroll") for (int n = 0; n < 2; ++n) _Pragma("unroll") for (int k = 0; k < 2; ++k) dst[n][k] = *(const PG8_LAS bf16x8*)(lds + PG8_SB(b, h) + boff + n * 2048 + k * 1024); } while (0)
; #define PG8_MMA(ai, bj, At, Bt) do { __builtin_amdgcn_s_setprio(1); _Pragma("unroll") for (int m = 0; m < 4; ++m) _Pragma("unroll") for (int n = 0; n < 2; ++n) _Pragma("unroll") for (int k = 0; k < 2; ++k) \
;         acc[ai][bj][m][n] = __builtin_amdgcn_mfma_f32_16x16x32_bf16(Bt[n][k], At[m][k], acc[ai][bj][m][n], 0, 0, 0); __builtin_amdgcn_s_setprio(0); } while (0)
; #define PG8_WAIT_V(n) asm volatile("s_waitcnt vmcnt(" #n ")" ::: "memory")
; template <class Epi, class Sched, bool ALIGN_EPI = false, bool SP2 = false>
; __device__ __forceinline__ void gemm_phase(PG8_LAS unsigned char* lds, const Gemm g, const Sched& S, const Epi& E) {
;     ...
;             PG8_LDB(B0, 0, 0); PG8_LDB(B1, 0, 1); PG8_SCHED; PG8_LDA(At, 0, 0); PG8_STAGE(PG8_SA(1, 1), a1 + hstep, voffA);
;             PG8_WAIT_V(8); PG8_WAIT_L(0); PG8_BAR; PG8_MMA(0, 0, At, B0); PG8_MMA(0, 1, At, B1); PG8_BAR; PG8_SCHED;
;             PG8_LDA(At, 0, 1); PG8_STAGE(PG8_SB(0, 0), b2, voffB); PG8_STAGE(PG8_SB(0, 1), b2 + hstep, voffB); PG8_STAGE(PG8_SA(0, 0), a2, voffA);
;             PG8_WAIT_V(8); PG8_WAIT_L(0); PG8_BAR; PG8_MMA(1, 0, At, B0); PG8_MMA(1, 1, At, B1); PG8_BAR; PG8_SCHED;
;             PG8_LDB(B0, 1, 0); PG8_LDB(B1, 1, 1); PG8_SCHED; PG8_LDA(At, 1, 0); PG8_STAGE(PG8_SA(0, 1), a2 + hstep, voffA);
;             PG8_WAIT_V(8); PG8_WAIT_L(0); PG8_BAR; PG8_MMA(0, 0, At, B0); PG8_MMA(0, 1, At, B1); PG8_BAR; PG8_SCHED;
;             PG8_LDA(At, 1, 1); PG8_STAGE(PG8_SB(1, 0), b3, voffB); PG8_STAGE(PG8_SB(1, 1), b3 + hstep, voffB); PG8_STAGE(PG8_SA(1, 0), a3, voffA);
;             PG8_WAIT_V(8); PG8_WAIT_L(0); PG8_BAR; PG8_MMA(1, 0, At, B0); PG8_MMA(1, 1, At, B1); PG8_BAR; PG8_SCHED;
	s_setprio 0
	v_lshl_add_u64 v[176:177], v[176:177], 0, s[12:13]
	s_mov_b32 m0, s100
	ds_read_b128 v[186:189], v183 offset:49152
	ds_read_b128 v[190:193], v183 offset:50176
	ds_read_b128 v[198:201], v183 offset:51200
	ds_read_b128 v[202:205], v183 offset:52224
	ds_read_b128 v[206:209], v183 offset:53248
	ds_read_b128 v[210:213], v183 offset:54272
	ds_read_b128 v[214:217], v183 offset:55296
	ds_read_b128 v[218:221], v183 offset:56320
	global_load_lds_dwordx4 v[176:177], off
	s_add_i32 m0, s100, 0x2000
	v_lshl_add_u64 v[176:177], v[194:195], 0, s[12:13]
	global_load_lds_dwordx4 v[176:177], off
	s_mov_b32 m0, s101
	s_nop 0
	global_load_lds_dwordx4 v154, s[28:29]
	s_add_i32 m0, s101, 0x2000
	v_lshl_add_u64 v[176:177], s[28:29], 0, v[158:159]
	global_load_lds_dwordx4 v[176:177], off
	s_mov_b32 m0, s39
	v_lshl_add_u64 v[176:177], v[222:223], 0, s[12:13]
	global_load_lds_dwordx4 v[176:177], off
	s_mov_b32 m0, s40
	v_lshl_add_u64 v[176:177], v[224:225], 0, s[12:13]
	global_load_lds_dwordx4 v[176:177], off
	s_waitcnt vmcnt(8) lgkmcnt(0)
	s_setprio 1
	s_barrier
	v_mfma_f32_16x16x32_bf16 v[56:59], v[128:131], v[186:189], v[56:59]
	v_mfma_f32_16x16x32_bf16 v[60:63], v[136:139], v[186:189], v[60:63]
	v_mfma_f32_16x16x32_bf16 v[40:43], v[128:131], v[198:201], v[40:43]
	v_mfma_f32_16x16x32_bf16 v[44:47], v[136:139], v[198:201], v[44:47]
	v_mfma_f32_16x16x32_bf16 v[24:27], v[128:131], v[206:209], v[24:27]
	v_mfma_f32_16x16x32_bf16 v[28:31], v[136:139], v[206:209], v[28:31]
	v_mfma_f32_16x16x32_bf16 v[8:11], v[128:131], v[214:217], v[8:11]
	v_mfma_f32_16x16x32_bf16 v[12:15], v[136:139], v[214:217], v[12:15]
	v_mfma_f32_16x16x32_bf16 v[56:59], v[132:135], v[190:193], v[56:59]
	v_mfma_f32_16x16x32_bf16 v[60:63], v[140:143], v[190:193], v[60:63]
	v_mfma_f32_16x16x32_bf16 v[40:43], v[132:135], v[202:205], v[40:43]
	v_mfma_f32_16x16x32_bf16 v[44:47], v[140:143], v[202:205], v[44:47]
	v_mfma_f32_16x16x32_bf16 v[24:27], v[132:135], v[210:213], v[24:27]
	v_mfma_f32_16x16x32_bf16 v[28:31], v[140:143], v[210:213], v[28:31]
	v_mfma_f32_16x16x32_bf16 v[8:11], v[132:135], v[218:221], v[8:11]
	v_mfma_f32_16x16x32_bf16 v[12:15], v[140:143], v[218:221], v[12:15]
	v_mfma_f32_16x16x32_bf16 v[52:55], v[144:147], v[186:189], v[52:55]
	v_mfma_f32_16x16x32_bf16 v[48:51], v[168:171], v[186:189], v[48:51]
	v_mfma_f32_16x16x32_bf16 v[36:39], v[144:147], v[198:201], v[36:39]
	v_mfma_f32_16x16x32_bf16 v[32:35], v[168:171], v[198:201], v[32:35]
	v_mfma_f32_16x16x32_bf16 v[20:23], v[144:147], v[206:209], v[20:23]
	v_mfma_f32_16x16x32_bf16 v[16:19], v[168:171], v[206:209], v[16:19]
	v_mfma_f32_16x16x32_bf16 v[4:7], v[144:147], v[214:217], v[4:7]
	v_mfma_f32_16x16x32_bf16 v[0:3], v[168:171], v[214:217], v[0:3]
	v_mfma_f32_16x16x32_bf16 v[52:55], v[148:151], v[190:193], v[52:55]
	v_mfma_f32_16x16x32_bf16 v[48:51], v[172:175], v[190:193], v[48:51]
	v_mfma_f32_16x16x32_bf16 v[36:39], v[148:151], v[202:205], v[36:39]
	v_mfma_f32_16x16x32_bf16 v[32:35], v[172:175], v[202:205], v[32:35]
	v_mfma_f32_16x16x32_bf16 v[20:23], v[148:151], v[210:213], v[20:23]
	v_mfma_f32_16x16x32_bf16 v[16:19], v[172:175], v[210:213], v[16:19]
	v_mfma_f32_16x16x32_bf16 v[4:7], v[148:151], v[218:221], v[4:7]
	v_mfma_f32_16x16x32_bf16 v[0:3], v[172:175], v[218:221], v[0:3]
	s_barrier
	s_setprio 0
	s_add_i32 s49, s49, 2
	s_add_u32 s26, s26, 0x100
	s_addc_u32 s27, s27, 0
	s_add_u32 s47, s47, 0x100
	s_addc_u32 s48, s48, 0
.LBB0_1180:
	ds_read_b128 v[128:131], v181
	ds_read_b128 v[132:135], v181 offset:1024
	ds_read_b128 v[136:139], v181 offset:2048
	ds_read_b128 v[140:143], v181 offset:3072
	ds_read_b128 v[144:147], v182
	ds_read_b128 v[148:151], v182 offset:1024
	ds_read_b128 v[168:171], v182 offset:2048
	ds_read_b128 v[172:175], v182 offset:3072
	s_add_u32 s28, s26, 0xfff80080
	s_addc_u32 s29, s27, -1
	s_cmp_eq_u32 s49, 28
	s_cselect_b32 s31, s7, s29
	s_cselect_b32 s30, s21, s28
	s_cselect_b32 s29, s19, s48
	s_cselect_b32 s28, s46, s47
	s_add_u32 s50, s28, 0x80000
	s_addc_u32 s51, s29, 0
	s_add_i32 m0, s35, 0xc000
	ds_read_b128 v[186:189], v183
	ds_read_b128 v[190:193], v183 offset:1024
	ds_read_b128 v[198:201], v183 offset:2048
	ds_read_b128 v[202:205], v183 offset:3072
	ds_read_b128 v[206:209], v183 offset:4096
	ds_read_b128 v[210:213], v183 offset:5120
	ds_read_b128 v[214:217], v183 offset:6144
	ds_read_b128 v[218:221], v183 offset:7168
	global_load_lds_dwordx4 v160, s[26:27]
	s_add_i32 m0, s35, 0xe000
	s_nop 0
	global_load_lds_dwordx4 v162, s[26:27]
	s_waitcnt vmcnt(8) lgkmcnt(0)
	s_setprio 1
	s_barrier
; #define PG8_STAGE(bufoff, gbase, voff) do { _Pragma("unroll") for (int _i = 0; _i < 2; ++_i) \
;         __builtin_amdgcn_global_load_lds((const unsigned*)((const char*)(gbase) + (voff)[_i]), (PG8_LAS unsigned*)(lds + (bufoff) + ldsw + _i * 8192), 16, 0, 0); } while (0)
; #define PG8_LDA(dst, b, h) do { _Pragma("unroll") for (int m = 0; m < 4; ++m) _Pragma("unroll") for (int k = 0; k < 2; ++k) dst[m][k] = *(const PG8_LAS bf16x8*)(lds + PG8_SA(b, h) + aoff + m * 2048 + k * 1024); } while (0)
; #define PG8_MMA(ai, bj, At, Bt) do { __builtin_amdgcn_s_setprio(1); _Pragma("unroll") for (int m = 0; m < 4; ++m) _Pragma("unroll") for (int n = 0; n < 2; ++n) _Pragma("unroll") for (int k = 0; k < 2; ++k) \
;         acc[ai][bj][m][n] = __builtin_amdgcn_mfma_f32_16x16x32_bf16(Bt[n][k], At[m][k], acc[ai][bj][m][n], 0, 0, 0); __builtin_amdgcn_s_setprio(0); } while (0)
; #define PG8_WAIT_V(n) asm volatile("s_waitcnt vmcnt(" #n ")" ::: "memory")
; #define PG8_WAIT_L(n) asm volatile("s_waitcnt lgkmcnt(" #n ")" ::: "memory")
; #define PG8_BAR __builtin_amdgcn_s_barrier()
; #define PG8_SCHED __builtin_amdgcn_sched_barrier(0)
; template <class Epi, class Sched, bool ALIGN_EPI = false, bool SP2 = false>
; __device__ __forceinline__ void gemm_phase(PG8_LAS unsigned char* lds, const Gemm g, const Sched& S, const Epi& E) {
;     ...
;             PG8_WAIT_V(8); PG8_WAIT_L(0); PG8_BAR; PG8_MMA(0, 0, At, B0); PG8_MMA(0, 1, At, B1); PG8_BAR; PG8_SCHED;
;             PG8_LDA(At, 0, 1); PG8_STAGE(PG8_SB(0, 0), b2, voffB); PG8_STAGE(PG8_SB(0, 1), b2 + hstep, voffB); PG8_STAGE(PG8_SA(0, 0), a2, voffA);
;             PG8_WAIT_V(8); PG8_WAIT_L(0); PG8_BAR; PG8_MMA(1, 0, At, B0); PG8_MMA(1, 1, At, B1); PG8_BAR; PG8_SCHED;
	v_mfma_f32_16x16x32_bf16 v[124:127], v[128:131], v[186:189], v[124:127]
	v_mfma_f32_16x16x32_bf16 v[120:123], v[136:139], v[186:189], v[120:123]
	v_mfma_f32_16x16x32_bf16 v[104:107], v[128:131], v[198:201], v[104:107]
	v_mfma_f32_16x16x32_bf16 v[108:111], v[136:139], v[198:201], v[108:111]
	v_mfma_f32_16x16x32_bf16 v[88:91], v[128:131], v[206:209], v[88:91]
	v_mfma_f32_16x16x32_bf16 v[92:95], v[136:139], v[206:209], v[92:95]
	v_mfma_f32_16x16x32_bf16 v[72:75], v[128:131], v[214:217], v[72:75]
	v_mfma_f32_16x16x32_bf16 v[76:79], v[136:139], v[214:217], v[76:79]
	v_mfma_f32_16x16x32_bf16 v[124:127], v[132:135], v[190:193], v[124:127]
	v_mfma_f32_16x16x32_bf16 v[120:123], v[140:143], v[190:193], v[120:123]
	v_mfma_f32_16x16x32_bf16 v[104:107], v[132:135], v[202:205], v[104:107]
	v_mfma_f32_16x16x32_bf16 v[108:111], v[140:143], v[202:205], v[108:111]
	v_mfma_f32_16x16x32_bf16 v[88:91], v[132:135], v[210:213], v[88:91]
	v_mfma_f32_16x16x32_bf16 v[92:95], v[140:143], v[210:213], v[92:95]
	v_mfma_f32_16x16x32_bf16 v[72:75], v[132:135], v[218:221], v[72:75]
	v_mfma_f32_16x16x32_bf16 v[76:79], v[140:143], v[218:221], v[76:79]
	v_mfma_f32_16x16x32_bf16 v[116:119], v[144:147], v[186:189], v[116:119]
	v_mfma_f32_16x16x32_bf16 v[112:115], v[168:171], v[186:189], v[112:115]
	v_mfma_f32_16x16x32_bf16 v[100:103], v[144:147], v[198:201], v[100:103]
	v_mfma_f32_16x16x32_bf16 v[96:99], v[168:171], v[198:201], v[96:99]
	v_mfma_f32_16x16x32_bf16 v[84:87], v[144:147], v[206:209], v[84:87]
	v_mfma_f32_16x16x32_bf16 v[80:83], v[168:171], v[206:209], v[80:83]
	v_mfma_f32_16x16x32_bf16 v[68:71], v[144:147], v[214:217], v[68:71]
	v_mfma_f32_16x16x32_bf16 v[64:67], v[168:171], v[214:217], v[64:67]
	v_mfma_f32_16x16x32_bf16 v[116:119], v[148:151], v[190:193], v[116:119]
	v_mfma_f32_16x16x32_bf16 v[112:115], v[172:175], v[190:193], v[112:115]
	v_mfma_f32_16x16x32_bf16 v[100:103], v[148:151], v[202:205], v[100:103]
	v_mfma_f32_16x16x32_bf16 v[96:99], v[172:175], v[202:205], v[96:99]
	v_mfma_f32_16x16x32_bf16 v[84:87], v[148:151], v[210:213], v[84:87]
	v_mfma_f32_16x16x32_bf16 v[80:83], v[172:175], v[210:213], v[80:83]
	v_mfma_f32_16x16x32_bf16 v[68:71], v[148:151], v[218:221], v[68:71]
	v_mfma_f32_16x16x32_bf16 v[64:67], v[172:175], v[218:221], v[64:67]
	s_barrier
	s_setprio 0
	v_lshl_add_u64 v[176:177], s[28:29], 0, v[154:155]
	s_mov_b32 m0, s98
	ds_read_b128 v[186:189], v183 offset:16384
	ds_read_b128 v[190:193], v183 offset:17408
	ds_read_b128 v[198:201], v183 offset:18432
	ds_read_b128 v[202:205], v183 offset:19456
	ds_read_b128 v[206:209], v183 offset:20480
	ds_read_b128 v[210:213], v183 offset:21504
	ds_read_b128 v[214:217], v183 offset:22528
	ds_read_b128 v[218:221], v183 offset:23552
	global_load_lds_dwordx4 v[176:177], off
	s_add_i32 m0, s98, 0x2000
	v_lshl_add_u64 v[194:195], s[28:29], 0, v[158:159]
	global_load_lds_dwordx4 v[194:195], off
	s_mov_b32 m0, s99
	v_lshl_add_u64 v[224:225], s[30:31], 0, v[156:157]
	global_load_lds_dwordx4 v154, s[50:51]
	s_add_i32 m0, s99, 0x2000
	s_nop 0
	global_load_lds_dwordx4 v158, s[50:51]
	s_mov_b32 m0, s35
	v_lshl_add_u64 v[222:223], s[30:31], 0, v[152:153]
	global_load_lds_dwordx4 v[222:223], off
	s_mov_b32 m0, s33
	s_nop 0
	global_load_lds_dwordx4 v[224:225], off
	s_waitcnt vmcnt(8) lgkmcnt(0)
	s_setprio 1
	s_barrier
	v_mfma_f32_16x16x32_bf16 v[56:59], v[128:131], v[186:189], v[56:59]
	v_mfma_f32_16x16x32_bf16 v[60:63], v[136:139], v[186:189], v[60:63]
	v_mfma_f32_16x16x32_bf16 v[40:43], v[128:131], v[198:201], v[40:43]
	v_mfma_f32_16x16x32_bf16 v[44:47], v[136:139], v[198:201], v[44:47]
	v_mfma_f32_16x16x32_bf16 v[24:27], v[128:131], v[206:209], v[24:27]
	v_mfma_f32_16x16x32_bf16 v[28:31], v[136:139], v[206:209], v[28:31]
	v_mfma_f32_16x16x32_bf16 v[8:11], v[128:131], v[214:217], v[8:11]
	v_mfma_f32_16x16x32_bf16 v[12:15], v[136:139], v[214:217], v[12:15]
	v_mfma_f32_16x16x32_bf16 v[56:59], v[132:135], v[190:193], v[56:59]
	v_mfma_f32_16x16x32_bf16 v[60:63], v[140:143], v[190:193], v[60:63]
	v_mfma_f32_16x16x32_bf16 v[40:43], v[132:135], v[202:205], v[40:43]
	v_mfma_f32_16x16x32_bf16 v[44:47], v[140:143], v[202:205], v[44:47]
	v_mfma_f32_16x16x32_bf16 v[24:27], v[132:135], v[210:213], v[24:27]
	v_mfma_f32_16x16x32_bf16 v[28:31], v[140:143], v[210:213], v[28:31]
	v_mfma_f32_16x16x32_bf16 v[8:11], v[132:135], v[218:221], v[8:11]
	v_mfma_f32_16x16x32_bf16 v[12:15], v[140:143], v[218:221], v[12:15]
	v_mfma_f32_16x16x32_bf16 v[52:55], v[144:147], v[186:189], v[52:55]
	v_mfma_f32_16x16x32_bf16 v[48:51], v[168:171], v[186:189], v[48:51]
	v_mfma_f32_16x16x32_bf16 v[36:39], v[144:147], v[198:201], v[36:39]
	v_mfma_f32_16x16x32_bf16 v[32:35], v[168:171], v[198:201], v[32:35]
	v_mfma_f32_16x16x32_bf16 v[20:23], v[144:147], v[206:209], v[20:23]
	v_mfma_f32_16x16x32_bf16 v[16:19], v[168:171], v[206:209], v[16:19]
	v_mfma_f32_16x16x32_bf16 v[4:7], v[144:147], v[214:217], v[4:7]
	v_mfma_f32_16x16x32_bf16 v[0:3], v[168:171], v[214:217], v[0:3]
	v_mfma_f32_16x16x32_bf16 v[52:55], v[148:151], v[190:193], v[52:55]
	v_mfma_f32_16x16x32_bf16 v[48:51], v[172:175], v[190:193], v[48:51]
	v_mfma_f32_16x16x32_bf16 v[36:39], v[148:151], v[202:205], v[36:39]
	v_mfma_f32_16x16x32_bf16 v[32:35], v[172:175], v[202:205], v[32:35]
	v_mfma_f32_16x16x32_bf16 v[20:23], v[148:151], v[210:213], v[20:23]
	v_mfma_f32_16x16x32_bf16 v[16:19], v[172:175], v[210:213], v[16:19]
	v_mfma_f32_16x16x32_bf16 v[4:7], v[148:151], v[218:221], v[4:7]
	v_mfma_f32_16x16x32_bf16 v[0:3], v[172:175], v[218:221], v[0:3]
	s_barrier
; #define PG8_STAGE(bufoff, gbase, voff) do { _Pragma("unroll") for (int _i = 0; _i < 2; ++_i) \
;         __builtin_amdgcn_global_load_lds((const unsigned*)((const char*)(gbase) + (voff)[_i]), (PG8_LAS unsigned*)(lds + (bufoff) + ldsw + _i * 8192), 16, 0, 0); } while (0)
; #define PG8_LDA(dst, b, h) do { _Pragma("unroll") for (int m = 0; m < 4; ++m) _Pragma("unroll") for (int k = 0; k < 2; ++k) dst[m][k] = *(const PG8_LAS bf16x8*)(lds + PG8_SA(b, h) + aoff + m * 2048 + k * 1024); } while (0)
; #define PG8_LDB(dst, b, h) do { _Pragma("unroll") for (int n = 0; n < 2; ++n) _Pragma("unroll") for (int k = 0; k < 2; ++k) dst[n][k] = *(const PG8_LAS bf16x8*)(lds + PG8_SB(b, h) + boff + n * 2048 + k * 1024); } while (0)
; #define PG8_MMA(ai, bj, At, Bt) do { __builtin_amdgcn_s_setprio(1); _Pragma("unroll") for (int m = 0; m < 4; ++m) _Pragma("unroll") for (int n = 0; n < 2; ++n) _Pragma("unroll") for (int k = 0; k < 2; ++k) \
;         acc[ai][bj][m][n] = __builtin_amdgcn_mfma_f32_16x16x32_bf16(Bt[n][k], At[m][k], acc[ai][bj][m][n], 0, 0, 0); __builtin_amdgcn_s_setprio(0); } while (0)
; #define PG8_WAIT_V(n) asm volatile("s_waitcnt vmcnt(" #n ")" ::: "memory")
; #define PG8_WAIT_L(n) asm volatile("s_waitcnt lgkmcnt(" #n ")" ::: "memory")
; #define PG8_BAR __builtin_amdgcn_s_barrier()
; #define PG8_SCHED __builtin_amdgcn_sched_barrier(0)
; template <class Epi, class Sched, bool ALIGN_EPI = false, bool SP2 = false>
; __device__ __forceinline__ void gemm_phase(PG8_LAS unsigned char* lds, const Gemm g, const Sched& S, const Epi& E) {
;     ...
;             PG8_LDB(B0, 1, 0); PG8_LDB(B1, 1, 1); PG8_SCHED; PG8_LDA(At, 1, 0); PG8_STAGE(PG8_SA(0, 1), a2 + hstep, voffA);
;             PG8_WAIT_V(8); PG8_WAIT_L(0); PG8_BAR; PG8_MMA(0, 0, At, B0); PG8_MMA(0, 1, At, B1); PG8_BAR; PG8_SCHED;
;             PG8_LDA(At, 1, 1); PG8_STAGE(PG8_SB(1, 0), b3, voffB); PG8_STAGE(PG8_SB(1, 1), b3 + hstep, voffB); PG8_STAGE(PG8_SA(1, 0), a3, voffA);
;             PG8_WAIT_V(8); PG8_WAIT_L(0); PG8_BAR; PG8_MMA(1, 0, At, B0); PG8_MMA(1, 1, At, B1); PG8_BAR; PG8_SCHED;
;     ...
;         if constexpr (ALIGN_EPI) { if (wr == 0) PG8_BAR; }
	s_setprio 0
	s_add_i32 s50, 0, 0x18000
	s_add_i32 s51, 0, 0x1c000
	v_add_u32_e32 v140, s50, v179
	v_add_u32_e32 v172, s51, v179
	ds_read_b128 v[128:131], v140
	ds_read_b128 v[132:135], v140 offset:1024
	ds_read_b128 v[136:139], v140 offset:2048
	ds_read_b128 v[140:143], v140 offset:3072
	ds_read_b128 v[144:147], v172
	ds_read_b128 v[148:151], v172 offset:1024
	ds_read_b128 v[168:171], v172 offset:2048
	ds_read_b128 v[172:175], v172 offset:3072
	s_add_u32 s30, s30, 0x80000
	s_addc_u32 s31, s31, 0
	s_add_u32 s28, s28, 0x80080
	s_addc_u32 s29, s29, 0
	s_mov_b32 m0, s36
	ds_read_b128 v[186:189], v183 offset:32768
	ds_read_b128 v[190:193], v183 offset:33792
	ds_read_b128 v[198:201], v183 offset:34816
	ds_read_b128 v[202:205], v183 offset:35840
	ds_read_b128 v[206:209], v183 offset:36864
	ds_read_b128 v[210:213], v183 offset:37888
	ds_read_b128 v[214:217], v183 offset:38912
	ds_read_b128 v[218:221], v183 offset:39936
	global_load_lds_dwordx4 v152, s[30:31]
	s_mov_b32 m0, s37
	s_nop 0
	global_load_lds_dwordx4 v156, s[30:31]
	s_waitcnt vmcnt(8) lgkmcnt(0)
	s_setprio 1
	s_barrier
	v_mfma_f32_16x16x32_bf16 v[124:127], v[128:131], v[186:189], v[124:127]
	v_mfma_f32_16x16x32_bf16 v[120:123], v[136:139], v[186:189], v[120:123]
	v_mfma_f32_16x16x32_bf16 v[104:107], v[128:131], v[198:201], v[104:107]
	v_mfma_f32_16x16x32_bf16 v[108:111], v[136:139], v[198:201], v[108:111]
	v_mfma_f32_16x16x32_bf16 v[88:91], v[128:131], v[206:209], v[88:91]
	v_mfma_f32_16x16x32_bf16 v[92:95], v[136:139], v[206:209], v[92:95]
	v_mfma_f32_16x16x32_bf16 v[72:75], v[128:131], v[214:217], v[72:75]
	v_mfma_f32_16x16x32_bf16 v[76:79], v[136:139], v[214:217], v[76:79]
	v_mfma_f32_16x16x32_bf16 v[124:127], v[132:135], v[190:193], v[124:127]
	v_mfma_f32_16x16x32_bf16 v[120:123], v[140:143], v[190:193], v[120:123]
	v_mfma_f32_16x16x32_bf16 v[104:107], v[132:135], v[202:205], v[104:107]
	v_mfma_f32_16x16x32_bf16 v[108:111], v[140:143], v[202:205], v[108:111]
	v_mfma_f32_16x16x32_bf16 v[88:91], v[132:135], v[210:213], v[88:91]
	v_mfma_f32_16x16x32_bf16 v[92:95], v[140:143], v[210:213], v[92:95]
	v_mfma_f32_16x16x32_bf16 v[72:75], v[132:135], v[218:221], v[72:75]
	v_mfma_f32_16x16x32_bf16 v[76:79], v[140:143], v[218:221], v[76:79]
	v_mfma_f32_16x16x32_bf16 v[116:119], v[144:147], v[186:189], v[116:119]
	v_mfma_f32_16x16x32_bf16 v[112:115], v[168:171], v[186:189], v[112:115]
	v_mfma_f32_16x16x32_bf16 v[100:103], v[144:147], v[198:201], v[100:103]
	v_mfma_f32_16x16x32_bf16 v[96:99], v[168:171], v[198:201], v[96:99]
	v_mfma_f32_16x16x32_bf16 v[84:87], v[144:147], v[206:209], v[84:87]
	v_mfma_f32_16x16x32_bf16 v[80:83], v[168:171], v[206:209], v[80:83]
	v_mfma_f32_16x16x32_bf16 v[68:71], v[144:147], v[214:217], v[68:71]
	v_mfma_f32_16x16x32_bf16 v[64:67], v[168:171], v[214:217], v[64:67]
	v_mfma_f32_16x16x32_bf16 v[116:119], v[148:151], v[190:193], v[116:119]
	v_mfma_f32_16x16x32_bf16 v[112:115], v[172:175], v[190:193], v[112:115]
	v_mfma_f32_16x16x32_bf16 v[100:103], v[148:151], v[202:205], v[100:103]
	v_mfma_f32_16x16x32_bf16 v[96:99], v[172:175], v[202:205], v[96:99]
	v_mfma_f32_16x16x32_bf16 v[84:87], v[148:151], v[210:213], v[84:87]
	v_mfma_f32_16x16x32_bf16 v[80:83], v[172:175], v[210:213], v[80:83]
	v_mfma_f32_16x16x32_bf16 v[68:71], v[148:151], v[218:221], v[68:71]
	v_mfma_f32_16x16x32_bf16 v[64:67], v[172:175], v[218:221], v[64:67]
	s_barrier
	s_setprio 0
	v_lshl_add_u64 v[176:177], v[176:177], 0, s[12:13]
	s_mov_b32 m0, s100
	ds_read_b128 v[186:189], v183 offset:49152
	ds_read_b128 v[190:193], v183 offset:50176
	ds_read_b128 v[198:201], v183 offset:51200
	ds_read_b128 v[202:205], v183 offset:52224
	ds_read_b128 v[206:209], v183 offset:53248
	ds_read_b128 v[210:213], v183 offset:54272
	ds_read_b128 v[214:217], v183 offset:55296
	ds_read_b128 v[218:221], v183 offset:56320
	global_load_lds_dwordx4 v[176:177], off
	s_add_i32 m0, s100, 0x2000
	v_lshl_add_u64 v[176:177], v[194:195], 0, s[12:13]
	global_load_lds_dwordx4 v[176:177], off
	s_mov_b32 m0, s101
	s_nop 0
	global_load_lds_dwordx4 v154, s[28:29]
	s_add_i32 m0, s101, 0x2000
	v_lshl_add_u64 v[176:177], s[28:29], 0, v[158:159]
	global_load_lds_dwordx4 v[176:177], off
	s_mov_b32 m0, s39
	v_lshl_add_u64 v[176:177], v[222:223], 0, s[12:13]
	global_load_lds_dwordx4 v[176:177], off
	s_mov_b32 m0, s40
	v_lshl_add_u64 v[176:177], v[224:225], 0, s[12:13]
	global_load_lds_dwordx4 v[176:177], off
	s_waitcnt vmcnt(8) lgkmcnt(0)
	s_setprio 1
	s_barrier
	v_mfma_f32_16x16x32_bf16 v[56:59], v[128:131], v[186:189], v[56:59]
	v_mfma_f32_16x16x32_bf16 v[60:63], v[136:139], v[186:189], v[60:63]
	v_mfma_f32_16x16x32_bf16 v[40:43], v[128:131], v[198:201], v[40:43]
	v_mfma_f32_16x16x32_bf16 v[44:47], v[136:139], v[198:201], v[44:47]
	v_mfma_f32_16x16x32_bf16 v[24:27], v[128:131], v[206:209], v[24:27]
	v_mfma_f32_16x16x32_bf16 v[28:31], v[136:139], v[206:209], v[28:31]
	v_mfma_f32_16x16x32_bf16 v[8:11], v[128:131], v[214:217], v[8:11]
	v_mfma_f32_16x16x32_bf16 v[12:15], v[136:139], v[214:217], v[12:15]
	v_mfma_f32_16x16x32_bf16 v[56:59], v[132:135], v[190:193], v[56:59]
	v_mfma_f32_16x16x32_bf16 v[60:63], v[140:143], v[190:193], v[60:63]
	v_mfma_f32_16x16x32_bf16 v[40:43], v[132:135], v[202:205], v[40:43]
	v_mfma_f32_16x16x32_bf16 v[44:47], v[140:143], v[202:205], v[44:47]
	v_mfma_f32_16x16x32_bf16 v[24:27], v[132:135], v[210:213], v[24:27]
	v_mfma_f32_16x16x32_bf16 v[28:31], v[140:143], v[210:213], v[28:31]
	v_mfma_f32_16x16x32_bf16 v[8:11], v[132:135], v[218:221], v[8:11]
	v_mfma_f32_16x16x32_bf16 v[12:15], v[140:143], v[218:221], v[12:15]
	v_mfma_f32_16x16x32_bf16 v[52:55], v[144:147], v[186:189], v[52:55]
	v_mfma_f32_16x16x32_bf16 v[48:51], v[168:171], v[186:189], v[48:51]
	v_mfma_f32_16x16x32_bf16 v[36:39], v[144:147], v[198:201], v[36:39]
	v_mfma_f32_16x16x32_bf16 v[32:35], v[168:171], v[198:201], v[32:35]
	v_mfma_f32_16x16x32_bf16 v[20:23], v[144:147], v[206:209], v[20:23]
	v_mfma_f32_16x16x32_bf16 v[16:19], v[168:171], v[206:209], v[16:19]
	v_mfma_f32_16x16x32_bf16 v[4:7], v[144:147], v[214:217], v[4:7]
	v_mfma_f32_16x16x32_bf16 v[0:3], v[168:171], v[214:217], v[0:3]
	v_mfma_f32_16x16x32_bf16 v[52:55], v[148:151], v[190:193], v[52:55]
	v_mfma_f32_16x16x32_bf16 v[48:51], v[172:175], v[190:193], v[48:51]
	v_mfma_f32_16x16x32_bf16 v[36:39], v[148:151], v[202:205], v[36:39]
	v_mfma_f32_16x16x32_bf16 v[32:35], v[172:175], v[202:205], v[32:35]
	v_mfma_f32_16x16x32_bf16 v[20:23], v[148:151], v[210:213], v[20:23]
	v_mfma_f32_16x16x32_bf16 v[16:19], v[172:175], v[210:213], v[16:19]
	v_mfma_f32_16x16x32_bf16 v[4:7], v[148:151], v[218:221], v[4:7]
	v_mfma_f32_16x16x32_bf16 v[0:3], v[172:175], v[218:221], v[0:3]
	s_barrier
	s_setprio 0
	s_add_i32 s49, s49, 2
	s_add_u32 s26, s26, 0x100
	s_addc_u32 s27, s27, 0
	s_add_u32 s47, s47, 0x100
	s_addc_u32 s48, s48, 0
	s_cmp_gt_u32 s49, 29
	s_cbranch_scc0 .LBB0_1180
	s_and_b64 vcc, exec, s[14:15]
	s_cbranch_vccz .LBB0_1183
	s_barrier

; #define PG8_STAGE(bufoff, gbase, voff) do { _Pragma("unroll") for (int _i = 0; _i < 2; ++_i) \
;         __builtin_amdgcn_global_load_lds((const unsigned*)((const char*)(gbase) + (voff)[_i]), (PG8_LAS unsigned*)(lds + (bufoff) + ldsw + _i * 8192), 16, 0, 0); } while (0)
; #define PG8_LDA(dst, b, h) do { _Pragma("unroll") for (int m = 0; m < 4; ++m) _Pragma("unroll") for (int k = 0; k < 2; ++k) dst[m][k] = *(const PG8_LAS bf16x8*)(lds + PG8_SA(b, h) + aoff + m * 2048 + k * 1024); } while (0)
; #define PG8_LDB(dst, b, h) do { _Pragma("unroll") for (int n = 0; n < 2; ++n) _Pragma("unroll") for (int k = 0; k < 2; ++k) dst[n][k] = *(const PG8_LAS bf16x8*)(lds + PG8_SB(b, h) + boff + n * 2048 + k * 1024); } while (0)
; #define PG8_MMA(ai, bj, At, Bt) do { __builtin_amdgcn_s_setprio(1); _Pragma("unroll") for (int m = 0; m < 4; ++m) _Pragma("unroll") for (int n = 0; n < 2; ++n) _Pragma("unroll") for (int k = 0; k < 2; ++k) \
;         acc[ai][bj][m][n] = __builtin_amdgcn_mfma_f32_16x16x32_bf16(Bt[n][k], At[m][k], acc[ai][bj][m][n], 0, 0, 0); __builtin_amdgcn_s_setprio(0); } while (0)
; #define PG8_BAR __builtin_amdgcn_s_barrier()
; template <class Epi, class Sched, bool ALIGN_EPI = false, bool SP2 = false>
; __device__ __forceinline__ void gemm_phase(PG8_LAS unsigned char* lds, const Gemm g, const Sched& S, const Epi& E) {
;     ...
;         const bool has_next = S.next(ui + 1, nxt);
;         const char* nA = has_next ? (const char*)g.A + (size_t)nxt.pm * tstep : cA; const char* nB = has_next ? (const char*)g.Bt + (size_t)nxt.pn * tstep : cB;
;         for (int t = 0; t < nt; t += 2) {
;             const bool last = (t == nt - 2);
;             const char* a1 = cA + (size_t)(t + 1) * kstep;
;             const char* a2 = last ? nA : cA + (size_t)(t + 2) * kstep; const char* b2 = last ? nB : cB + (size_t)(t + 2) * kstep;
;             const char* a3 = a2 + kstep; const char* b3 = b2 + kstep;
;             if (last && has_next) S.a_ready(nxt);
;             if constexpr (SP2) {
;             PG8_LDB(B0, 0, 0); PG8_LDB(B1, 0, 1); PG8_SCHED; PG8_LDA(At, 0, 0); PG8_STAGE(PG8_SA(1, 1), a1 + hstep, voffA);
;             PG8_WAIT_V(8); PG8_WAIT_L(0); PG8_BAR; PG8_MMA(0, 0, At, B0); PG8_MMA(0, 1, At, B1); PG8_BAR; PG8_SCHED;
;             PG8_LDA(At, 0, 1); PG8_STAGE(PG8_SB(0, 0), b2, voffB); PG8_STAGE(PG8_SB(0, 1), b2 + hstep, voffB); PG8_STAGE(PG8_SA(0, 0), a2, voffA);
.LBB0_1372:
	s_ashr_i32 s29, s28, 31
	s_lshl_b64 s[34:35], s[28:29], 20
	s_add_u32 s34, s74, s34
	s_addc_u32 s35, s75, s35
	s_and_b64 s[36:37], s[30:31], exec
	s_cselect_b32 s29, s35, s9
	s_cselect_b32 s39, s34, s8
	s_ashr_i32 s27, s26, 31
	s_lshl_b64 s[36:37], s[26:27], 20
	v_readlane_b32 s44, v254, 22
	v_readlane_b32 s45, v254, 23
	s_add_u32 s36, s44, s36
	s_addc_u32 s37, s45, s37
	s_and_b64 s[44:45], s[30:31], exec
	s_cselect_b32 s27, s37, s43
	s_cselect_b32 s41, s36, s42
	s_add_u32 s8, s8, 0x80080
	s_addc_u32 s9, s9, 0
	s_add_u32 s48, s42, 0x100
	s_addc_u32 s49, s43, 0
	s_mov_b32 s66, -2
	s_add_i32 s98, s47, 0x10000
	s_add_i32 s99, s47, 0x14000
	s_add_i32 s100, s47, 0x18000
	s_add_i32 s101, s47, 0x1c000
	ds_read_b128 v[108:111], v173
	ds_read_b128 v[112:115], v173 offset:1024
	ds_read_b128 v[116:119], v173 offset:2048
	ds_read_b128 v[120:123], v173 offset:3072
	ds_read_b128 v[178:181], v175
	ds_read_b128 v[182:185], v175 offset:1024
	ds_read_b128 v[186:189], v175 offset:2048
	ds_read_b128 v[190:193], v175 offset:3072
	s_add_u32 s42, s8, 0xfff80080
	s_addc_u32 s43, s9, -1
	s_cmp_eq_u32 s66, 28
	s_cselect_b32 s45, s29, s43
	s_cselect_b32 s44, s39, s42
	s_cselect_b32 s43, s27, s49
	s_cselect_b32 s42, s41, s48
	s_add_u32 s68, s42, 0x80000
	s_addc_u32 s69, s43, 0
	s_add_i32 m0, s50, 0xc000
	ds_read_b128 v[198:201], v177
	ds_read_b128 v[202:205], v177 offset:1024
	ds_read_b128 v[206:209], v177 offset:2048
	ds_read_b128 v[210:213], v177 offset:3072
	ds_read_b128 v[214:217], v177 offset:4096
	ds_read_b128 v[218:221], v177 offset:5120
	ds_read_b128 v[222:225], v177 offset:6144
	ds_read_b128 v[226:229], v177 offset:7168
	global_load_lds_dwordx4 v154, s[8:9]
	s_add_i32 m0, s50, 0xe000
	s_nop 0
	global_load_lds_dwordx4 v156, s[8:9]
	s_waitcnt lgkmcnt(0)
	s_setprio 1
	s_barrier
	v_mfma_f32_16x16x32_bf16 v[140:143], v[108:111], v[198:201], 0
	v_mfma_f32_16x16x32_bf16 v[136:139], v[116:119], v[198:201], 0
	v_mfma_f32_16x16x32_bf16 v[100:103], v[108:111], v[206:209], 0
	v_mfma_f32_16x16x32_bf16 v[124:127], v[116:119], v[206:209], 0
	v_mfma_f32_16x16x32_bf16 v[84:87], v[108:111], v[214:217], 0
	v_mfma_f32_16x16x32_bf16 v[92:95], v[116:119], v[214:217], 0
	v_mfma_f32_16x16x32_bf16 v[68:71], v[108:111], v[222:225], 0
	v_mfma_f32_16x16x32_bf16 v[76:79], v[116:119], v[222:225], 0
	v_mfma_f32_16x16x32_bf16 v[140:143], v[112:115], v[202:205], v[140:143]
	v_mfma_f32_16x16x32_bf16 v[136:139], v[120:123], v[202:205], v[136:139]
	v_mfma_f32_16x16x32_bf16 v[100:103], v[112:115], v[210:213], v[100:103]
	v_mfma_f32_16x16x32_bf16 v[124:127], v[120:123], v[210:213], v[124:127]
	v_mfma_f32_16x16x32_bf16 v[84:87], v[112:115], v[218:221], v[84:87]
	v_mfma_f32_16x16x32_bf16 v[92:95], v[120:123], v[218:221], v[92:95]
	v_mfma_f32_16x16x32_bf16 v[68:71], v[112:115], v[226:229], v[68:71]
	v_mfma_f32_16x16x32_bf16 v[76:79], v[120:123], v[226:229], v[76:79]
	v_mfma_f32_16x16x32_bf16 v[128:131], v[178:181], v[198:201], 0
	v_mfma_f32_16x16x32_bf16 v[132:135], v[186:189], v[198:201], 0
	v_mfma_f32_16x16x32_bf16 v[104:107], v[178:181], v[206:209], 0
	v_mfma_f32_16x16x32_bf16 v[96:99], v[186:189], v[206:209], 0
	v_mfma_f32_16x16x32_bf16 v[88:91], v[178:181], v[214:217], 0
	v_mfma_f32_16x16x32_bf16 v[80:83], v[186:189], v[214:217], 0
	v_mfma_f32_16x16x32_bf16 v[72:75], v[178:181], v[222:225], 0
	v_mfma_f32_16x16x32_bf16 v[64:67], v[186:189], v[222:225], 0
	v_mfma_f32_16x16x32_bf16 v[128:131], v[182:185], v[202:205], v[128:131]
	v_mfma_f32_16x16x32_bf16 v[132:135], v[190:193], v[202:205], v[132:135]
	v_mfma_f32_16x16x32_bf16 v[104:107], v[182:185], v[210:213], v[104:107]
	v_mfma_f32_16x16x32_bf16 v[96:99], v[190:193], v[210:213], v[96:99]
	v_mfma_f32_16x16x32_bf16 v[88:91], v[182:185], v[218:221], v[88:91]
	v_mfma_f32_16x16x32_bf16 v[80:83], v[190:193], v[218:221], v[80:83]
	v_mfma_f32_16x16x32_bf16 v[72:75], v[182:185], v[226:229], v[72:75]
	v_mfma_f32_16x16x32_bf16 v[64:67], v[190:193], v[226:229], v[64:67]
	s_barrier
	s_setprio 0
	v_lshl_add_u64 v[160:161], s[42:43], 0, v[144:145]
	s_mov_b32 m0, s98
	ds_read_b128 v[198:201], v177 offset:16384
	ds_read_b128 v[202:205], v177 offset:17408
	ds_read_b128 v[206:209], v177 offset:18432
	ds_read_b128 v[210:213], v177 offset:19456
	ds_read_b128 v[214:217], v177 offset:20480
	ds_read_b128 v[218:221], v177 offset:21504
	ds_read_b128 v[222:225], v177 offset:22528
	ds_read_b128 v[226:229], v177 offset:23552
	global_load_lds_dwordx4 v[160:161], off
	s_add_i32 m0, s98, 0x2000
	v_lshl_add_u64 v[164:165], s[42:43], 0, v[146:147]
	global_load_lds_dwordx4 v[164:165], off
	s_mov_b32 m0, s99
	v_lshl_add_u64 v[194:195], s[44:45], 0, v[146:147]
	global_load_lds_dwordx4 v144, s[68:69]
	s_add_i32 m0, s99, 0x2000
	s_nop 0
	global_load_lds_dwordx4 v146, s[68:69]
	s_mov_b32 m0, s50
	v_lshl_add_u64 v[170:171], s[44:45], 0, v[144:145]
	global_load_lds_dwordx4 v[170:171], off
	s_mov_b32 m0, s51
	s_nop 0
	global_load_lds_dwordx4 v[194:195], off
	s_waitcnt lgkmcnt(0)
	s_setprio 1
	s_barrier
; #define PG8_STAGE(bufoff, gbase, voff) do { _Pragma("unroll") for (int _i = 0; _i < 2; ++_i) \
;         __builtin_amdgcn_global_load_lds((const unsigned*)((const char*)(gbase) + (voff)[_i]), (PG8_LAS unsigned*)(lds + (bufoff) + ldsw + _i * 8192), 16, 0, 0); } while (0)
; #define PG8_LDA(dst, b, h) do { _Pragma("unroll") for (int m = 0; m < 4; ++m) _Pragma("unroll") for (int k = 0; k < 2; ++k) dst[m][k] = *(const PG8_LAS bf16x8*)(lds + PG8_SA(b, h) + aoff + m * 2048 + k * 1024); } while (0)
; #define PG8_LDB(dst, b, h) do { _Pragma("unroll") for (int n = 0; n < 2; ++n) _Pragma("unroll") for (int k = 0; k < 2; ++k) dst[n][k] = *(const PG8_LAS bf16x8*)(lds + PG8_SB(b, h) + boff + n * 2048 + k * 1024); } while (0)
; #define PG8_MMA(ai, bj, At, Bt) do { __builtin_amdgcn_s_setprio(1); _Pragma("unroll") for (int m = 0; m < 4; ++m) _Pragma("unroll") for (int n = 0; n < 2; ++n) _Pragma("unroll") for (int k = 0; k < 2; ++k) \
;         acc[ai][bj][m][n] = __builtin_amdgcn_mfma_f32_16x16x32_bf16(Bt[n][k], At[m][k], acc[ai][bj][m][n], 0, 0, 0); __builtin_amdgcn_s_setprio(0); } while (0)
; #define PG8_WAIT_V(n) asm volatile("s_waitcnt vmcnt(" #n ")" ::: "memory")
; #define PG8_WAIT_L(n) asm volatile("s_waitcnt lgkmcnt(" #n ")" ::: "memory")
; #define PG8_BAR __builtin_amdgcn_s_barrier()
; #define PG8_SCHED __builtin_amdgcn_sched_barrier(0)
; template <class Epi, class Sched, bool ALIGN_EPI = false, bool SP2 = false>
; __device__ __forceinline__ void gemm_phase(PG8_LAS unsigned char* lds, const Gemm g, const Sched& S, const Epi& E) {
;     ...
;             PG8_WAIT_V(8); PG8_WAIT_L(0); PG8_BAR; PG8_MMA(1, 0, At, B0); PG8_MMA(1, 1, At, B1); PG8_BAR; PG8_SCHED;
;             PG8_LDB(B0, 1, 0); PG8_LDB(B1, 1, 1); PG8_SCHED; PG8_LDA(At, 1, 0); PG8_STAGE(PG8_SA(0, 1), a2 + hstep, voffA);
;             PG8_WAIT_V(8); PG8_WAIT_L(0); PG8_BAR; PG8_MMA(0, 0, At, B0); PG8_MMA(0, 1, At, B1); PG8_BAR; PG8_SCHED;
	v_mfma_f32_16x16x32_bf16 v[60:63], v[108:111], v[198:201], 0
	v_mfma_f32_16x16x32_bf16 v[56:59], v[116:119], v[198:201], 0
	v_mfma_f32_16x16x32_bf16 v[36:39], v[108:111], v[206:209], 0
	v_mfma_f32_16x16x32_bf16 v[44:47], v[116:119], v[206:209], 0
	v_mfma_f32_16x16x32_bf16 v[20:23], v[108:111], v[214:217], 0
	v_mfma_f32_16x16x32_bf16 v[28:31], v[116:119], v[214:217], 0
	v_mfma_f32_16x16x32_bf16 v[4:7], v[108:111], v[222:225], 0
	v_mfma_f32_16x16x32_bf16 v[12:15], v[116:119], v[222:225], 0
	v_mfma_f32_16x16x32_bf16 v[60:63], v[112:115], v[202:205], v[60:63]
	v_mfma_f32_16x16x32_bf16 v[56:59], v[120:123], v[202:205], v[56:59]
	v_mfma_f32_16x16x32_bf16 v[36:39], v[112:115], v[210:213], v[36:39]
	v_mfma_f32_16x16x32_bf16 v[44:47], v[120:123], v[210:213], v[44:47]
	v_mfma_f32_16x16x32_bf16 v[20:23], v[112:115], v[218:221], v[20:23]
	v_mfma_f32_16x16x32_bf16 v[28:31], v[120:123], v[218:221], v[28:31]
	v_mfma_f32_16x16x32_bf16 v[4:7], v[112:115], v[226:229], v[4:7]
	v_mfma_f32_16x16x32_bf16 v[12:15], v[120:123], v[226:229], v[12:15]
	v_mfma_f32_16x16x32_bf16 v[48:51], v[178:181], v[198:201], 0
	v_mfma_f32_16x16x32_bf16 v[52:55], v[186:189], v[198:201], 0
	v_mfma_f32_16x16x32_bf16 v[40:43], v[178:181], v[206:209], 0
	v_mfma_f32_16x16x32_bf16 v[32:35], v[186:189], v[206:209], 0
	v_mfma_f32_16x16x32_bf16 v[24:27], v[178:181], v[214:217], 0
	v_mfma_f32_16x16x32_bf16 v[16:19], v[186:189], v[214:217], 0
	v_mfma_f32_16x16x32_bf16 v[8:11], v[178:181], v[222:225], 0
	v_mfma_f32_16x16x32_bf16 v[0:3], v[186:189], v[222:225], 0
	v_mfma_f32_16x16x32_bf16 v[48:51], v[182:185], v[202:205], v[48:51]
	v_mfma_f32_16x16x32_bf16 v[52:55], v[190:193], v[202:205], v[52:55]
	v_mfma_f32_16x16x32_bf16 v[40:43], v[182:185], v[210:213], v[40:43]
	v_mfma_f32_16x16x32_bf16 v[32:35], v[190:193], v[210:213], v[32:35]
	v_mfma_f32_16x16x32_bf16 v[24:27], v[182:185], v[218:221], v[24:27]
	v_mfma_f32_16x16x32_bf16 v[16:19], v[190:193], v[218:221], v[16:19]
	v_mfma_f32_16x16x32_bf16 v[8:11], v[182:185], v[226:229], v[8:11]
	v_mfma_f32_16x16x32_bf16 v[0:3], v[190:193], v[226:229], v[0:3]
	s_barrier
	s_setprio 0
	s_add_i32 s67, 0, 0x18000
	s_add_i32 s68, 0, 0x1c000
	v_add_u32_e32 v120, s67, v167
	v_add_u32_e32 v162, s68, v167
	ds_read_b128 v[108:111], v120
	ds_read_b128 v[112:115], v120 offset:1024
	ds_read_b128 v[116:119], v120 offset:2048
	ds_read_b128 v[120:123], v120 offset:3072
	ds_read_b128 v[178:181], v162
	ds_read_b128 v[182:185], v162 offset:1024
	ds_read_b128 v[186:189], v162 offset:2048
	ds_read_b128 v[190:193], v162 offset:3072
	s_add_u32 s44, s44, 0x80000
	s_addc_u32 s45, s45, 0
	s_add_u32 s42, s42, 0x80080
	s_addc_u32 s43, s43, 0
	s_mov_b32 m0, s52
	ds_read_b128 v[198:201], v177 offset:32768
	ds_read_b128 v[202:205], v177 offset:33792
	ds_read_b128 v[206:209], v177 offset:34816
	ds_read_b128 v[210:213], v177 offset:35840
	ds_read_b128 v[214:217], v177 offset:36864
	ds_read_b128 v[218:221], v177 offset:37888
	ds_read_b128 v[222:225], v177 offset:38912
	ds_read_b128 v[226:229], v177 offset:39936
	global_load_lds_dwordx4 v144, s[44:45]
	s_mov_b32 m0, s53
	v_lshl_add_u64 v[230:231], s[44:45], 0, v[146:147]
	global_load_lds_dwordx4 v[230:231], off
	s_waitcnt vmcnt(8) lgkmcnt(0)
	s_setprio 1
	s_barrier
	v_mfma_f32_16x16x32_bf16 v[140:143], v[108:111], v[198:201], v[140:143]
	v_mfma_f32_16x16x32_bf16 v[136:139], v[116:119], v[198:201], v[136:139]
	v_mfma_f32_16x16x32_bf16 v[100:103], v[108:111], v[206:209], v[100:103]
	v_mfma_f32_16x16x32_bf16 v[124:127], v[116:119], v[206:209], v[124:127]
	v_mfma_f32_16x16x32_bf16 v[84:87], v[108:111], v[214:217], v[84:87]
	v_mfma_f32_16x16x32_bf16 v[92:95], v[116:119], v[214:217], v[92:95]
	v_mfma_f32_16x16x32_bf16 v[68:71], v[108:111], v[222:225], v[68:71]
	v_mfma_f32_16x16x32_bf16 v[76:79], v[116:119], v[222:225], v[76:79]
	v_mfma_f32_16x16x32_bf16 v[140:143], v[112:115], v[202:205], v[140:143]
	v_mfma_f32_16x16x32_bf16 v[136:139], v[120:123], v[202:205], v[136:139]
	v_mfma_f32_16x16x32_bf16 v[100:103], v[112:115], v[210:213], v[100:103]
	v_mfma_f32_16x16x32_bf16 v[124:127], v[120:123], v[210:213], v[124:127]
	v_mfma_f32_16x16x32_bf16 v[84:87], v[112:115], v[218:221], v[84:87]
	v_mfma_f32_16x16x32_bf16 v[92:95], v[120:123], v[218:221], v[92:95]
	v_mfma_f32_16x16x32_bf16 v[68:71], v[112:115], v[226:229], v[68:71]
	v_mfma_f32_16x16x32_bf16 v[76:79], v[120:123], v[226:229], v[76:79]
	v_mfma_f32_16x16x32_bf16 v[128:131], v[178:181], v[198:201], v[128:131]
	v_mfma_f32_16x16x32_bf16 v[132:135], v[186:189], v[198:201], v[132:135]
	v_mfma_f32_16x16x32_bf16 v[104:107], v[178:181], v[206:209], v[104:107]
	v_mfma_f32_16x16x32_bf16 v[96:99], v[186:189], v[206:209], v[96:99]
	v_mfma_f32_16x16x32_bf16 v[88:91], v[178:181], v[214:217], v[88:91]
	v_mfma_f32_16x16x32_bf16 v[80:83], v[186:189], v[214:217], v[80:83]
	v_mfma_f32_16x16x32_bf16 v[72:75], v[178:181], v[222:225], v[72:75]
	v_mfma_f32_16x16x32_bf16 v[64:67], v[186:189], v[222:225], v[64:67]
	v_mfma_f32_16x16x32_bf16 v[128:131], v[182:185], v[202:205], v[128:131]
	v_mfma_f32_16x16x32_bf16 v[132:135], v[190:193], v[202:205], v[132:135]
	v_mfma_f32_16x16x32_bf16 v[104:107], v[182:185], v[210:213], v[104:107]
	v_mfma_f32_16x16x32_bf16 v[96:99], v[190:193], v[210:213], v[96:99]
	v_mfma_f32_16x16x32_bf16 v[88:91], v[182:185], v[218:221], v[88:91]
	v_mfma_f32_16x16x32_bf16 v[80:83], v[190:193], v[218:221], v[80:83]
	v_mfma_f32_16x16x32_bf16 v[72:75], v[182:185], v[226:229], v[72:75]
	v_mfma_f32_16x16x32_bf16 v[64:67], v[190:193], v[226:229], v[64:67]
	s_barrier
; #define PG8_STAGE(bufoff, gbase, voff) do { _Pragma("unroll") for (int _i = 0; _i < 2; ++_i) \
;         __builtin_amdgcn_global_load_lds((const unsigned*)((const char*)(gbase) + (voff)[_i]), (PG8_LAS unsigned*)(lds + (bufoff) + ldsw + _i * 8192), 16, 0, 0); } while (0)
; #define PG8_LDA(dst, b, h) do { _Pragma("unroll") for (int m = 0; m < 4; ++m) _Pragma("unroll") for (int k = 0; k < 2; ++k) dst[m][k] = *(const PG8_LAS bf16x8*)(lds + PG8_SA(b, h) + aoff + m * 2048 + k * 1024); } while (0)
; #define PG8_LDB(dst, b, h) do { _Pragma("unroll") for (int n = 0; n < 2; ++n) _Pragma("unroll") for (int k = 0; k < 2; ++k) dst[n][k] = *(const PG8_LAS bf16x8*)(lds + PG8_SB(b, h) + boff + n * 2048 + k * 1024); } while (0)
; #define PG8_MMA(ai, bj, At, Bt) do { __builtin_amdgcn_s_setprio(1); _Pragma("unroll") for (int m = 0; m < 4; ++m) _Pragma("unroll") for (int n = 0; n < 2; ++n) _Pragma("unroll") for (int k = 0; k < 2; ++k) \
;         acc[ai][bj][m][n] = __builtin_amdgcn_mfma_f32_16x16x32_bf16(Bt[n][k], At[m][k], acc[ai][bj][m][n], 0, 0, 0); __builtin_amdgcn_s_setprio(0); } while (0)
; #define PG8_WAIT_V(n) asm volatile("s_waitcnt vmcnt(" #n ")" ::: "memory")
; template <class Epi, class Sched, bool ALIGN_EPI = false, bool SP2 = false>
; __device__ __forceinline__ void gemm_phase(PG8_LAS unsigned char* lds, const Gemm g, const Sched& S, const Epi& E) {
;     ...
;             PG8_LDB(B0, 0, 0); PG8_LDB(B1, 0, 1); PG8_SCHED; PG8_LDA(At, 0, 0); PG8_STAGE(PG8_SA(1, 1), a1 + hstep, voffA);
;             PG8_WAIT_V(8); PG8_WAIT_L(0); PG8_BAR; PG8_MMA(0, 0, At, B0); PG8_MMA(0, 1, At, B1); PG8_BAR; PG8_SCHED;
;             PG8_LDA(At, 0, 1); PG8_STAGE(PG8_SB(0, 0), b2, voffB); PG8_STAGE(PG8_SB(0, 1), b2 + hstep, voffB); PG8_STAGE(PG8_SA(0, 0), a2, voffA);
;             PG8_WAIT_V(8); PG8_WAIT_L(0); PG8_BAR; PG8_MMA(1, 0, At, B0); PG8_MMA(1, 1, At, B1); PG8_BAR; PG8_SCHED;
;             PG8_LDB(B0, 1, 0); PG8_LDB(B1, 1, 1); PG8_SCHED; PG8_LDA(At, 1, 0); PG8_STAGE(PG8_SA(0, 1), a2 + hstep, voffA);
;             PG8_WAIT_V(8); PG8_WAIT_L(0); PG8_BAR; PG8_MMA(0, 0, At, B0); PG8_MMA(0, 1, At, B1); PG8_BAR; PG8_SCHED;
;             PG8_LDA(At, 1, 1); PG8_STAGE(PG8_SB(1, 0), b3, voffB); PG8_STAGE(PG8_SB(1, 1), b3 + hstep, voffB); PG8_STAGE(PG8_SA(1, 0), a3, voffA);
;             PG8_WAIT_V(8); PG8_WAIT_L(0); PG8_BAR; PG8_MMA(1, 0, At, B0); PG8_MMA(1, 1, At, B1); PG8_BAR; PG8_SCHED;
	s_setprio 0
	v_lshl_add_u64 v[160:161], v[160:161], 0, s[16:17]
	s_mov_b32 m0, s100
	ds_read_b128 v[198:201], v177 offset:49152
	ds_read_b128 v[202:205], v177 offset:50176
	ds_read_b128 v[206:209], v177 offset:51200
	ds_read_b128 v[210:213], v177 offset:52224
	ds_read_b128 v[214:217], v177 offset:53248
	ds_read_b128 v[218:221], v177 offset:54272
	ds_read_b128 v[222:225], v177 offset:55296
	ds_read_b128 v[226:229], v177 offset:56320
	global_load_lds_dwordx4 v[160:161], off
	s_add_i32 m0, s100, 0x2000
	v_lshl_add_u64 v[160:161], v[164:165], 0, s[16:17]
	global_load_lds_dwordx4 v[160:161], off
	s_mov_b32 m0, s101
	s_nop 0
	global_load_lds_dwordx4 v144, s[42:43]
	s_add_i32 m0, s101, 0x2000
	v_lshl_add_u64 v[160:161], s[42:43], 0, v[146:147]
	global_load_lds_dwordx4 v[160:161], off
	s_mov_b32 m0, s55
	v_lshl_add_u64 v[160:161], v[170:171], 0, s[16:17]
	global_load_lds_dwordx4 v[160:161], off
	s_mov_b32 m0, s56
	v_lshl_add_u64 v[160:161], v[194:195], 0, s[16:17]
	global_load_lds_dwordx4 v[160:161], off
	s_waitcnt vmcnt(8) lgkmcnt(0)
	s_setprio 1
	s_barrier
	v_mfma_f32_16x16x32_bf16 v[60:63], v[108:111], v[198:201], v[60:63]
	v_mfma_f32_16x16x32_bf16 v[56:59], v[116:119], v[198:201], v[56:59]
	v_mfma_f32_16x16x32_bf16 v[36:39], v[108:111], v[206:209], v[36:39]
	v_mfma_f32_16x16x32_bf16 v[44:47], v[116:119], v[206:209], v[44:47]
	v_mfma_f32_16x16x32_bf16 v[20:23], v[108:111], v[214:217], v[20:23]
	v_mfma_f32_16x16x32_bf16 v[28:31], v[116:119], v[214:217], v[28:31]
	v_mfma_f32_16x16x32_bf16 v[4:7], v[108:111], v[222:225], v[4:7]
	v_mfma_f32_16x16x32_bf16 v[12:15], v[116:119], v[222:225], v[12:15]
	v_mfma_f32_16x16x32_bf16 v[60:63], v[112:115], v[202:205], v[60:63]
	v_mfma_f32_16x16x32_bf16 v[56:59], v[120:123], v[202:205], v[56:59]
	v_mfma_f32_16x16x32_bf16 v[36:39], v[112:115], v[210:213], v[36:39]
	v_mfma_f32_16x16x32_bf16 v[44:47], v[120:123], v[210:213], v[44:47]
	v_mfma_f32_16x16x32_bf16 v[20:23], v[112:115], v[218:221], v[20:23]
	v_mfma_f32_16x16x32_bf16 v[28:31], v[120:123], v[218:221], v[28:31]
	v_mfma_f32_16x16x32_bf16 v[4:7], v[112:115], v[226:229], v[4:7]
	v_mfma_f32_16x16x32_bf16 v[12:15], v[120:123], v[226:229], v[12:15]
	v_mfma_f32_16x16x32_bf16 v[48:51], v[178:181], v[198:201], v[48:51]
	v_mfma_f32_16x16x32_bf16 v[52:55], v[186:189], v[198:201], v[52:55]
	v_mfma_f32_16x16x32_bf16 v[40:43], v[178:181], v[206:209], v[40:43]
	v_mfma_f32_16x16x32_bf16 v[32:35], v[186:189], v[206:209], v[32:35]
	v_mfma_f32_16x16x32_bf16 v[24:27], v[178:181], v[214:217], v[24:27]
	v_mfma_f32_16x16x32_bf16 v[16:19], v[186:189], v[214:217], v[16:19]
	v_mfma_f32_16x16x32_bf16 v[8:11], v[178:181], v[222:225], v[8:11]
	v_mfma_f32_16x16x32_bf16 v[0:3], v[186:189], v[222:225], v[0:3]
	v_mfma_f32_16x16x32_bf16 v[48:51], v[182:185], v[202:205], v[48:51]
	v_mfma_f32_16x16x32_bf16 v[52:55], v[190:193], v[202:205], v[52:55]
	v_mfma_f32_16x16x32_bf16 v[40:43], v[182:185], v[210:213], v[40:43]
	v_mfma_f32_16x16x32_bf16 v[32:35], v[190:193], v[210:213], v[32:35]
	v_mfma_f32_16x16x32_bf16 v[24:27], v[182:185], v[218:221], v[24:27]
	v_mfma_f32_16x16x32_bf16 v[16:19], v[190:193], v[218:221], v[16:19]
	v_mfma_f32_16x16x32_bf16 v[8:11], v[182:185], v[226:229], v[8:11]
	v_mfma_f32_16x16x32_bf16 v[0:3], v[190:193], v[226:229], v[0:3]
	s_barrier
	s_setprio 0
	s_add_i32 s66, s66, 2
	s_add_u32 s8, s8, 0x100
	s_addc_u32 s9, s9, 0
	s_add_u32 s48, s48, 0x100
	s_addc_u32 s49, s49, 0
.LBB0_1373:
	ds_read_b128 v[108:111], v173
	ds_read_b128 v[112:115], v173 offset:1024
	ds_read_b128 v[116:119], v173 offset:2048
	ds_read_b128 v[120:123], v173 offset:3072
	ds_read_b128 v[178:181], v175
	ds_read_b128 v[182:185], v175 offset:1024
	ds_read_b128 v[186:189], v175 offset:2048
	ds_read_b128 v[190:193], v175 offset:3072
	s_add_u32 s42, s8, 0xfff80080
	s_addc_u32 s43, s9, -1
	s_cmp_eq_u32 s66, 28
	s_cselect_b32 s45, s29, s43
	s_cselect_b32 s44, s39, s42
	s_cselect_b32 s43, s27, s49
	s_cselect_b32 s42, s41, s48
	s_add_u32 s68, s42, 0x80000
	s_addc_u32 s69, s43, 0
	s_add_i32 m0, s50, 0xc000
	ds_read_b128 v[198:201], v177
	ds_read_b128 v[202:205], v177 offset:1024
	ds_read_b128 v[206:209], v177 offset:2048
	ds_read_b128 v[210:213], v177 offset:3072
	ds_read_b128 v[214:217], v177 offset:4096
	ds_read_b128 v[218:221], v177 offset:5120
	ds_read_b128 v[222:225], v177 offset:6144
	ds_read_b128 v[226:229], v177 offset:7168
	global_load_lds_dwordx4 v154, s[8:9]
	s_add_i32 m0, s50, 0xe000
	s_nop 0
	global_load_lds_dwordx4 v156, s[8:9]
	s_waitcnt vmcnt(8) lgkmcnt(0)
	s_setprio 1
	s_barrier
; #define PG8_STAGE(bufoff, gbase, voff) do { _Pragma("unroll") for (int _i = 0; _i < 2; ++_i) \
;         __builtin_amdgcn_global_load_lds((const unsigned*)((const char*)(gbase) + (voff)[_i]), (PG8_LAS unsigned*)(lds + (bufoff) + ldsw + _i * 8192), 16, 0, 0); } while (0)
; #define PG8_LDA(dst, b, h) do { _Pragma("unroll") for (int m = 0; m < 4; ++m) _Pragma("unroll") for (int k = 0; k < 2; ++k) dst[m][k] = *(const PG8_LAS bf16x8*)(lds + PG8_SA(b, h) + aoff + m * 2048 + k * 1024); } while (0)
; #define PG8_MMA(ai, bj, At, Bt) do { __builtin_amdgcn_s_setprio(1); _Pragma("unroll") for (int m = 0; m < 4; ++m) _Pragma("unroll") for (int n = 0; n < 2; ++n) _Pragma("unroll") for (int k = 0; k < 2; ++k) \
;         acc[ai][bj][m][n] = __builtin_amdgcn_mfma_f32_16x16x32_bf16(Bt[n][k], At[m][k], acc[ai][bj][m][n], 0, 0, 0); __builtin_amdgcn_s_setprio(0); } while (0)
; #define PG8_WAIT_V(n) asm volatile("s_waitcnt vmcnt(" #n ")" ::: "memory")
; #define PG8_WAIT_L(n) asm volatile("s_waitcnt lgkmcnt(" #n ")" ::: "memory")
; #define PG8_BAR __builtin_amdgcn_s_barrier()
; #define PG8_SCHED __builtin_amdgcn_sched_barrier(0)
; template <class Epi, class Sched, bool ALIGN_EPI = false, bool SP2 = false>
; __device__ __forceinline__ void gemm_phase(PG8_LAS unsigned char* lds, const Gemm g, const Sched& S, const Epi& E) {
;     ...
;             PG8_WAIT_V(8); PG8_WAIT_L(0); PG8_BAR; PG8_MMA(0, 0, At, B0); PG8_MMA(0, 1, At, B1); PG8_BAR; PG8_SCHED;
;             PG8_LDA(At, 0, 1); PG8_STAGE(PG8_SB(0, 0), b2, voffB); PG8_STAGE(PG8_SB(0, 1), b2 + hstep, voffB); PG8_STAGE(PG8_SA(0, 0), a2, voffA);
;             PG8_WAIT_V(8); PG8_WAIT_L(0); PG8_BAR; PG8_MMA(1, 0, At, B0); PG8_MMA(1, 1, At, B1); PG8_BAR; PG8_SCHED;
	v_mfma_f32_16x16x32_bf16 v[140:143], v[108:111], v[198:201], v[140:143]
	v_mfma_f32_16x16x32_bf16 v[136:139], v[116:119], v[198:201], v[136:139]
	v_mfma_f32_16x16x32_bf16 v[100:103], v[108:111], v[206:209], v[100:103]
	v_mfma_f32_16x16x32_bf16 v[124:127], v[116:119], v[206:209], v[124:127]
	v_mfma_f32_16x16x32_bf16 v[84:87], v[108:111], v[214:217], v[84:87]
	v_mfma_f32_16x16x32_bf16 v[92:95], v[116:119], v[214:217], v[92:95]
	v_mfma_f32_16x16x32_bf16 v[68:71], v[108:111], v[222:225], v[68:71]
	v_mfma_f32_16x16x32_bf16 v[76:79], v[116:119], v[222:225], v[76:79]
	v_mfma_f32_16x16x32_bf16 v[140:143], v[112:115], v[202:205], v[140:143]
	v_mfma_f32_16x16x32_bf16 v[136:139], v[120:123], v[202:205], v[136:139]
	v_mfma_f32_16x16x32_bf16 v[100:103], v[112:115], v[210:213], v[100:103]
	v_mfma_f32_16x16x32_bf16 v[124:127], v[120:123], v[210:213], v[124:127]
	v_mfma_f32_16x16x32_bf16 v[84:87], v[112:115], v[218:221], v[84:87]
	v_mfma_f32_16x16x32_bf16 v[92:95], v[120:123], v[218:221], v[92:95]
	v_mfma_f32_16x16x32_bf16 v[68:71], v[112:115], v[226:229], v[68:71]
	v_mfma_f32_16x16x32_bf16 v[76:79], v[120:123], v[226:229], v[76:79]
	v_mfma_f32_16x16x32_bf16 v[128:131], v[178:181], v[198:201], v[128:131]
	v_mfma_f32_16x16x32_bf16 v[132:135], v[186:189], v[198:201], v[132:135]
	v_mfma_f32_16x16x32_bf16 v[104:107], v[178:181], v[206:209], v[104:107]
	v_mfma_f32_16x16x32_bf16 v[96:99], v[186:189], v[206:209], v[96:99]
	v_mfma_f32_16x16x32_bf16 v[88:91], v[178:181], v[214:217], v[88:91]
	v_mfma_f32_16x16x32_bf16 v[80:83], v[186:189], v[214:217], v[80:83]
	v_mfma_f32_16x16x32_bf16 v[72:75], v[178:181], v[222:225], v[72:75]
	v_mfma_f32_16x16x32_bf16 v[64:67], v[186:189], v[222:225], v[64:67]
	v_mfma_f32_16x16x32_bf16 v[128:131], v[182:185], v[202:205], v[128:131]
	v_mfma_f32_16x16x32_bf16 v[132:135], v[190:193], v[202:205], v[132:135]
	v_mfma_f32_16x16x32_bf16 v[104:107], v[182:185], v[210:213], v[104:107]
	v_mfma_f32_16x16x32_bf16 v[96:99], v[190:193], v[210:213], v[96:99]
	v_mfma_f32_16x16x32_bf16 v[88:91], v[182:185], v[218:221], v[88:91]
	v_mfma_f32_16x16x32_bf16 v[80:83], v[190:193], v[218:221], v[80:83]
	v_mfma_f32_16x16x32_bf16 v[72:75], v[182:185], v[226:229], v[72:75]
	v_mfma_f32_16x16x32_bf16 v[64:67], v[190:193], v[226:229], v[64:67]
	s_barrier
	s_setprio 0
	v_lshl_add_u64 v[160:161], s[42:43], 0, v[144:145]
	s_mov_b32 m0, s98
	ds_read_b128 v[198:201], v177 offset:16384
	ds_read_b128 v[202:205], v177 offset:17408
	ds_read_b128 v[206:209], v177 offset:18432
	ds_read_b128 v[210:213], v177 offset:19456
	ds_read_b128 v[214:217], v177 offset:20480
	ds_read_b128 v[218:221], v177 offset:21504
	ds_read_b128 v[222:225], v177 offset:22528
	ds_read_b128 v[226:229], v177 offset:23552
	global_load_lds_dwordx4 v[160:161], off
	s_add_i32 m0, s98, 0x2000
	v_lshl_add_u64 v[164:165], s[42:43], 0, v[146:147]
	global_load_lds_dwordx4 v[164:165], off
	s_mov_b32 m0, s99
	v_lshl_add_u64 v[194:195], s[44:45], 0, v[146:147]
	global_load_lds_dwordx4 v144, s[68:69]
	s_add_i32 m0, s99, 0x2000
	s_nop 0
	global_load_lds_dwordx4 v146, s[68:69]
	s_mov_b32 m0, s50
	v_lshl_add_u64 v[170:171], s[44:45], 0, v[144:145]
	global_load_lds_dwordx4 v[170:171], off
	s_mov_b32 m0, s51
	s_nop 0
	global_load_lds_dwordx4 v[194:195], off
	s_waitcnt vmcnt(8) lgkmcnt(0)
	s_setprio 1
	s_barrier
	v_mfma_f32_16x16x32_bf16 v[60:63], v[108:111], v[198:201], v[60:63]
	v_mfma_f32_16x16x32_bf16 v[56:59], v[116:119], v[198:201], v[56:59]
	v_mfma_f32_16x16x32_bf16 v[36:39], v[108:111], v[206:209], v[36:39]
	v_mfma_f32_16x16x32_bf16 v[44:47], v[116:119], v[206:209], v[44:47]
	v_mfma_f32_16x16x32_bf16 v[20:23], v[108:111], v[214:217], v[20:23]
	v_mfma_f32_16x16x32_bf16 v[28:31], v[116:119], v[214:217], v[28:31]
	v_mfma_f32_16x16x32_bf16 v[4:7], v[108:111], v[222:225], v[4:7]
	v_mfma_f32_16x16x32_bf16 v[12:15], v[116:119], v[222:225], v[12:15]
	v_mfma_f32_16x16x32_bf16 v[60:63], v[112:115], v[202:205], v[60:63]
	v_mfma_f32_16x16x32_bf16 v[56:59], v[120:123], v[202:205], v[56:59]
	v_mfma_f32_16x16x32_bf16 v[36:39], v[112:115], v[210:213], v[36:39]
	v_mfma_f32_16x16x32_bf16 v[44:47], v[120:123], v[210:213], v[44:47]
	v_mfma_f32_16x16x32_bf16 v[20:23], v[112:115], v[218:221], v[20:23]
	v_mfma_f32_16x16x32_bf16 v[28:31], v[120:123], v[218:221], v[28:31]
	v_mfma_f32_16x16x32_bf16 v[4:7], v[112:115], v[226:229], v[4:7]
	v_mfma_f32_16x16x32_bf16 v[12:15], v[120:123], v[226:229], v[12:15]
	v_mfma_f32_16x16x32_bf16 v[48:51], v[178:181], v[198:201], v[48:51]
	v_mfma_f32_16x16x32_bf16 v[52:55], v[186:189], v[198:201], v[52:55]
	v_mfma_f32_16x16x32_bf16 v[40:43], v[178:181], v[206:209], v[40:43]
	v_mfma_f32_16x16x32_bf16 v[32:35], v[186:189], v[206:209], v[32:35]
	v_mfma_f32_16x16x32_bf16 v[24:27], v[178:181], v[214:217], v[24:27]
	v_mfma_f32_16x16x32_bf16 v[16:19], v[186:189], v[214:217], v[16:19]
	v_mfma_f32_16x16x32_bf16 v[8:11], v[178:181], v[222:225], v[8:11]
	v_mfma_f32_16x16x32_bf16 v[0:3], v[186:189], v[222:225], v[0:3]
	v_mfma_f32_16x16x32_bf16 v[48:51], v[182:185], v[202:205], v[48:51]
	v_mfma_f32_16x16x32_bf16 v[52:55], v[190:193], v[202:205], v[52:55]
	v_mfma_f32_16x16x32_bf16 v[40:43], v[182:185], v[210:213], v[40:43]
	v_mfma_f32_16x16x32_bf16 v[32:35], v[190:193], v[210:213], v[32:35]
	v_mfma_f32_16x16x32_bf16 v[24:27], v[182:185], v[218:221], v[24:27]
	v_mfma_f32_16x16x32_bf16 v[16:19], v[190:193], v[218:221], v[16:19]
	v_mfma_f32_16x16x32_bf16 v[8:11], v[182:185], v[226:229], v[8:11]
	v_mfma_f32_16x16x32_bf16 v[0:3], v[190:193], v[226:229], v[0:3]
	s_barrier
; #define PG8_STAGE(bufoff, gbase, voff) do { _Pragma("unroll") for (int _i = 0; _i < 2; ++_i) \
;         __builtin_amdgcn_global_load_lds((const unsigned*)((const char*)(gbase) + (voff)[_i]), (PG8_LAS unsigned*)(lds + (bufoff) + ldsw + _i * 8192), 16, 0, 0); } while (0)
; #define PG8_LDA(dst, b, h) do { _Pragma("unroll") for (int m = 0; m < 4; ++m) _Pragma("unroll") for (int k = 0; k < 2; ++k) dst[m][k] = *(const PG8_LAS bf16x8*)(lds + PG8_SA(b, h) + aoff + m * 2048 + k * 1024); } while (0)
; #define PG8_LDB(dst, b, h) do { _Pragma("unroll") for (int n = 0; n < 2; ++n) _Pragma("unroll") for (int k = 0; k < 2; ++k) dst[n][k] = *(const PG8_LAS bf16x8*)(lds + PG8_SB(b, h) + boff + n * 2048 + k * 1024); } while (0)
; #define PG8_MMA(ai, bj, At, Bt) do { __builtin_amdgcn_s_setprio(1); _Pragma("unroll") for (int m = 0; m < 4; ++m) _Pragma("unroll") for (int n = 0; n < 2; ++n) _Pragma("unroll") for (int k = 0; k < 2; ++k) \
;         acc[ai][bj][m][n] = __builtin_amdgcn_mfma_f32_16x16x32_bf16(Bt[n][k], At[m][k], acc[ai][bj][m][n], 0, 0, 0); __builtin_amdgcn_s_setprio(0); } while (0)
; #define PG8_WAIT_V(n) asm volatile("s_waitcnt vmcnt(" #n ")" ::: "memory")
; #define PG8_WAIT_L(n) asm volatile("s_waitcnt lgkmcnt(" #n ")" ::: "memory")
; #define PG8_BAR __builtin_amdgcn_s_barrier()
; #define PG8_SCHED __builtin_amdgcn_sched_barrier(0)
; template <class Epi, class Sched, bool ALIGN_EPI = false, bool SP2 = false>
; __device__ __forceinline__ void gemm_phase(PG8_LAS unsigned char* lds, const Gemm g, const Sched& S, const Epi& E) {
;     ...
;             PG8_LDB(B0, 1, 0); PG8_LDB(B1, 1, 1); PG8_SCHED; PG8_LDA(At, 1, 0); PG8_STAGE(PG8_SA(0, 1), a2 + hstep, voffA);
;             PG8_WAIT_V(8); PG8_WAIT_L(0); PG8_BAR; PG8_MMA(0, 0, At, B0); PG8_MMA(0, 1, At, B1); PG8_BAR; PG8_SCHED;
;             PG8_LDA(At, 1, 1); PG8_STAGE(PG8_SB(1, 0), b3, voffB); PG8_STAGE(PG8_SB(1, 1), b3 + hstep, voffB); PG8_STAGE(PG8_SA(1, 0), a3, voffA);
;             PG8_WAIT_V(8); PG8_WAIT_L(0); PG8_BAR; PG8_MMA(1, 0, At, B0); PG8_MMA(1, 1, At, B1); PG8_BAR; PG8_SCHED;
;     ...
;         if constexpr (ALIGN_EPI) { if (wr == 0) PG8_BAR; }
	s_setprio 0
	s_add_i32 s67, 0, 0x18000
	s_add_i32 s68, 0, 0x1c000
	v_add_u32_e32 v120, s67, v167
	v_add_u32_e32 v162, s68, v167
	ds_read_b128 v[108:111], v120
	ds_read_b128 v[112:115], v120 offset:1024
	ds_read_b128 v[116:119], v120 offset:2048
	ds_read_b128 v[120:123], v120 offset:3072
	ds_read_b128 v[178:181], v162
	ds_read_b128 v[182:185], v162 offset:1024
	ds_read_b128 v[186:189], v162 offset:2048
	ds_read_b128 v[190:193], v162 offset:3072
	s_add_u32 s44, s44, 0x80000
	s_addc_u32 s45, s45, 0
	s_add_u32 s42, s42, 0x80080
	s_addc_u32 s43, s43, 0
	s_mov_b32 m0, s52
	ds_read_b128 v[198:201], v177 offset:32768
	ds_read_b128 v[202:205], v177 offset:33792
	ds_read_b128 v[206:209], v177 offset:34816
	ds_read_b128 v[210:213], v177 offset:35840
	ds_read_b128 v[214:217], v177 offset:36864
	ds_read_b128 v[218:221], v177 offset:37888
	ds_read_b128 v[222:225], v177 offset:38912
	ds_read_b128 v[226:229], v177 offset:39936
	global_load_lds_dwordx4 v144, s[44:45]
	s_mov_b32 m0, s53
	s_nop 0
	global_load_lds_dwordx4 v146, s[44:45]
	s_waitcnt vmcnt(8) lgkmcnt(0)
	s_setprio 1
	s_barrier
	v_mfma_f32_16x16x32_bf16 v[140:143], v[108:111], v[198:201], v[140:143]
	v_mfma_f32_16x16x32_bf16 v[136:139], v[116:119], v[198:201], v[136:139]
	v_mfma_f32_16x16x32_bf16 v[100:103], v[108:111], v[206:209], v[100:103]
	v_mfma_f32_16x16x32_bf16 v[124:127], v[116:119], v[206:209], v[124:127]
	v_mfma_f32_16x16x32_bf16 v[84:87], v[108:111], v[214:217], v[84:87]
	v_mfma_f32_16x16x32_bf16 v[92:95], v[116:119], v[214:217], v[92:95]
	v_mfma_f32_16x16x32_bf16 v[68:71], v[108:111], v[222:225], v[68:71]
	v_mfma_f32_16x16x32_bf16 v[76:79], v[116:119], v[222:225], v[76:79]
	v_mfma_f32_16x16x32_bf16 v[140:143], v[112:115], v[202:205], v[140:143]
	v_mfma_f32_16x16x32_bf16 v[136:139], v[120:123], v[202:205], v[136:139]
	v_mfma_f32_16x16x32_bf16 v[100:103], v[112:115], v[210:213], v[100:103]
	v_mfma_f32_16x16x32_bf16 v[124:127], v[120:123], v[210:213], v[124:127]
	v_mfma_f32_16x16x32_bf16 v[84:87], v[112:115], v[218:221], v[84:87]
	v_mfma_f32_16x16x32_bf16 v[92:95], v[120:123], v[218:221], v[92:95]
	v_mfma_f32_16x16x32_bf16 v[68:71], v[112:115], v[226:229], v[68:71]
	v_mfma_f32_16x16x32_bf16 v[76:79], v[120:123], v[226:229], v[76:79]
	v_mfma_f32_16x16x32_bf16 v[128:131], v[178:181], v[198:201], v[128:131]
	v_mfma_f32_16x16x32_bf16 v[132:135], v[186:189], v[198:201], v[132:135]
	v_mfma_f32_16x16x32_bf16 v[104:107], v[178:181], v[206:209], v[104:107]
	v_mfma_f32_16x16x32_bf16 v[96:99], v[186:189], v[206:209], v[96:99]
	v_mfma_f32_16x16x32_bf16 v[88:91], v[178:181], v[214:217], v[88:91]
	v_mfma_f32_16x16x32_bf16 v[80:83], v[186:189], v[214:217], v[80:83]
	v_mfma_f32_16x16x32_bf16 v[72:75], v[178:181], v[222:225], v[72:75]
	v_mfma_f32_16x16x32_bf16 v[64:67], v[186:189], v[222:225], v[64:67]
	v_mfma_f32_16x16x32_bf16 v[128:131], v[182:185], v[202:205], v[128:131]
	v_mfma_f32_16x16x32_bf16 v[132:135], v[190:193], v[202:205], v[132:135]
	v_mfma_f32_16x16x32_bf16 v[104:107], v[182:185], v[210:213], v[104:107]
	v_mfma_f32_16x16x32_bf16 v[96:99], v[190:193], v[210:213], v[96:99]
	v_mfma_f32_16x16x32_bf16 v[88:91], v[182:185], v[218:221], v[88:91]
	v_mfma_f32_16x16x32_bf16 v[80:83], v[190:193], v[218:221], v[80:83]
	v_mfma_f32_16x16x32_bf16 v[72:75], v[182:185], v[226:229], v[72:75]
	v_mfma_f32_16x16x32_bf16 v[64:67], v[190:193], v[226:229], v[64:67]
	s_barrier
	s_setprio 0
	v_lshl_add_u64 v[160:161], v[160:161], 0, s[16:17]
	s_mov_b32 m0, s100
	ds_read_b128 v[198:201], v177 offset:49152
	ds_read_b128 v[202:205], v177 offset:50176
	ds_read_b128 v[206:209], v177 offset:51200
	ds_read_b128 v[210:213], v177 offset:52224
	ds_read_b128 v[214:217], v177 offset:53248
	ds_read_b128 v[218:221], v177 offset:54272
	ds_read_b128 v[222:225], v177 offset:55296
	ds_read_b128 v[226:229], v177 offset:56320
	global_load_lds_dwordx4 v[160:161], off
	s_add_i32 m0, s100, 0x2000
	v_lshl_add_u64 v[160:161], v[164:165], 0, s[16:17]
	global_load_lds_dwordx4 v[160:161], off
	s_mov_b32 m0, s101
	s_nop 0
	global_load_lds_dwordx4 v144, s[42:43]
	s_add_i32 m0, s101, 0x2000
	v_lshl_add_u64 v[160:161], s[42:43], 0, v[146:147]
	global_load_lds_dwordx4 v[160:161], off
	s_mov_b32 m0, s55
	v_lshl_add_u64 v[160:161], v[170:171], 0, s[16:17]
	global_load_lds_dwordx4 v[160:161], off
	s_mov_b32 m0, s56
	v_lshl_add_u64 v[160:161], v[194:195], 0, s[16:17]
	global_load_lds_dwordx4 v[160:161], off
	s_waitcnt vmcnt(8) lgkmcnt(0)
	s_setprio 1
	s_barrier
	v_mfma_f32_16x16x32_bf16 v[60:63], v[108:111], v[198:201], v[60:63]
	v_mfma_f32_16x16x32_bf16 v[56:59], v[116:119], v[198:201], v[56:59]
	v_mfma_f32_16x16x32_bf16 v[36:39], v[108:111], v[206:209], v[36:39]
	v_mfma_f32_16x16x32_bf16 v[44:47], v[116:119], v[206:209], v[44:47]
	v_mfma_f32_16x16x32_bf16 v[20:23], v[108:111], v[214:217], v[20:23]
	v_mfma_f32_16x16x32_bf16 v[28:31], v[116:119], v[214:217], v[28:31]
	v_mfma_f32_16x16x32_bf16 v[4:7], v[108:111], v[222:225], v[4:7]
	v_mfma_f32_16x16x32_bf16 v[12:15], v[116:119], v[222:225], v[12:15]
	v_mfma_f32_16x16x32_bf16 v[60:63], v[112:115], v[202:205], v[60:63]
	v_mfma_f32_16x16x32_bf16 v[56:59], v[120:123], v[202:205], v[56:59]
	v_mfma_f32_16x16x32_bf16 v[36:39], v[112:115], v[210:213], v[36:39]
	v_mfma_f32_16x16x32_bf16 v[44:47], v[120:123], v[210:213], v[44:47]
	v_mfma_f32_16x16x32_bf16 v[20:23], v[112:115], v[218:221], v[20:23]
	v_mfma_f32_16x16x32_bf16 v[28:31], v[120:123], v[218:221], v[28:31]
	v_mfma_f32_16x16x32_bf16 v[4:7], v[112:115], v[226:229], v[4:7]
	v_mfma_f32_16x16x32_bf16 v[12:15], v[120:123], v[226:229], v[12:15]
	v_mfma_f32_16x16x32_bf16 v[48:51], v[178:181], v[198:201], v[48:51]
	v_mfma_f32_16x16x32_bf16 v[52:55], v[186:189], v[198:201], v[52:55]
	v_mfma_f32_16x16x32_bf16 v[40:43], v[178:181], v[206:209], v[40:43]
	v_mfma_f32_16x16x32_bf16 v[32:35], v[186:189], v[206:209], v[32:35]
	v_mfma_f32_16x16x32_bf16 v[24:27], v[178:181], v[214:217], v[24:27]
	v_mfma_f32_16x16x32_bf16 v[16:19], v[186:189], v[214:217], v[16:19]
	v_mfma_f32_16x16x32_bf16 v[8:11], v[178:181], v[222:225], v[8:11]
	v_mfma_f32_16x16x32_bf16 v[0:3], v[186:189], v[222:225], v[0:3]
	v_mfma_f32_16x16x32_bf16 v[48:51], v[182:185], v[202:205], v[48:51]
	v_mfma_f32_16x16x32_bf16 v[52:55], v[190:193], v[202:205], v[52:55]
	v_mfma_f32_16x16x32_bf16 v[40:43], v[182:185], v[210:213], v[40:43]
	v_mfma_f32_16x16x32_bf16 v[32:35], v[190:193], v[210:213], v[32:35]
	v_mfma_f32_16x16x32_bf16 v[24:27], v[182:185], v[218:221], v[24:27]
	v_mfma_f32_16x16x32_bf16 v[16:19], v[190:193], v[218:221], v[16:19]
	v_mfma_f32_16x16x32_bf16 v[8:11], v[182:185], v[226:229], v[8:11]
	v_mfma_f32_16x16x32_bf16 v[0:3], v[190:193], v[226:229], v[0:3]
	s_barrier
	s_setprio 0
	s_add_i32 s66, s66, 2
	s_add_u32 s8, s8, 0x100
	s_addc_u32 s9, s9, 0
	s_add_u32 s48, s48, 0x100
	s_addc_u32 s49, s49, 0
	s_cmp_gt_u32 s66, 29
	s_cbranch_scc0 .LBB0_1373
	s_and_b64 vcc, exec, s[18:19]
	s_cbranch_vccz .LBB0_1376
	s_barrier

; #define PG8_STAGE(bufoff, gbase, voff) do { _Pragma("unroll") for (int _i = 0; _i < 2; ++_i) \
;         __builtin_amdgcn_global_load_lds((const unsigned*)((const char*)(gbase) + (voff)[_i]), (PG8_LAS unsigned*)(lds + (bufoff) + ldsw + _i * 8192), 16, 0, 0); } while (0)
; #define PG8_LDA(dst, b, h) do { _Pragma("unroll") for (int m = 0; m < 4; ++m) _Pragma("unroll") for (int k = 0; k < 2; ++k) dst[m][k] = *(const PG8_LAS bf16x8*)(lds + PG8_SA(b, h) + aoff + m * 2048 + k * 1024); } while (0)
; #define PG8_LDB(dst, b, h) do { _Pragma("unroll") for (int n = 0; n < 2; ++n) _Pragma("unroll") for (int k = 0; k < 2; ++k) dst[n][k] = *(const PG8_LAS bf16x8*)(lds + PG8_SB(b, h) + boff + n * 2048 + k * 1024); } while (0)
; #define PG8_MMA(ai, bj, At, Bt) do { __builtin_amdgcn_s_setprio(1); _Pragma("unroll") for (int m = 0; m < 4; ++m) _Pragma("unroll") for (int n = 0; n < 2; ++n) _Pragma("unroll") for (int k = 0; k < 2; ++k) \
;         acc[ai][bj][m][n] = __builtin_amdgcn_mfma_f32_16x16x32_bf16(Bt[n][k], At[m][k], acc[ai][bj][m][n], 0, 0, 0); __builtin_amdgcn_s_setprio(0); } while (0)
; #define PG8_BAR __builtin_amdgcn_s_barrier()
; template <class Epi, class Sched, bool ALIGN_EPI = false, bool SP2 = false>
; __device__ __forceinline__ void gemm_phase(PG8_LAS unsigned char* lds, const Gemm g, const Sched& S, const Epi& E) {
;     ...
;         const bool has_next = S.next(ui + 1, nxt);
;         const char* nA = has_next ? (const char*)g.A + (size_t)nxt.pm * tstep : cA; const char* nB = has_next ? (const char*)g.Bt + (size_t)nxt.pn * tstep : cB;
;         for (int t = 0; t < nt; t += 2) {
;             const bool last = (t == nt - 2);
;             const char* a1 = cA + (size_t)(t + 1) * kstep;
;             const char* a2 = last ? nA : cA + (size_t)(t + 2) * kstep; const char* b2 = last ? nB : cB + (size_t)(t + 2) * kstep;
;             const char* a3 = a2 + kstep; const char* b3 = b2 + kstep;
;             if (last && has_next) S.a_ready(nxt);
;             if constexpr (SP2) {
;             PG8_LDB(B0, 0, 0); PG8_LDB(B1, 0, 1); PG8_SCHED; PG8_LDA(At, 0, 0); PG8_STAGE(PG8_SA(1, 1), a1 + hstep, voffA);
;             PG8_WAIT_V(8); PG8_WAIT_L(0); PG8_BAR; PG8_MMA(0, 0, At, B0); PG8_MMA(0, 1, At, B1); PG8_BAR; PG8_SCHED;
;             PG8_LDA(At, 0, 1); PG8_STAGE(PG8_SB(0, 0), b2, voffB); PG8_STAGE(PG8_SB(0, 1), b2 + hstep, voffB); PG8_STAGE(PG8_SA(0, 0), a2, voffA);
.LBB0_1548:
	s_ashr_i32 s13, s12, 31
	s_lshl_b64 s[14:15], s[12:13], 20
	s_add_u32 s14, s60, s14
	s_addc_u32 s15, s61, s15
	s_and_b64 s[16:17], s[0:1], exec
	s_cselect_b32 s13, s15, s21
	s_cselect_b32 s39, s14, s20
	s_ashr_i32 s11, s10, 31
	s_lshl_b64 s[16:17], s[10:11], 20
	s_add_u32 s16, s72, s16
	s_addc_u32 s17, s73, s17
	s_and_b64 s[24:25], s[0:1], exec
	s_cselect_b32 s11, s17, s23
	s_cselect_b32 s40, s16, s22
	s_add_u32 s20, s20, 0x80080
	s_addc_u32 s21, s21, 0
	s_add_u32 s41, s22, 0x100
	s_addc_u32 s42, s23, 0
	s_mov_b32 s43, -2
	s_add_i32 s98, s27, 0x10000
	s_add_i32 s99, s27, 0x14000
	s_add_i32 s100, s27, 0x18000
	s_add_i32 s101, s27, 0x1c000
	ds_read_b128 v[144:147], v155
	ds_read_b128 v[148:151], v155 offset:1024
	ds_read_b128 v[158:161], v155 offset:2048
	ds_read_b128 v[162:165], v155 offset:3072
	ds_read_b128 v[166:169], v156
	ds_read_b128 v[170:173], v156 offset:1024
	ds_read_b128 v[174:177], v156 offset:2048
	ds_read_b128 v[178:181], v156 offset:3072
	s_add_u32 s22, s20, 0xfff80080
	s_addc_u32 s23, s21, -1
	s_cmp_eq_u32 s43, 28
	s_cselect_b32 s25, s13, s23
	s_cselect_b32 s24, s39, s22
	s_cselect_b32 s23, s11, s42
	s_cselect_b32 s22, s40, s41
	s_add_u32 s44, s22, 0x80000
	s_addc_u32 s45, s23, 0
	s_add_i32 m0, s19, 0xc000
	ds_read_b128 v[182:185], v157
	ds_read_b128 v[186:189], v157 offset:1024
	ds_read_b128 v[190:193], v157 offset:2048
	ds_read_b128 v[194:197], v157 offset:3072
	ds_read_b128 v[198:201], v157 offset:4096
	ds_read_b128 v[202:205], v157 offset:5120
	ds_read_b128 v[206:209], v157 offset:6144
	ds_read_b128 v[210:213], v157 offset:7168
	global_load_lds_dwordx4 v136, s[20:21]
	s_add_i32 m0, s19, 0xe000
	s_nop 0
	global_load_lds_dwordx4 v138, s[20:21]
	s_waitcnt lgkmcnt(0)
	s_setprio 1
	s_barrier
	v_mfma_f32_16x16x32_bf16 v[124:127], v[144:147], v[182:185], 0
	v_mfma_f32_16x16x32_bf16 v[120:123], v[158:161], v[182:185], 0
	v_mfma_f32_16x16x32_bf16 v[108:111], v[144:147], v[190:193], 0
	v_mfma_f32_16x16x32_bf16 v[104:107], v[158:161], v[190:193], 0
	v_mfma_f32_16x16x32_bf16 v[88:91], v[144:147], v[198:201], 0
	v_mfma_f32_16x16x32_bf16 v[92:95], v[158:161], v[198:201], 0
	v_mfma_f32_16x16x32_bf16 v[72:75], v[144:147], v[206:209], 0
	v_mfma_f32_16x16x32_bf16 v[76:79], v[158:161], v[206:209], 0
	v_mfma_f32_16x16x32_bf16 v[124:127], v[148:151], v[186:189], v[124:127]
	v_mfma_f32_16x16x32_bf16 v[120:123], v[162:165], v[186:189], v[120:123]
	v_mfma_f32_16x16x32_bf16 v[108:111], v[148:151], v[194:197], v[108:111]
	v_mfma_f32_16x16x32_bf16 v[104:107], v[162:165], v[194:197], v[104:107]
	v_mfma_f32_16x16x32_bf16 v[88:91], v[148:151], v[202:205], v[88:91]
	v_mfma_f32_16x16x32_bf16 v[92:95], v[162:165], v[202:205], v[92:95]
	v_mfma_f32_16x16x32_bf16 v[72:75], v[148:151], v[210:213], v[72:75]
	v_mfma_f32_16x16x32_bf16 v[76:79], v[162:165], v[210:213], v[76:79]
	v_mfma_f32_16x16x32_bf16 v[116:119], v[166:169], v[182:185], 0
	v_mfma_f32_16x16x32_bf16 v[112:115], v[174:177], v[182:185], 0
	v_mfma_f32_16x16x32_bf16 v[96:99], v[166:169], v[190:193], 0
	v_mfma_f32_16x16x32_bf16 v[100:103], v[174:177], v[190:193], 0
	v_mfma_f32_16x16x32_bf16 v[80:83], v[166:169], v[198:201], 0
	v_mfma_f32_16x16x32_bf16 v[84:87], v[174:177], v[198:201], 0
	v_mfma_f32_16x16x32_bf16 v[64:67], v[166:169], v[206:209], 0
	v_mfma_f32_16x16x32_bf16 v[68:71], v[174:177], v[206:209], 0
	v_mfma_f32_16x16x32_bf16 v[116:119], v[170:173], v[186:189], v[116:119]
	v_mfma_f32_16x16x32_bf16 v[112:115], v[178:181], v[186:189], v[112:115]
	v_mfma_f32_16x16x32_bf16 v[96:99], v[170:173], v[194:197], v[96:99]
	v_mfma_f32_16x16x32_bf16 v[100:103], v[178:181], v[194:197], v[100:103]
	v_mfma_f32_16x16x32_bf16 v[80:83], v[170:173], v[202:205], v[80:83]
	v_mfma_f32_16x16x32_bf16 v[84:87], v[178:181], v[202:205], v[84:87]
	v_mfma_f32_16x16x32_bf16 v[64:67], v[170:173], v[210:213], v[64:67]
	v_mfma_f32_16x16x32_bf16 v[68:71], v[178:181], v[210:213], v[68:71]
	s_barrier
	s_setprio 0
	v_lshl_add_u64 v[214:215], s[22:23], 0, v[130:131]
	s_mov_b32 m0, s98
	ds_read_b128 v[182:185], v157 offset:16384
	ds_read_b128 v[186:189], v157 offset:17408
	ds_read_b128 v[190:193], v157 offset:18432
	ds_read_b128 v[194:197], v157 offset:19456
	ds_read_b128 v[198:201], v157 offset:20480
	ds_read_b128 v[202:205], v157 offset:21504
	ds_read_b128 v[206:209], v157 offset:22528
	ds_read_b128 v[210:213], v157 offset:23552
	global_load_lds_dwordx4 v[214:215], off
	s_add_i32 m0, s98, 0x2000
	v_lshl_add_u64 v[216:217], s[22:23], 0, v[134:135]
	global_load_lds_dwordx4 v[216:217], off
	s_mov_b32 m0, s99
	v_lshl_add_u64 v[220:221], s[24:25], 0, v[132:133]
	global_load_lds_dwordx4 v130, s[44:45]
	s_add_i32 m0, s99, 0x2000
	s_nop 0
	global_load_lds_dwordx4 v134, s[44:45]
	s_mov_b32 m0, s19
	v_lshl_add_u64 v[218:219], s[24:25], 0, v[128:129]
	global_load_lds_dwordx4 v[218:219], off
	s_mov_b32 m0, s28
	s_nop 0
	global_load_lds_dwordx4 v[220:221], off
	s_waitcnt lgkmcnt(0)
	s_setprio 1
	s_barrier
; #define PG8_STAGE(bufoff, gbase, voff) do { _Pragma("unroll") for (int _i = 0; _i < 2; ++_i) \
;         __builtin_amdgcn_global_load_lds((const unsigned*)((const char*)(gbase) + (voff)[_i]), (PG8_LAS unsigned*)(lds + (bufoff) + ldsw + _i * 8192), 16, 0, 0); } while (0)
; #define PG8_LDA(dst, b, h) do { _Pragma("unroll") for (int m = 0; m < 4; ++m) _Pragma("unroll") for (int k = 0; k < 2; ++k) dst[m][k] = *(const PG8_LAS bf16x8*)(lds + PG8_SA(b, h) + aoff + m * 2048 + k * 1024); } while (0)
; #define PG8_LDB(dst, b, h) do { _Pragma("unroll") for (int n = 0; n < 2; ++n) _Pragma("unroll") for (int k = 0; k < 2; ++k) dst[n][k] = *(const PG8_LAS bf16x8*)(lds + PG8_SB(b, h) + boff + n * 2048 + k * 1024); } while (0)
; #define PG8_MMA(ai, bj, At, Bt) do { __builtin_amdgcn_s_setprio(1); _Pragma("unroll") for (int m = 0; m < 4; ++m) _Pragma("unroll") for (int n = 0; n < 2; ++n) _Pragma("unroll") for (int k = 0; k < 2; ++k) \
;         acc[ai][bj][m][n] = __builtin_amdgcn_mfma_f32_16x16x32_bf16(Bt[n][k], At[m][k], acc[ai][bj][m][n], 0, 0, 0); __builtin_amdgcn_s_setprio(0); } while (0)
; #define PG8_WAIT_V(n) asm volatile("s_waitcnt vmcnt(" #n ")" ::: "memory")
; #define PG8_WAIT_L(n) asm volatile("s_waitcnt lgkmcnt(" #n ")" ::: "memory")
; #define PG8_BAR __builtin_amdgcn_s_barrier()
; #define PG8_SCHED __builtin_amdgcn_sched_barrier(0)
; template <class Epi, class Sched, bool ALIGN_EPI = false, bool SP2 = false>
; __device__ __forceinline__ void gemm_phase(PG8_LAS unsigned char* lds, const Gemm g, const Sched& S, const Epi& E) {
;     ...
;             PG8_WAIT_V(8); PG8_WAIT_L(0); PG8_BAR; PG8_MMA(1, 0, At, B0); PG8_MMA(1, 1, At, B1); PG8_BAR; PG8_SCHED;
;             PG8_LDB(B0, 1, 0); PG8_LDB(B1, 1, 1); PG8_SCHED; PG8_LDA(At, 1, 0); PG8_STAGE(PG8_SA(0, 1), a2 + hstep, voffA);
;             PG8_WAIT_V(8); PG8_WAIT_L(0); PG8_BAR; PG8_MMA(0, 0, At, B0); PG8_MMA(0, 1, At, B1); PG8_BAR; PG8_SCHED;
	v_mfma_f32_16x16x32_bf16 v[56:59], v[144:147], v[182:185], 0
	v_mfma_f32_16x16x32_bf16 v[60:63], v[158:161], v[182:185], 0
	v_mfma_f32_16x16x32_bf16 v[40:43], v[144:147], v[190:193], 0
	v_mfma_f32_16x16x32_bf16 v[44:47], v[158:161], v[190:193], 0
	v_mfma_f32_16x16x32_bf16 v[24:27], v[144:147], v[198:201], 0
	v_mfma_f32_16x16x32_bf16 v[28:31], v[158:161], v[198:201], 0
	v_mfma_f32_16x16x32_bf16 v[8:11], v[144:147], v[206:209], 0
	v_mfma_f32_16x16x32_bf16 v[12:15], v[158:161], v[206:209], 0
	v_mfma_f32_16x16x32_bf16 v[56:59], v[148:151], v[186:189], v[56:59]
	v_mfma_f32_16x16x32_bf16 v[60:63], v[162:165], v[186:189], v[60:63]
	v_mfma_f32_16x16x32_bf16 v[40:43], v[148:151], v[194:197], v[40:43]
	v_mfma_f32_16x16x32_bf16 v[44:47], v[162:165], v[194:197], v[44:47]
	v_mfma_f32_16x16x32_bf16 v[24:27], v[148:151], v[202:205], v[24:27]
	v_mfma_f32_16x16x32_bf16 v[28:31], v[162:165], v[202:205], v[28:31]
	v_mfma_f32_16x16x32_bf16 v[8:11], v[148:151], v[210:213], v[8:11]
	v_mfma_f32_16x16x32_bf16 v[12:15], v[162:165], v[210:213], v[12:15]
	v_mfma_f32_16x16x32_bf16 v[48:51], v[166:169], v[182:185], 0
	v_mfma_f32_16x16x32_bf16 v[52:55], v[174:177], v[182:185], 0
	v_mfma_f32_16x16x32_bf16 v[32:35], v[166:169], v[190:193], 0
	v_mfma_f32_16x16x32_bf16 v[36:39], v[174:177], v[190:193], 0
	v_mfma_f32_16x16x32_bf16 v[16:19], v[166:169], v[198:201], 0
	v_mfma_f32_16x16x32_bf16 v[20:23], v[174:177], v[198:201], 0
	v_mfma_f32_16x16x32_bf16 v[0:3], v[166:169], v[206:209], 0
	v_mfma_f32_16x16x32_bf16 v[4:7], v[174:177], v[206:209], 0
	v_mfma_f32_16x16x32_bf16 v[48:51], v[170:173], v[186:189], v[48:51]
	v_mfma_f32_16x16x32_bf16 v[52:55], v[178:181], v[186:189], v[52:55]
	v_mfma_f32_16x16x32_bf16 v[32:35], v[170:173], v[194:197], v[32:35]
	v_mfma_f32_16x16x32_bf16 v[36:39], v[178:181], v[194:197], v[36:39]
	v_mfma_f32_16x16x32_bf16 v[16:19], v[170:173], v[202:205], v[16:19]
	v_mfma_f32_16x16x32_bf16 v[20:23], v[178:181], v[202:205], v[20:23]
	v_mfma_f32_16x16x32_bf16 v[0:3], v[170:173], v[210:213], v[0:3]
	v_mfma_f32_16x16x32_bf16 v[4:7], v[178:181], v[210:213], v[4:7]
	s_barrier
	s_setprio 0
	s_add_i32 s44, 0, 0x18000
	s_add_i32 s45, 0, 0x1c000
	v_add_u32_e32 v162, s44, v153
	v_add_u32_e32 v178, s45, v153
	ds_read_b128 v[144:147], v162
	ds_read_b128 v[148:151], v162 offset:1024
	ds_read_b128 v[158:161], v162 offset:2048
	ds_read_b128 v[162:165], v162 offset:3072
	ds_read_b128 v[166:169], v178
	ds_read_b128 v[170:173], v178 offset:1024
	ds_read_b128 v[174:177], v178 offset:2048
	ds_read_b128 v[178:181], v178 offset:3072
	s_add_u32 s24, s24, 0x80000
	s_addc_u32 s25, s25, 0
	s_add_u32 s22, s22, 0x80080
	s_addc_u32 s23, s23, 0
	s_mov_b32 m0, s29
	ds_read_b128 v[182:185], v157 offset:32768
	ds_read_b128 v[186:189], v157 offset:33792
	ds_read_b128 v[190:193], v157 offset:34816
	ds_read_b128 v[194:197], v157 offset:35840
	ds_read_b128 v[198:201], v157 offset:36864
	ds_read_b128 v[202:205], v157 offset:37888
	ds_read_b128 v[206:209], v157 offset:38912
	ds_read_b128 v[210:213], v157 offset:39936
	global_load_lds_dwordx4 v128, s[24:25]
	s_mov_b32 m0, s30
	v_lshl_add_u64 v[222:223], s[24:25], 0, v[132:133]
	global_load_lds_dwordx4 v[222:223], off
	s_waitcnt vmcnt(8) lgkmcnt(0)
	s_setprio 1
	s_barrier
	v_mfma_f32_16x16x32_bf16 v[124:127], v[144:147], v[182:185], v[124:127]
	v_mfma_f32_16x16x32_bf16 v[120:123], v[158:161], v[182:185], v[120:123]
	v_mfma_f32_16x16x32_bf16 v[108:111], v[144:147], v[190:193], v[108:111]
	v_mfma_f32_16x16x32_bf16 v[104:107], v[158:161], v[190:193], v[104:107]
	v_mfma_f32_16x16x32_bf16 v[88:91], v[144:147], v[198:201], v[88:91]
	v_mfma_f32_16x16x32_bf16 v[92:95], v[158:161], v[198:201], v[92:95]
	v_mfma_f32_16x16x32_bf16 v[72:75], v[144:147], v[206:209], v[72:75]
	v_mfma_f32_16x16x32_bf16 v[76:79], v[158:161], v[206:209], v[76:79]
	v_mfma_f32_16x16x32_bf16 v[124:127], v[148:151], v[186:189], v[124:127]
	v_mfma_f32_16x16x32_bf16 v[120:123], v[162:165], v[186:189], v[120:123]
	v_mfma_f32_16x16x32_bf16 v[108:111], v[148:151], v[194:197], v[108:111]
	v_mfma_f32_16x16x32_bf16 v[104:107], v[162:165], v[194:197], v[104:107]
	v_mfma_f32_16x16x32_bf16 v[88:91], v[148:151], v[202:205], v[88:91]
	v_mfma_f32_16x16x32_bf16 v[92:95], v[162:165], v[202:205], v[92:95]
	v_mfma_f32_16x16x32_bf16 v[72:75], v[148:151], v[210:213], v[72:75]
	v_mfma_f32_16x16x32_bf16 v[76:79], v[162:165], v[210:213], v[76:79]
	v_mfma_f32_16x16x32_bf16 v[116:119], v[166:169], v[182:185], v[116:119]
	v_mfma_f32_16x16x32_bf16 v[112:115], v[174:177], v[182:185], v[112:115]
	v_mfma_f32_16x16x32_bf16 v[96:99], v[166:169], v[190:193], v[96:99]
	v_mfma_f32_16x16x32_bf16 v[100:103], v[174:177], v[190:193], v[100:103]
	v_mfma_f32_16x16x32_bf16 v[80:83], v[166:169], v[198:201], v[80:83]
	v_mfma_f32_16x16x32_bf16 v[84:87], v[174:177], v[198:201], v[84:87]
	v_mfma_f32_16x16x32_bf16 v[64:67], v[166:169], v[206:209], v[64:67]
	v_mfma_f32_16x16x32_bf16 v[68:71], v[174:177], v[206:209], v[68:71]
	v_mfma_f32_16x16x32_bf16 v[116:119], v[170:173], v[186:189], v[116:119]
	v_mfma_f32_16x16x32_bf16 v[112:115], v[178:181], v[186:189], v[112:115]
	v_mfma_f32_16x16x32_bf16 v[96:99], v[170:173], v[194:197], v[96:99]
	v_mfma_f32_16x16x32_bf16 v[100:103], v[178:181], v[194:197], v[100:103]
	v_mfma_f32_16x16x32_bf16 v[80:83], v[170:173], v[202:205], v[80:83]
	v_mfma_f32_16x16x32_bf16 v[84:87], v[178:181], v[202:205], v[84:87]
	v_mfma_f32_16x16x32_bf16 v[64:67], v[170:173], v[210:213], v[64:67]
	v_mfma_f32_16x16x32_bf16 v[68:71], v[178:181], v[210:213], v[68:71]
	s_barrier
; #define PG8_STAGE(bufoff, gbase, voff) do { _Pragma("unroll") for (int _i = 0; _i < 2; ++_i) \
;         __builtin_amdgcn_global_load_lds((const unsigned*)((const char*)(gbase) + (voff)[_i]), (PG8_LAS unsigned*)(lds + (bufoff) + ldsw + _i * 8192), 16, 0, 0); } while (0)
; #define PG8_LDA(dst, b, h) do { _Pragma("unroll") for (int m = 0; m < 4; ++m) _Pragma("unroll") for (int k = 0; k < 2; ++k) dst[m][k] = *(const PG8_LAS bf16x8*)(lds + PG8_SA(b, h) + aoff + m * 2048 + k * 1024); } while (0)
; #define PG8_LDB(dst, b, h) do { _Pragma("unroll") for (int n = 0; n < 2; ++n) _Pragma("unroll") for (int k = 0; k < 2; ++k) dst[n][k] = *(const PG8_LAS bf16x8*)(lds + PG8_SB(b, h) + boff + n * 2048 + k * 1024); } while (0)
; #define PG8_MMA(ai, bj, At, Bt) do { __builtin_amdgcn_s_setprio(1); _Pragma("unroll") for (int m = 0; m < 4; ++m) _Pragma("unroll") for (int n = 0; n < 2; ++n) _Pragma("unroll") for (int k = 0; k < 2; ++k) \
;         acc[ai][bj][m][n] = __builtin_amdgcn_mfma_f32_16x16x32_bf16(Bt[n][k], At[m][k], acc[ai][bj][m][n], 0, 0, 0); __builtin_amdgcn_s_setprio(0); } while (0)
; #define PG8_WAIT_V(n) asm volatile("s_waitcnt vmcnt(" #n ")" ::: "memory")
; template <class Epi, class Sched, bool ALIGN_EPI = false, bool SP2 = false>
; __device__ __forceinline__ void gemm_phase(PG8_LAS unsigned char* lds, const Gemm g, const Sched& S, const Epi& E) {
;     ...
;             PG8_LDB(B0, 0, 0); PG8_LDB(B1, 0, 1); PG8_SCHED; PG8_LDA(At, 0, 0); PG8_STAGE(PG8_SA(1, 1), a1 + hstep, voffA);
;             PG8_WAIT_V(8); PG8_WAIT_L(0); PG8_BAR; PG8_MMA(0, 0, At, B0); PG8_MMA(0, 1, At, B1); PG8_BAR; PG8_SCHED;
;             PG8_LDA(At, 0, 1); PG8_STAGE(PG8_SB(0, 0), b2, voffB); PG8_STAGE(PG8_SB(0, 1), b2 + hstep, voffB); PG8_STAGE(PG8_SA(0, 0), a2, voffA);
;             PG8_WAIT_V(8); PG8_WAIT_L(0); PG8_BAR; PG8_MMA(1, 0, At, B0); PG8_MMA(1, 1, At, B1); PG8_BAR; PG8_SCHED;
;             PG8_LDB(B0, 1, 0); PG8_LDB(B1, 1, 1); PG8_SCHED; PG8_LDA(At, 1, 0); PG8_STAGE(PG8_SA(0, 1), a2 + hstep, voffA);
;             PG8_WAIT_V(8); PG8_WAIT_L(0); PG8_BAR; PG8_MMA(0, 0, At, B0); PG8_MMA(0, 1, At, B1); PG8_BAR; PG8_SCHED;
;             PG8_LDA(At, 1, 1); PG8_STAGE(PG8_SB(1, 0), b3, voffB); PG8_STAGE(PG8_SB(1, 1), b3 + hstep, voffB); PG8_STAGE(PG8_SA(1, 0), a3, voffA);
;             PG8_WAIT_V(8); PG8_WAIT_L(0); PG8_BAR; PG8_MMA(1, 0, At, B0); PG8_MMA(1, 1, At, B1); PG8_BAR; PG8_SCHED;
	s_setprio 0
	v_lshl_add_u64 v[214:215], v[214:215], 0, s[4:5]
	s_mov_b32 m0, s100
	ds_read_b128 v[182:185], v157 offset:49152
	ds_read_b128 v[186:189], v157 offset:50176
	ds_read_b128 v[190:193], v157 offset:51200
	ds_read_b128 v[194:197], v157 offset:52224
	ds_read_b128 v[198:201], v157 offset:53248
	ds_read_b128 v[202:205], v157 offset:54272
	ds_read_b128 v[206:209], v157 offset:55296
	ds_read_b128 v[210:213], v157 offset:56320
	global_load_lds_dwordx4 v[214:215], off
	s_add_i32 m0, s100, 0x2000
	v_lshl_add_u64 v[214:215], v[216:217], 0, s[4:5]
	global_load_lds_dwordx4 v[214:215], off
	s_mov_b32 m0, s101
	s_nop 0
	global_load_lds_dwordx4 v130, s[22:23]
	s_add_i32 m0, s101, 0x2000
	v_lshl_add_u64 v[214:215], s[22:23], 0, v[134:135]
	global_load_lds_dwordx4 v[214:215], off
	s_mov_b32 m0, s33
	v_lshl_add_u64 v[214:215], v[218:219], 0, s[4:5]
	global_load_lds_dwordx4 v[214:215], off
	s_mov_b32 m0, s34
	v_lshl_add_u64 v[214:215], v[220:221], 0, s[4:5]
	global_load_lds_dwordx4 v[214:215], off
	s_waitcnt vmcnt(8) lgkmcnt(0)
	s_setprio 1
	s_barrier
	v_mfma_f32_16x16x32_bf16 v[56:59], v[144:147], v[182:185], v[56:59]
	v_mfma_f32_16x16x32_bf16 v[60:63], v[158:161], v[182:185], v[60:63]
	v_mfma_f32_16x16x32_bf16 v[40:43], v[144:147], v[190:193], v[40:43]
	v_mfma_f32_16x16x32_bf16 v[44:47], v[158:161], v[190:193], v[44:47]
	v_mfma_f32_16x16x32_bf16 v[24:27], v[144:147], v[198:201], v[24:27]
	v_mfma_f32_16x16x32_bf16 v[28:31], v[158:161], v[198:201], v[28:31]
	v_mfma_f32_16x16x32_bf16 v[8:11], v[144:147], v[206:209], v[8:11]
	v_mfma_f32_16x16x32_bf16 v[12:15], v[158:161], v[206:209], v[12:15]
	v_mfma_f32_16x16x32_bf16 v[56:59], v[148:151], v[186:189], v[56:59]
	v_mfma_f32_16x16x32_bf16 v[60:63], v[162:165], v[186:189], v[60:63]
	v_mfma_f32_16x16x32_bf16 v[40:43], v[148:151], v[194:197], v[40:43]
	v_mfma_f32_16x16x32_bf16 v[44:47], v[162:165], v[194:197], v[44:47]
	v_mfma_f32_16x16x32_bf16 v[24:27], v[148:151], v[202:205], v[24:27]
	v_mfma_f32_16x16x32_bf16 v[28:31], v[162:165], v[202:205], v[28:31]
	v_mfma_f32_16x16x32_bf16 v[8:11], v[148:151], v[210:213], v[8:11]
	v_mfma_f32_16x16x32_bf16 v[12:15], v[162:165], v[210:213], v[12:15]
	v_mfma_f32_16x16x32_bf16 v[48:51], v[166:169], v[182:185], v[48:51]
	v_mfma_f32_16x16x32_bf16 v[52:55], v[174:177], v[182:185], v[52:55]
	v_mfma_f32_16x16x32_bf16 v[32:35], v[166:169], v[190:193], v[32:35]
	v_mfma_f32_16x16x32_bf16 v[36:39], v[174:177], v[190:193], v[36:39]
	v_mfma_f32_16x16x32_bf16 v[16:19], v[166:169], v[198:201], v[16:19]
	v_mfma_f32_16x16x32_bf16 v[20:23], v[174:177], v[198:201], v[20:23]
	v_mfma_f32_16x16x32_bf16 v[0:3], v[166:169], v[206:209], v[0:3]
	v_mfma_f32_16x16x32_bf16 v[4:7], v[174:177], v[206:209], v[4:7]
	v_mfma_f32_16x16x32_bf16 v[48:51], v[170:173], v[186:189], v[48:51]
	v_mfma_f32_16x16x32_bf16 v[52:55], v[178:181], v[186:189], v[52:55]
	v_mfma_f32_16x16x32_bf16 v[32:35], v[170:173], v[194:197], v[32:35]
	v_mfma_f32_16x16x32_bf16 v[36:39], v[178:181], v[194:197], v[36:39]
	v_mfma_f32_16x16x32_bf16 v[16:19], v[170:173], v[202:205], v[16:19]
	v_mfma_f32_16x16x32_bf16 v[20:23], v[178:181], v[202:205], v[20:23]
	v_mfma_f32_16x16x32_bf16 v[0:3], v[170:173], v[210:213], v[0:3]
	v_mfma_f32_16x16x32_bf16 v[4:7], v[178:181], v[210:213], v[4:7]
	s_barrier
	s_setprio 0
	s_add_i32 s43, s43, 2
	s_add_u32 s20, s20, 0x100
	s_addc_u32 s21, s21, 0
	s_add_u32 s41, s41, 0x100
	s_addc_u32 s42, s42, 0
.LBB0_1549:
	ds_read_b128 v[144:147], v155
	ds_read_b128 v[148:151], v155 offset:1024
	ds_read_b128 v[158:161], v155 offset:2048
	ds_read_b128 v[162:165], v155 offset:3072
	ds_read_b128 v[166:169], v156
	ds_read_b128 v[170:173], v156 offset:1024
	ds_read_b128 v[174:177], v156 offset:2048
	ds_read_b128 v[178:181], v156 offset:3072
	s_add_u32 s22, s20, 0xfff80080
	s_addc_u32 s23, s21, -1
	s_cmp_eq_u32 s43, 28
	s_cselect_b32 s25, s13, s23
	s_cselect_b32 s24, s39, s22
	s_cselect_b32 s23, s11, s42
	s_cselect_b32 s22, s40, s41
	s_add_u32 s44, s22, 0x80000
	s_addc_u32 s45, s23, 0
	s_add_i32 m0, s19, 0xc000
	ds_read_b128 v[182:185], v157
	ds_read_b128 v[186:189], v157 offset:1024
	ds_read_b128 v[190:193], v157 offset:2048
	ds_read_b128 v[194:197], v157 offset:3072
	ds_read_b128 v[198:201], v157 offset:4096
	ds_read_b128 v[202:205], v157 offset:5120
	ds_read_b128 v[206:209], v157 offset:6144
	ds_read_b128 v[210:213], v157 offset:7168
	global_load_lds_dwordx4 v136, s[20:21]
	s_add_i32 m0, s19, 0xe000
	s_nop 0
	global_load_lds_dwordx4 v138, s[20:21]
	s_waitcnt vmcnt(8) lgkmcnt(0)
	s_setprio 1
	s_barrier
; #define PG8_STAGE(bufoff, gbase, voff) do { _Pragma("unroll") for (int _i = 0; _i < 2; ++_i) \
;         __builtin_amdgcn_global_load_lds((const unsigned*)((const char*)(gbase) + (voff)[_i]), (PG8_LAS unsigned*)(lds + (bufoff) + ldsw + _i * 8192), 16, 0, 0); } while (0)
; #define PG8_LDA(dst, b, h) do { _Pragma("unroll") for (int m = 0; m < 4; ++m) _Pragma("unroll") for (int k = 0; k < 2; ++k) dst[m][k] = *(const PG8_LAS bf16x8*)(lds + PG8_SA(b, h) + aoff + m * 2048 + k * 1024); } while (0)
; #define PG8_MMA(ai, bj, At, Bt) do { __builtin_amdgcn_s_setprio(1); _Pragma("unroll") for (int m = 0; m < 4; ++m) _Pragma("unroll") for (int n = 0; n < 2; ++n) _Pragma("unroll") for (int k = 0; k < 2; ++k) \
;         acc[ai][bj][m][n] = __builtin_amdgcn_mfma_f32_16x16x32_bf16(Bt[n][k], At[m][k], acc[ai][bj][m][n], 0, 0, 0); __builtin_amdgcn_s_setprio(0); } while (0)
; #define PG8_WAIT_V(n) asm volatile("s_waitcnt vmcnt(" #n ")" ::: "memory")
; #define PG8_WAIT_L(n) asm volatile("s_waitcnt lgkmcnt(" #n ")" ::: "memory")
; #define PG8_BAR __builtin_amdgcn_s_barrier()
; #define PG8_SCHED __builtin_amdgcn_sched_barrier(0)
; template <class Epi, class Sched, bool ALIGN_EPI = false, bool SP2 = false>
; __device__ __forceinline__ void gemm_phase(PG8_LAS unsigned char* lds, const Gemm g, const Sched& S, const Epi& E) {
;     ...
;             PG8_WAIT_V(8); PG8_WAIT_L(0); PG8_BAR; PG8_MMA(0, 0, At, B0); PG8_MMA(0, 1, At, B1); PG8_BAR; PG8_SCHED;
;             PG8_LDA(At, 0, 1); PG8_STAGE(PG8_SB(0, 0), b2, voffB); PG8_STAGE(PG8_SB(0, 1), b2 + hstep, voffB); PG8_STAGE(PG8_SA(0, 0), a2, voffA);
;             PG8_WAIT_V(8); PG8_WAIT_L(0); PG8_BAR; PG8_MMA(1, 0, At, B0); PG8_MMA(1, 1, At, B1); PG8_BAR; PG8_SCHED;
	v_mfma_f32_16x16x32_bf16 v[124:127], v[144:147], v[182:185], v[124:127]
	v_mfma_f32_16x16x32_bf16 v[120:123], v[158:161], v[182:185], v[120:123]
	v_mfma_f32_16x16x32_bf16 v[108:111], v[144:147], v[190:193], v[108:111]
	v_mfma_f32_16x16x32_bf16 v[104:107], v[158:161], v[190:193], v[104:107]
	v_mfma_f32_16x16x32_bf16 v[88:91], v[144:147], v[198:201], v[88:91]
	v_mfma_f32_16x16x32_bf16 v[92:95], v[158:161], v[198:201], v[92:95]
	v_mfma_f32_16x16x32_bf16 v[72:75], v[144:147], v[206:209], v[72:75]
	v_mfma_f32_16x16x32_bf16 v[76:79], v[158:161], v[206:209], v[76:79]
	v_mfma_f32_16x16x32_bf16 v[124:127], v[148:151], v[186:189], v[124:127]
	v_mfma_f32_16x16x32_bf16 v[120:123], v[162:165], v[186:189], v[120:123]
	v_mfma_f32_16x16x32_bf16 v[108:111], v[148:151], v[194:197], v[108:111]
	v_mfma_f32_16x16x32_bf16 v[104:107], v[162:165], v[194:197], v[104:107]
	v_mfma_f32_16x16x32_bf16 v[88:91], v[148:151], v[202:205], v[88:91]
	v_mfma_f32_16x16x32_bf16 v[92:95], v[162:165], v[202:205], v[92:95]
	v_mfma_f32_16x16x32_bf16 v[72:75], v[148:151], v[210:213], v[72:75]
	v_mfma_f32_16x16x32_bf16 v[76:79], v[162:165], v[210:213], v[76:79]
	v_mfma_f32_16x16x32_bf16 v[116:119], v[166:169], v[182:185], v[116:119]
	v_mfma_f32_16x16x32_bf16 v[112:115], v[174:177], v[182:185], v[112:115]
	v_mfma_f32_16x16x32_bf16 v[96:99], v[166:169], v[190:193], v[96:99]
	v_mfma_f32_16x16x32_bf16 v[100:103], v[174:177], v[190:193], v[100:103]
	v_mfma_f32_16x16x32_bf16 v[80:83], v[166:169], v[198:201], v[80:83]
	v_mfma_f32_16x16x32_bf16 v[84:87], v[174:177], v[198:201], v[84:87]
	v_mfma_f32_16x16x32_bf16 v[64:67], v[166:169], v[206:209], v[64:67]
	v_mfma_f32_16x16x32_bf16 v[68:71], v[174:177], v[206:209], v[68:71]
	v_mfma_f32_16x16x32_bf16 v[116:119], v[170:173], v[186:189], v[116:119]
	v_mfma_f32_16x16x32_bf16 v[112:115], v[178:181], v[186:189], v[112:115]
	v_mfma_f32_16x16x32_bf16 v[96:99], v[170:173], v[194:197], v[96:99]
	v_mfma_f32_16x16x32_bf16 v[100:103], v[178:181], v[194:197], v[100:103]
	v_mfma_f32_16x16x32_bf16 v[80:83], v[170:173], v[202:205], v[80:83]
	v_mfma_f32_16x16x32_bf16 v[84:87], v[178:181], v[202:205], v[84:87]
	v_mfma_f32_16x16x32_bf16 v[64:67], v[170:173], v[210:213], v[64:67]
	v_mfma_f32_16x16x32_bf16 v[68:71], v[178:181], v[210:213], v[68:71]
	s_barrier
	s_setprio 0
	v_lshl_add_u64 v[214:215], s[22:23], 0, v[130:131]
	s_mov_b32 m0, s98
	ds_read_b128 v[182:185], v157 offset:16384
	ds_read_b128 v[186:189], v157 offset:17408
	ds_read_b128 v[190:193], v157 offset:18432
	ds_read_b128 v[194:197], v157 offset:19456
	ds_read_b128 v[198:201], v157 offset:20480
	ds_read_b128 v[202:205], v157 offset:21504
	ds_read_b128 v[206:209], v157 offset:22528
	ds_read_b128 v[210:213], v157 offset:23552
	global_load_lds_dwordx4 v[214:215], off
	s_add_i32 m0, s98, 0x2000
	v_lshl_add_u64 v[216:217], s[22:23], 0, v[134:135]
	global_load_lds_dwordx4 v[216:217], off
	s_mov_b32 m0, s99
	v_lshl_add_u64 v[220:221], s[24:25], 0, v[132:133]
	global_load_lds_dwordx4 v130, s[44:45]
	s_add_i32 m0, s99, 0x2000
	s_nop 0
	global_load_lds_dwordx4 v134, s[44:45]
	s_mov_b32 m0, s19
	v_lshl_add_u64 v[218:219], s[24:25], 0, v[128:129]
	global_load_lds_dwordx4 v[218:219], off
	s_mov_b32 m0, s28
	s_nop 0
	global_load_lds_dwordx4 v[220:221], off
	s_waitcnt vmcnt(8) lgkmcnt(0)
	s_setprio 1
	s_barrier
	v_mfma_f32_16x16x32_bf16 v[56:59], v[144:147], v[182:185], v[56:59]
	v_mfma_f32_16x16x32_bf16 v[60:63], v[158:161], v[182:185], v[60:63]
	v_mfma_f32_16x16x32_bf16 v[40:43], v[144:147], v[190:193], v[40:43]
	v_mfma_f32_16x16x32_bf16 v[44:47], v[158:161], v[190:193], v[44:47]
	v_mfma_f32_16x16x32_bf16 v[24:27], v[144:147], v[198:201], v[24:27]
	v_mfma_f32_16x16x32_bf16 v[28:31], v[158:161], v[198:201], v[28:31]
	v_mfma_f32_16x16x32_bf16 v[8:11], v[144:147], v[206:209], v[8:11]
	v_mfma_f32_16x16x32_bf16 v[12:15], v[158:161], v[206:209], v[12:15]
	v_mfma_f32_16x16x32_bf16 v[56:59], v[148:151], v[186:189], v[56:59]
	v_mfma_f32_16x16x32_bf16 v[60:63], v[162:165], v[186:189], v[60:63]
	v_mfma_f32_16x16x32_bf16 v[40:43], v[148:151], v[194:197], v[40:43]
	v_mfma_f32_16x16x32_bf16 v[44:47], v[162:165], v[194:197], v[44:47]
	v_mfma_f32_16x16x32_bf16 v[24:27], v[148:151], v[202:205], v[24:27]
	v_mfma_f32_16x16x32_bf16 v[28:31], v[162:165], v[202:205], v[28:31]
	v_mfma_f32_16x16x32_bf16 v[8:11], v[148:151], v[210:213], v[8:11]
	v_mfma_f32_16x16x32_bf16 v[12:15], v[162:165], v[210:213], v[12:15]
	v_mfma_f32_16x16x32_bf16 v[48:51], v[166:169], v[182:185], v[48:51]
	v_mfma_f32_16x16x32_bf16 v[52:55], v[174:177], v[182:185], v[52:55]
	v_mfma_f32_16x16x32_bf16 v[32:35], v[166:169], v[190:193], v[32:35]
	v_mfma_f32_16x16x32_bf16 v[36:39], v[174:177], v[190:193], v[36:39]
	v_mfma_f32_16x16x32_bf16 v[16:19], v[166:169], v[198:201], v[16:19]
	v_mfma_f32_16x16x32_bf16 v[20:23], v[174:177], v[198:201], v[20:23]
	v_mfma_f32_16x16x32_bf16 v[0:3], v[166:169], v[206:209], v[0:3]
	v_mfma_f32_16x16x32_bf16 v[4:7], v[174:177], v[206:209], v[4:7]
	v_mfma_f32_16x16x32_bf16 v[48:51], v[170:173], v[186:189], v[48:51]
	v_mfma_f32_16x16x32_bf16 v[52:55], v[178:181], v[186:189], v[52:55]
	v_mfma_f32_16x16x32_bf16 v[32:35], v[170:173], v[194:197], v[32:35]
	v_mfma_f32_16x16x32_bf16 v[36:39], v[178:181], v[194:197], v[36:39]
	v_mfma_f32_16x16x32_bf16 v[16:19], v[170:173], v[202:205], v[16:19]
	v_mfma_f32_16x16x32_bf16 v[20:23], v[178:181], v[202:205], v[20:23]
	v_mfma_f32_16x16x32_bf16 v[0:3], v[170:173], v[210:213], v[0:3]
	v_mfma_f32_16x16x32_bf16 v[4:7], v[178:181], v[210:213], v[4:7]
	s_barrier
; #define PG8_STAGE(bufoff, gbase, voff) do { _Pragma("unroll") for (int _i = 0; _i < 2; ++_i) \
;         __builtin_amdgcn_global_load_lds((const unsigned*)((const char*)(gbase) + (voff)[_i]), (PG8_LAS unsigned*)(lds + (bufoff) + ldsw + _i * 8192), 16, 0, 0); } while (0)
; #define PG8_LDA(dst, b, h) do { _Pragma("unroll") for (int m = 0; m < 4; ++m) _Pragma("unroll") for (int k = 0; k < 2; ++k) dst[m][k] = *(const PG8_LAS bf16x8*)(lds + PG8_SA(b, h) + aoff + m * 2048 + k * 1024); } while (0)
; #define PG8_LDB(dst, b, h) do { _Pragma("unroll") for (int n = 0; n < 2; ++n) _Pragma("unroll") for (int k = 0; k < 2; ++k) dst[n][k] = *(const PG8_LAS bf16x8*)(lds + PG8_SB(b, h) + boff + n * 2048 + k * 1024); } while (0)
; #define PG8_MMA(ai, bj, At, Bt) do { __builtin_amdgcn_s_setprio(1); _Pragma("unroll") for (int m = 0; m < 4; ++m) _Pragma("unroll") for (int n = 0; n < 2; ++n) _Pragma("unroll") for (int k = 0; k < 2; ++k) \
;         acc[ai][bj][m][n] = __builtin_amdgcn_mfma_f32_16x16x32_bf16(Bt[n][k], At[m][k], acc[ai][bj][m][n], 0, 0, 0); __builtin_amdgcn_s_setprio(0); } while (0)
; #define PG8_WAIT_V(n) asm volatile("s_waitcnt vmcnt(" #n ")" ::: "memory")
; #define PG8_WAIT_L(n) asm volatile("s_waitcnt lgkmcnt(" #n ")" ::: "memory")
; #define PG8_BAR __builtin_amdgcn_s_barrier()
; #define PG8_SCHED __builtin_amdgcn_sched_barrier(0)
; template <class Epi, class Sched, bool ALIGN_EPI = false, bool SP2 = false>
; __device__ __forceinline__ void gemm_phase(PG8_LAS unsigned char* lds, const Gemm g, const Sched& S, const Epi& E) {
;     ...
;             PG8_LDB(B0, 1, 0); PG8_LDB(B1, 1, 1); PG8_SCHED; PG8_LDA(At, 1, 0); PG8_STAGE(PG8_SA(0, 1), a2 + hstep, voffA);
;             PG8_WAIT_V(8); PG8_WAIT_L(0); PG8_BAR; PG8_MMA(0, 0, At, B0); PG8_MMA(0, 1, At, B1); PG8_BAR; PG8_SCHED;
;             PG8_LDA(At, 1, 1); PG8_STAGE(PG8_SB(1, 0), b3, voffB); PG8_STAGE(PG8_SB(1, 1), b3 + hstep, voffB); PG8_STAGE(PG8_SA(1, 0), a3, voffA);
;             PG8_WAIT_V(8); PG8_WAIT_L(0); PG8_BAR; PG8_MMA(1, 0, At, B0); PG8_MMA(1, 1, At, B1); PG8_BAR; PG8_SCHED;
;     ...
;         if constexpr (ALIGN_EPI) { if (wr == 0) PG8_BAR; }
	s_setprio 0
	s_add_i32 s44, 0, 0x18000
	s_add_i32 s45, 0, 0x1c000
	v_add_u32_e32 v162, s44, v153
	v_add_u32_e32 v178, s45, v153
	ds_read_b128 v[144:147], v162
	ds_read_b128 v[148:151], v162 offset:1024
	ds_read_b128 v[158:161], v162 offset:2048
	ds_read_b128 v[162:165], v162 offset:3072
	ds_read_b128 v[166:169], v178
	ds_read_b128 v[170:173], v178 offset:1024
	ds_read_b128 v[174:177], v178 offset:2048
	ds_read_b128 v[178:181], v178 offset:3072
	s_add_u32 s24, s24, 0x80000
	s_addc_u32 s25, s25, 0
	s_add_u32 s22, s22, 0x80080
	s_addc_u32 s23, s23, 0
	s_mov_b32 m0, s29
	ds_read_b128 v[182:185], v157 offset:32768
	ds_read_b128 v[186:189], v157 offset:33792
	ds_read_b128 v[190:193], v157 offset:34816
	ds_read_b128 v[194:197], v157 offset:35840
	ds_read_b128 v[198:201], v157 offset:36864
	ds_read_b128 v[202:205], v157 offset:37888
	ds_read_b128 v[206:209], v157 offset:38912
	ds_read_b128 v[210:213], v157 offset:39936
	global_load_lds_dwordx4 v128, s[24:25]
	s_mov_b32 m0, s30
	s_nop 0
	global_load_lds_dwordx4 v132, s[24:25]
	s_waitcnt vmcnt(8) lgkmcnt(0)
	s_setprio 1
	s_barrier
	v_mfma_f32_16x16x32_bf16 v[124:127], v[144:147], v[182:185], v[124:127]
	v_mfma_f32_16x16x32_bf16 v[120:123], v[158:161], v[182:185], v[120:123]
	v_mfma_f32_16x16x32_bf16 v[108:111], v[144:147], v[190:193], v[108:111]
	v_mfma_f32_16x16x32_bf16 v[104:107], v[158:161], v[190:193], v[104:107]
	v_mfma_f32_16x16x32_bf16 v[88:91], v[144:147], v[198:201], v[88:91]
	v_mfma_f32_16x16x32_bf16 v[92:95], v[158:161], v[198:201], v[92:95]
	v_mfma_f32_16x16x32_bf16 v[72:75], v[144:147], v[206:209], v[72:75]
	v_mfma_f32_16x16x32_bf16 v[76:79], v[158:161], v[206:209], v[76:79]
	v_mfma_f32_16x16x32_bf16 v[124:127], v[148:151], v[186:189], v[124:127]
	v_mfma_f32_16x16x32_bf16 v[120:123], v[162:165], v[186:189], v[120:123]
	v_mfma_f32_16x16x32_bf16 v[108:111], v[148:151], v[194:197], v[108:111]
	v_mfma_f32_16x16x32_bf16 v[104:107], v[162:165], v[194:197], v[104:107]
	v_mfma_f32_16x16x32_bf16 v[88:91], v[148:151], v[202:205], v[88:91]
	v_mfma_f32_16x16x32_bf16 v[92:95], v[162:165], v[202:205], v[92:95]
	v_mfma_f32_16x16x32_bf16 v[72:75], v[148:151], v[210:213], v[72:75]
	v_mfma_f32_16x16x32_bf16 v[76:79], v[162:165], v[210:213], v[76:79]
	v_mfma_f32_16x16x32_bf16 v[116:119], v[166:169], v[182:185], v[116:119]
	v_mfma_f32_16x16x32_bf16 v[112:115], v[174:177], v[182:185], v[112:115]
	v_mfma_f32_16x16x32_bf16 v[96:99], v[166:169], v[190:193], v[96:99]
	v_mfma_f32_16x16x32_bf16 v[100:103], v[174:177], v[190:193], v[100:103]
	v_mfma_f32_16x16x32_bf16 v[80:83], v[166:169], v[198:201], v[80:83]
	v_mfma_f32_16x16x32_bf16 v[84:87], v[174:177], v[198:201], v[84:87]
	v_mfma_f32_16x16x32_bf16 v[64:67], v[166:169], v[206:209], v[64:67]
	v_mfma_f32_16x16x32_bf16 v[68:71], v[174:177], v[206:209], v[68:71]
	v_mfma_f32_16x16x32_bf16 v[116:119], v[170:173], v[186:189], v[116:119]
	v_mfma_f32_16x16x32_bf16 v[112:115], v[178:181], v[186:189], v[112:115]
	v_mfma_f32_16x16x32_bf16 v[96:99], v[170:173], v[194:197], v[96:99]
	v_mfma_f32_16x16x32_bf16 v[100:103], v[178:181], v[194:197], v[100:103]
	v_mfma_f32_16x16x32_bf16 v[80:83], v[170:173], v[202:205], v[80:83]
	v_mfma_f32_16x16x32_bf16 v[84:87], v[178:181], v[202:205], v[84:87]
	v_mfma_f32_16x16x32_bf16 v[64:67], v[170:173], v[210:213], v[64:67]
	v_mfma_f32_16x16x32_bf16 v[68:71], v[178:181], v[210:213], v[68:71]
	s_barrier
	s_setprio 0
	v_lshl_add_u64 v[214:215], v[214:215], 0, s[4:5]
	s_mov_b32 m0, s100
	ds_read_b128 v[182:185], v157 offset:49152
	ds_read_b128 v[186:189], v157 offset:50176
	ds_read_b128 v[190:193], v157 offset:51200
	ds_read_b128 v[194:197], v157 offset:52224
	ds_read_b128 v[198:201], v157 offset:53248
	ds_read_b128 v[202:205], v157 offset:54272
	ds_read_b128 v[206:209], v157 offset:55296
	ds_read_b128 v[210:213], v157 offset:56320
	global_load_lds_dwordx4 v[214:215], off
	s_add_i32 m0, s100, 0x2000
	v_lshl_add_u64 v[214:215], v[216:217], 0, s[4:5]
	global_load_lds_dwordx4 v[214:215], off
	s_mov_b32 m0, s101
	s_nop 0
	global_load_lds_dwordx4 v130, s[22:23]
	s_add_i32 m0, s101, 0x2000
	v_lshl_add_u64 v[214:215], s[22:23], 0, v[134:135]
	global_load_lds_dwordx4 v[214:215], off
	s_mov_b32 m0, s33
	v_lshl_add_u64 v[214:215], v[218:219], 0, s[4:5]
	global_load_lds_dwordx4 v[214:215], off
	s_mov_b32 m0, s34
	v_lshl_add_u64 v[214:215], v[220:221], 0, s[4:5]
	global_load_lds_dwordx4 v[214:215], off
	s_waitcnt vmcnt(8) lgkmcnt(0)
	s_setprio 1
	s_barrier
	v_mfma_f32_16x16x32_bf16 v[56:59], v[144:147], v[182:185], v[56:59]
	v_mfma_f32_16x16x32_bf16 v[60:63], v[158:161], v[182:185], v[60:63]
	v_mfma_f32_16x16x32_bf16 v[40:43], v[144:147], v[190:193], v[40:43]
	v_mfma_f32_16x16x32_bf16 v[44:47], v[158:161], v[190:193], v[44:47]
	v_mfma_f32_16x16x32_bf16 v[24:27], v[144:147], v[198:201], v[24:27]
	v_mfma_f32_16x16x32_bf16 v[28:31], v[158:161], v[198:201], v[28:31]
	v_mfma_f32_16x16x32_bf16 v[8:11], v[144:147], v[206:209], v[8:11]
	v_mfma_f32_16x16x32_bf16 v[12:15], v[158:161], v[206:209], v[12:15]
	v_mfma_f32_16x16x32_bf16 v[56:59], v[148:151], v[186:189], v[56:59]
	v_mfma_f32_16x16x32_bf16 v[60:63], v[162:165], v[186:189], v[60:63]
	v_mfma_f32_16x16x32_bf16 v[40:43], v[148:151], v[194:197], v[40:43]
	v_mfma_f32_16x16x32_bf16 v[44:47], v[162:165], v[194:197], v[44:47]
	v_mfma_f32_16x16x32_bf16 v[24:27], v[148:151], v[202:205], v[24:27]
	v_mfma_f32_16x16x32_bf16 v[28:31], v[162:165], v[202:205], v[28:31]
	v_mfma_f32_16x16x32_bf16 v[8:11], v[148:151], v[210:213], v[8:11]
	v_mfma_f32_16x16x32_bf16 v[12:15], v[162:165], v[210:213], v[12:15]
	v_mfma_f32_16x16x32_bf16 v[48:51], v[166:169], v[182:185], v[48:51]
	v_mfma_f32_16x16x32_bf16 v[52:55], v[174:177], v[182:185], v[52:55]
	v_mfma_f32_16x16x32_bf16 v[32:35], v[166:169], v[190:193], v[32:35]
	v_mfma_f32_16x16x32_bf16 v[36:39], v[174:177], v[190:193], v[36:39]
	v_mfma_f32_16x16x32_bf16 v[16:19], v[166:169], v[198:201], v[16:19]
	v_mfma_f32_16x16x32_bf16 v[20:23], v[174:177], v[198:201], v[20:23]
	v_mfma_f32_16x16x32_bf16 v[0:3], v[166:169], v[206:209], v[0:3]
	v_mfma_f32_16x16x32_bf16 v[4:7], v[174:177], v[206:209], v[4:7]
	v_mfma_f32_16x16x32_bf16 v[48:51], v[170:173], v[186:189], v[48:51]
	v_mfma_f32_16x16x32_bf16 v[52:55], v[178:181], v[186:189], v[52:55]
	v_mfma_f32_16x16x32_bf16 v[32:35], v[170:173], v[194:197], v[32:35]
	v_mfma_f32_16x16x32_bf16 v[36:39], v[178:181], v[194:197], v[36:39]
	v_mfma_f32_16x16x32_bf16 v[16:19], v[170:173], v[202:205], v[16:19]
	v_mfma_f32_16x16x32_bf16 v[20:23], v[178:181], v[202:205], v[20:23]
	v_mfma_f32_16x16x32_bf16 v[0:3], v[170:173], v[210:213], v[0:3]
	v_mfma_f32_16x16x32_bf16 v[4:7], v[178:181], v[210:213], v[4:7]
	s_barrier
	s_setprio 0
	s_add_i32 s43, s43, 2
	s_add_u32 s20, s20, 0x100
	s_addc_u32 s21, s21, 0
	s_add_u32 s41, s41, 0x100
	s_addc_u32 s42, s42, 0
	s_cmp_gt_u32 s43, 29
	s_cbranch_scc0 .LBB0_1549
	s_and_b64 vcc, exec, s[6:7]
	s_cbranch_vccz .LBB0_1552
	s_barrier
